# canonicalizing v_max removal extended to all phases (HgIn epilogue etc.) + recurrence S-scaling VALU moved behind the batched LDS reads, on top of v51
# baseline (speedup 1.0000x reference)
.LBB0_907:
	s_andn2_b64 vcc, exec, s[0:1]
	v_readlane_b32 s64, v255, 23
	s_waitcnt lgkmcnt(0)
	s_barrier
	s_cbranch_vccnz .LBB0_912
	v_cmp_gt_u32_e32 vcc, 8, v204
	s_and_saveexec_b64 s[4:5], vcc
	s_cbranch_execz .LBB0_911
	s_lshl_b32 s0, s14, 9
	s_add_i32 s0, s0, 0
	s_add_i32 s0, s0, 0x10000
	v_add_u32_e32 v0, s0, v158
	ds_read2st64_b64 v[12:15], v0 offset0:1 offset1:2
	s_lshl_b32 s1, s84, 1
	s_or_b32 s1, s1, s25
	s_lshl_b32 s0, s14, 13
	s_waitcnt lgkmcnt(0)
	v_max_f32_e32 v1, v12, v12
	v_max_f32_e32 v3, v156, v1
	ds_read_b64 v[0:1], v0 offset:1536
	s_mul_hi_i32 s2, s1, 0x2100
	s_mulk_i32 s1, 0x2100
	v_readlane_b32 s3, v255, 44
	s_add_u32 s6, s3, s1
	s_waitcnt lgkmcnt(0)
	v_max3_f32 v3, v3, v14, v0
	v_sub_f32_e32 v12, v12, v3
	v_sub_f32_e32 v16, v156, v3
	v_mul_f32_e32 v12, 0x3dd53b94, v12
	s_addc_u32 s7, s76, s2
	s_add_i32 s0, s0, 0
	v_mul_f32_e32 v16, 0x3dd53b94, v16
	v_exp_f32_e32 v38, v12
	v_sub_f32_e32 v12, v14, v3
	v_add_u32_e32 v14, s0, v206
	v_exp_f32_e32 v36, v16
	ds_read_b128 v[16:19], v14 offset:15360
	v_mul_f32_e32 v12, 0x3dd53b94, v12
	v_exp_f32_e32 v12, v12
	v_sub_f32_e32 v0, v0, v3
	v_mul_f32_e32 v0, 0x3dd53b94, v0
	s_waitcnt lgkmcnt(0)
	v_pk_mul_f32 v[16:17], v[38:39], v[16:17] op_sel_hi:[0,1]
	v_pk_mul_f32 v[18:19], v[38:39], v[18:19] op_sel_hi:[0,1]
	v_pk_fma_f32 v[20:21], v[74:75], v[36:37], v[18:19] op_sel_hi:[1,0,1]
	v_pk_fma_f32 v[22:23], v[72:73], v[36:37], v[16:17] op_sel_hi:[1,0,1]
	ds_read_b128 v[16:19], v14 offset:23552
	v_exp_f32_e32 v0, v0
	s_lshl_b32 s0, s15, 7
	s_ashr_i32 s1, s0, 31
	s_cmp_lt_u32 s14, 4
	s_waitcnt lgkmcnt(0)
	v_pk_fma_f32 v[22:23], v[12:13], v[16:17], v[22:23] op_sel_hi:[0,1,1]
	v_pk_fma_f32 v[20:21], v[12:13], v[18:19], v[20:21] op_sel_hi:[0,1,1]
	ds_read_b128 v[16:19], v14 offset:31744
	v_cmp_gt_u32_e32 vcc, 16, v159
	s_waitcnt lgkmcnt(0)
	v_pk_fma_f32 v[18:19], v[0:1], v[18:19], v[20:21] op_sel_hi:[0,1,1]
	v_pk_fma_f32 v[16:17], v[0:1], v[16:17], v[22:23] op_sel_hi:[0,1,1]
	ds_read_b128 v[20:23], v14 offset:14336
	s_waitcnt lgkmcnt(0)
	v_pk_mul_f32 v[20:21], v[38:39], v[20:21] op_sel_hi:[0,1]
	v_pk_mul_f32 v[22:23], v[38:39], v[22:23] op_sel_hi:[0,1]
	v_pk_fma_f32 v[24:25], v[70:71], v[36:37], v[22:23] op_sel_hi:[1,0,1]
	v_pk_fma_f32 v[26:27], v[68:69], v[36:37], v[20:21] op_sel_hi:[1,0,1]
	ds_read_b128 v[20:23], v14 offset:22528
	s_waitcnt lgkmcnt(0)
	v_pk_fma_f32 v[26:27], v[12:13], v[20:21], v[26:27] op_sel_hi:[0,1,1]
	v_pk_fma_f32 v[24:25], v[12:13], v[22:23], v[24:25] op_sel_hi:[0,1,1]
	ds_read_b128 v[20:23], v14 offset:30720
	s_waitcnt lgkmcnt(0)
	v_pk_fma_f32 v[22:23], v[0:1], v[22:23], v[24:25] op_sel_hi:[0,1,1]
	v_pk_fma_f32 v[20:21], v[0:1], v[20:21], v[26:27] op_sel_hi:[0,1,1]
	ds_read_b128 v[24:27], v14 offset:13312
	s_waitcnt lgkmcnt(0)
	v_pk_mul_f32 v[24:25], v[38:39], v[24:25] op_sel_hi:[0,1]
	v_pk_mul_f32 v[26:27], v[38:39], v[26:27] op_sel_hi:[0,1]
	v_pk_fma_f32 v[28:29], v[66:67], v[36:37], v[26:27] op_sel_hi:[1,0,1]
	v_pk_fma_f32 v[30:31], v[64:65], v[36:37], v[24:25] op_sel_hi:[1,0,1]
	ds_read_b128 v[24:27], v14 offset:21504
	s_waitcnt lgkmcnt(0)
	v_pk_fma_f32 v[30:31], v[12:13], v[24:25], v[30:31] op_sel_hi:[0,1,1]
	v_pk_fma_f32 v[28:29], v[12:13], v[26:27], v[28:29] op_sel_hi:[0,1,1]
	ds_read_b128 v[24:27], v14 offset:29696
	s_waitcnt lgkmcnt(0)
	v_pk_fma_f32 v[26:27], v[0:1], v[26:27], v[28:29] op_sel_hi:[0,1,1]
	v_pk_fma_f32 v[24:25], v[0:1], v[24:25], v[30:31] op_sel_hi:[0,1,1]
	ds_read_b128 v[28:31], v14 offset:12288
	s_waitcnt lgkmcnt(0)
	v_pk_mul_f32 v[28:29], v[38:39], v[28:29] op_sel_hi:[0,1]
	v_pk_mul_f32 v[30:31], v[38:39], v[30:31] op_sel_hi:[0,1]
	v_pk_fma_f32 v[32:33], v[62:63], v[36:37], v[30:31] op_sel_hi:[1,0,1]
	v_pk_fma_f32 v[34:35], v[60:61], v[36:37], v[28:29] op_sel_hi:[1,0,1]
	ds_read_b128 v[28:31], v14 offset:20480
	s_waitcnt lgkmcnt(0)
	v_pk_fma_f32 v[34:35], v[12:13], v[28:29], v[34:35] op_sel_hi:[0,1,1]
	v_pk_fma_f32 v[32:33], v[12:13], v[30:31], v[32:33] op_sel_hi:[0,1,1]
	ds_read_b128 v[28:31], v14 offset:28672
	s_waitcnt lgkmcnt(0)
	v_pk_fma_f32 v[30:31], v[0:1], v[30:31], v[32:33] op_sel_hi:[0,1,1]
	v_pk_fma_f32 v[28:29], v[0:1], v[28:29], v[34:35] op_sel_hi:[0,1,1]
	ds_read_b128 v[32:35], v14 offset:11264
	s_waitcnt lgkmcnt(0)
	v_pk_mul_f32 v[32:33], v[38:39], v[32:33] op_sel_hi:[0,1]
	v_pk_mul_f32 v[34:35], v[38:39], v[34:35] op_sel_hi:[0,1]
	v_pk_fma_f32 v[40:41], v[58:59], v[36:37], v[34:35] op_sel_hi:[1,0,1]
	v_pk_fma_f32 v[42:43], v[56:57], v[36:37], v[32:33] op_sel_hi:[1,0,1]
	ds_read_b128 v[32:35], v14 offset:19456
	s_waitcnt lgkmcnt(0)
	v_pk_fma_f32 v[42:43], v[12:13], v[32:33], v[42:43] op_sel_hi:[0,1,1]
	v_pk_fma_f32 v[40:41], v[12:13], v[34:35], v[40:41] op_sel_hi:[0,1,1]
	ds_read_b128 v[32:35], v14 offset:27648
	s_waitcnt lgkmcnt(0)
	v_pk_fma_f32 v[34:35], v[0:1], v[34:35], v[40:41] op_sel_hi:[0,1,1]
	v_pk_fma_f32 v[32:33], v[0:1], v[32:33], v[42:43] op_sel_hi:[0,1,1]
	ds_read_b128 v[40:43], v14 offset:10240
	s_waitcnt lgkmcnt(0)
	v_pk_mul_f32 v[40:41], v[38:39], v[40:41] op_sel_hi:[0,1]
	v_pk_mul_f32 v[42:43], v[38:39], v[42:43] op_sel_hi:[0,1]
	v_pk_fma_f32 v[44:45], v[54:55], v[36:37], v[42:43] op_sel_hi:[1,0,1]
	v_pk_fma_f32 v[46:47], v[52:53], v[36:37], v[40:41] op_sel_hi:[1,0,1]
	ds_read_b128 v[40:43], v14 offset:18432
	s_waitcnt lgkmcnt(0)
	v_pk_fma_f32 v[46:47], v[12:13], v[40:41], v[46:47] op_sel_hi:[0,1,1]
	v_pk_fma_f32 v[44:45], v[12:13], v[42:43], v[44:45] op_sel_hi:[0,1,1]
	ds_read_b128 v[40:43], v14 offset:26624
	s_waitcnt lgkmcnt(0)
	v_pk_fma_f32 v[42:43], v[0:1], v[42:43], v[44:45] op_sel_hi:[0,1,1]
	v_pk_fma_f32 v[40:41], v[0:1], v[40:41], v[46:47] op_sel_hi:[0,1,1]
	ds_read_b128 v[44:47], v14 offset:9216
	s_waitcnt lgkmcnt(0)
	v_pk_mul_f32 v[44:45], v[38:39], v[44:45] op_sel_hi:[0,1]
	v_pk_mul_f32 v[46:47], v[38:39], v[46:47] op_sel_hi:[0,1]
	v_pk_fma_f32 v[46:47], v[10:11], v[36:37], v[46:47] op_sel_hi:[1,0,1]
	v_pk_fma_f32 v[44:45], v[8:9], v[36:37], v[44:45] op_sel_hi:[1,0,1]
	ds_read_b128 v[8:11], v14 offset:17408
	s_waitcnt lgkmcnt(0)
	v_pk_fma_f32 v[44:45], v[12:13], v[8:9], v[44:45] op_sel_hi:[0,1,1]
	v_pk_fma_f32 v[46:47], v[12:13], v[10:11], v[46:47] op_sel_hi:[0,1,1]
	ds_read_b128 v[8:11], v14 offset:25600
	s_waitcnt lgkmcnt(0)
	v_pk_fma_f32 v[10:11], v[0:1], v[10:11], v[46:47] op_sel_hi:[0,1,1]
	v_pk_fma_f32 v[8:9], v[0:1], v[8:9], v[44:45] op_sel_hi:[0,1,1]
	ds_read_b128 v[44:47], v14 offset:8192
	s_waitcnt lgkmcnt(0)
	v_pk_mul_f32 v[44:45], v[38:39], v[44:45] op_sel_hi:[0,1]
	v_pk_mul_f32 v[46:47], v[38:39], v[46:47] op_sel_hi:[0,1]
	v_pk_fma_f32 v[46:47], v[6:7], v[36:37], v[46:47] op_sel_hi:[1,0,1]
	v_pk_fma_f32 v[44:45], v[4:5], v[36:37], v[44:45] op_sel_hi:[1,0,1]
	ds_read_b128 v[4:7], v14 offset:16384
	s_waitcnt lgkmcnt(0)
	v_pk_fma_f32 v[44:45], v[12:13], v[4:5], v[44:45] op_sel_hi:[0,1,1]
	v_pk_fma_f32 v[46:47], v[12:13], v[6:7], v[46:47] op_sel_hi:[0,1,1]
	ds_read_b128 v[4:7], v14 offset:24576
	s_waitcnt lgkmcnt(0)
	v_pk_fma_f32 v[4:5], v[0:1], v[4:5], v[44:45] op_sel_hi:[0,1,1]
	v_lshlrev_b32_e32 v44, 10, v204
	v_mov_b32_e32 v45, v2
	v_lshl_add_u64 v[44:45], s[6:7], 0, v[44:45]
	v_pk_fma_f32 v[6:7], v[0:1], v[6:7], v[46:47] op_sel_hi:[0,1,1]
	v_lshl_add_u64 v[44:45], s[0:1], 2, v[44:45]
	v_lshlrev_b32_e32 v46, 4, v205
	v_mov_b32_e32 v47, v2
	s_cselect_b64 s[0:1], -1, 0
	v_lshl_add_u64 v[44:45], v[44:45], 0, v[46:47]
	s_and_b64 s[0:1], s[0:1], vcc
	global_store_dwordx4 v[44:45], v[4:7], off
	global_store_dwordx4 v[44:45], v[8:11], off offset:64
	global_store_dwordx4 v[44:45], v[40:43], off offset:128
	global_store_dwordx4 v[44:45], v[32:35], off offset:192
	global_store_dwordx4 v[44:45], v[28:31], off offset:256
	global_store_dwordx4 v[44:45], v[24:27], off offset:320
	global_store_dwordx4 v[44:45], v[20:23], off offset:384
	global_store_dwordx4 v[44:45], v[16:19], off offset:448
	s_and_b64 exec, exec, s[0:1]
	s_cbranch_execz .LBB0_911
	v_mul_f32_e32 v4, v13, v38
	v_fmac_f32_e32 v4, v157, v36
	v_fmac_f32_e32 v4, v15, v12
	v_fmac_f32_e32 v4, v1, v0
	v_lshlrev_b32_e32 v0, 2, v204
	v_mov_b32_e32 v1, v2
	v_lshl_add_u64 v[0:1], s[6:7], 0, v[0:1]
	v_add_co_u32_e32 v0, vcc, 0x2000, v0
	s_nop 1
	v_addc_co_u32_e32 v1, vcc, 0, v1, vcc
	global_store_dword v[0:1], v3, off
	global_store_dword v[0:1], v4, off offset:32

.LBB0_1148:
	global_load_dwordx4 v[48:51], v[78:79], off
	global_load_dwordx4 v[44:47], v[82:83], off
	global_load_dwordx4 v[40:43], v[84:85], off
	v_mul_f32_e64 v58, |v56|, s69
	v_max_f32_e32 v59, v56, v56
	v_mul_f32_e64 v60, |v57|, s69
	v_exp_f32_e32 v67, v58
	v_min_f32_e32 v62, 0, v59
	v_exp_f32_e32 v59, v60
	v_max_f32_e32 v61, v57, v57
	v_mul_f32_e64 v66, |v55|, s69
	v_cmp_lt_f32_e32 vcc, 0, v57
	v_min_f32_e32 v63, 0, v61
	v_exp_f32_e32 v69, v66
	v_add_f32_e32 v66, 1.0, v67
	v_cndmask_b32_e32 v61, 1.0, v59, vcc
	v_cmp_lt_f32_e32 vcc, 0, v56
	v_add_f32_e32 v70, 1.0, v59
	v_cmp_gt_f32_e64 s[4:5], s74, v70
	v_cndmask_b32_e32 v60, 1.0, v67, vcc
	v_cmp_gt_f32_e32 vcc, s74, v66
	v_cndmask_b32_e64 v67, 0, 32, s[4:5]
	v_ldexp_f32 v67, v70, v67
	v_cndmask_b32_e64 v59, 0, 32, vcc
	v_ldexp_f32 v59, v66, v59
	v_log_f32_e32 v59, v59
	v_log_f32_e32 v67, v67
	v_mul_f32_e64 v64, |v54|, s69
	v_exp_f32_e32 v68, v64
	v_mul_f32_e32 v75, 0x3f317217, v59
	v_mul_f32_e32 v87, 0x3f317217, v67
	v_fma_f32 v75, v59, s75, -v75
	v_fma_f32 v87, v67, s75, -v87
	v_fmac_f32_e32 v75, 0x3377d1cf, v59
	v_rcp_f32_e32 v64, v66
	v_cndmask_b32_e32 v66, 0, v226, vcc
	v_fmac_f32_e32 v87, 0x3377d1cf, v67
	v_fmac_f32_e32 v75, 0x3f317217, v59
	v_cmp_lt_f32_e64 vcc, |v59|, s63
	v_max_f32_e32 v65, v54, v54
	v_add_f32_e32 v71, 1.0, v68
	v_fmac_f32_e32 v87, 0x3f317217, v67
	v_cndmask_b32_e32 v59, v59, v75, vcc
	v_cmp_lt_f32_e64 vcc, |v67|, s63
	v_min_f32_e32 v58, 0, v65
	v_rcp_f32_e32 v65, v70
	v_cmp_gt_f32_e64 s[6:7], s74, v71
	v_cndmask_b32_e64 v70, 0, v226, s[4:5]
	v_cndmask_b32_e32 v67, v67, v87, vcc
	v_cndmask_b32_e64 v73, 0, 32, s[6:7]
	v_sub_f32_e32 v66, v59, v66
	v_sub_f32_e32 v67, v67, v70
	v_ldexp_f32 v73, v71, v73
	v_pk_add_f32 v[62:63], v[62:63], v[66:67] neg_lo:[0,1] neg_hi:[0,1]
	v_log_f32_e32 v73, v73
	v_add_f32_e32 v72, 1.0, v69
	v_cndmask_b32_e64 v74, 0, v226, s[6:7]
	v_mul_f32_e32 v88, 0x3f317217, v73
	v_fma_f32 v88, v73, s75, -v88
	v_fmac_f32_e32 v88, 0x3377d1cf, v73
	v_fmac_f32_e32 v88, 0x3f317217, v73
	v_cmp_lt_f32_e64 vcc, |v73|, s63
	s_waitcnt vmcnt(2)
	v_pk_add_f32 v[62:63], v[62:63], v[48:49]
	s_waitcnt vmcnt(1)
	v_pk_add_f32 v[48:49], v[62:63], v[44:45] neg_lo:[0,1] neg_hi:[0,1]
	v_max_f32_e32 v59, v44, v44
	v_mul_f32_e64 v44, |v48|, s69
	v_max_f32_e32 v66, v45, v45
	v_mul_f32_e64 v45, |v49|, s69
	v_exp_f32_e32 v67, v44
	v_exp_f32_e32 v70, v45
	v_max_f32_e32 v44, v62, v59
	v_cndmask_b32_e32 v73, v73, v88, vcc
	v_add_f32_e32 v59, 1.0, v67
	v_add_f32_e32 v62, 1.0, v70
	v_cmp_gt_f32_e32 vcc, s74, v59
	v_max_f32_e32 v45, v63, v66
	v_cmp_gt_f32_e64 s[4:5], s74, v62
	v_cndmask_b32_e64 v63, 0, 32, vcc
	v_ldexp_f32 v59, v59, v63
	v_cndmask_b32_e64 v66, 0, 32, s[4:5]
	v_ldexp_f32 v62, v62, v66
	v_log_f32_e32 v59, v59
	v_log_f32_e32 v62, v62
	v_cndmask_b32_e32 v63, 0, v226, vcc
	v_cndmask_b32_e64 v66, 0, v226, s[4:5]
	v_mul_f32_e32 v67, 0x3f317217, v59
	v_mul_f32_e32 v70, 0x3f317217, v62
	v_fma_f32 v67, v59, s75, -v67
	v_fma_f32 v70, v62, s75, -v70
	v_fmac_f32_e32 v67, 0x3377d1cf, v59
	v_fmac_f32_e32 v70, 0x3377d1cf, v62
	v_fmac_f32_e32 v67, 0x3f317217, v59
	v_cmp_lt_f32_e64 vcc, |v59|, s63
	v_fmac_f32_e32 v70, 0x3f317217, v62
	s_waitcnt vmcnt(0)
	v_pk_mul_f32 v[40:41], v[60:61], v[40:41]
	v_cndmask_b32_e32 v59, v59, v67, vcc
	v_cmp_lt_f32_e64 vcc, |v62|, s63
	v_sub_f32_e32 v67, v59, v63
	v_pk_mul_f32 v[40:41], v[64:65], v[40:41]
	v_cndmask_b32_e32 v62, v62, v70, vcc
	v_cmp_gt_f32_e32 vcc, s74, v72
	v_sub_f32_e32 v66, v62, v66
	v_sub_f32_e32 v62, v73, v74
	v_cndmask_b32_e64 v59, 0, 32, vcc
	v_ldexp_f32 v59, v72, v59
	v_log_f32_e32 v63, v59
	v_max_f32_e32 v59, v55, v55
	v_min_f32_e32 v59, 0, v59
	v_rcp_f32_e32 v60, v71
	v_mul_f32_e32 v70, 0x3f317217, v63
	v_fma_f32 v70, v63, s75, -v70
	v_fmac_f32_e32 v70, 0x3377d1cf, v63
	v_fmac_f32_e32 v70, 0x3f317217, v63
	v_cmp_lt_f32_e64 s[4:5], |v63|, s63
	v_cvt_pk_bf16_f32 v40, v40, v41
	s_nop 0
	v_cndmask_b32_e64 v63, v63, v70, s[4:5]
	v_cndmask_b32_e32 v70, 0, v226, vcc
	v_sub_f32_e32 v63, v63, v70
	v_pk_add_f32 v[58:59], v[58:59], v[62:63] neg_lo:[0,1] neg_hi:[0,1]
	s_nop 0
	v_pk_add_f32 v[50:51], v[58:59], v[50:51]
	s_nop 0
	v_pk_add_f32 v[58:59], v[50:51], v[46:47] neg_lo:[0,1] neg_hi:[0,1]
	v_mul_f32_e64 v62, |v58|, s69
	v_exp_f32_e32 v62, v62
	v_mul_f32_e64 v63, |v59|, s69
	v_exp_f32_e32 v63, v63
	v_max_f32_e32 v46, v50, v46
	v_add_f32_e32 v61, 1.0, v62
	v_cmp_gt_f32_e32 vcc, s74, v61
	v_add_f32_e32 v63, 1.0, v63
	v_cndmask_b32_e64 v62, 0, 32, vcc
	v_ldexp_f32 v61, v61, v62
	v_log_f32_e32 v62, v61
	v_max_f32_e32 v47, v51, v47
	v_rcp_f32_e32 v61, v72
	v_mul_f32_e32 v50, 0x3f317217, v62
	v_fma_f32 v50, v62, s75, -v50
	v_fmac_f32_e32 v50, 0x3377d1cf, v62
	v_fmac_f32_e32 v50, 0x3f317217, v62
	v_cmp_lt_f32_e64 s[4:5], |v62|, s63
	s_nop 1
	v_cndmask_b32_e64 v50, v62, v50, s[4:5]
	v_cndmask_b32_e32 v62, 0, v226, vcc
	v_cmp_gt_f32_e32 vcc, s74, v63
	v_sub_f32_e32 v50, v50, v62
	s_nop 0
	v_cndmask_b32_e64 v64, 0, 32, vcc
	v_ldexp_f32 v63, v63, v64
	v_log_f32_e32 v63, v63
	v_cndmask_b32_e32 v62, 0, v226, vcc
	v_cmp_lt_f32_e64 vcc, |v49|, s49
	v_mul_f32_e32 v51, 0x3f317217, v63
	v_fma_f32 v51, v63, s75, -v51
	v_fmac_f32_e32 v51, 0x3377d1cf, v63
	v_fmac_f32_e32 v51, 0x3f317217, v63
	v_cmp_lt_f32_e64 s[4:5], |v63|, s63
	v_cndmask_b32_e32 v49, 0, v66, vcc
	v_cmp_lt_f32_e64 vcc, |v48|, s49
	v_cndmask_b32_e64 v51, v63, v51, s[4:5]
	v_sub_f32_e32 v51, v51, v62
	v_cndmask_b32_e32 v48, 0, v67, vcc
	v_cmp_lt_f32_e64 vcc, |v59|, s49
	v_pk_add_f32 v[44:45], v[44:45], v[48:49]
	s_nop 0
	v_cndmask_b32_e32 v51, 0, v51, vcc
	v_cmp_lt_f32_e64 vcc, |v58|, s49
	s_nop 1
	v_cndmask_b32_e32 v50, 0, v50, vcc
	v_cmp_lt_f32_e32 vcc, 0, v55
	v_pk_add_f32 v[46:47], v[46:47], v[50:51]
	s_nop 0
	v_cndmask_b32_e32 v49, 1.0, v69, vcc
	v_cmp_lt_f32_e32 vcc, 0, v54
	s_nop 1
	v_cndmask_b32_e32 v48, 1.0, v68, vcc
	v_pk_mul_f32 v[42:43], v[48:49], v[42:43]
	v_lshl_add_u64 v[48:49], v[52:53], 2, s[94:95]
	v_pk_mul_f32 v[42:43], v[60:61], v[42:43]
	global_store_dwordx4 v[48:49], v[44:47], off
	v_cvt_pk_bf16_f32 v41, v42, v43
	s_nop 0
	v_lshl_add_u64 v[44:45], v[52:53], 1, s[84:85]
	global_store_dwordx2 v[44:45], v[40:41], off

.LBB0_1213:
	v_mov_b32_e32 v195, v2
	v_or_b32_e32 v170, 4, v194
	v_or_b32_e32 v169, 8, v194
	v_or_b32_e32 v168, 12, v194
	s_and_b64 vcc, exec, s[2:3]
	s_cbranch_vccz .LBB0_1230
	s_mov_b64 s[0:1], -1
	s_and_b64 vcc, exec, s[14:15]
	s_cbranch_vccz .LBB0_1216
	v_lshlrev_b32_e32 v124, 2, v194
	global_load_dwordx4 v[160:163], v124, s[86:87]
	global_load_dwordx4 v[156:159], v124, s[66:67]
	global_load_dwordx4 v[164:167], v124, s[56:57]
	v_mul_f32_e64 v125, |v152|, s69
	v_mul_f32_e64 v129, |v153|, s69
	v_exp_f32_e32 v125, v125
	v_exp_f32_e32 v146, v129
	v_mul_f32_e64 v137, |v154|, s69
	v_max_f32_e32 v142, v154, v154
	v_cmp_lt_f32_e32 vcc, 0, v153
	v_max_f32_e32 v136, v153, v153
	v_mul_f32_e64 v143, |v155|, s69
	v_exp_f32_e32 v171, v137
	v_min_f32_e32 v124, 0, v142
	v_add_f32_e32 v142, 1.0, v125
	v_cndmask_b32_e32 v137, 1.0, v146, vcc
	v_cmp_lt_f32_e32 vcc, 0, v152
	v_min_f32_e32 v129, 0, v136
	v_exp_f32_e32 v180, v143
	v_add_f32_e32 v143, 1.0, v146
	v_cndmask_b32_e32 v136, 1.0, v125, vcc
	v_cmp_gt_f32_e32 vcc, s74, v142
	v_cmp_gt_f32_e64 s[10:11], s74, v143
	v_rcp_f32_e32 v147, v143
	v_cndmask_b32_e64 v125, 0, 32, vcc
	v_cndmask_b32_e64 v150, 0, 32, s[10:11]
	v_ldexp_f32 v125, v142, v125
	v_ldexp_f32 v143, v143, v150
	v_log_f32_e32 v125, v125
	v_log_f32_e32 v143, v143
	v_rcp_f32_e32 v146, v142
	v_cndmask_b32_e32 v142, 0, v226, vcc
	v_mul_f32_e32 v184, 0x3f317217, v125
	v_mul_f32_e32 v185, 0x3f317217, v143
	v_fma_f32 v184, v125, s75, -v184
	v_fma_f32 v185, v143, s75, -v185
	v_fmac_f32_e32 v184, 0x3377d1cf, v125
	v_fmac_f32_e32 v185, 0x3377d1cf, v143
	v_fmac_f32_e32 v184, 0x3f317217, v125
	v_cmp_lt_f32_e64 vcc, |v125|, s63
	v_add_f32_e32 v181, 1.0, v171
	v_fmac_f32_e32 v185, 0x3f317217, v143
	v_cndmask_b32_e32 v125, v125, v184, vcc
	v_cmp_lt_f32_e64 vcc, |v143|, s63
	v_max_f32_e32 v128, v152, v152
	v_cmp_gt_f32_e64 s[12:13], s74, v181
	v_cndmask_b32_e64 v150, 0, v226, s[10:11]
	v_cndmask_b32_e32 v143, v143, v185, vcc
	v_min_f32_e32 v128, 0, v128
	v_cndmask_b32_e64 v151, 0, 32, s[12:13]
	v_sub_f32_e32 v142, v125, v142
	v_sub_f32_e32 v143, v143, v150
	v_ldexp_f32 v151, v181, v151
	v_pk_add_f32 v[128:129], v[128:129], v[142:143] neg_lo:[0,1] neg_hi:[0,1]
	v_log_f32_e32 v151, v151
	v_add_f32_e32 v182, 1.0, v180
	v_cndmask_b32_e64 v183, 0, v226, s[12:13]
	s_mov_b64 s[0:1], 0
	v_mul_f32_e32 v186, 0x3f317217, v151
	v_fma_f32 v186, v151, s75, -v186
	v_fmac_f32_e32 v186, 0x3377d1cf, v151
	v_fmac_f32_e32 v186, 0x3f317217, v151
	v_cmp_lt_f32_e64 vcc, |v151|, s63
	s_waitcnt vmcnt(0)
	v_pk_add_f32 v[128:129], v[128:129], v[160:161]
	s_nop 0
	v_pk_add_f32 v[142:143], v[128:129], v[156:157] neg_lo:[0,1] neg_hi:[0,1]
	v_max_f32_e32 v125, v156, v156
	v_mul_f32_e64 v156, |v142|, s69
	v_max_f32_e32 v150, v157, v157
	v_mul_f32_e64 v157, |v143|, s69
	v_exp_f32_e32 v156, v156
	v_exp_f32_e32 v157, v157
	v_max_f32_e32 v128, v128, v125
	v_cndmask_b32_e32 v151, v151, v186, vcc
	v_add_f32_e32 v125, 1.0, v156
	v_max_f32_e32 v129, v129, v150
	v_add_f32_e32 v150, 1.0, v157
	v_cmp_gt_f32_e32 vcc, s74, v125
	v_cmp_gt_f32_e64 s[10:11], s74, v150
	s_nop 0
	v_cndmask_b32_e64 v156, 0, 32, vcc
	v_cndmask_b32_e64 v157, 0, 32, s[10:11]
	v_ldexp_f32 v125, v125, v156
	v_ldexp_f32 v150, v150, v157
	v_log_f32_e32 v125, v125
	v_log_f32_e32 v150, v150
	v_cndmask_b32_e32 v156, 0, v226, vcc
	v_cndmask_b32_e64 v157, 0, v226, s[10:11]
	v_mul_f32_e32 v160, 0x3f317217, v125
	v_mul_f32_e32 v161, 0x3f317217, v150
	v_fma_f32 v160, v125, s75, -v160
	v_fma_f32 v161, v150, s75, -v161
	v_fmac_f32_e32 v160, 0x3377d1cf, v125
	v_fmac_f32_e32 v161, 0x3377d1cf, v150
	v_fmac_f32_e32 v160, 0x3f317217, v125
	v_cmp_lt_f32_e64 vcc, |v125|, s63
	v_fmac_f32_e32 v161, 0x3f317217, v150
	s_nop 0
	v_cndmask_b32_e32 v125, v125, v160, vcc
	v_cmp_lt_f32_e64 vcc, |v150|, s63
	v_sub_f32_e32 v160, v125, v156
	s_nop 0
	v_cndmask_b32_e32 v150, v150, v161, vcc
	v_cmp_gt_f32_e32 vcc, s74, v182
	v_sub_f32_e32 v161, v150, v157
	v_sub_f32_e32 v150, v151, v183
	v_cndmask_b32_e64 v125, 0, 32, vcc
	v_ldexp_f32 v125, v182, v125
	v_log_f32_e32 v156, v125
	v_max_f32_e32 v125, v155, v155
	v_min_f32_e32 v125, 0, v125
	v_mul_f32_e32 v151, 0x3f317217, v156
	v_fma_f32 v151, v156, s75, -v151
	v_fmac_f32_e32 v151, 0x3377d1cf, v156
	v_fmac_f32_e32 v151, 0x3f317217, v156
	v_cmp_lt_f32_e64 s[10:11], |v156|, s63
	s_nop 1
	v_cndmask_b32_e64 v151, v156, v151, s[10:11]
	v_cndmask_b32_e32 v156, 0, v226, vcc
	v_sub_f32_e32 v151, v151, v156
	v_pk_add_f32 v[124:125], v[124:125], v[150:151] neg_lo:[0,1] neg_hi:[0,1]
	s_nop 0
	v_pk_add_f32 v[150:151], v[124:125], v[162:163]
	s_nop 0
	v_pk_add_f32 v[156:157], v[150:151], v[158:159] neg_lo:[0,1] neg_hi:[0,1]
	s_nop 0
	v_mul_f32_e64 v124, |v156|, s69
	v_exp_f32_e32 v162, v124
	v_pk_mul_f32 v[124:125], v[136:137], v[164:165]
	v_rcp_f32_e32 v136, v181
	v_pk_mul_f32 v[124:125], v[146:147], v[124:125]
	v_add_f32_e32 v137, 1.0, v162
	v_cmp_gt_f32_e32 vcc, s74, v137
	s_nop 1
	v_cndmask_b32_e64 v146, 0, 32, vcc
	v_ldexp_f32 v137, v137, v146
	v_log_f32_e32 v147, v137
	v_max_f32_e32 v146, v158, v158
	v_mul_f32_e64 v158, |v157|, s69
	v_exp_f32_e32 v158, v158
	v_max_f32_e32 v146, v150, v146
	v_mul_f32_e32 v150, 0x3f317217, v147
	v_fma_f32 v150, v147, s75, -v150
	v_fmac_f32_e32 v150, 0x3377d1cf, v147
	v_fmac_f32_e32 v150, 0x3f317217, v147
	v_cmp_lt_f32_e64 s[10:11], |v147|, s63
	v_add_f32_e32 v158, 1.0, v158
	v_rcp_f32_e32 v137, v182
	v_cndmask_b32_e64 v147, v147, v150, s[10:11]
	v_cndmask_b32_e32 v150, 0, v226, vcc
	v_cmp_gt_f32_e32 vcc, s74, v158
	v_sub_f32_e32 v150, v147, v150
	v_cndmask_b32_e64 v162, 0, 32, vcc
	v_ldexp_f32 v158, v158, v162
	v_log_f32_e32 v158, v158
	v_max_f32_e32 v147, v151, v159
	v_mul_f32_e32 v151, 0x3f317217, v158
	v_fma_f32 v151, v158, s75, -v151
	v_fmac_f32_e32 v151, 0x3377d1cf, v158
	v_fmac_f32_e32 v151, 0x3f317217, v158
	v_cmp_lt_f32_e64 s[10:11], |v158|, s63
	s_nop 1
	v_cndmask_b32_e64 v151, v158, v151, s[10:11]
	v_cndmask_b32_e32 v158, 0, v226, vcc
	v_cmp_lt_f32_e64 vcc, |v143|, s49
	v_sub_f32_e32 v151, v151, v158
	s_nop 0
	v_cndmask_b32_e32 v143, 0, v161, vcc
	v_cmp_lt_f32_e64 vcc, |v142|, s49
	s_nop 1
	v_cndmask_b32_e32 v142, 0, v160, vcc
	v_cmp_lt_f32_e64 vcc, |v157|, s49
	s_nop 1
	v_cndmask_b32_e32 v151, 0, v151, vcc
	v_cmp_lt_f32_e64 vcc, |v156|, s49
	v_pk_add_f32 v[156:157], v[128:129], v[142:143]
	s_nop 0
	v_cndmask_b32_e32 v150, 0, v150, vcc
	v_cmp_lt_f32_e32 vcc, 0, v155
	v_pk_add_f32 v[158:159], v[146:147], v[150:151]
	s_nop 0
	v_cndmask_b32_e32 v129, 1.0, v180, vcc
	v_cmp_lt_f32_e32 vcc, 0, v154
	s_nop 1
	v_cndmask_b32_e32 v128, 1.0, v171, vcc
	v_pk_mul_f32 v[128:129], v[128:129], v[166:167]
	s_nop 0
	v_pk_mul_f32 v[128:129], v[136:137], v[128:129]
	v_lshl_add_u64 v[136:137], v[210:211], 2, s[94:95]
	global_store_dwordx4 v[136:137], v[156:159], off

.LBB0_1218:
	s_add_u32 s0, s22, s0
	s_addc_u32 s1, s23, s1
	v_lshl_add_u64 v[136:137], v[210:211], 1, s[0:1]
	v_cvt_pk_bf16_f32 v124, v124, v125
	v_cvt_pk_bf16_f32 v125, v128, v129
	v_mov_b32_e32 v209, v208
	global_store_dwordx2 v[136:137], v[124:125], off
	v_pk_mul_f32 v[124:125], v[138:139], v[208:209]
	s_mov_b64 s[0:1], -1
	s_and_b64 vcc, exec, s[14:15]
	s_cbranch_vccz .LBB0_1220
	v_lshlrev_b32_e32 v128, 2, v194
	v_lshlrev_b32_e32 v142, 2, v170
	global_load_dwordx4 v[150:153], v128, s[86:87] offset:16
	global_load_dwordx4 v[136:139], v142, s[66:67]
	global_load_dwordx4 v[154:157], v142, s[56:57]
	v_mul_f32_e64 v143, |v148|, s69
	v_max_f32_e32 v146, v148, v148
	v_mul_f32_e64 v147, |v149|, s69
	v_exp_f32_e32 v143, v143
	v_min_f32_e32 v158, 0, v146
	v_exp_f32_e32 v146, v147
	v_mul_f32_e64 v162, |v125|, s69
	v_exp_f32_e32 v165, v162
	v_add_f32_e32 v162, 1.0, v143
	v_cmp_lt_f32_e32 vcc, 0, v149
	v_add_f32_e32 v163, 1.0, v146
	v_cmp_gt_f32_e64 s[10:11], s74, v162
	v_cndmask_b32_e32 v147, 1.0, v146, vcc
	v_cmp_lt_f32_e32 vcc, 0, v148
	v_cmp_gt_f32_e64 s[12:13], s74, v163
	v_max_f32_e32 v161, v124, v124
	v_cndmask_b32_e32 v146, 1.0, v143, vcc
	v_cndmask_b32_e64 v143, 0, 32, s[10:11]
	v_cndmask_b32_e64 v167, 0, 32, s[12:13]
	v_ldexp_f32 v143, v162, v143
	v_min_f32_e32 v142, 0, v161
	v_rcp_f32_e32 v161, v163
	v_ldexp_f32 v163, v163, v167
	v_log_f32_e32 v143, v143
	v_mul_f32_e64 v160, |v124|, s69
	v_log_f32_e32 v163, v163
	v_exp_f32_e32 v164, v160
	v_mul_f32_e32 v180, 0x3f317217, v143
	v_fma_f32 v180, v143, s75, -v180
	v_mul_f32_e32 v181, 0x3f317217, v163
	v_add_f32_e32 v166, 1.0, v164
	v_fma_f32 v181, v163, s75, -v181
	v_fmac_f32_e32 v180, 0x3377d1cf, v143
	v_rcp_f32_e32 v160, v162
	v_cmp_gt_f32_e32 vcc, s74, v166
	v_cndmask_b32_e64 v162, 0, v226, s[10:11]
	v_fmac_f32_e32 v181, 0x3377d1cf, v163
	v_fmac_f32_e32 v180, 0x3f317217, v143
	v_cmp_lt_f32_e64 s[10:11], |v143|, s63
	v_cndmask_b32_e64 v171, 0, 32, vcc
	v_fmac_f32_e32 v181, 0x3f317217, v163
	v_cndmask_b32_e64 v143, v143, v180, s[10:11]
	v_cmp_lt_f32_e64 s[10:11], |v163|, s63
	v_max_f32_e32 v159, v149, v149
	v_ldexp_f32 v167, v166, v171
	v_cndmask_b32_e64 v171, 0, v226, s[12:13]
	v_cndmask_b32_e64 v163, v163, v181, s[10:11]
	v_min_f32_e32 v159, 0, v159
	v_sub_f32_e32 v162, v143, v162
	v_sub_f32_e32 v163, v163, v171
	v_pk_add_f32 v[158:159], v[158:159], v[162:163] neg_lo:[0,1] neg_hi:[0,1]
	v_log_f32_e32 v167, v167
	v_or_b32_e32 v128, v206, v170
	v_mov_b32_e32 v129, v207
	v_lshl_add_u64 v[128:129], v[128:129], 2, s[94:95]
	v_mul_f32_e32 v182, 0x3f317217, v167
	v_fma_f32 v182, v167, s75, -v182
	v_fmac_f32_e32 v182, 0x3377d1cf, v167
	v_fmac_f32_e32 v182, 0x3f317217, v167
	v_cmp_lt_f32_e64 s[10:11], |v167|, s63
	s_mov_b64 s[0:1], 0
	s_waitcnt vmcnt(0)
	v_pk_add_f32 v[150:151], v[158:159], v[150:151]
	s_nop 0
	v_pk_add_f32 v[158:159], v[150:151], v[136:137] neg_lo:[0,1] neg_hi:[0,1]
	v_max_f32_e32 v143, v136, v136
	v_mul_f32_e64 v136, |v158|, s69
	v_max_f32_e32 v162, v137, v137
	v_mul_f32_e64 v137, |v159|, s69
	v_exp_f32_e32 v136, v136
	v_exp_f32_e32 v137, v137
	v_cndmask_b32_e64 v167, v167, v182, s[10:11]
	v_max_f32_e32 v150, v150, v143
	v_add_f32_e32 v136, 1.0, v136
	v_add_f32_e32 v137, 1.0, v137
	v_cmp_gt_f32_e64 s[10:11], s74, v136
	v_cmp_gt_f32_e64 s[12:13], s74, v137
	v_max_f32_e32 v151, v151, v162
	v_cndmask_b32_e64 v143, 0, 32, s[10:11]
	v_cndmask_b32_e64 v162, 0, 32, s[12:13]
	v_ldexp_f32 v136, v136, v143
	v_ldexp_f32 v137, v137, v162
	v_log_f32_e32 v136, v136
	v_log_f32_e32 v137, v137
	v_cndmask_b32_e64 v143, 0, v226, s[10:11]
	v_cndmask_b32_e64 v162, 0, v226, s[12:13]
	v_mul_f32_e32 v163, 0x3f317217, v136
	v_mul_f32_e32 v171, 0x3f317217, v137
	v_fma_f32 v163, v136, s75, -v163
	v_fma_f32 v171, v137, s75, -v171
	v_fmac_f32_e32 v163, 0x3377d1cf, v136
	v_fmac_f32_e32 v171, 0x3377d1cf, v137
	v_fmac_f32_e32 v163, 0x3f317217, v136
	v_cmp_lt_f32_e64 s[10:11], |v136|, s63
	v_fmac_f32_e32 v171, 0x3f317217, v137
	s_nop 0
	v_cndmask_b32_e64 v136, v136, v163, s[10:11]
	v_cmp_lt_f32_e64 s[10:11], |v137|, s63
	v_sub_f32_e32 v163, v136, v143
	v_cndmask_b32_e32 v136, 0, v226, vcc
	v_cndmask_b32_e64 v137, v137, v171, s[10:11]
	v_add_f32_e32 v171, 1.0, v165
	v_cmp_gt_f32_e32 vcc, s74, v171
	v_sub_f32_e32 v162, v137, v162
	v_sub_f32_e32 v136, v167, v136
	v_cndmask_b32_e64 v137, 0, 32, vcc
	v_ldexp_f32 v137, v171, v137
	v_log_f32_e32 v137, v137
	v_max_f32_e32 v143, v125, v125
	v_min_f32_e32 v143, 0, v143
	v_mul_f32_e32 v167, 0x3f317217, v137
	v_fma_f32 v167, v137, s75, -v167
	v_fmac_f32_e32 v167, 0x3377d1cf, v137
	v_fmac_f32_e32 v167, 0x3f317217, v137
	v_cmp_lt_f32_e64 s[10:11], |v137|, s63
	s_nop 1
	v_cndmask_b32_e64 v137, v137, v167, s[10:11]
	v_cndmask_b32_e32 v167, 0, v226, vcc
	v_sub_f32_e32 v137, v137, v167
	v_pk_add_f32 v[136:137], v[142:143], v[136:137] neg_lo:[0,1] neg_hi:[0,1]
	s_nop 0
	v_pk_add_f32 v[142:143], v[136:137], v[152:153]
	s_nop 0
	v_pk_add_f32 v[152:153], v[142:143], v[138:139] neg_lo:[0,1] neg_hi:[0,1]
	v_mul_f32_e64 v136, |v152|, s69
	v_exp_f32_e32 v167, v136
	v_pk_mul_f32 v[136:137], v[146:147], v[154:155]
	v_mul_f32_e64 v155, |v153|, s69
	v_exp_f32_e32 v155, v155
	v_add_f32_e32 v147, 1.0, v167
	v_cmp_gt_f32_e32 vcc, s74, v147
	v_max_f32_e32 v138, v142, v138
	v_add_f32_e32 v155, 1.0, v155
	v_cndmask_b32_e64 v154, 0, 32, vcc
	v_ldexp_f32 v147, v147, v154
	v_log_f32_e32 v154, v147
	v_pk_mul_f32 v[136:137], v[160:161], v[136:137]
	v_max_f32_e32 v139, v143, v139
	v_mul_f32_e32 v142, 0x3f317217, v154
	v_fma_f32 v142, v154, s75, -v142
	v_fmac_f32_e32 v142, 0x3377d1cf, v154
	v_fmac_f32_e32 v142, 0x3f317217, v154
	v_cmp_lt_f32_e64 s[10:11], |v154|, s63
	v_rcp_f32_e32 v146, v166
	v_rcp_f32_e32 v147, v171
	v_cndmask_b32_e64 v142, v154, v142, s[10:11]
	v_cndmask_b32_e32 v154, 0, v226, vcc
	v_cmp_gt_f32_e32 vcc, s74, v155
	v_sub_f32_e32 v154, v142, v154
	s_nop 0
	v_cndmask_b32_e64 v160, 0, 32, vcc
	v_ldexp_f32 v155, v155, v160
	v_log_f32_e32 v155, v155
	v_cndmask_b32_e32 v143, 0, v226, vcc
	v_cmp_lt_f32_e64 vcc, |v159|, s49
	v_mul_f32_e32 v142, 0x3f317217, v155
	v_fma_f32 v142, v155, s75, -v142
	v_fmac_f32_e32 v142, 0x3377d1cf, v155
	v_fmac_f32_e32 v142, 0x3f317217, v155
	v_cmp_lt_f32_e64 s[10:11], |v155|, s63
	s_nop 1
	v_cndmask_b32_e64 v142, v155, v142, s[10:11]
	v_sub_f32_e32 v155, v142, v143
	v_cndmask_b32_e32 v143, 0, v162, vcc
	v_cmp_lt_f32_e64 vcc, |v158|, s49
	s_nop 1
	v_cndmask_b32_e32 v142, 0, v163, vcc
	v_cmp_lt_f32_e64 vcc, |v153|, s49
	v_pk_add_f32 v[150:151], v[150:151], v[142:143]
	s_nop 0
	v_cndmask_b32_e32 v153, 0, v155, vcc
	v_cmp_lt_f32_e64 vcc, |v152|, s49
	s_nop 1
	v_cndmask_b32_e32 v152, 0, v154, vcc
	v_cmp_lt_f32_e32 vcc, 0, v125
	v_pk_add_f32 v[152:153], v[138:139], v[152:153]
	global_store_dwordx4 v[128:129], v[150:153], off
	v_cndmask_b32_e32 v139, 1.0, v165, vcc
	v_cmp_lt_f32_e32 vcc, 0, v124
	s_nop 1
	v_cndmask_b32_e32 v138, 1.0, v164, vcc
	v_pk_mul_f32 v[138:139], v[138:139], v[156:157]
	s_nop 0
	v_pk_mul_f32 v[138:139], v[146:147], v[138:139]

.LBB0_1222:
	s_add_u32 s0, s22, s0
	s_addc_u32 s1, s23, s1
	v_lshl_add_u64 v[124:125], v[206:207], 0, v[194:195]
	v_mov_b32_e32 v209, v208
	v_lshl_add_u64 v[128:129], v[124:125], 1, s[0:1]
	v_cvt_pk_bf16_f32 v136, v136, v137
	v_cvt_pk_bf16_f32 v137, v138, v139
	v_pk_mul_f32 v[142:143], v[130:131], v[208:209]
	s_mov_b64 s[0:1], -1
	s_and_b64 vcc, exec, s[14:15]
	global_store_dwordx2 v[128:129], v[136:137], off offset:8
	s_cbranch_vccz .LBB0_1224
	v_lshlrev_b32_e32 v128, 2, v194
	v_lshlrev_b32_e32 v146, 2, v169
	global_load_dwordx4 v[136:139], v128, s[86:87] offset:32
	s_nop 0
	global_load_dwordx4 v[128:131], v146, s[66:67]
	v_mul_f32_e64 v152, |v144|, s69
	global_load_dwordx4 v[146:149], v146, s[56:57]
	v_max_f32_e32 v153, v144, v144
	v_mul_f32_e64 v154, |v145|, s69
	v_exp_f32_e32 v161, v152
	v_min_f32_e32 v156, 0, v153
	v_exp_f32_e32 v153, v154
	v_mul_f32_e64 v160, |v143|, s69
	v_exp_f32_e32 v163, v160
	v_add_f32_e32 v160, 1.0, v161
	v_max_f32_e32 v155, v145, v145
	v_add_f32_e32 v164, 1.0, v153
	v_cmp_lt_f32_e32 vcc, 0, v145
	v_cmp_gt_f32_e64 s[10:11], s74, v160
	v_min_f32_e32 v157, 0, v155
	v_cndmask_b32_e32 v155, 1.0, v153, vcc
	v_cmp_lt_f32_e32 vcc, 0, v144
	v_cndmask_b32_e64 v153, 0, 32, s[10:11]
	v_cmp_gt_f32_e64 s[12:13], s74, v164
	v_cndmask_b32_e32 v154, 1.0, v161, vcc
	v_ldexp_f32 v153, v160, v153
	v_cndmask_b32_e64 v161, 0, 32, s[12:13]
	v_ldexp_f32 v161, v164, v161
	v_log_f32_e32 v153, v153
	v_mul_f32_e64 v158, |v142|, s69
	v_log_f32_e32 v161, v161
	v_exp_f32_e32 v162, v158
	v_mul_f32_e32 v167, 0x3f317217, v153
	v_fma_f32 v167, v153, s75, -v167
	v_mul_f32_e32 v171, 0x3f317217, v161
	v_add_f32_e32 v165, 1.0, v162
	v_fma_f32 v171, v161, s75, -v171
	v_fmac_f32_e32 v167, 0x3377d1cf, v153
	v_rcp_f32_e32 v158, v160
	v_cmp_gt_f32_e32 vcc, s74, v165
	v_cndmask_b32_e64 v160, 0, v226, s[10:11]
	v_fmac_f32_e32 v171, 0x3377d1cf, v161
	v_fmac_f32_e32 v167, 0x3f317217, v153
	v_cmp_lt_f32_e64 s[10:11], |v153|, s63
	v_max_f32_e32 v159, v142, v142
	v_cndmask_b32_e64 v166, 0, 32, vcc
	v_fmac_f32_e32 v171, 0x3f317217, v161
	v_cndmask_b32_e64 v153, v153, v167, s[10:11]
	v_cmp_lt_f32_e64 s[10:11], |v161|, s63
	v_min_f32_e32 v152, 0, v159
	v_rcp_f32_e32 v159, v164
	v_ldexp_f32 v164, v165, v166
	v_cndmask_b32_e64 v166, 0, v226, s[12:13]
	v_cndmask_b32_e64 v161, v161, v171, s[10:11]
	v_sub_f32_e32 v160, v153, v160
	v_sub_f32_e32 v161, v161, v166
	v_pk_add_f32 v[156:157], v[156:157], v[160:161] neg_lo:[0,1] neg_hi:[0,1]
	v_log_f32_e32 v164, v164
	v_or_b32_e32 v150, v206, v169
	v_mov_b32_e32 v151, v207
	s_mov_b64 s[0:1], 0
	v_mul_f32_e32 v180, 0x3f317217, v164
	v_fma_f32 v180, v164, s75, -v180
	v_fmac_f32_e32 v180, 0x3377d1cf, v164
	v_fmac_f32_e32 v180, 0x3f317217, v164
	v_cmp_lt_f32_e64 s[10:11], |v164|, s63
	s_waitcnt vmcnt(0)
	v_pk_add_f32 v[136:137], v[156:157], v[136:137]
	s_nop 0
	v_pk_add_f32 v[156:157], v[136:137], v[128:129] neg_lo:[0,1] neg_hi:[0,1]
	v_max_f32_e32 v153, v128, v128
	v_mul_f32_e64 v128, |v156|, s69
	v_max_f32_e32 v160, v129, v129
	v_mul_f32_e64 v129, |v157|, s69
	v_exp_f32_e32 v128, v128
	v_exp_f32_e32 v129, v129
	v_cndmask_b32_e64 v164, v164, v180, s[10:11]
	v_max_f32_e32 v136, v136, v153
	v_add_f32_e32 v128, 1.0, v128
	v_add_f32_e32 v129, 1.0, v129
	v_cmp_gt_f32_e64 s[10:11], s74, v128
	v_cmp_gt_f32_e64 s[12:13], s74, v129
	v_max_f32_e32 v137, v137, v160
	v_cndmask_b32_e64 v153, 0, 32, s[10:11]
	v_cndmask_b32_e64 v160, 0, 32, s[12:13]
	v_ldexp_f32 v128, v128, v153
	v_ldexp_f32 v129, v129, v160
	v_log_f32_e32 v128, v128
	v_log_f32_e32 v129, v129
	v_cndmask_b32_e64 v153, 0, v226, s[10:11]
	v_cndmask_b32_e64 v160, 0, v226, s[12:13]
	v_mul_f32_e32 v161, 0x3f317217, v128
	v_mul_f32_e32 v166, 0x3f317217, v129
	v_fma_f32 v161, v128, s75, -v161
	v_fma_f32 v166, v129, s75, -v166
	v_fmac_f32_e32 v161, 0x3377d1cf, v128
	v_fmac_f32_e32 v166, 0x3377d1cf, v129
	v_fmac_f32_e32 v161, 0x3f317217, v128
	v_cmp_lt_f32_e64 s[10:11], |v128|, s63
	v_fmac_f32_e32 v166, 0x3f317217, v129
	s_nop 0
	v_cndmask_b32_e64 v128, v128, v161, s[10:11]
	v_cmp_lt_f32_e64 s[10:11], |v129|, s63
	v_sub_f32_e32 v161, v128, v153
	v_cndmask_b32_e32 v128, 0, v226, vcc
	v_cndmask_b32_e64 v129, v129, v166, s[10:11]
	v_add_f32_e32 v166, 1.0, v163
	v_cmp_gt_f32_e32 vcc, s74, v166
	v_sub_f32_e32 v160, v129, v160
	v_sub_f32_e32 v128, v164, v128
	v_cndmask_b32_e64 v129, 0, 32, vcc
	v_ldexp_f32 v129, v166, v129
	v_log_f32_e32 v129, v129
	v_max_f32_e32 v153, v143, v143
	v_min_f32_e32 v153, 0, v153
	v_mul_f32_e32 v164, 0x3f317217, v129
	v_fma_f32 v164, v129, s75, -v164
	v_fmac_f32_e32 v164, 0x3377d1cf, v129
	v_fmac_f32_e32 v164, 0x3f317217, v129
	v_cmp_lt_f32_e64 s[10:11], |v129|, s63
	s_nop 1
	v_cndmask_b32_e64 v129, v129, v164, s[10:11]
	v_cndmask_b32_e32 v164, 0, v226, vcc
	v_sub_f32_e32 v129, v129, v164
	v_pk_add_f32 v[128:129], v[152:153], v[128:129] neg_lo:[0,1] neg_hi:[0,1]
	s_nop 0
	v_pk_add_f32 v[138:139], v[128:129], v[138:139]
	s_nop 0
	v_pk_add_f32 v[152:153], v[138:139], v[130:131] neg_lo:[0,1] neg_hi:[0,1]
	v_mul_f32_e64 v128, |v152|, s69
	v_exp_f32_e32 v164, v128
	v_pk_mul_f32 v[128:129], v[154:155], v[146:147]
	v_mul_f32_e64 v155, |v153|, s69
	v_exp_f32_e32 v155, v155
	v_add_f32_e32 v147, 1.0, v164
	v_cmp_gt_f32_e32 vcc, s74, v147
	v_max_f32_e32 v130, v138, v130
	v_add_f32_e32 v155, 1.0, v155
	v_cndmask_b32_e64 v154, 0, 32, vcc
	v_ldexp_f32 v147, v147, v154
	v_log_f32_e32 v154, v147
	v_pk_mul_f32 v[128:129], v[158:159], v[128:129]
	v_max_f32_e32 v131, v139, v131
	v_mul_f32_e32 v138, 0x3f317217, v154
	v_fma_f32 v138, v154, s75, -v138
	v_fmac_f32_e32 v138, 0x3377d1cf, v154
	v_fmac_f32_e32 v138, 0x3f317217, v154
	v_cmp_lt_f32_e64 s[10:11], |v154|, s63
	v_rcp_f32_e32 v146, v165
	v_rcp_f32_e32 v147, v166
	v_cndmask_b32_e64 v138, v154, v138, s[10:11]
	v_cndmask_b32_e32 v154, 0, v226, vcc
	v_cmp_gt_f32_e32 vcc, s74, v155
	v_sub_f32_e32 v138, v138, v154
	s_nop 0
	v_cndmask_b32_e64 v158, 0, 32, vcc
	v_ldexp_f32 v155, v155, v158
	v_log_f32_e32 v155, v155
	v_cndmask_b32_e32 v154, 0, v226, vcc
	v_cmp_lt_f32_e64 vcc, |v157|, s49
	v_mul_f32_e32 v139, 0x3f317217, v155
	v_fma_f32 v139, v155, s75, -v139
	v_fmac_f32_e32 v139, 0x3377d1cf, v155
	v_fmac_f32_e32 v139, 0x3f317217, v155
	v_cmp_lt_f32_e64 s[10:11], |v155|, s63
	s_nop 1
	v_cndmask_b32_e64 v139, v155, v139, s[10:11]
	v_cndmask_b32_e32 v155, 0, v160, vcc
	v_cmp_lt_f32_e64 vcc, |v156|, s49
	v_sub_f32_e32 v139, v139, v154
	s_nop 0
	v_cndmask_b32_e32 v154, 0, v161, vcc
	v_cmp_lt_f32_e64 vcc, |v153|, s49
	v_pk_add_f32 v[136:137], v[136:137], v[154:155]
	s_nop 0
	v_cndmask_b32_e32 v139, 0, v139, vcc
	v_cmp_lt_f32_e64 vcc, |v152|, s49
	s_nop 1
	v_cndmask_b32_e32 v138, 0, v138, vcc
	v_cmp_lt_f32_e32 vcc, 0, v143
	v_pk_add_f32 v[138:139], v[130:131], v[138:139]
	s_nop 0
	v_cndmask_b32_e32 v131, 1.0, v163, vcc
	v_cmp_lt_f32_e32 vcc, 0, v142
	s_nop 1
	v_cndmask_b32_e32 v130, 1.0, v162, vcc
	v_pk_mul_f32 v[130:131], v[130:131], v[148:149]
	s_nop 0
	v_pk_mul_f32 v[130:131], v[146:147], v[130:131]
	v_lshl_add_u64 v[146:147], v[150:151], 2, s[94:95]
	global_store_dwordx4 v[146:147], v[136:139], off

.LBB0_1226:
	s_add_u32 s0, s22, s0
	s_addc_u32 s1, s23, s1
	v_mov_b32_e32 v209, v208
	v_lshl_add_u64 v[124:125], v[124:125], 1, s[0:1]
	v_cvt_pk_bf16_f32 v128, v128, v129
	v_cvt_pk_bf16_f32 v129, v130, v131
	v_or_b32_e32 v206, v206, v168
	v_pk_mul_f32 v[142:143], v[126:127], v[208:209]
	s_mov_b64 s[0:1], -1
	s_and_b64 vcc, exec, s[14:15]
	global_store_dwordx2 v[124:125], v[128:129], off offset:16
	s_cbranch_vccz .LBB0_1228
	v_lshlrev_b32_e32 v124, 2, v194
	v_lshlrev_b32_e32 v136, 2, v168
	global_load_dwordx4 v[128:131], v124, s[86:87] offset:48
	s_nop 0
	global_load_dwordx4 v[124:127], v136, s[66:67]
	v_mul_f32_e64 v144, |v140|, s69
	global_load_dwordx4 v[136:139], v136, s[56:57]
	v_max_f32_e32 v145, v140, v140
	v_mul_f32_e64 v146, |v141|, s69
	v_exp_f32_e32 v153, v144
	v_min_f32_e32 v148, 0, v145
	v_exp_f32_e32 v145, v146
	v_max_f32_e32 v147, v141, v141
	v_mul_f32_e64 v152, |v143|, s69
	v_cmp_lt_f32_e32 vcc, 0, v141
	v_min_f32_e32 v149, 0, v147
	v_exp_f32_e32 v155, v152
	v_add_f32_e32 v152, 1.0, v153
	v_cndmask_b32_e32 v147, 1.0, v145, vcc
	v_cmp_lt_f32_e32 vcc, 0, v140
	v_add_f32_e32 v156, 1.0, v145
	v_cmp_gt_f32_e64 s[10:11], s74, v156
	v_cndmask_b32_e32 v146, 1.0, v153, vcc
	v_cmp_gt_f32_e32 vcc, s74, v152
	v_cndmask_b32_e64 v153, 0, 32, s[10:11]
	v_ldexp_f32 v153, v156, v153
	v_cndmask_b32_e64 v145, 0, 32, vcc
	v_ldexp_f32 v145, v152, v145
	v_log_f32_e32 v145, v145
	v_log_f32_e32 v153, v153
	v_mul_f32_e64 v150, |v142|, s69
	v_exp_f32_e32 v154, v150
	v_mul_f32_e32 v161, 0x3f317217, v145
	v_mul_f32_e32 v162, 0x3f317217, v153
	v_fma_f32 v161, v145, s75, -v161
	v_fma_f32 v162, v153, s75, -v162
	v_fmac_f32_e32 v161, 0x3377d1cf, v145
	v_rcp_f32_e32 v150, v152
	v_cndmask_b32_e32 v152, 0, v226, vcc
	v_fmac_f32_e32 v162, 0x3377d1cf, v153
	v_fmac_f32_e32 v161, 0x3f317217, v145
	v_cmp_lt_f32_e64 vcc, |v145|, s63
	v_max_f32_e32 v151, v142, v142
	v_add_f32_e32 v157, 1.0, v154
	v_fmac_f32_e32 v162, 0x3f317217, v153
	v_cndmask_b32_e32 v145, v145, v161, vcc
	v_cmp_lt_f32_e64 vcc, |v153|, s63
	v_min_f32_e32 v144, 0, v151
	v_rcp_f32_e32 v151, v156
	v_cmp_gt_f32_e64 s[12:13], s74, v157
	v_cndmask_b32_e64 v156, 0, v226, s[10:11]
	v_cndmask_b32_e32 v153, v153, v162, vcc
	v_cndmask_b32_e64 v159, 0, 32, s[12:13]
	v_sub_f32_e32 v152, v145, v152
	v_sub_f32_e32 v153, v153, v156
	v_ldexp_f32 v159, v157, v159
	v_pk_add_f32 v[148:149], v[148:149], v[152:153] neg_lo:[0,1] neg_hi:[0,1]
	v_log_f32_e32 v159, v159
	v_add_f32_e32 v158, 1.0, v155
	v_cndmask_b32_e64 v160, 0, v226, s[12:13]
	s_mov_b64 s[0:1], 0
	v_mul_f32_e32 v163, 0x3f317217, v159
	v_fma_f32 v163, v159, s75, -v163
	v_fmac_f32_e32 v163, 0x3377d1cf, v159
	v_fmac_f32_e32 v163, 0x3f317217, v159
	v_cmp_lt_f32_e64 vcc, |v159|, s63
	s_waitcnt vmcnt(0)
	v_pk_add_f32 v[148:149], v[148:149], v[128:129]
	s_nop 0
	v_pk_add_f32 v[128:129], v[148:149], v[124:125] neg_lo:[0,1] neg_hi:[0,1]
	v_max_f32_e32 v145, v124, v124
	v_mul_f32_e64 v124, |v128|, s69
	v_max_f32_e32 v152, v125, v125
	v_mul_f32_e64 v125, |v129|, s69
	v_exp_f32_e32 v153, v124
	v_exp_f32_e32 v156, v125
	v_max_f32_e32 v124, v148, v145
	v_cndmask_b32_e32 v159, v159, v163, vcc
	v_add_f32_e32 v145, 1.0, v153
	v_add_f32_e32 v148, 1.0, v156
	v_cmp_gt_f32_e32 vcc, s74, v145
	v_max_f32_e32 v125, v149, v152
	v_cmp_gt_f32_e64 s[10:11], s74, v148
	v_cndmask_b32_e64 v149, 0, 32, vcc
	v_ldexp_f32 v145, v145, v149
	v_cndmask_b32_e64 v152, 0, 32, s[10:11]
	v_ldexp_f32 v148, v148, v152
	v_log_f32_e32 v145, v145
	v_log_f32_e32 v148, v148
	v_cndmask_b32_e32 v149, 0, v226, vcc
	v_cndmask_b32_e64 v152, 0, v226, s[10:11]
	v_mul_f32_e32 v153, 0x3f317217, v145
	v_mul_f32_e32 v156, 0x3f317217, v148
	v_fma_f32 v153, v145, s75, -v153
	v_fma_f32 v156, v148, s75, -v156
	v_fmac_f32_e32 v153, 0x3377d1cf, v145
	v_fmac_f32_e32 v156, 0x3377d1cf, v148
	v_fmac_f32_e32 v153, 0x3f317217, v145
	v_cmp_lt_f32_e64 vcc, |v145|, s63
	v_fmac_f32_e32 v156, 0x3f317217, v148
	v_pk_mul_f32 v[136:137], v[146:147], v[136:137]
	v_cndmask_b32_e32 v145, v145, v153, vcc
	v_cmp_lt_f32_e64 vcc, |v148|, s63
	v_sub_f32_e32 v153, v145, v149
	v_pk_mul_f32 v[136:137], v[150:151], v[136:137]
	v_cndmask_b32_e32 v148, v148, v156, vcc
	v_cmp_gt_f32_e32 vcc, s74, v158
	v_sub_f32_e32 v152, v148, v152
	v_sub_f32_e32 v148, v159, v160
	v_cndmask_b32_e64 v145, 0, 32, vcc
	v_ldexp_f32 v145, v158, v145
	v_log_f32_e32 v149, v145
	v_max_f32_e32 v145, v143, v143
	v_min_f32_e32 v145, 0, v145
	v_rcp_f32_e32 v146, v157
	v_mul_f32_e32 v156, 0x3f317217, v149
	v_fma_f32 v156, v149, s75, -v156
	v_fmac_f32_e32 v156, 0x3377d1cf, v149
	v_fmac_f32_e32 v156, 0x3f317217, v149
	v_cmp_lt_f32_e64 s[10:11], |v149|, s63
	s_nop 1
	v_cndmask_b32_e64 v149, v149, v156, s[10:11]
	v_cndmask_b32_e32 v156, 0, v226, vcc
	v_sub_f32_e32 v149, v149, v156
	v_pk_add_f32 v[144:145], v[144:145], v[148:149] neg_lo:[0,1] neg_hi:[0,1]
	s_nop 0
	v_pk_add_f32 v[130:131], v[144:145], v[130:131]
	s_nop 0
	v_pk_add_f32 v[144:145], v[130:131], v[126:127] neg_lo:[0,1] neg_hi:[0,1]
	v_mul_f32_e64 v148, |v144|, s69
	v_exp_f32_e32 v148, v148
	v_mul_f32_e64 v149, |v145|, s69
	v_exp_f32_e32 v149, v149
	v_max_f32_e32 v126, v130, v126
	v_add_f32_e32 v147, 1.0, v148
	v_cmp_gt_f32_e32 vcc, s74, v147
	v_add_f32_e32 v149, 1.0, v149
	v_cndmask_b32_e64 v148, 0, 32, vcc
	v_ldexp_f32 v147, v147, v148
	v_log_f32_e32 v148, v147
	v_max_f32_e32 v127, v131, v127
	v_rcp_f32_e32 v147, v158
	v_mul_f32_e32 v130, 0x3f317217, v148
	v_fma_f32 v130, v148, s75, -v130
	v_fmac_f32_e32 v130, 0x3377d1cf, v148
	v_fmac_f32_e32 v130, 0x3f317217, v148
	v_cmp_lt_f32_e64 s[10:11], |v148|, s63
	s_nop 1
	v_cndmask_b32_e64 v130, v148, v130, s[10:11]
	v_cndmask_b32_e32 v148, 0, v226, vcc
	v_cmp_gt_f32_e32 vcc, s74, v149
	v_sub_f32_e32 v130, v130, v148
	s_nop 0
	v_cndmask_b32_e64 v150, 0, 32, vcc
	v_ldexp_f32 v149, v149, v150
	v_log_f32_e32 v149, v149
	v_cndmask_b32_e32 v148, 0, v226, vcc
	v_cmp_lt_f32_e64 vcc, |v129|, s49
	v_mul_f32_e32 v131, 0x3f317217, v149
	v_fma_f32 v131, v149, s75, -v131
	v_fmac_f32_e32 v131, 0x3377d1cf, v149
	v_fmac_f32_e32 v131, 0x3f317217, v149
	v_cmp_lt_f32_e64 s[10:11], |v149|, s63
	v_cndmask_b32_e32 v129, 0, v152, vcc
	v_cmp_lt_f32_e64 vcc, |v128|, s49
	v_cndmask_b32_e64 v131, v149, v131, s[10:11]
	v_sub_f32_e32 v131, v131, v148
	v_cndmask_b32_e32 v128, 0, v153, vcc
	v_cmp_lt_f32_e64 vcc, |v145|, s49
	v_pk_add_f32 v[124:125], v[124:125], v[128:129]
	s_nop 0
	v_cndmask_b32_e32 v131, 0, v131, vcc
	v_cmp_lt_f32_e64 vcc, |v144|, s49
	s_nop 1
	v_cndmask_b32_e32 v130, 0, v130, vcc
	v_cmp_lt_f32_e32 vcc, 0, v143
	v_pk_add_f32 v[126:127], v[126:127], v[130:131]
	v_lshl_add_u64 v[130:131], v[206:207], 2, s[94:95]
	v_cndmask_b32_e32 v129, 1.0, v155, vcc
	v_cmp_lt_f32_e32 vcc, 0, v142
	global_store_dwordx4 v[130:131], v[124:127], off
	s_nop 0
	v_cndmask_b32_e32 v128, 1.0, v154, vcc
	v_pk_mul_f32 v[128:129], v[128:129], v[138:139]
	v_lshl_add_u64 v[124:125], v[206:207], 1, s[84:85]
	v_pk_mul_f32 v[128:129], v[146:147], v[128:129]
	v_cvt_pk_bf16_f32 v126, v136, v137
	v_cvt_pk_bf16_f32 v127, v128, v129
	global_store_dwordx2 v[124:125], v[126:127], off

.LBB0_1249:
	v_cndmask_b32_e64 v104, 0, 1, s[14:15]
	s_and_b64 vcc, exec, s[0:1]
	v_cmp_ne_u32_e64 s[10:11], 1, v104
	s_cbranch_vccz .LBB0_1266
	s_and_b64 vcc, exec, s[10:11]
	s_mov_b64 s[0:1], -1
	s_cbranch_vccnz .LBB0_1252
	v_lshlrev_b32_e32 v104, 2, v194
	global_load_dwordx4 v[140:143], v104, s[86:87]
	global_load_dwordx4 v[136:139], v104, s[66:67]
	global_load_dwordx4 v[144:147], v104, s[56:57]
	v_mul_f32_e64 v105, |v132|, s69
	v_mul_f32_e64 v109, |v133|, s69
	v_exp_f32_e32 v105, v105
	v_exp_f32_e32 v126, v109
	v_mul_f32_e64 v113, |v134|, s69
	v_max_f32_e32 v122, v134, v134
	v_cmp_lt_f32_e32 vcc, 0, v133
	v_max_f32_e32 v112, v133, v133
	v_mul_f32_e64 v123, |v135|, s69
	v_exp_f32_e32 v148, v113
	v_min_f32_e32 v104, 0, v122
	v_add_f32_e32 v122, 1.0, v105
	v_cndmask_b32_e32 v113, 1.0, v126, vcc
	v_cmp_lt_f32_e32 vcc, 0, v132
	v_min_f32_e32 v109, 0, v112
	v_exp_f32_e32 v149, v123
	v_add_f32_e32 v123, 1.0, v126
	v_cndmask_b32_e32 v112, 1.0, v105, vcc
	v_cmp_gt_f32_e32 vcc, s74, v122
	v_cmp_gt_f32_e64 s[14:15], s74, v123
	v_rcp_f32_e32 v127, v123
	v_cndmask_b32_e64 v105, 0, 32, vcc
	v_cndmask_b32_e64 v130, 0, 32, s[14:15]
	v_ldexp_f32 v105, v122, v105
	v_ldexp_f32 v123, v123, v130
	v_log_f32_e32 v105, v105
	v_log_f32_e32 v123, v123
	v_rcp_f32_e32 v126, v122
	v_cndmask_b32_e32 v122, 0, v226, vcc
	v_mul_f32_e32 v158, 0x3f317217, v105
	v_mul_f32_e32 v159, 0x3f317217, v123
	v_fma_f32 v158, v105, s75, -v158
	v_fma_f32 v159, v123, s75, -v159
	v_fmac_f32_e32 v158, 0x3377d1cf, v105
	v_fmac_f32_e32 v159, 0x3377d1cf, v123
	v_fmac_f32_e32 v158, 0x3f317217, v105
	v_cmp_lt_f32_e64 vcc, |v105|, s63
	v_add_f32_e32 v150, 1.0, v148
	v_fmac_f32_e32 v159, 0x3f317217, v123
	v_cndmask_b32_e32 v105, v105, v158, vcc
	v_cmp_lt_f32_e64 vcc, |v123|, s63
	v_max_f32_e32 v108, v132, v132
	v_cmp_gt_f32_e64 s[16:17], s74, v150
	v_cndmask_b32_e64 v130, 0, v226, s[14:15]
	v_cndmask_b32_e32 v123, v123, v159, vcc
	v_min_f32_e32 v108, 0, v108
	v_cndmask_b32_e64 v131, 0, 32, s[16:17]
	v_sub_f32_e32 v122, v105, v122
	v_sub_f32_e32 v123, v123, v130
	v_ldexp_f32 v131, v150, v131
	v_pk_add_f32 v[108:109], v[108:109], v[122:123] neg_lo:[0,1] neg_hi:[0,1]
	v_log_f32_e32 v131, v131
	v_add_f32_e32 v151, 1.0, v149
	v_cndmask_b32_e64 v155, 0, v226, s[16:17]
	s_mov_b64 s[0:1], 0
	v_mul_f32_e32 v160, 0x3f317217, v131
	v_fma_f32 v160, v131, s75, -v160
	v_fmac_f32_e32 v160, 0x3377d1cf, v131
	v_fmac_f32_e32 v160, 0x3f317217, v131
	v_cmp_lt_f32_e64 vcc, |v131|, s63
	s_waitcnt vmcnt(0)
	v_pk_add_f32 v[108:109], v[108:109], v[140:141]
	s_nop 0
	v_pk_add_f32 v[122:123], v[108:109], v[136:137] neg_lo:[0,1] neg_hi:[0,1]
	v_max_f32_e32 v105, v136, v136
	v_mul_f32_e64 v136, |v122|, s69
	v_max_f32_e32 v130, v137, v137
	v_mul_f32_e64 v137, |v123|, s69
	v_exp_f32_e32 v136, v136
	v_exp_f32_e32 v137, v137
	v_max_f32_e32 v108, v108, v105
	v_cndmask_b32_e32 v131, v131, v160, vcc
	v_add_f32_e32 v105, 1.0, v136
	v_max_f32_e32 v109, v109, v130
	v_add_f32_e32 v130, 1.0, v137
	v_cmp_gt_f32_e32 vcc, s74, v105
	v_cmp_gt_f32_e64 s[14:15], s74, v130
	s_nop 0
	v_cndmask_b32_e64 v136, 0, 32, vcc
	v_cndmask_b32_e64 v137, 0, 32, s[14:15]
	v_ldexp_f32 v105, v105, v136
	v_ldexp_f32 v130, v130, v137
	v_log_f32_e32 v105, v105
	v_log_f32_e32 v130, v130
	v_cndmask_b32_e32 v136, 0, v226, vcc
	v_cndmask_b32_e64 v137, 0, v226, s[14:15]
	v_mul_f32_e32 v140, 0x3f317217, v105
	v_mul_f32_e32 v141, 0x3f317217, v130
	v_fma_f32 v140, v105, s75, -v140
	v_fma_f32 v141, v130, s75, -v141
	v_fmac_f32_e32 v140, 0x3377d1cf, v105
	v_fmac_f32_e32 v141, 0x3377d1cf, v130
	v_fmac_f32_e32 v140, 0x3f317217, v105
	v_cmp_lt_f32_e64 vcc, |v105|, s63
	v_fmac_f32_e32 v141, 0x3f317217, v130
	s_nop 0
	v_cndmask_b32_e32 v105, v105, v140, vcc
	v_cmp_lt_f32_e64 vcc, |v130|, s63
	v_sub_f32_e32 v140, v105, v136
	s_nop 0
	v_cndmask_b32_e32 v130, v130, v141, vcc
	v_cmp_gt_f32_e32 vcc, s74, v151
	v_sub_f32_e32 v141, v130, v137
	v_sub_f32_e32 v130, v131, v155
	v_cndmask_b32_e64 v105, 0, 32, vcc
	v_ldexp_f32 v105, v151, v105
	v_log_f32_e32 v136, v105
	v_max_f32_e32 v105, v135, v135
	v_min_f32_e32 v105, 0, v105
	v_mul_f32_e32 v131, 0x3f317217, v136
	v_fma_f32 v131, v136, s75, -v131
	v_fmac_f32_e32 v131, 0x3377d1cf, v136
	v_fmac_f32_e32 v131, 0x3f317217, v136
	v_cmp_lt_f32_e64 s[14:15], |v136|, s63
	s_nop 1
	v_cndmask_b32_e64 v131, v136, v131, s[14:15]
	v_cndmask_b32_e32 v136, 0, v226, vcc
	v_sub_f32_e32 v131, v131, v136
	v_pk_add_f32 v[104:105], v[104:105], v[130:131] neg_lo:[0,1] neg_hi:[0,1]
	s_nop 0
	v_pk_add_f32 v[130:131], v[104:105], v[142:143]
	s_nop 0
	v_pk_add_f32 v[136:137], v[130:131], v[138:139] neg_lo:[0,1] neg_hi:[0,1]
	s_nop 0
	v_mul_f32_e64 v104, |v136|, s69
	v_exp_f32_e32 v142, v104
	v_pk_mul_f32 v[104:105], v[112:113], v[144:145]
	v_rcp_f32_e32 v112, v150
	v_pk_mul_f32 v[104:105], v[126:127], v[104:105]
	v_add_f32_e32 v113, 1.0, v142
	v_cmp_gt_f32_e32 vcc, s74, v113
	s_nop 1
	v_cndmask_b32_e64 v126, 0, 32, vcc
	v_ldexp_f32 v113, v113, v126
	v_log_f32_e32 v127, v113
	v_max_f32_e32 v126, v138, v138
	v_mul_f32_e64 v138, |v137|, s69
	v_exp_f32_e32 v138, v138
	v_max_f32_e32 v126, v130, v126
	v_mul_f32_e32 v130, 0x3f317217, v127
	v_fma_f32 v130, v127, s75, -v130
	v_fmac_f32_e32 v130, 0x3377d1cf, v127
	v_fmac_f32_e32 v130, 0x3f317217, v127
	v_cmp_lt_f32_e64 s[14:15], |v127|, s63
	v_add_f32_e32 v138, 1.0, v138
	v_rcp_f32_e32 v113, v151
	v_cndmask_b32_e64 v127, v127, v130, s[14:15]
	v_cndmask_b32_e32 v130, 0, v226, vcc
	v_cmp_gt_f32_e32 vcc, s74, v138
	v_sub_f32_e32 v130, v127, v130
	v_cndmask_b32_e64 v142, 0, 32, vcc
	v_ldexp_f32 v138, v138, v142
	v_log_f32_e32 v138, v138
	v_max_f32_e32 v127, v131, v139
	v_mul_f32_e32 v131, 0x3f317217, v138
	v_fma_f32 v131, v138, s75, -v131
	v_fmac_f32_e32 v131, 0x3377d1cf, v138
	v_fmac_f32_e32 v131, 0x3f317217, v138
	v_cmp_lt_f32_e64 s[14:15], |v138|, s63
	s_nop 1
	v_cndmask_b32_e64 v131, v138, v131, s[14:15]
	v_cndmask_b32_e32 v138, 0, v226, vcc
	v_cmp_lt_f32_e64 vcc, |v123|, s49
	v_sub_f32_e32 v131, v131, v138
	s_nop 0
	v_cndmask_b32_e32 v123, 0, v141, vcc
	v_cmp_lt_f32_e64 vcc, |v122|, s49
	s_nop 1
	v_cndmask_b32_e32 v122, 0, v140, vcc
	v_cmp_lt_f32_e64 vcc, |v137|, s49
	s_nop 1
	v_cndmask_b32_e32 v131, 0, v131, vcc
	v_cmp_lt_f32_e64 vcc, |v136|, s49
	v_pk_add_f32 v[136:137], v[108:109], v[122:123]
	s_nop 0
	v_cndmask_b32_e32 v130, 0, v130, vcc
	v_cmp_lt_f32_e32 vcc, 0, v135
	v_pk_add_f32 v[138:139], v[126:127], v[130:131]
	s_nop 0
	v_cndmask_b32_e32 v109, 1.0, v149, vcc
	v_cmp_lt_f32_e32 vcc, 0, v134
	s_nop 1
	v_cndmask_b32_e32 v108, 1.0, v148, vcc
	v_pk_mul_f32 v[108:109], v[108:109], v[146:147]
	s_nop 0
	v_pk_mul_f32 v[108:109], v[112:113], v[108:109]
	v_lshl_add_u64 v[112:113], v[156:157], 2, s[94:95]
	global_store_dwordx4 v[112:113], v[136:139], off

.LBB0_1254:
	s_add_u32 s0, s22, s0
	s_addc_u32 s1, s23, s1
	v_lshl_add_u64 v[112:113], v[156:157], 1, s[0:1]
	v_cvt_pk_bf16_f32 v104, v104, v105
	v_cvt_pk_bf16_f32 v105, v108, v109
	v_mov_b32_e32 v155, v154
	global_store_dwordx2 v[112:113], v[104:105], off
	v_pk_mul_f32 v[104:105], v[114:115], v[154:155]
	s_and_b64 vcc, exec, s[10:11]
	s_mov_b64 s[0:1], -1
	s_cbranch_vccnz .LBB0_1256
	v_lshlrev_b32_e32 v108, 2, v194
	v_lshlrev_b32_e32 v122, 2, v170
	global_load_dwordx4 v[130:133], v108, s[86:87] offset:16
	global_load_dwordx4 v[112:115], v122, s[66:67]
	global_load_dwordx4 v[134:137], v122, s[56:57]
	v_mul_f32_e64 v123, |v128|, s69
	v_max_f32_e32 v126, v128, v128
	v_mul_f32_e64 v127, |v129|, s69
	v_exp_f32_e32 v123, v123
	v_min_f32_e32 v138, 0, v126
	v_exp_f32_e32 v126, v127
	v_mul_f32_e64 v142, |v105|, s69
	v_exp_f32_e32 v145, v142
	v_add_f32_e32 v142, 1.0, v123
	v_cmp_lt_f32_e32 vcc, 0, v129
	v_add_f32_e32 v143, 1.0, v126
	v_cmp_gt_f32_e64 s[14:15], s74, v142
	v_cndmask_b32_e32 v127, 1.0, v126, vcc
	v_cmp_lt_f32_e32 vcc, 0, v128
	v_cmp_gt_f32_e64 s[16:17], s74, v143
	v_max_f32_e32 v141, v104, v104
	v_cndmask_b32_e32 v126, 1.0, v123, vcc
	v_cndmask_b32_e64 v123, 0, 32, s[14:15]
	v_cndmask_b32_e64 v147, 0, 32, s[16:17]
	v_ldexp_f32 v123, v142, v123
	v_min_f32_e32 v122, 0, v141
	v_rcp_f32_e32 v141, v143
	v_ldexp_f32 v143, v143, v147
	v_log_f32_e32 v123, v123
	v_mul_f32_e64 v140, |v104|, s69
	v_log_f32_e32 v143, v143
	v_exp_f32_e32 v144, v140
	v_mul_f32_e32 v149, 0x3f317217, v123
	v_fma_f32 v149, v123, s75, -v149
	v_mul_f32_e32 v150, 0x3f317217, v143
	v_add_f32_e32 v146, 1.0, v144
	v_fma_f32 v150, v143, s75, -v150
	v_fmac_f32_e32 v149, 0x3377d1cf, v123
	v_rcp_f32_e32 v140, v142
	v_cmp_gt_f32_e32 vcc, s74, v146
	v_cndmask_b32_e64 v142, 0, v226, s[14:15]
	v_fmac_f32_e32 v150, 0x3377d1cf, v143
	v_fmac_f32_e32 v149, 0x3f317217, v123
	v_cmp_lt_f32_e64 s[14:15], |v123|, s63
	v_cndmask_b32_e64 v148, 0, 32, vcc
	v_fmac_f32_e32 v150, 0x3f317217, v143
	v_cndmask_b32_e64 v123, v123, v149, s[14:15]
	v_cmp_lt_f32_e64 s[14:15], |v143|, s63
	v_max_f32_e32 v139, v129, v129
	v_ldexp_f32 v147, v146, v148
	v_cndmask_b32_e64 v148, 0, v226, s[16:17]
	v_cndmask_b32_e64 v143, v143, v150, s[14:15]
	v_min_f32_e32 v139, 0, v139
	v_sub_f32_e32 v142, v123, v142
	v_sub_f32_e32 v143, v143, v148
	v_pk_add_f32 v[138:139], v[138:139], v[142:143] neg_lo:[0,1] neg_hi:[0,1]
	v_log_f32_e32 v147, v147
	v_or_b32_e32 v108, v152, v170
	v_mov_b32_e32 v109, v153
	v_lshl_add_u64 v[108:109], v[108:109], 2, s[94:95]
	v_mul_f32_e32 v151, 0x3f317217, v147
	v_fma_f32 v151, v147, s75, -v151
	v_fmac_f32_e32 v151, 0x3377d1cf, v147
	v_fmac_f32_e32 v151, 0x3f317217, v147
	v_cmp_lt_f32_e64 s[14:15], |v147|, s63
	s_mov_b64 s[0:1], 0
	s_waitcnt vmcnt(0)
	v_pk_add_f32 v[130:131], v[138:139], v[130:131]
	s_nop 0
	v_pk_add_f32 v[138:139], v[130:131], v[112:113] neg_lo:[0,1] neg_hi:[0,1]
	v_max_f32_e32 v123, v112, v112
	v_mul_f32_e64 v112, |v138|, s69
	v_max_f32_e32 v142, v113, v113
	v_mul_f32_e64 v113, |v139|, s69
	v_exp_f32_e32 v112, v112
	v_exp_f32_e32 v113, v113
	v_cndmask_b32_e64 v147, v147, v151, s[14:15]
	v_max_f32_e32 v130, v130, v123
	v_add_f32_e32 v112, 1.0, v112
	v_add_f32_e32 v113, 1.0, v113
	v_cmp_gt_f32_e64 s[14:15], s74, v112
	v_cmp_gt_f32_e64 s[16:17], s74, v113
	v_max_f32_e32 v131, v131, v142
	v_cndmask_b32_e64 v123, 0, 32, s[14:15]
	v_cndmask_b32_e64 v142, 0, 32, s[16:17]
	v_ldexp_f32 v112, v112, v123
	v_ldexp_f32 v113, v113, v142
	v_log_f32_e32 v112, v112
	v_log_f32_e32 v113, v113
	v_cndmask_b32_e64 v123, 0, v226, s[14:15]
	v_cndmask_b32_e64 v142, 0, v226, s[16:17]
	v_mul_f32_e32 v143, 0x3f317217, v112
	v_mul_f32_e32 v148, 0x3f317217, v113
	v_fma_f32 v143, v112, s75, -v143
	v_fma_f32 v148, v113, s75, -v148
	v_fmac_f32_e32 v143, 0x3377d1cf, v112
	v_fmac_f32_e32 v148, 0x3377d1cf, v113
	v_fmac_f32_e32 v143, 0x3f317217, v112
	v_cmp_lt_f32_e64 s[14:15], |v112|, s63
	v_fmac_f32_e32 v148, 0x3f317217, v113
	s_nop 0
	v_cndmask_b32_e64 v112, v112, v143, s[14:15]
	v_cmp_lt_f32_e64 s[14:15], |v113|, s63
	v_sub_f32_e32 v143, v112, v123
	v_cndmask_b32_e32 v112, 0, v226, vcc
	v_cndmask_b32_e64 v113, v113, v148, s[14:15]
	v_add_f32_e32 v148, 1.0, v145
	v_cmp_gt_f32_e32 vcc, s74, v148
	v_sub_f32_e32 v142, v113, v142
	v_sub_f32_e32 v112, v147, v112
	v_cndmask_b32_e64 v113, 0, 32, vcc
	v_ldexp_f32 v113, v148, v113
	v_log_f32_e32 v113, v113
	v_max_f32_e32 v123, v105, v105
	v_min_f32_e32 v123, 0, v123
	v_mul_f32_e32 v147, 0x3f317217, v113
	v_fma_f32 v147, v113, s75, -v147
	v_fmac_f32_e32 v147, 0x3377d1cf, v113
	v_fmac_f32_e32 v147, 0x3f317217, v113
	v_cmp_lt_f32_e64 s[14:15], |v113|, s63
	s_nop 1
	v_cndmask_b32_e64 v113, v113, v147, s[14:15]
	v_cndmask_b32_e32 v147, 0, v226, vcc
	v_sub_f32_e32 v113, v113, v147
	v_pk_add_f32 v[112:113], v[122:123], v[112:113] neg_lo:[0,1] neg_hi:[0,1]
	s_nop 0
	v_pk_add_f32 v[122:123], v[112:113], v[132:133]
	s_nop 0
	v_pk_add_f32 v[132:133], v[122:123], v[114:115] neg_lo:[0,1] neg_hi:[0,1]
	v_mul_f32_e64 v112, |v132|, s69
	v_exp_f32_e32 v147, v112
	v_pk_mul_f32 v[112:113], v[126:127], v[134:135]
	v_mul_f32_e64 v135, |v133|, s69
	v_exp_f32_e32 v135, v135
	v_add_f32_e32 v127, 1.0, v147
	v_cmp_gt_f32_e32 vcc, s74, v127
	v_max_f32_e32 v114, v122, v114
	v_add_f32_e32 v135, 1.0, v135
	v_cndmask_b32_e64 v134, 0, 32, vcc
	v_ldexp_f32 v127, v127, v134
	v_log_f32_e32 v134, v127
	v_pk_mul_f32 v[112:113], v[140:141], v[112:113]
	v_max_f32_e32 v115, v123, v115
	v_mul_f32_e32 v122, 0x3f317217, v134
	v_fma_f32 v122, v134, s75, -v122
	v_fmac_f32_e32 v122, 0x3377d1cf, v134
	v_fmac_f32_e32 v122, 0x3f317217, v134
	v_cmp_lt_f32_e64 s[14:15], |v134|, s63
	v_rcp_f32_e32 v126, v146
	v_rcp_f32_e32 v127, v148
	v_cndmask_b32_e64 v122, v134, v122, s[14:15]
	v_cndmask_b32_e32 v134, 0, v226, vcc
	v_cmp_gt_f32_e32 vcc, s74, v135
	v_sub_f32_e32 v134, v122, v134
	s_nop 0
	v_cndmask_b32_e64 v140, 0, 32, vcc
	v_ldexp_f32 v135, v135, v140
	v_log_f32_e32 v135, v135
	v_cndmask_b32_e32 v123, 0, v226, vcc
	v_cmp_lt_f32_e64 vcc, |v139|, s49
	v_mul_f32_e32 v122, 0x3f317217, v135
	v_fma_f32 v122, v135, s75, -v122
	v_fmac_f32_e32 v122, 0x3377d1cf, v135
	v_fmac_f32_e32 v122, 0x3f317217, v135
	v_cmp_lt_f32_e64 s[14:15], |v135|, s63
	s_nop 1
	v_cndmask_b32_e64 v122, v135, v122, s[14:15]
	v_sub_f32_e32 v135, v122, v123
	v_cndmask_b32_e32 v123, 0, v142, vcc
	v_cmp_lt_f32_e64 vcc, |v138|, s49
	s_nop 1
	v_cndmask_b32_e32 v122, 0, v143, vcc
	v_cmp_lt_f32_e64 vcc, |v133|, s49
	v_pk_add_f32 v[130:131], v[130:131], v[122:123]
	s_nop 0
	v_cndmask_b32_e32 v133, 0, v135, vcc
	v_cmp_lt_f32_e64 vcc, |v132|, s49
	s_nop 1
	v_cndmask_b32_e32 v132, 0, v134, vcc
	v_cmp_lt_f32_e32 vcc, 0, v105
	v_pk_add_f32 v[132:133], v[114:115], v[132:133]
	global_store_dwordx4 v[108:109], v[130:133], off
	v_cndmask_b32_e32 v115, 1.0, v145, vcc
	v_cmp_lt_f32_e32 vcc, 0, v104
	s_nop 1
	v_cndmask_b32_e32 v114, 1.0, v144, vcc
	v_pk_mul_f32 v[114:115], v[114:115], v[136:137]
	s_nop 0
	v_pk_mul_f32 v[114:115], v[126:127], v[114:115]

.LBB0_1258:
	s_add_u32 s0, s22, s0
	s_addc_u32 s1, s23, s1
	v_lshl_add_u64 v[104:105], v[152:153], 0, v[194:195]
	v_mov_b32_e32 v155, v154
	v_lshl_add_u64 v[108:109], v[104:105], 1, s[0:1]
	v_cvt_pk_bf16_f32 v112, v112, v113
	v_cvt_pk_bf16_f32 v113, v114, v115
	v_pk_mul_f32 v[122:123], v[110:111], v[154:155]
	s_and_b64 vcc, exec, s[10:11]
	s_mov_b64 s[0:1], -1
	global_store_dwordx2 v[108:109], v[112:113], off offset:8
	s_cbranch_vccnz .LBB0_1260
	v_lshlrev_b32_e32 v108, 2, v194
	v_lshlrev_b32_e32 v126, 2, v169
	global_load_dwordx4 v[112:115], v108, s[86:87] offset:32
	s_nop 0
	global_load_dwordx4 v[108:111], v126, s[66:67]
	v_mul_f32_e64 v132, |v124|, s69
	global_load_dwordx4 v[126:129], v126, s[56:57]
	v_max_f32_e32 v133, v124, v124
	v_mul_f32_e64 v134, |v125|, s69
	v_exp_f32_e32 v141, v132
	v_min_f32_e32 v136, 0, v133
	v_exp_f32_e32 v133, v134
	v_mul_f32_e64 v140, |v123|, s69
	v_exp_f32_e32 v143, v140
	v_add_f32_e32 v140, 1.0, v141
	v_max_f32_e32 v135, v125, v125
	v_add_f32_e32 v144, 1.0, v133
	v_cmp_lt_f32_e32 vcc, 0, v125
	v_cmp_gt_f32_e64 s[14:15], s74, v140
	v_min_f32_e32 v137, 0, v135
	v_cndmask_b32_e32 v135, 1.0, v133, vcc
	v_cmp_lt_f32_e32 vcc, 0, v124
	v_cndmask_b32_e64 v133, 0, 32, s[14:15]
	v_cmp_gt_f32_e64 s[16:17], s74, v144
	v_cndmask_b32_e32 v134, 1.0, v141, vcc
	v_ldexp_f32 v133, v140, v133
	v_cndmask_b32_e64 v141, 0, 32, s[16:17]
	v_ldexp_f32 v141, v144, v141
	v_log_f32_e32 v133, v133
	v_mul_f32_e64 v138, |v122|, s69
	v_log_f32_e32 v141, v141
	v_exp_f32_e32 v142, v138
	v_mul_f32_e32 v147, 0x3f317217, v133
	v_fma_f32 v147, v133, s75, -v147
	v_mul_f32_e32 v148, 0x3f317217, v141
	v_add_f32_e32 v145, 1.0, v142
	v_fma_f32 v148, v141, s75, -v148
	v_fmac_f32_e32 v147, 0x3377d1cf, v133
	v_rcp_f32_e32 v138, v140
	v_cmp_gt_f32_e32 vcc, s74, v145
	v_cndmask_b32_e64 v140, 0, v226, s[14:15]
	v_fmac_f32_e32 v148, 0x3377d1cf, v141
	v_fmac_f32_e32 v147, 0x3f317217, v133
	v_cmp_lt_f32_e64 s[14:15], |v133|, s63
	v_max_f32_e32 v139, v122, v122
	v_cndmask_b32_e64 v146, 0, 32, vcc
	v_fmac_f32_e32 v148, 0x3f317217, v141
	v_cndmask_b32_e64 v133, v133, v147, s[14:15]
	v_cmp_lt_f32_e64 s[14:15], |v141|, s63
	v_min_f32_e32 v132, 0, v139
	v_rcp_f32_e32 v139, v144
	v_ldexp_f32 v144, v145, v146
	v_cndmask_b32_e64 v146, 0, v226, s[16:17]
	v_cndmask_b32_e64 v141, v141, v148, s[14:15]
	v_sub_f32_e32 v140, v133, v140
	v_sub_f32_e32 v141, v141, v146
	v_pk_add_f32 v[136:137], v[136:137], v[140:141] neg_lo:[0,1] neg_hi:[0,1]
	v_log_f32_e32 v144, v144
	v_or_b32_e32 v130, v152, v169
	v_mov_b32_e32 v131, v153
	s_mov_b64 s[0:1], 0
	v_mul_f32_e32 v149, 0x3f317217, v144
	v_fma_f32 v149, v144, s75, -v149
	v_fmac_f32_e32 v149, 0x3377d1cf, v144
	v_fmac_f32_e32 v149, 0x3f317217, v144
	v_cmp_lt_f32_e64 s[14:15], |v144|, s63
	s_waitcnt vmcnt(0)
	v_pk_add_f32 v[112:113], v[136:137], v[112:113]
	s_nop 0
	v_pk_add_f32 v[136:137], v[112:113], v[108:109] neg_lo:[0,1] neg_hi:[0,1]
	v_max_f32_e32 v133, v108, v108
	v_mul_f32_e64 v108, |v136|, s69
	v_max_f32_e32 v140, v109, v109
	v_mul_f32_e64 v109, |v137|, s69
	v_exp_f32_e32 v108, v108
	v_exp_f32_e32 v109, v109
	v_cndmask_b32_e64 v144, v144, v149, s[14:15]
	v_max_f32_e32 v112, v112, v133
	v_add_f32_e32 v108, 1.0, v108
	v_add_f32_e32 v109, 1.0, v109
	v_cmp_gt_f32_e64 s[14:15], s74, v108
	v_cmp_gt_f32_e64 s[16:17], s74, v109
	v_max_f32_e32 v113, v113, v140
	v_cndmask_b32_e64 v133, 0, 32, s[14:15]
	v_cndmask_b32_e64 v140, 0, 32, s[16:17]
	v_ldexp_f32 v108, v108, v133
	v_ldexp_f32 v109, v109, v140
	v_log_f32_e32 v108, v108
	v_log_f32_e32 v109, v109
	v_cndmask_b32_e64 v133, 0, v226, s[14:15]
	v_cndmask_b32_e64 v140, 0, v226, s[16:17]
	v_mul_f32_e32 v141, 0x3f317217, v108
	v_mul_f32_e32 v146, 0x3f317217, v109
	v_fma_f32 v141, v108, s75, -v141
	v_fma_f32 v146, v109, s75, -v146
	v_fmac_f32_e32 v141, 0x3377d1cf, v108
	v_fmac_f32_e32 v146, 0x3377d1cf, v109
	v_fmac_f32_e32 v141, 0x3f317217, v108
	v_cmp_lt_f32_e64 s[14:15], |v108|, s63
	v_fmac_f32_e32 v146, 0x3f317217, v109
	s_nop 0
	v_cndmask_b32_e64 v108, v108, v141, s[14:15]
	v_cmp_lt_f32_e64 s[14:15], |v109|, s63
	v_sub_f32_e32 v141, v108, v133
	v_cndmask_b32_e32 v108, 0, v226, vcc
	v_cndmask_b32_e64 v109, v109, v146, s[14:15]
	v_add_f32_e32 v146, 1.0, v143
	v_cmp_gt_f32_e32 vcc, s74, v146
	v_sub_f32_e32 v140, v109, v140
	v_sub_f32_e32 v108, v144, v108
	v_cndmask_b32_e64 v109, 0, 32, vcc
	v_ldexp_f32 v109, v146, v109
	v_log_f32_e32 v109, v109
	v_max_f32_e32 v133, v123, v123
	v_min_f32_e32 v133, 0, v133
	v_mul_f32_e32 v144, 0x3f317217, v109
	v_fma_f32 v144, v109, s75, -v144
	v_fmac_f32_e32 v144, 0x3377d1cf, v109
	v_fmac_f32_e32 v144, 0x3f317217, v109
	v_cmp_lt_f32_e64 s[14:15], |v109|, s63
	s_nop 1
	v_cndmask_b32_e64 v109, v109, v144, s[14:15]
	v_cndmask_b32_e32 v144, 0, v226, vcc
	v_sub_f32_e32 v109, v109, v144
	v_pk_add_f32 v[108:109], v[132:133], v[108:109] neg_lo:[0,1] neg_hi:[0,1]
	s_nop 0
	v_pk_add_f32 v[114:115], v[108:109], v[114:115]
	s_nop 0
	v_pk_add_f32 v[132:133], v[114:115], v[110:111] neg_lo:[0,1] neg_hi:[0,1]
	v_mul_f32_e64 v108, |v132|, s69
	v_exp_f32_e32 v144, v108
	v_pk_mul_f32 v[108:109], v[134:135], v[126:127]
	v_mul_f32_e64 v135, |v133|, s69
	v_exp_f32_e32 v135, v135
	v_add_f32_e32 v127, 1.0, v144
	v_cmp_gt_f32_e32 vcc, s74, v127
	v_max_f32_e32 v110, v114, v110
	v_add_f32_e32 v135, 1.0, v135
	v_cndmask_b32_e64 v134, 0, 32, vcc
	v_ldexp_f32 v127, v127, v134
	v_log_f32_e32 v134, v127
	v_pk_mul_f32 v[108:109], v[138:139], v[108:109]
	v_max_f32_e32 v111, v115, v111
	v_mul_f32_e32 v114, 0x3f317217, v134
	v_fma_f32 v114, v134, s75, -v114
	v_fmac_f32_e32 v114, 0x3377d1cf, v134
	v_fmac_f32_e32 v114, 0x3f317217, v134
	v_cmp_lt_f32_e64 s[14:15], |v134|, s63
	v_rcp_f32_e32 v126, v145
	v_rcp_f32_e32 v127, v146
	v_cndmask_b32_e64 v114, v134, v114, s[14:15]
	v_cndmask_b32_e32 v134, 0, v226, vcc
	v_cmp_gt_f32_e32 vcc, s74, v135
	v_sub_f32_e32 v114, v114, v134
	s_nop 0
	v_cndmask_b32_e64 v138, 0, 32, vcc
	v_ldexp_f32 v135, v135, v138
	v_log_f32_e32 v135, v135
	v_cndmask_b32_e32 v134, 0, v226, vcc
	v_cmp_lt_f32_e64 vcc, |v137|, s49
	v_mul_f32_e32 v115, 0x3f317217, v135
	v_fma_f32 v115, v135, s75, -v115
	v_fmac_f32_e32 v115, 0x3377d1cf, v135
	v_fmac_f32_e32 v115, 0x3f317217, v135
	v_cmp_lt_f32_e64 s[14:15], |v135|, s63
	s_nop 1
	v_cndmask_b32_e64 v115, v135, v115, s[14:15]
	v_cndmask_b32_e32 v135, 0, v140, vcc
	v_cmp_lt_f32_e64 vcc, |v136|, s49
	v_sub_f32_e32 v115, v115, v134
	s_nop 0
	v_cndmask_b32_e32 v134, 0, v141, vcc
	v_cmp_lt_f32_e64 vcc, |v133|, s49
	v_pk_add_f32 v[112:113], v[112:113], v[134:135]
	s_nop 0
	v_cndmask_b32_e32 v115, 0, v115, vcc
	v_cmp_lt_f32_e64 vcc, |v132|, s49
	s_nop 1
	v_cndmask_b32_e32 v114, 0, v114, vcc
	v_cmp_lt_f32_e32 vcc, 0, v123
	v_pk_add_f32 v[114:115], v[110:111], v[114:115]
	s_nop 0
	v_cndmask_b32_e32 v111, 1.0, v143, vcc
	v_cmp_lt_f32_e32 vcc, 0, v122
	s_nop 1
	v_cndmask_b32_e32 v110, 1.0, v142, vcc
	v_pk_mul_f32 v[110:111], v[110:111], v[128:129]
	s_nop 0
	v_pk_mul_f32 v[110:111], v[126:127], v[110:111]
	v_lshl_add_u64 v[126:127], v[130:131], 2, s[94:95]
	global_store_dwordx4 v[126:127], v[112:115], off

.LBB0_1262:
	s_add_u32 s0, s22, s0
	s_addc_u32 s1, s23, s1
	v_mov_b32_e32 v155, v154
	v_lshl_add_u64 v[104:105], v[104:105], 1, s[0:1]
	v_cvt_pk_bf16_f32 v108, v108, v109
	v_cvt_pk_bf16_f32 v109, v110, v111
	v_or_b32_e32 v152, v152, v168
	v_pk_mul_f32 v[122:123], v[106:107], v[154:155]
	s_and_b64 vcc, exec, s[10:11]
	s_mov_b64 s[0:1], -1
	global_store_dwordx2 v[104:105], v[108:109], off offset:16
	s_cbranch_vccnz .LBB0_1264
	v_lshlrev_b32_e32 v104, 2, v194
	v_lshlrev_b32_e32 v112, 2, v168
	global_load_dwordx4 v[108:111], v104, s[86:87] offset:48
	s_nop 0
	global_load_dwordx4 v[104:107], v112, s[66:67]
	v_mul_f32_e64 v124, |v120|, s69
	global_load_dwordx4 v[112:115], v112, s[56:57]
	v_max_f32_e32 v125, v120, v120
	v_mul_f32_e64 v126, |v121|, s69
	v_exp_f32_e32 v133, v124
	v_min_f32_e32 v128, 0, v125
	v_exp_f32_e32 v125, v126
	v_max_f32_e32 v127, v121, v121
	v_mul_f32_e64 v132, |v123|, s69
	v_cmp_lt_f32_e32 vcc, 0, v121
	v_min_f32_e32 v129, 0, v127
	v_exp_f32_e32 v135, v132
	v_add_f32_e32 v132, 1.0, v133
	v_cndmask_b32_e32 v127, 1.0, v125, vcc
	v_cmp_lt_f32_e32 vcc, 0, v120
	v_add_f32_e32 v136, 1.0, v125
	v_cmp_gt_f32_e64 s[14:15], s74, v136
	v_cndmask_b32_e32 v126, 1.0, v133, vcc
	v_cmp_gt_f32_e32 vcc, s74, v132
	v_cndmask_b32_e64 v133, 0, 32, s[14:15]
	v_ldexp_f32 v133, v136, v133
	v_cndmask_b32_e64 v125, 0, 32, vcc
	v_ldexp_f32 v125, v132, v125
	v_log_f32_e32 v125, v125
	v_log_f32_e32 v133, v133
	v_mul_f32_e64 v130, |v122|, s69
	v_exp_f32_e32 v134, v130
	v_mul_f32_e32 v141, 0x3f317217, v125
	v_mul_f32_e32 v142, 0x3f317217, v133
	v_fma_f32 v141, v125, s75, -v141
	v_fma_f32 v142, v133, s75, -v142
	v_fmac_f32_e32 v141, 0x3377d1cf, v125
	v_rcp_f32_e32 v130, v132
	v_cndmask_b32_e32 v132, 0, v226, vcc
	v_fmac_f32_e32 v142, 0x3377d1cf, v133
	v_fmac_f32_e32 v141, 0x3f317217, v125
	v_cmp_lt_f32_e64 vcc, |v125|, s63
	v_max_f32_e32 v131, v122, v122
	v_add_f32_e32 v137, 1.0, v134
	v_fmac_f32_e32 v142, 0x3f317217, v133
	v_cndmask_b32_e32 v125, v125, v141, vcc
	v_cmp_lt_f32_e64 vcc, |v133|, s63
	v_min_f32_e32 v124, 0, v131
	v_rcp_f32_e32 v131, v136
	v_cmp_gt_f32_e64 s[16:17], s74, v137
	v_cndmask_b32_e64 v136, 0, v226, s[14:15]
	v_cndmask_b32_e32 v133, v133, v142, vcc
	v_cndmask_b32_e64 v139, 0, 32, s[16:17]
	v_sub_f32_e32 v132, v125, v132
	v_sub_f32_e32 v133, v133, v136
	v_ldexp_f32 v139, v137, v139
	v_pk_add_f32 v[128:129], v[128:129], v[132:133] neg_lo:[0,1] neg_hi:[0,1]
	v_log_f32_e32 v139, v139
	v_add_f32_e32 v138, 1.0, v135
	v_cndmask_b32_e64 v140, 0, v226, s[16:17]
	s_mov_b64 s[0:1], 0
	v_mul_f32_e32 v143, 0x3f317217, v139
	v_fma_f32 v143, v139, s75, -v143
	v_fmac_f32_e32 v143, 0x3377d1cf, v139
	v_fmac_f32_e32 v143, 0x3f317217, v139
	v_cmp_lt_f32_e64 vcc, |v139|, s63
	s_waitcnt vmcnt(0)
	v_pk_add_f32 v[128:129], v[128:129], v[108:109]
	s_nop 0
	v_pk_add_f32 v[108:109], v[128:129], v[104:105] neg_lo:[0,1] neg_hi:[0,1]
	v_max_f32_e32 v125, v104, v104
	v_mul_f32_e64 v104, |v108|, s69
	v_max_f32_e32 v132, v105, v105
	v_mul_f32_e64 v105, |v109|, s69
	v_exp_f32_e32 v133, v104
	v_exp_f32_e32 v136, v105
	v_max_f32_e32 v104, v128, v125
	v_cndmask_b32_e32 v139, v139, v143, vcc
	v_add_f32_e32 v125, 1.0, v133
	v_add_f32_e32 v128, 1.0, v136
	v_cmp_gt_f32_e32 vcc, s74, v125
	v_max_f32_e32 v105, v129, v132
	v_cmp_gt_f32_e64 s[14:15], s74, v128
	v_cndmask_b32_e64 v129, 0, 32, vcc
	v_ldexp_f32 v125, v125, v129
	v_cndmask_b32_e64 v132, 0, 32, s[14:15]
	v_ldexp_f32 v128, v128, v132
	v_log_f32_e32 v125, v125
	v_log_f32_e32 v128, v128
	v_cndmask_b32_e32 v129, 0, v226, vcc
	v_cndmask_b32_e64 v132, 0, v226, s[14:15]
	v_mul_f32_e32 v133, 0x3f317217, v125
	v_mul_f32_e32 v136, 0x3f317217, v128
	v_fma_f32 v133, v125, s75, -v133
	v_fma_f32 v136, v128, s75, -v136
	v_fmac_f32_e32 v133, 0x3377d1cf, v125
	v_fmac_f32_e32 v136, 0x3377d1cf, v128
	v_fmac_f32_e32 v133, 0x3f317217, v125
	v_cmp_lt_f32_e64 vcc, |v125|, s63
	v_fmac_f32_e32 v136, 0x3f317217, v128
	v_pk_mul_f32 v[112:113], v[126:127], v[112:113]
	v_cndmask_b32_e32 v125, v125, v133, vcc
	v_cmp_lt_f32_e64 vcc, |v128|, s63
	v_sub_f32_e32 v133, v125, v129
	v_pk_mul_f32 v[112:113], v[130:131], v[112:113]
	v_cndmask_b32_e32 v128, v128, v136, vcc
	v_cmp_gt_f32_e32 vcc, s74, v138
	v_sub_f32_e32 v132, v128, v132
	v_sub_f32_e32 v128, v139, v140
	v_cndmask_b32_e64 v125, 0, 32, vcc
	v_ldexp_f32 v125, v138, v125
	v_log_f32_e32 v129, v125
	v_max_f32_e32 v125, v123, v123
	v_min_f32_e32 v125, 0, v125
	v_rcp_f32_e32 v126, v137
	v_mul_f32_e32 v136, 0x3f317217, v129
	v_fma_f32 v136, v129, s75, -v136
	v_fmac_f32_e32 v136, 0x3377d1cf, v129
	v_fmac_f32_e32 v136, 0x3f317217, v129
	v_cmp_lt_f32_e64 s[14:15], |v129|, s63
	s_nop 1
	v_cndmask_b32_e64 v129, v129, v136, s[14:15]
	v_cndmask_b32_e32 v136, 0, v226, vcc
	v_sub_f32_e32 v129, v129, v136
	v_pk_add_f32 v[124:125], v[124:125], v[128:129] neg_lo:[0,1] neg_hi:[0,1]
	s_nop 0
	v_pk_add_f32 v[110:111], v[124:125], v[110:111]
	s_nop 0
	v_pk_add_f32 v[124:125], v[110:111], v[106:107] neg_lo:[0,1] neg_hi:[0,1]
	v_mul_f32_e64 v128, |v124|, s69
	v_exp_f32_e32 v128, v128
	v_mul_f32_e64 v129, |v125|, s69
	v_exp_f32_e32 v129, v129
	v_max_f32_e32 v106, v110, v106
	v_add_f32_e32 v127, 1.0, v128
	v_cmp_gt_f32_e32 vcc, s74, v127
	v_add_f32_e32 v129, 1.0, v129
	v_cndmask_b32_e64 v128, 0, 32, vcc
	v_ldexp_f32 v127, v127, v128
	v_log_f32_e32 v128, v127
	v_max_f32_e32 v107, v111, v107
	v_rcp_f32_e32 v127, v138
	v_mul_f32_e32 v110, 0x3f317217, v128
	v_fma_f32 v110, v128, s75, -v110
	v_fmac_f32_e32 v110, 0x3377d1cf, v128
	v_fmac_f32_e32 v110, 0x3f317217, v128
	v_cmp_lt_f32_e64 s[14:15], |v128|, s63
	s_nop 1
	v_cndmask_b32_e64 v110, v128, v110, s[14:15]
	v_cndmask_b32_e32 v128, 0, v226, vcc
	v_cmp_gt_f32_e32 vcc, s74, v129
	v_sub_f32_e32 v110, v110, v128
	s_nop 0
	v_cndmask_b32_e64 v130, 0, 32, vcc
	v_ldexp_f32 v129, v129, v130
	v_log_f32_e32 v129, v129
	v_cndmask_b32_e32 v128, 0, v226, vcc
	v_cmp_lt_f32_e64 vcc, |v109|, s49
	v_mul_f32_e32 v111, 0x3f317217, v129
	v_fma_f32 v111, v129, s75, -v111
	v_fmac_f32_e32 v111, 0x3377d1cf, v129
	v_fmac_f32_e32 v111, 0x3f317217, v129
	v_cmp_lt_f32_e64 s[14:15], |v129|, s63
	v_cndmask_b32_e32 v109, 0, v132, vcc
	v_cmp_lt_f32_e64 vcc, |v108|, s49
	v_cndmask_b32_e64 v111, v129, v111, s[14:15]
	v_sub_f32_e32 v111, v111, v128
	v_cndmask_b32_e32 v108, 0, v133, vcc
	v_cmp_lt_f32_e64 vcc, |v125|, s49
	v_pk_add_f32 v[104:105], v[104:105], v[108:109]
	s_nop 0
	v_cndmask_b32_e32 v111, 0, v111, vcc
	v_cmp_lt_f32_e64 vcc, |v124|, s49
	s_nop 1
	v_cndmask_b32_e32 v110, 0, v110, vcc
	v_cmp_lt_f32_e32 vcc, 0, v123
	v_pk_add_f32 v[106:107], v[106:107], v[110:111]
	v_lshl_add_u64 v[110:111], v[152:153], 2, s[94:95]
	v_cndmask_b32_e32 v109, 1.0, v135, vcc
	v_cmp_lt_f32_e32 vcc, 0, v122
	global_store_dwordx4 v[110:111], v[104:107], off
	s_nop 0
	v_cndmask_b32_e32 v108, 1.0, v134, vcc
	v_pk_mul_f32 v[108:109], v[108:109], v[114:115]
	v_lshl_add_u64 v[104:105], v[152:153], 1, s[84:85]
	v_pk_mul_f32 v[108:109], v[126:127], v[108:109]
	v_cvt_pk_bf16_f32 v106, v112, v113
	v_cvt_pk_bf16_f32 v107, v108, v109
	global_store_dwordx2 v[104:105], v[106:107], off

.LBB0_1285:
	s_and_b64 vcc, exec, s[0:1]
	s_cbranch_vccz .LBB0_1302
	s_and_b64 vcc, exec, s[10:11]
	s_mov_b64 s[0:1], -1
	s_cbranch_vccnz .LBB0_1288
	v_lshlrev_b32_e32 v84, 2, v194
	global_load_dwordx4 v[120:123], v84, s[86:87]
	global_load_dwordx4 v[116:119], v84, s[66:67]
	global_load_dwordx4 v[124:127], v84, s[56:57]
	v_mul_f32_e64 v85, |v112|, s69
	v_mul_f32_e64 v89, |v113|, s69
	v_exp_f32_e32 v85, v85
	v_exp_f32_e32 v106, v89
	v_mul_f32_e64 v93, |v114|, s69
	v_max_f32_e32 v102, v114, v114
	v_cmp_lt_f32_e32 vcc, 0, v113
	v_max_f32_e32 v92, v113, v113
	v_mul_f32_e64 v103, |v115|, s69
	v_exp_f32_e32 v128, v93
	v_min_f32_e32 v84, 0, v102
	v_add_f32_e32 v102, 1.0, v85
	v_cndmask_b32_e32 v93, 1.0, v106, vcc
	v_cmp_lt_f32_e32 vcc, 0, v112
	v_min_f32_e32 v89, 0, v92
	v_exp_f32_e32 v129, v103
	v_add_f32_e32 v103, 1.0, v106
	v_cndmask_b32_e32 v92, 1.0, v85, vcc
	v_cmp_gt_f32_e32 vcc, s74, v102
	v_cmp_gt_f32_e64 s[14:15], s74, v103
	v_rcp_f32_e32 v107, v103
	v_cndmask_b32_e64 v85, 0, 32, vcc
	v_cndmask_b32_e64 v110, 0, 32, s[14:15]
	v_ldexp_f32 v85, v102, v85
	v_ldexp_f32 v103, v103, v110
	v_log_f32_e32 v85, v85
	v_log_f32_e32 v103, v103
	v_rcp_f32_e32 v106, v102
	v_cndmask_b32_e32 v102, 0, v226, vcc
	v_mul_f32_e32 v138, 0x3f317217, v85
	v_mul_f32_e32 v139, 0x3f317217, v103
	v_fma_f32 v138, v85, s75, -v138
	v_fma_f32 v139, v103, s75, -v139
	v_fmac_f32_e32 v138, 0x3377d1cf, v85
	v_fmac_f32_e32 v139, 0x3377d1cf, v103
	v_fmac_f32_e32 v138, 0x3f317217, v85
	v_cmp_lt_f32_e64 vcc, |v85|, s63
	v_add_f32_e32 v130, 1.0, v128
	v_fmac_f32_e32 v139, 0x3f317217, v103
	v_cndmask_b32_e32 v85, v85, v138, vcc
	v_cmp_lt_f32_e64 vcc, |v103|, s63
	v_max_f32_e32 v88, v112, v112
	v_cmp_gt_f32_e64 s[16:17], s74, v130
	v_cndmask_b32_e64 v110, 0, v226, s[14:15]
	v_cndmask_b32_e32 v103, v103, v139, vcc
	v_min_f32_e32 v88, 0, v88
	v_cndmask_b32_e64 v111, 0, 32, s[16:17]
	v_sub_f32_e32 v102, v85, v102
	v_sub_f32_e32 v103, v103, v110
	v_ldexp_f32 v111, v130, v111
	v_pk_add_f32 v[88:89], v[88:89], v[102:103] neg_lo:[0,1] neg_hi:[0,1]
	v_log_f32_e32 v111, v111
	v_add_f32_e32 v131, 1.0, v129
	v_cndmask_b32_e64 v135, 0, v226, s[16:17]
	s_mov_b64 s[0:1], 0
	v_mul_f32_e32 v140, 0x3f317217, v111
	v_fma_f32 v140, v111, s75, -v140
	v_fmac_f32_e32 v140, 0x3377d1cf, v111
	v_fmac_f32_e32 v140, 0x3f317217, v111
	v_cmp_lt_f32_e64 vcc, |v111|, s63
	s_waitcnt vmcnt(0)
	v_pk_add_f32 v[88:89], v[88:89], v[120:121]
	s_nop 0
	v_pk_add_f32 v[102:103], v[88:89], v[116:117] neg_lo:[0,1] neg_hi:[0,1]
	v_max_f32_e32 v85, v116, v116
	v_mul_f32_e64 v116, |v102|, s69
	v_max_f32_e32 v110, v117, v117
	v_mul_f32_e64 v117, |v103|, s69
	v_exp_f32_e32 v116, v116
	v_exp_f32_e32 v117, v117
	v_max_f32_e32 v88, v88, v85
	v_cndmask_b32_e32 v111, v111, v140, vcc
	v_add_f32_e32 v85, 1.0, v116
	v_max_f32_e32 v89, v89, v110
	v_add_f32_e32 v110, 1.0, v117
	v_cmp_gt_f32_e32 vcc, s74, v85
	v_cmp_gt_f32_e64 s[14:15], s74, v110
	s_nop 0
	v_cndmask_b32_e64 v116, 0, 32, vcc
	v_cndmask_b32_e64 v117, 0, 32, s[14:15]
	v_ldexp_f32 v85, v85, v116
	v_ldexp_f32 v110, v110, v117
	v_log_f32_e32 v85, v85
	v_log_f32_e32 v110, v110
	v_cndmask_b32_e32 v116, 0, v226, vcc
	v_cndmask_b32_e64 v117, 0, v226, s[14:15]
	v_mul_f32_e32 v120, 0x3f317217, v85
	v_mul_f32_e32 v121, 0x3f317217, v110
	v_fma_f32 v120, v85, s75, -v120
	v_fma_f32 v121, v110, s75, -v121
	v_fmac_f32_e32 v120, 0x3377d1cf, v85
	v_fmac_f32_e32 v121, 0x3377d1cf, v110
	v_fmac_f32_e32 v120, 0x3f317217, v85
	v_cmp_lt_f32_e64 vcc, |v85|, s63
	v_fmac_f32_e32 v121, 0x3f317217, v110
	s_nop 0
	v_cndmask_b32_e32 v85, v85, v120, vcc
	v_cmp_lt_f32_e64 vcc, |v110|, s63
	v_sub_f32_e32 v120, v85, v116
	s_nop 0
	v_cndmask_b32_e32 v110, v110, v121, vcc
	v_cmp_gt_f32_e32 vcc, s74, v131
	v_sub_f32_e32 v121, v110, v117
	v_sub_f32_e32 v110, v111, v135
	v_cndmask_b32_e64 v85, 0, 32, vcc
	v_ldexp_f32 v85, v131, v85
	v_log_f32_e32 v116, v85
	v_max_f32_e32 v85, v115, v115
	v_min_f32_e32 v85, 0, v85
	v_mul_f32_e32 v111, 0x3f317217, v116
	v_fma_f32 v111, v116, s75, -v111
	v_fmac_f32_e32 v111, 0x3377d1cf, v116
	v_fmac_f32_e32 v111, 0x3f317217, v116
	v_cmp_lt_f32_e64 s[14:15], |v116|, s63
	s_nop 1
	v_cndmask_b32_e64 v111, v116, v111, s[14:15]
	v_cndmask_b32_e32 v116, 0, v226, vcc
	v_sub_f32_e32 v111, v111, v116
	v_pk_add_f32 v[84:85], v[84:85], v[110:111] neg_lo:[0,1] neg_hi:[0,1]
	s_nop 0
	v_pk_add_f32 v[110:111], v[84:85], v[122:123]
	s_nop 0
	v_pk_add_f32 v[116:117], v[110:111], v[118:119] neg_lo:[0,1] neg_hi:[0,1]
	s_nop 0
	v_mul_f32_e64 v84, |v116|, s69
	v_exp_f32_e32 v122, v84
	v_pk_mul_f32 v[84:85], v[92:93], v[124:125]
	v_rcp_f32_e32 v92, v130
	v_pk_mul_f32 v[84:85], v[106:107], v[84:85]
	v_add_f32_e32 v93, 1.0, v122
	v_cmp_gt_f32_e32 vcc, s74, v93
	s_nop 1
	v_cndmask_b32_e64 v106, 0, 32, vcc
	v_ldexp_f32 v93, v93, v106
	v_log_f32_e32 v107, v93
	v_max_f32_e32 v106, v118, v118
	v_mul_f32_e64 v118, |v117|, s69
	v_exp_f32_e32 v118, v118
	v_max_f32_e32 v106, v110, v106
	v_mul_f32_e32 v110, 0x3f317217, v107
	v_fma_f32 v110, v107, s75, -v110
	v_fmac_f32_e32 v110, 0x3377d1cf, v107
	v_fmac_f32_e32 v110, 0x3f317217, v107
	v_cmp_lt_f32_e64 s[14:15], |v107|, s63
	v_add_f32_e32 v118, 1.0, v118
	v_rcp_f32_e32 v93, v131
	v_cndmask_b32_e64 v107, v107, v110, s[14:15]
	v_cndmask_b32_e32 v110, 0, v226, vcc
	v_cmp_gt_f32_e32 vcc, s74, v118
	v_sub_f32_e32 v110, v107, v110
	v_cndmask_b32_e64 v122, 0, 32, vcc
	v_ldexp_f32 v118, v118, v122
	v_log_f32_e32 v118, v118
	v_max_f32_e32 v107, v111, v119
	v_mul_f32_e32 v111, 0x3f317217, v118
	v_fma_f32 v111, v118, s75, -v111
	v_fmac_f32_e32 v111, 0x3377d1cf, v118
	v_fmac_f32_e32 v111, 0x3f317217, v118
	v_cmp_lt_f32_e64 s[14:15], |v118|, s63
	s_nop 1
	v_cndmask_b32_e64 v111, v118, v111, s[14:15]
	v_cndmask_b32_e32 v118, 0, v226, vcc
	v_cmp_lt_f32_e64 vcc, |v103|, s49
	v_sub_f32_e32 v111, v111, v118
	s_nop 0
	v_cndmask_b32_e32 v103, 0, v121, vcc
	v_cmp_lt_f32_e64 vcc, |v102|, s49
	s_nop 1
	v_cndmask_b32_e32 v102, 0, v120, vcc
	v_cmp_lt_f32_e64 vcc, |v117|, s49
	s_nop 1
	v_cndmask_b32_e32 v111, 0, v111, vcc
	v_cmp_lt_f32_e64 vcc, |v116|, s49
	v_pk_add_f32 v[116:117], v[88:89], v[102:103]
	s_nop 0
	v_cndmask_b32_e32 v110, 0, v110, vcc
	v_cmp_lt_f32_e32 vcc, 0, v115
	v_pk_add_f32 v[118:119], v[106:107], v[110:111]
	s_nop 0
	v_cndmask_b32_e32 v89, 1.0, v129, vcc
	v_cmp_lt_f32_e32 vcc, 0, v114
	s_nop 1
	v_cndmask_b32_e32 v88, 1.0, v128, vcc
	v_pk_mul_f32 v[88:89], v[88:89], v[126:127]
	s_nop 0
	v_pk_mul_f32 v[88:89], v[92:93], v[88:89]
	v_lshl_add_u64 v[92:93], v[136:137], 2, s[94:95]
	global_store_dwordx4 v[92:93], v[116:119], off

.LBB0_1290:
	s_add_u32 s0, s22, s0
	s_addc_u32 s1, s23, s1
	v_lshl_add_u64 v[92:93], v[136:137], 1, s[0:1]
	v_cvt_pk_bf16_f32 v84, v84, v85
	v_cvt_pk_bf16_f32 v85, v88, v89
	v_mov_b32_e32 v135, v134
	global_store_dwordx2 v[92:93], v[84:85], off
	v_pk_mul_f32 v[84:85], v[94:95], v[134:135]
	s_and_b64 vcc, exec, s[10:11]
	s_mov_b64 s[0:1], -1
	s_cbranch_vccnz .LBB0_1292
	v_lshlrev_b32_e32 v88, 2, v194
	v_lshlrev_b32_e32 v102, 2, v170
	global_load_dwordx4 v[110:113], v88, s[86:87] offset:16
	global_load_dwordx4 v[92:95], v102, s[66:67]
	global_load_dwordx4 v[114:117], v102, s[56:57]
	v_mul_f32_e64 v103, |v108|, s69
	v_max_f32_e32 v106, v108, v108
	v_mul_f32_e64 v107, |v109|, s69
	v_exp_f32_e32 v103, v103
	v_min_f32_e32 v118, 0, v106
	v_exp_f32_e32 v106, v107
	v_mul_f32_e64 v122, |v85|, s69
	v_exp_f32_e32 v125, v122
	v_add_f32_e32 v122, 1.0, v103
	v_cmp_lt_f32_e32 vcc, 0, v109
	v_add_f32_e32 v123, 1.0, v106
	v_cmp_gt_f32_e64 s[14:15], s74, v122
	v_cndmask_b32_e32 v107, 1.0, v106, vcc
	v_cmp_lt_f32_e32 vcc, 0, v108
	v_cmp_gt_f32_e64 s[16:17], s74, v123
	v_max_f32_e32 v121, v84, v84
	v_cndmask_b32_e32 v106, 1.0, v103, vcc
	v_cndmask_b32_e64 v103, 0, 32, s[14:15]
	v_cndmask_b32_e64 v127, 0, 32, s[16:17]
	v_ldexp_f32 v103, v122, v103
	v_min_f32_e32 v102, 0, v121
	v_rcp_f32_e32 v121, v123
	v_ldexp_f32 v123, v123, v127
	v_log_f32_e32 v103, v103
	v_mul_f32_e64 v120, |v84|, s69
	v_log_f32_e32 v123, v123
	v_exp_f32_e32 v124, v120
	v_mul_f32_e32 v129, 0x3f317217, v103
	v_fma_f32 v129, v103, s75, -v129
	v_mul_f32_e32 v130, 0x3f317217, v123
	v_add_f32_e32 v126, 1.0, v124
	v_fma_f32 v130, v123, s75, -v130
	v_fmac_f32_e32 v129, 0x3377d1cf, v103
	v_rcp_f32_e32 v120, v122
	v_cmp_gt_f32_e32 vcc, s74, v126
	v_cndmask_b32_e64 v122, 0, v226, s[14:15]
	v_fmac_f32_e32 v130, 0x3377d1cf, v123
	v_fmac_f32_e32 v129, 0x3f317217, v103
	v_cmp_lt_f32_e64 s[14:15], |v103|, s63
	v_cndmask_b32_e64 v128, 0, 32, vcc
	v_fmac_f32_e32 v130, 0x3f317217, v123
	v_cndmask_b32_e64 v103, v103, v129, s[14:15]
	v_cmp_lt_f32_e64 s[14:15], |v123|, s63
	v_max_f32_e32 v119, v109, v109
	v_ldexp_f32 v127, v126, v128
	v_cndmask_b32_e64 v128, 0, v226, s[16:17]
	v_cndmask_b32_e64 v123, v123, v130, s[14:15]
	v_min_f32_e32 v119, 0, v119
	v_sub_f32_e32 v122, v103, v122
	v_sub_f32_e32 v123, v123, v128
	v_pk_add_f32 v[118:119], v[118:119], v[122:123] neg_lo:[0,1] neg_hi:[0,1]
	v_log_f32_e32 v127, v127
	v_or_b32_e32 v88, v132, v170
	v_mov_b32_e32 v89, v133
	v_lshl_add_u64 v[88:89], v[88:89], 2, s[94:95]
	v_mul_f32_e32 v131, 0x3f317217, v127
	v_fma_f32 v131, v127, s75, -v131
	v_fmac_f32_e32 v131, 0x3377d1cf, v127
	v_fmac_f32_e32 v131, 0x3f317217, v127
	v_cmp_lt_f32_e64 s[14:15], |v127|, s63
	s_mov_b64 s[0:1], 0
	s_waitcnt vmcnt(0)
	v_pk_add_f32 v[110:111], v[118:119], v[110:111]
	s_nop 0
	v_pk_add_f32 v[118:119], v[110:111], v[92:93] neg_lo:[0,1] neg_hi:[0,1]
	v_max_f32_e32 v103, v92, v92
	v_mul_f32_e64 v92, |v118|, s69
	v_max_f32_e32 v122, v93, v93
	v_mul_f32_e64 v93, |v119|, s69
	v_exp_f32_e32 v92, v92
	v_exp_f32_e32 v93, v93
	v_cndmask_b32_e64 v127, v127, v131, s[14:15]
	v_max_f32_e32 v110, v110, v103
	v_add_f32_e32 v92, 1.0, v92
	v_add_f32_e32 v93, 1.0, v93
	v_cmp_gt_f32_e64 s[14:15], s74, v92
	v_cmp_gt_f32_e64 s[16:17], s74, v93
	v_max_f32_e32 v111, v111, v122
	v_cndmask_b32_e64 v103, 0, 32, s[14:15]
	v_cndmask_b32_e64 v122, 0, 32, s[16:17]
	v_ldexp_f32 v92, v92, v103
	v_ldexp_f32 v93, v93, v122
	v_log_f32_e32 v92, v92
	v_log_f32_e32 v93, v93
	v_cndmask_b32_e64 v103, 0, v226, s[14:15]
	v_cndmask_b32_e64 v122, 0, v226, s[16:17]
	v_mul_f32_e32 v123, 0x3f317217, v92
	v_mul_f32_e32 v128, 0x3f317217, v93
	v_fma_f32 v123, v92, s75, -v123
	v_fma_f32 v128, v93, s75, -v128
	v_fmac_f32_e32 v123, 0x3377d1cf, v92
	v_fmac_f32_e32 v128, 0x3377d1cf, v93
	v_fmac_f32_e32 v123, 0x3f317217, v92
	v_cmp_lt_f32_e64 s[14:15], |v92|, s63
	v_fmac_f32_e32 v128, 0x3f317217, v93
	s_nop 0
	v_cndmask_b32_e64 v92, v92, v123, s[14:15]
	v_cmp_lt_f32_e64 s[14:15], |v93|, s63
	v_sub_f32_e32 v123, v92, v103
	v_cndmask_b32_e32 v92, 0, v226, vcc
	v_cndmask_b32_e64 v93, v93, v128, s[14:15]
	v_add_f32_e32 v128, 1.0, v125
	v_cmp_gt_f32_e32 vcc, s74, v128
	v_sub_f32_e32 v122, v93, v122
	v_sub_f32_e32 v92, v127, v92
	v_cndmask_b32_e64 v93, 0, 32, vcc
	v_ldexp_f32 v93, v128, v93
	v_log_f32_e32 v93, v93
	v_max_f32_e32 v103, v85, v85
	v_min_f32_e32 v103, 0, v103
	v_mul_f32_e32 v127, 0x3f317217, v93
	v_fma_f32 v127, v93, s75, -v127
	v_fmac_f32_e32 v127, 0x3377d1cf, v93
	v_fmac_f32_e32 v127, 0x3f317217, v93
	v_cmp_lt_f32_e64 s[14:15], |v93|, s63
	s_nop 1
	v_cndmask_b32_e64 v93, v93, v127, s[14:15]
	v_cndmask_b32_e32 v127, 0, v226, vcc
	v_sub_f32_e32 v93, v93, v127
	v_pk_add_f32 v[92:93], v[102:103], v[92:93] neg_lo:[0,1] neg_hi:[0,1]
	s_nop 0
	v_pk_add_f32 v[102:103], v[92:93], v[112:113]
	s_nop 0
	v_pk_add_f32 v[112:113], v[102:103], v[94:95] neg_lo:[0,1] neg_hi:[0,1]
	v_mul_f32_e64 v92, |v112|, s69
	v_exp_f32_e32 v127, v92
	v_pk_mul_f32 v[92:93], v[106:107], v[114:115]
	v_mul_f32_e64 v115, |v113|, s69
	v_exp_f32_e32 v115, v115
	v_add_f32_e32 v107, 1.0, v127
	v_cmp_gt_f32_e32 vcc, s74, v107
	v_max_f32_e32 v94, v102, v94
	v_add_f32_e32 v115, 1.0, v115
	v_cndmask_b32_e64 v114, 0, 32, vcc
	v_ldexp_f32 v107, v107, v114
	v_log_f32_e32 v114, v107
	v_pk_mul_f32 v[92:93], v[120:121], v[92:93]
	v_max_f32_e32 v95, v103, v95
	v_mul_f32_e32 v102, 0x3f317217, v114
	v_fma_f32 v102, v114, s75, -v102
	v_fmac_f32_e32 v102, 0x3377d1cf, v114
	v_fmac_f32_e32 v102, 0x3f317217, v114
	v_cmp_lt_f32_e64 s[14:15], |v114|, s63
	v_rcp_f32_e32 v106, v126
	v_rcp_f32_e32 v107, v128
	v_cndmask_b32_e64 v102, v114, v102, s[14:15]
	v_cndmask_b32_e32 v114, 0, v226, vcc
	v_cmp_gt_f32_e32 vcc, s74, v115
	v_sub_f32_e32 v114, v102, v114
	s_nop 0
	v_cndmask_b32_e64 v120, 0, 32, vcc
	v_ldexp_f32 v115, v115, v120
	v_log_f32_e32 v115, v115
	v_cndmask_b32_e32 v103, 0, v226, vcc
	v_cmp_lt_f32_e64 vcc, |v119|, s49
	v_mul_f32_e32 v102, 0x3f317217, v115
	v_fma_f32 v102, v115, s75, -v102
	v_fmac_f32_e32 v102, 0x3377d1cf, v115
	v_fmac_f32_e32 v102, 0x3f317217, v115
	v_cmp_lt_f32_e64 s[14:15], |v115|, s63
	s_nop 1
	v_cndmask_b32_e64 v102, v115, v102, s[14:15]
	v_sub_f32_e32 v115, v102, v103
	v_cndmask_b32_e32 v103, 0, v122, vcc
	v_cmp_lt_f32_e64 vcc, |v118|, s49
	s_nop 1
	v_cndmask_b32_e32 v102, 0, v123, vcc
	v_cmp_lt_f32_e64 vcc, |v113|, s49
	v_pk_add_f32 v[110:111], v[110:111], v[102:103]
	s_nop 0
	v_cndmask_b32_e32 v113, 0, v115, vcc
	v_cmp_lt_f32_e64 vcc, |v112|, s49
	s_nop 1
	v_cndmask_b32_e32 v112, 0, v114, vcc
	v_cmp_lt_f32_e32 vcc, 0, v85
	v_pk_add_f32 v[112:113], v[94:95], v[112:113]
	global_store_dwordx4 v[88:89], v[110:113], off
	v_cndmask_b32_e32 v95, 1.0, v125, vcc
	v_cmp_lt_f32_e32 vcc, 0, v84
	s_nop 1
	v_cndmask_b32_e32 v94, 1.0, v124, vcc
	v_pk_mul_f32 v[94:95], v[94:95], v[116:117]
	s_nop 0
	v_pk_mul_f32 v[94:95], v[106:107], v[94:95]

.LBB0_1294:
	s_add_u32 s0, s22, s0
	s_addc_u32 s1, s23, s1
	v_lshl_add_u64 v[84:85], v[132:133], 0, v[194:195]
	v_mov_b32_e32 v135, v134
	v_lshl_add_u64 v[88:89], v[84:85], 1, s[0:1]
	v_cvt_pk_bf16_f32 v92, v92, v93
	v_cvt_pk_bf16_f32 v93, v94, v95
	v_pk_mul_f32 v[102:103], v[90:91], v[134:135]
	s_and_b64 vcc, exec, s[10:11]
	s_mov_b64 s[0:1], -1
	global_store_dwordx2 v[88:89], v[92:93], off offset:8
	s_cbranch_vccnz .LBB0_1296
	v_lshlrev_b32_e32 v88, 2, v194
	v_lshlrev_b32_e32 v106, 2, v169
	global_load_dwordx4 v[92:95], v88, s[86:87] offset:32
	s_nop 0
	global_load_dwordx4 v[88:91], v106, s[66:67]
	v_mul_f32_e64 v112, |v104|, s69
	global_load_dwordx4 v[106:109], v106, s[56:57]
	v_max_f32_e32 v113, v104, v104
	v_mul_f32_e64 v114, |v105|, s69
	v_exp_f32_e32 v121, v112
	v_min_f32_e32 v116, 0, v113
	v_exp_f32_e32 v113, v114
	v_mul_f32_e64 v120, |v103|, s69
	v_exp_f32_e32 v123, v120
	v_add_f32_e32 v120, 1.0, v121
	v_max_f32_e32 v115, v105, v105
	v_add_f32_e32 v124, 1.0, v113
	v_cmp_lt_f32_e32 vcc, 0, v105
	v_cmp_gt_f32_e64 s[14:15], s74, v120
	v_min_f32_e32 v117, 0, v115
	v_cndmask_b32_e32 v115, 1.0, v113, vcc
	v_cmp_lt_f32_e32 vcc, 0, v104
	v_cndmask_b32_e64 v113, 0, 32, s[14:15]
	v_cmp_gt_f32_e64 s[16:17], s74, v124
	v_cndmask_b32_e32 v114, 1.0, v121, vcc
	v_ldexp_f32 v113, v120, v113
	v_cndmask_b32_e64 v121, 0, 32, s[16:17]
	v_ldexp_f32 v121, v124, v121
	v_log_f32_e32 v113, v113
	v_mul_f32_e64 v118, |v102|, s69
	v_log_f32_e32 v121, v121
	v_exp_f32_e32 v122, v118
	v_mul_f32_e32 v127, 0x3f317217, v113
	v_fma_f32 v127, v113, s75, -v127
	v_mul_f32_e32 v128, 0x3f317217, v121
	v_add_f32_e32 v125, 1.0, v122
	v_fma_f32 v128, v121, s75, -v128
	v_fmac_f32_e32 v127, 0x3377d1cf, v113
	v_rcp_f32_e32 v118, v120
	v_cmp_gt_f32_e32 vcc, s74, v125
	v_cndmask_b32_e64 v120, 0, v226, s[14:15]
	v_fmac_f32_e32 v128, 0x3377d1cf, v121
	v_fmac_f32_e32 v127, 0x3f317217, v113
	v_cmp_lt_f32_e64 s[14:15], |v113|, s63
	v_max_f32_e32 v119, v102, v102
	v_cndmask_b32_e64 v126, 0, 32, vcc
	v_fmac_f32_e32 v128, 0x3f317217, v121
	v_cndmask_b32_e64 v113, v113, v127, s[14:15]
	v_cmp_lt_f32_e64 s[14:15], |v121|, s63
	v_min_f32_e32 v112, 0, v119
	v_rcp_f32_e32 v119, v124
	v_ldexp_f32 v124, v125, v126
	v_cndmask_b32_e64 v126, 0, v226, s[16:17]
	v_cndmask_b32_e64 v121, v121, v128, s[14:15]
	v_sub_f32_e32 v120, v113, v120
	v_sub_f32_e32 v121, v121, v126
	v_pk_add_f32 v[116:117], v[116:117], v[120:121] neg_lo:[0,1] neg_hi:[0,1]
	v_log_f32_e32 v124, v124
	v_or_b32_e32 v110, v132, v169
	v_mov_b32_e32 v111, v133
	s_mov_b64 s[0:1], 0
	v_mul_f32_e32 v129, 0x3f317217, v124
	v_fma_f32 v129, v124, s75, -v129
	v_fmac_f32_e32 v129, 0x3377d1cf, v124
	v_fmac_f32_e32 v129, 0x3f317217, v124
	v_cmp_lt_f32_e64 s[14:15], |v124|, s63
	s_waitcnt vmcnt(0)
	v_pk_add_f32 v[92:93], v[116:117], v[92:93]
	s_nop 0
	v_pk_add_f32 v[116:117], v[92:93], v[88:89] neg_lo:[0,1] neg_hi:[0,1]
	v_max_f32_e32 v113, v88, v88
	v_mul_f32_e64 v88, |v116|, s69
	v_max_f32_e32 v120, v89, v89
	v_mul_f32_e64 v89, |v117|, s69
	v_exp_f32_e32 v88, v88
	v_exp_f32_e32 v89, v89
	v_cndmask_b32_e64 v124, v124, v129, s[14:15]
	v_max_f32_e32 v92, v92, v113
	v_add_f32_e32 v88, 1.0, v88
	v_add_f32_e32 v89, 1.0, v89
	v_cmp_gt_f32_e64 s[14:15], s74, v88
	v_cmp_gt_f32_e64 s[16:17], s74, v89
	v_max_f32_e32 v93, v93, v120
	v_cndmask_b32_e64 v113, 0, 32, s[14:15]
	v_cndmask_b32_e64 v120, 0, 32, s[16:17]
	v_ldexp_f32 v88, v88, v113
	v_ldexp_f32 v89, v89, v120
	v_log_f32_e32 v88, v88
	v_log_f32_e32 v89, v89
	v_cndmask_b32_e64 v113, 0, v226, s[14:15]
	v_cndmask_b32_e64 v120, 0, v226, s[16:17]
	v_mul_f32_e32 v121, 0x3f317217, v88
	v_mul_f32_e32 v126, 0x3f317217, v89
	v_fma_f32 v121, v88, s75, -v121
	v_fma_f32 v126, v89, s75, -v126
	v_fmac_f32_e32 v121, 0x3377d1cf, v88
	v_fmac_f32_e32 v126, 0x3377d1cf, v89
	v_fmac_f32_e32 v121, 0x3f317217, v88
	v_cmp_lt_f32_e64 s[14:15], |v88|, s63
	v_fmac_f32_e32 v126, 0x3f317217, v89
	s_nop 0
	v_cndmask_b32_e64 v88, v88, v121, s[14:15]
	v_cmp_lt_f32_e64 s[14:15], |v89|, s63
	v_sub_f32_e32 v121, v88, v113
	v_cndmask_b32_e32 v88, 0, v226, vcc
	v_cndmask_b32_e64 v89, v89, v126, s[14:15]
	v_add_f32_e32 v126, 1.0, v123
	v_cmp_gt_f32_e32 vcc, s74, v126
	v_sub_f32_e32 v120, v89, v120
	v_sub_f32_e32 v88, v124, v88
	v_cndmask_b32_e64 v89, 0, 32, vcc
	v_ldexp_f32 v89, v126, v89
	v_log_f32_e32 v89, v89
	v_max_f32_e32 v113, v103, v103
	v_min_f32_e32 v113, 0, v113
	v_mul_f32_e32 v124, 0x3f317217, v89
	v_fma_f32 v124, v89, s75, -v124
	v_fmac_f32_e32 v124, 0x3377d1cf, v89
	v_fmac_f32_e32 v124, 0x3f317217, v89
	v_cmp_lt_f32_e64 s[14:15], |v89|, s63
	s_nop 1
	v_cndmask_b32_e64 v89, v89, v124, s[14:15]
	v_cndmask_b32_e32 v124, 0, v226, vcc
	v_sub_f32_e32 v89, v89, v124
	v_pk_add_f32 v[88:89], v[112:113], v[88:89] neg_lo:[0,1] neg_hi:[0,1]
	s_nop 0
	v_pk_add_f32 v[94:95], v[88:89], v[94:95]
	s_nop 0
	v_pk_add_f32 v[112:113], v[94:95], v[90:91] neg_lo:[0,1] neg_hi:[0,1]
	v_mul_f32_e64 v88, |v112|, s69
	v_exp_f32_e32 v124, v88
	v_pk_mul_f32 v[88:89], v[114:115], v[106:107]
	v_mul_f32_e64 v115, |v113|, s69
	v_exp_f32_e32 v115, v115
	v_add_f32_e32 v107, 1.0, v124
	v_cmp_gt_f32_e32 vcc, s74, v107
	v_max_f32_e32 v90, v94, v90
	v_add_f32_e32 v115, 1.0, v115
	v_cndmask_b32_e64 v114, 0, 32, vcc
	v_ldexp_f32 v107, v107, v114
	v_log_f32_e32 v114, v107
	v_pk_mul_f32 v[88:89], v[118:119], v[88:89]
	v_max_f32_e32 v91, v95, v91
	v_mul_f32_e32 v94, 0x3f317217, v114
	v_fma_f32 v94, v114, s75, -v94
	v_fmac_f32_e32 v94, 0x3377d1cf, v114
	v_fmac_f32_e32 v94, 0x3f317217, v114
	v_cmp_lt_f32_e64 s[14:15], |v114|, s63
	v_rcp_f32_e32 v106, v125
	v_rcp_f32_e32 v107, v126
	v_cndmask_b32_e64 v94, v114, v94, s[14:15]
	v_cndmask_b32_e32 v114, 0, v226, vcc
	v_cmp_gt_f32_e32 vcc, s74, v115
	v_sub_f32_e32 v94, v94, v114
	s_nop 0
	v_cndmask_b32_e64 v118, 0, 32, vcc
	v_ldexp_f32 v115, v115, v118
	v_log_f32_e32 v115, v115
	v_cndmask_b32_e32 v114, 0, v226, vcc
	v_cmp_lt_f32_e64 vcc, |v117|, s49
	v_mul_f32_e32 v95, 0x3f317217, v115
	v_fma_f32 v95, v115, s75, -v95
	v_fmac_f32_e32 v95, 0x3377d1cf, v115
	v_fmac_f32_e32 v95, 0x3f317217, v115
	v_cmp_lt_f32_e64 s[14:15], |v115|, s63
	s_nop 1
	v_cndmask_b32_e64 v95, v115, v95, s[14:15]
	v_cndmask_b32_e32 v115, 0, v120, vcc
	v_cmp_lt_f32_e64 vcc, |v116|, s49
	v_sub_f32_e32 v95, v95, v114
	s_nop 0
	v_cndmask_b32_e32 v114, 0, v121, vcc
	v_cmp_lt_f32_e64 vcc, |v113|, s49
	v_pk_add_f32 v[92:93], v[92:93], v[114:115]
	s_nop 0
	v_cndmask_b32_e32 v95, 0, v95, vcc
	v_cmp_lt_f32_e64 vcc, |v112|, s49
	s_nop 1
	v_cndmask_b32_e32 v94, 0, v94, vcc
	v_cmp_lt_f32_e32 vcc, 0, v103
	v_pk_add_f32 v[94:95], v[90:91], v[94:95]
	s_nop 0
	v_cndmask_b32_e32 v91, 1.0, v123, vcc
	v_cmp_lt_f32_e32 vcc, 0, v102
	s_nop 1
	v_cndmask_b32_e32 v90, 1.0, v122, vcc
	v_pk_mul_f32 v[90:91], v[90:91], v[108:109]
	s_nop 0
	v_pk_mul_f32 v[90:91], v[106:107], v[90:91]
	v_lshl_add_u64 v[106:107], v[110:111], 2, s[94:95]
	global_store_dwordx4 v[106:107], v[92:95], off

.LBB0_1298:
	s_add_u32 s0, s22, s0
	s_addc_u32 s1, s23, s1
	v_mov_b32_e32 v135, v134
	v_lshl_add_u64 v[84:85], v[84:85], 1, s[0:1]
	v_cvt_pk_bf16_f32 v88, v88, v89
	v_cvt_pk_bf16_f32 v89, v90, v91
	v_or_b32_e32 v132, v132, v168
	v_pk_mul_f32 v[102:103], v[86:87], v[134:135]
	s_and_b64 vcc, exec, s[10:11]
	s_mov_b64 s[0:1], -1
	global_store_dwordx2 v[84:85], v[88:89], off offset:16
	s_cbranch_vccnz .LBB0_1300
	v_lshlrev_b32_e32 v84, 2, v194
	v_lshlrev_b32_e32 v92, 2, v168
	global_load_dwordx4 v[88:91], v84, s[86:87] offset:48
	s_nop 0
	global_load_dwordx4 v[84:87], v92, s[66:67]
	v_mul_f32_e64 v104, |v100|, s69
	global_load_dwordx4 v[92:95], v92, s[56:57]
	v_max_f32_e32 v105, v100, v100
	v_mul_f32_e64 v106, |v101|, s69
	v_exp_f32_e32 v113, v104
	v_min_f32_e32 v108, 0, v105
	v_exp_f32_e32 v105, v106
	v_max_f32_e32 v107, v101, v101
	v_mul_f32_e64 v112, |v103|, s69
	v_cmp_lt_f32_e32 vcc, 0, v101
	v_min_f32_e32 v109, 0, v107
	v_exp_f32_e32 v115, v112
	v_add_f32_e32 v112, 1.0, v113
	v_cndmask_b32_e32 v107, 1.0, v105, vcc
	v_cmp_lt_f32_e32 vcc, 0, v100
	v_add_f32_e32 v116, 1.0, v105
	v_cmp_gt_f32_e64 s[14:15], s74, v116
	v_cndmask_b32_e32 v106, 1.0, v113, vcc
	v_cmp_gt_f32_e32 vcc, s74, v112
	v_cndmask_b32_e64 v113, 0, 32, s[14:15]
	v_ldexp_f32 v113, v116, v113
	v_cndmask_b32_e64 v105, 0, 32, vcc
	v_ldexp_f32 v105, v112, v105
	v_log_f32_e32 v105, v105
	v_log_f32_e32 v113, v113
	v_mul_f32_e64 v110, |v102|, s69
	v_exp_f32_e32 v114, v110
	v_mul_f32_e32 v121, 0x3f317217, v105
	v_mul_f32_e32 v122, 0x3f317217, v113
	v_fma_f32 v121, v105, s75, -v121
	v_fma_f32 v122, v113, s75, -v122
	v_fmac_f32_e32 v121, 0x3377d1cf, v105
	v_rcp_f32_e32 v110, v112
	v_cndmask_b32_e32 v112, 0, v226, vcc
	v_fmac_f32_e32 v122, 0x3377d1cf, v113
	v_fmac_f32_e32 v121, 0x3f317217, v105
	v_cmp_lt_f32_e64 vcc, |v105|, s63
	v_max_f32_e32 v111, v102, v102
	v_add_f32_e32 v117, 1.0, v114
	v_fmac_f32_e32 v122, 0x3f317217, v113
	v_cndmask_b32_e32 v105, v105, v121, vcc
	v_cmp_lt_f32_e64 vcc, |v113|, s63
	v_min_f32_e32 v104, 0, v111
	v_rcp_f32_e32 v111, v116
	v_cmp_gt_f32_e64 s[16:17], s74, v117
	v_cndmask_b32_e64 v116, 0, v226, s[14:15]
	v_cndmask_b32_e32 v113, v113, v122, vcc
	v_cndmask_b32_e64 v119, 0, 32, s[16:17]
	v_sub_f32_e32 v112, v105, v112
	v_sub_f32_e32 v113, v113, v116
	v_ldexp_f32 v119, v117, v119
	v_pk_add_f32 v[108:109], v[108:109], v[112:113] neg_lo:[0,1] neg_hi:[0,1]
	v_log_f32_e32 v119, v119
	v_add_f32_e32 v118, 1.0, v115
	v_cndmask_b32_e64 v120, 0, v226, s[16:17]
	s_mov_b64 s[0:1], 0
	v_mul_f32_e32 v123, 0x3f317217, v119
	v_fma_f32 v123, v119, s75, -v123
	v_fmac_f32_e32 v123, 0x3377d1cf, v119
	v_fmac_f32_e32 v123, 0x3f317217, v119
	v_cmp_lt_f32_e64 vcc, |v119|, s63
	s_waitcnt vmcnt(0)
	v_pk_add_f32 v[108:109], v[108:109], v[88:89]
	s_nop 0
	v_pk_add_f32 v[88:89], v[108:109], v[84:85] neg_lo:[0,1] neg_hi:[0,1]
	v_max_f32_e32 v105, v84, v84
	v_mul_f32_e64 v84, |v88|, s69
	v_max_f32_e32 v112, v85, v85
	v_mul_f32_e64 v85, |v89|, s69
	v_exp_f32_e32 v113, v84
	v_exp_f32_e32 v116, v85
	v_max_f32_e32 v84, v108, v105
	v_cndmask_b32_e32 v119, v119, v123, vcc
	v_add_f32_e32 v105, 1.0, v113
	v_add_f32_e32 v108, 1.0, v116
	v_cmp_gt_f32_e32 vcc, s74, v105
	v_max_f32_e32 v85, v109, v112
	v_cmp_gt_f32_e64 s[14:15], s74, v108
	v_cndmask_b32_e64 v109, 0, 32, vcc
	v_ldexp_f32 v105, v105, v109
	v_cndmask_b32_e64 v112, 0, 32, s[14:15]
	v_ldexp_f32 v108, v108, v112
	v_log_f32_e32 v105, v105
	v_log_f32_e32 v108, v108
	v_cndmask_b32_e32 v109, 0, v226, vcc
	v_cndmask_b32_e64 v112, 0, v226, s[14:15]
	v_mul_f32_e32 v113, 0x3f317217, v105
	v_mul_f32_e32 v116, 0x3f317217, v108
	v_fma_f32 v113, v105, s75, -v113
	v_fma_f32 v116, v108, s75, -v116
	v_fmac_f32_e32 v113, 0x3377d1cf, v105
	v_fmac_f32_e32 v116, 0x3377d1cf, v108
	v_fmac_f32_e32 v113, 0x3f317217, v105
	v_cmp_lt_f32_e64 vcc, |v105|, s63
	v_fmac_f32_e32 v116, 0x3f317217, v108
	v_pk_mul_f32 v[92:93], v[106:107], v[92:93]
	v_cndmask_b32_e32 v105, v105, v113, vcc
	v_cmp_lt_f32_e64 vcc, |v108|, s63
	v_sub_f32_e32 v113, v105, v109
	v_pk_mul_f32 v[92:93], v[110:111], v[92:93]
	v_cndmask_b32_e32 v108, v108, v116, vcc
	v_cmp_gt_f32_e32 vcc, s74, v118
	v_sub_f32_e32 v112, v108, v112
	v_sub_f32_e32 v108, v119, v120
	v_cndmask_b32_e64 v105, 0, 32, vcc
	v_ldexp_f32 v105, v118, v105
	v_log_f32_e32 v109, v105
	v_max_f32_e32 v105, v103, v103
	v_min_f32_e32 v105, 0, v105
	v_rcp_f32_e32 v106, v117
	v_mul_f32_e32 v116, 0x3f317217, v109
	v_fma_f32 v116, v109, s75, -v116
	v_fmac_f32_e32 v116, 0x3377d1cf, v109
	v_fmac_f32_e32 v116, 0x3f317217, v109
	v_cmp_lt_f32_e64 s[14:15], |v109|, s63
	s_nop 1
	v_cndmask_b32_e64 v109, v109, v116, s[14:15]
	v_cndmask_b32_e32 v116, 0, v226, vcc
	v_sub_f32_e32 v109, v109, v116
	v_pk_add_f32 v[104:105], v[104:105], v[108:109] neg_lo:[0,1] neg_hi:[0,1]
	s_nop 0
	v_pk_add_f32 v[90:91], v[104:105], v[90:91]
	s_nop 0
	v_pk_add_f32 v[104:105], v[90:91], v[86:87] neg_lo:[0,1] neg_hi:[0,1]
	v_mul_f32_e64 v108, |v104|, s69
	v_exp_f32_e32 v108, v108
	v_mul_f32_e64 v109, |v105|, s69
	v_exp_f32_e32 v109, v109
	v_max_f32_e32 v86, v90, v86
	v_add_f32_e32 v107, 1.0, v108
	v_cmp_gt_f32_e32 vcc, s74, v107
	v_add_f32_e32 v109, 1.0, v109
	v_cndmask_b32_e64 v108, 0, 32, vcc
	v_ldexp_f32 v107, v107, v108
	v_log_f32_e32 v108, v107
	v_max_f32_e32 v87, v91, v87
	v_rcp_f32_e32 v107, v118
	v_mul_f32_e32 v90, 0x3f317217, v108
	v_fma_f32 v90, v108, s75, -v90
	v_fmac_f32_e32 v90, 0x3377d1cf, v108
	v_fmac_f32_e32 v90, 0x3f317217, v108
	v_cmp_lt_f32_e64 s[14:15], |v108|, s63
	s_nop 1
	v_cndmask_b32_e64 v90, v108, v90, s[14:15]
	v_cndmask_b32_e32 v108, 0, v226, vcc
	v_cmp_gt_f32_e32 vcc, s74, v109
	v_sub_f32_e32 v90, v90, v108
	s_nop 0
	v_cndmask_b32_e64 v110, 0, 32, vcc
	v_ldexp_f32 v109, v109, v110
	v_log_f32_e32 v109, v109
	v_cndmask_b32_e32 v108, 0, v226, vcc
	v_cmp_lt_f32_e64 vcc, |v89|, s49
	v_mul_f32_e32 v91, 0x3f317217, v109
	v_fma_f32 v91, v109, s75, -v91
	v_fmac_f32_e32 v91, 0x3377d1cf, v109
	v_fmac_f32_e32 v91, 0x3f317217, v109
	v_cmp_lt_f32_e64 s[14:15], |v109|, s63
	v_cndmask_b32_e32 v89, 0, v112, vcc
	v_cmp_lt_f32_e64 vcc, |v88|, s49
	v_cndmask_b32_e64 v91, v109, v91, s[14:15]
	v_sub_f32_e32 v91, v91, v108
	v_cndmask_b32_e32 v88, 0, v113, vcc
	v_cmp_lt_f32_e64 vcc, |v105|, s49
	v_pk_add_f32 v[84:85], v[84:85], v[88:89]
	s_nop 0
	v_cndmask_b32_e32 v91, 0, v91, vcc
	v_cmp_lt_f32_e64 vcc, |v104|, s49
	s_nop 1
	v_cndmask_b32_e32 v90, 0, v90, vcc
	v_cmp_lt_f32_e32 vcc, 0, v103
	v_pk_add_f32 v[86:87], v[86:87], v[90:91]
	v_lshl_add_u64 v[90:91], v[132:133], 2, s[94:95]
	v_cndmask_b32_e32 v89, 1.0, v115, vcc
	v_cmp_lt_f32_e32 vcc, 0, v102
	global_store_dwordx4 v[90:91], v[84:87], off
	s_nop 0
	v_cndmask_b32_e32 v88, 1.0, v114, vcc
	v_pk_mul_f32 v[88:89], v[88:89], v[94:95]
	v_lshl_add_u64 v[84:85], v[132:133], 1, s[84:85]
	v_pk_mul_f32 v[88:89], v[106:107], v[88:89]
	v_cvt_pk_bf16_f32 v86, v92, v93
	v_cvt_pk_bf16_f32 v87, v88, v89
	global_store_dwordx2 v[84:85], v[86:87], off

.LBB0_1321:
	s_and_b64 vcc, exec, s[0:1]
	s_cbranch_vccz .LBB0_1338
	s_and_b64 vcc, exec, s[10:11]
	s_mov_b64 s[0:1], -1
	s_cbranch_vccnz .LBB0_1324
	v_lshlrev_b32_e32 v68, 2, v194
	global_load_dwordx4 v[100:103], v68, s[86:87]
	global_load_dwordx4 v[96:99], v68, s[66:67]
	global_load_dwordx4 v[104:107], v68, s[56:57]
	v_mul_f32_e64 v69, |v92|, s69
	v_max_f32_e32 v72, v92, v92
	v_mul_f32_e64 v73, |v93|, s69
	v_exp_f32_e32 v86, v69
	v_min_f32_e32 v68, 0, v72
	v_exp_f32_e32 v72, v73
	v_mul_f32_e64 v83, |v95|, s69
	v_cmp_lt_f32_e32 vcc, 0, v93
	v_max_f32_e32 v76, v93, v93
	v_mul_f32_e64 v77, |v94|, s69
	v_max_f32_e32 v82, v94, v94
	v_exp_f32_e32 v91, v83
	v_add_f32_e32 v73, 1.0, v86
	v_cndmask_b32_e32 v83, 1.0, v72, vcc
	v_cmp_lt_f32_e32 vcc, 0, v92
	v_min_f32_e32 v69, 0, v76
	v_exp_f32_e32 v90, v77
	v_min_f32_e32 v76, 0, v82
	v_add_f32_e32 v77, 1.0, v72
	v_cndmask_b32_e32 v82, 1.0, v86, vcc
	v_cmp_gt_f32_e32 vcc, s74, v73
	v_cmp_gt_f32_e64 s[14:15], s74, v77
	v_rcp_f32_e32 v87, v77
	v_cndmask_b32_e64 v72, 0, 32, vcc
	v_cndmask_b32_e64 v110, 0, 32, s[14:15]
	v_ldexp_f32 v72, v73, v72
	v_ldexp_f32 v77, v77, v110
	v_log_f32_e32 v72, v72
	v_log_f32_e32 v77, v77
	v_rcp_f32_e32 v86, v73
	v_cndmask_b32_e32 v73, 0, v226, vcc
	v_mul_f32_e32 v118, 0x3f317217, v72
	v_mul_f32_e32 v119, 0x3f317217, v77
	v_fma_f32 v118, v72, s75, -v118
	v_fma_f32 v119, v77, s75, -v119
	v_fmac_f32_e32 v118, 0x3377d1cf, v72
	v_fmac_f32_e32 v119, 0x3377d1cf, v77
	v_fmac_f32_e32 v118, 0x3f317217, v72
	v_cmp_lt_f32_e64 vcc, |v72|, s63
	v_add_f32_e32 v108, 1.0, v90
	v_fmac_f32_e32 v119, 0x3f317217, v77
	v_cndmask_b32_e32 v72, v72, v118, vcc
	v_cmp_lt_f32_e64 vcc, |v77|, s63
	v_cmp_gt_f32_e64 s[16:17], s74, v108
	v_cndmask_b32_e64 v110, 0, v226, s[14:15]
	v_cndmask_b32_e32 v77, v77, v119, vcc
	v_cndmask_b32_e64 v111, 0, 32, s[16:17]
	v_sub_f32_e32 v72, v72, v73
	v_sub_f32_e32 v73, v77, v110
	v_ldexp_f32 v111, v108, v111
	v_pk_add_f32 v[68:69], v[68:69], v[72:73] neg_lo:[0,1] neg_hi:[0,1]
	v_log_f32_e32 v111, v111
	v_add_f32_e32 v109, 1.0, v91
	v_cndmask_b32_e64 v115, 0, v226, s[16:17]
	s_mov_b64 s[0:1], 0
	v_mul_f32_e32 v120, 0x3f317217, v111
	v_fma_f32 v120, v111, s75, -v120
	v_fmac_f32_e32 v120, 0x3377d1cf, v111
	v_fmac_f32_e32 v120, 0x3f317217, v111
	v_cmp_lt_f32_e64 vcc, |v111|, s63
	s_waitcnt vmcnt(0)
	v_pk_add_f32 v[68:69], v[68:69], v[100:101]
	s_nop 0
	v_pk_add_f32 v[72:73], v[68:69], v[96:97] neg_lo:[0,1] neg_hi:[0,1]
	v_max_f32_e32 v77, v96, v96
	v_mul_f32_e64 v96, |v72|, s69
	v_max_f32_e32 v100, v97, v97
	v_mul_f32_e64 v97, |v73|, s69
	v_exp_f32_e32 v96, v96
	v_exp_f32_e32 v97, v97
	v_max_f32_e32 v68, v68, v77
	v_cndmask_b32_e32 v111, v111, v120, vcc
	v_add_f32_e32 v77, 1.0, v96
	v_add_f32_e32 v96, 1.0, v97
	v_cmp_gt_f32_e32 vcc, s74, v77
	v_cmp_gt_f32_e64 s[14:15], s74, v96
	v_max_f32_e32 v69, v69, v100
	v_cndmask_b32_e64 v97, 0, 32, vcc
	v_cndmask_b32_e64 v100, 0, 32, s[14:15]
	v_ldexp_f32 v77, v77, v97
	v_ldexp_f32 v96, v96, v100
	v_log_f32_e32 v77, v77
	v_log_f32_e32 v96, v96
	v_cndmask_b32_e32 v97, 0, v226, vcc
	v_cndmask_b32_e64 v100, 0, v226, s[14:15]
	v_mul_f32_e32 v101, 0x3f317217, v77
	v_mul_f32_e32 v110, 0x3f317217, v96
	v_fma_f32 v101, v77, s75, -v101
	v_fma_f32 v110, v96, s75, -v110
	v_fmac_f32_e32 v101, 0x3377d1cf, v77
	v_fmac_f32_e32 v110, 0x3377d1cf, v96
	v_fmac_f32_e32 v101, 0x3f317217, v77
	v_cmp_lt_f32_e64 vcc, |v77|, s63
	v_fmac_f32_e32 v110, 0x3f317217, v96
	s_nop 0
	v_cndmask_b32_e32 v77, v77, v101, vcc
	v_cmp_lt_f32_e64 vcc, |v96|, s63
	s_nop 1
	v_cndmask_b32_e32 v96, v96, v110, vcc
	v_cmp_gt_f32_e32 vcc, s74, v109
	v_sub_f32_e32 v110, v77, v97
	v_sub_f32_e32 v118, v96, v100
	v_cndmask_b32_e64 v77, 0, 32, vcc
	v_ldexp_f32 v77, v109, v77
	v_log_f32_e32 v97, v77
	v_max_f32_e32 v77, v95, v95
	v_sub_f32_e32 v96, v111, v115
	v_min_f32_e32 v77, 0, v77
	v_mul_f32_e32 v100, 0x3f317217, v97
	v_fma_f32 v100, v97, s75, -v100
	v_fmac_f32_e32 v100, 0x3377d1cf, v97
	v_fmac_f32_e32 v100, 0x3f317217, v97
	v_cmp_lt_f32_e64 s[14:15], |v97|, s63
	s_nop 1
	v_cndmask_b32_e64 v97, v97, v100, s[14:15]
	v_cndmask_b32_e32 v100, 0, v226, vcc
	v_sub_f32_e32 v97, v97, v100
	v_pk_add_f32 v[76:77], v[76:77], v[96:97] neg_lo:[0,1] neg_hi:[0,1]
	s_nop 0
	v_pk_add_f32 v[96:97], v[76:77], v[102:103]
	s_nop 0
	v_pk_add_f32 v[100:101], v[96:97], v[98:99] neg_lo:[0,1] neg_hi:[0,1]
	s_nop 0
	v_mul_f32_e64 v76, |v100|, s69
	v_exp_f32_e32 v102, v76
	v_pk_mul_f32 v[76:77], v[82:83], v[104:105]
	v_rcp_f32_e32 v82, v108
	v_pk_mul_f32 v[76:77], v[86:87], v[76:77]
	v_add_f32_e32 v83, 1.0, v102
	v_cmp_gt_f32_e32 vcc, s74, v83
	s_nop 1
	v_cndmask_b32_e64 v86, 0, 32, vcc
	v_ldexp_f32 v83, v83, v86
	v_log_f32_e32 v87, v83
	v_max_f32_e32 v86, v98, v98
	v_mul_f32_e64 v98, |v101|, s69
	v_exp_f32_e32 v98, v98
	v_max_f32_e32 v86, v96, v86
	v_mul_f32_e32 v96, 0x3f317217, v87
	v_fma_f32 v96, v87, s75, -v96
	v_fmac_f32_e32 v96, 0x3377d1cf, v87
	v_fmac_f32_e32 v96, 0x3f317217, v87
	v_cmp_lt_f32_e64 s[14:15], |v87|, s63
	v_add_f32_e32 v98, 1.0, v98
	v_rcp_f32_e32 v83, v109
	v_cndmask_b32_e64 v87, v87, v96, s[14:15]
	v_cndmask_b32_e32 v96, 0, v226, vcc
	v_cmp_gt_f32_e32 vcc, s74, v98
	v_sub_f32_e32 v96, v87, v96
	v_cndmask_b32_e64 v102, 0, 32, vcc
	v_ldexp_f32 v98, v98, v102
	v_log_f32_e32 v98, v98
	v_max_f32_e32 v87, v97, v99
	v_mul_f32_e32 v97, 0x3f317217, v98
	v_fma_f32 v97, v98, s75, -v97
	v_fmac_f32_e32 v97, 0x3377d1cf, v98
	v_fmac_f32_e32 v97, 0x3f317217, v98
	v_cmp_lt_f32_e64 s[14:15], |v98|, s63
	s_nop 1
	v_cndmask_b32_e64 v97, v98, v97, s[14:15]
	v_cndmask_b32_e32 v98, 0, v226, vcc
	v_cmp_lt_f32_e64 vcc, |v73|, s49
	v_sub_f32_e32 v97, v97, v98
	s_nop 0
	v_cndmask_b32_e32 v73, 0, v118, vcc
	v_cmp_lt_f32_e64 vcc, |v72|, s49
	s_nop 1
	v_cndmask_b32_e32 v72, 0, v110, vcc
	v_cmp_lt_f32_e64 vcc, |v101|, s49
	s_nop 1
	v_cndmask_b32_e32 v97, 0, v97, vcc
	v_cmp_lt_f32_e64 vcc, |v100|, s49
	s_nop 1
	v_cndmask_b32_e32 v96, 0, v96, vcc
	v_cmp_lt_f32_e32 vcc, 0, v95
	v_pk_add_f32 v[98:99], v[86:87], v[96:97]
	v_pk_add_f32 v[96:97], v[68:69], v[72:73]
	v_cndmask_b32_e32 v69, 1.0, v91, vcc
	v_cmp_lt_f32_e32 vcc, 0, v94
	v_lshl_add_u64 v[72:73], v[116:117], 2, s[94:95]
	global_store_dwordx4 v[72:73], v[96:99], off
	v_cndmask_b32_e32 v68, 1.0, v90, vcc
	v_pk_mul_f32 v[68:69], v[68:69], v[106:107]
	s_nop 0
	v_pk_mul_f32 v[68:69], v[82:83], v[68:69]

.LBB0_1326:
	s_add_u32 s0, s22, s0
	s_addc_u32 s1, s23, s1
	v_mov_b32_e32 v115, v114
	v_lshl_add_u64 v[72:73], v[116:117], 1, s[0:1]
	v_cvt_pk_bf16_f32 v76, v76, v77
	v_cvt_pk_bf16_f32 v77, v68, v69
	v_pk_mul_f32 v[68:69], v[78:79], v[114:115]
	s_and_b64 vcc, exec, s[10:11]
	s_mov_b64 s[0:1], -1
	global_store_dwordx2 v[72:73], v[76:77], off
	s_cbranch_vccnz .LBB0_1328
	v_lshlrev_b32_e32 v72, 2, v194
	v_lshlrev_b32_e32 v82, 2, v170
	global_load_dwordx4 v[90:93], v72, s[86:87] offset:16
	global_load_dwordx4 v[76:79], v82, s[66:67]
	global_load_dwordx4 v[94:97], v82, s[56:57]
	v_mul_f32_e64 v83, |v88|, s69
	v_mul_f32_e64 v87, |v89|, s69
	v_exp_f32_e32 v104, v83
	v_exp_f32_e32 v87, v87
	v_mul_f32_e64 v99, |v68|, s69
	v_cmp_lt_f32_e32 vcc, 0, v89
	v_max_f32_e32 v98, v89, v89
	v_exp_f32_e32 v102, v99
	v_add_f32_e32 v105, 1.0, v104
	v_cndmask_b32_e32 v99, 1.0, v87, vcc
	v_cmp_lt_f32_e32 vcc, 0, v88
	v_min_f32_e32 v83, 0, v98
	v_add_f32_e32 v106, 1.0, v87
	v_cndmask_b32_e32 v98, 1.0, v104, vcc
	v_cmp_gt_f32_e32 vcc, s74, v105
	v_cmp_gt_f32_e64 s[14:15], s74, v106
	v_max_f32_e32 v86, v88, v88
	v_cndmask_b32_e64 v87, 0, 32, vcc
	v_cndmask_b32_e64 v104, 0, 32, s[14:15]
	v_ldexp_f32 v87, v105, v87
	v_ldexp_f32 v104, v106, v104
	v_log_f32_e32 v87, v87
	v_log_f32_e32 v104, v104
	v_max_f32_e32 v100, v68, v68
	v_add_f32_e32 v107, 1.0, v102
	v_mul_f32_e32 v109, 0x3f317217, v87
	v_mul_f32_e32 v110, 0x3f317217, v104
	v_fma_f32 v109, v87, s75, -v109
	v_fma_f32 v110, v104, s75, -v110
	v_fmac_f32_e32 v109, 0x3377d1cf, v87
	v_min_f32_e32 v82, 0, v86
	v_min_f32_e32 v86, 0, v100
	v_rcp_f32_e32 v100, v105
	v_cmp_gt_f32_e64 s[16:17], s74, v107
	v_cndmask_b32_e32 v105, 0, v226, vcc
	v_fmac_f32_e32 v110, 0x3377d1cf, v104
	v_fmac_f32_e32 v109, 0x3f317217, v87
	v_cmp_lt_f32_e64 vcc, |v87|, s63
	v_mul_f32_e64 v101, |v69|, s69
	v_cndmask_b32_e64 v108, 0, 32, s[16:17]
	v_fmac_f32_e32 v110, 0x3f317217, v104
	v_cndmask_b32_e32 v87, v87, v109, vcc
	v_cmp_lt_f32_e64 vcc, |v104|, s63
	v_exp_f32_e32 v103, v101
	v_rcp_f32_e32 v101, v106
	v_ldexp_f32 v106, v107, v108
	v_cndmask_b32_e64 v108, 0, v226, s[14:15]
	v_cndmask_b32_e32 v109, v104, v110, vcc
	v_sub_f32_e32 v104, v87, v105
	v_sub_f32_e32 v105, v109, v108
	v_pk_add_f32 v[82:83], v[82:83], v[104:105] neg_lo:[0,1] neg_hi:[0,1]
	v_log_f32_e32 v106, v106
	v_or_b32_e32 v72, v112, v170
	v_mov_b32_e32 v73, v113
	v_lshl_add_u64 v[72:73], v[72:73], 2, s[94:95]
	v_mul_f32_e32 v111, 0x3f317217, v106
	v_fma_f32 v111, v106, s75, -v111
	v_fmac_f32_e32 v111, 0x3377d1cf, v106
	v_fmac_f32_e32 v111, 0x3f317217, v106
	v_cmp_lt_f32_e64 vcc, |v106|, s63
	s_mov_b64 s[0:1], 0
	s_waitcnt vmcnt(0)
	v_pk_add_f32 v[90:91], v[82:83], v[90:91]
	s_nop 0
	v_pk_add_f32 v[82:83], v[90:91], v[76:77] neg_lo:[0,1] neg_hi:[0,1]
	v_max_f32_e32 v87, v76, v76
	v_mul_f32_e64 v76, |v82|, s69
	v_max_f32_e32 v104, v77, v77
	v_mul_f32_e64 v77, |v83|, s69
	v_exp_f32_e32 v105, v76
	v_exp_f32_e32 v108, v77
	v_max_f32_e32 v76, v90, v87
	v_cndmask_b32_e32 v106, v106, v111, vcc
	v_add_f32_e32 v87, 1.0, v105
	v_add_f32_e32 v90, 1.0, v108
	v_cmp_gt_f32_e32 vcc, s74, v87
	v_max_f32_e32 v77, v91, v104
	v_cmp_gt_f32_e64 s[14:15], s74, v90
	v_cndmask_b32_e64 v91, 0, 32, vcc
	v_ldexp_f32 v87, v87, v91
	v_cndmask_b32_e64 v104, 0, 32, s[14:15]
	v_ldexp_f32 v90, v90, v104
	v_log_f32_e32 v87, v87
	v_log_f32_e32 v90, v90
	v_cndmask_b32_e32 v91, 0, v226, vcc
	v_cndmask_b32_e64 v104, 0, v226, s[14:15]
	v_mul_f32_e32 v105, 0x3f317217, v87
	v_mul_f32_e32 v108, 0x3f317217, v90
	v_fma_f32 v105, v87, s75, -v105
	v_fma_f32 v108, v90, s75, -v108
	v_fmac_f32_e32 v105, 0x3377d1cf, v87
	v_fmac_f32_e32 v108, 0x3377d1cf, v90
	v_fmac_f32_e32 v105, 0x3f317217, v87
	v_cmp_lt_f32_e64 vcc, |v87|, s63
	v_fmac_f32_e32 v108, 0x3f317217, v90
	s_nop 0
	v_cndmask_b32_e32 v87, v87, v105, vcc
	v_cmp_lt_f32_e64 vcc, |v90|, s63
	v_sub_f32_e32 v105, v87, v91
	v_cndmask_b32_e64 v87, 0, v226, s[16:17]
	v_cndmask_b32_e32 v90, v90, v108, vcc
	v_add_f32_e32 v108, 1.0, v103
	v_cmp_gt_f32_e32 vcc, s74, v108
	v_sub_f32_e32 v104, v90, v104
	s_nop 0
	v_cndmask_b32_e64 v90, 0, 32, vcc
	v_ldexp_f32 v90, v108, v90
	v_log_f32_e32 v91, v90
	v_sub_f32_e32 v90, v106, v87
	v_max_f32_e32 v87, v69, v69
	v_min_f32_e32 v87, 0, v87
	v_mul_f32_e32 v106, 0x3f317217, v91
	v_fma_f32 v106, v91, s75, -v106
	v_fmac_f32_e32 v106, 0x3377d1cf, v91
	v_fmac_f32_e32 v106, 0x3f317217, v91
	v_cmp_lt_f32_e64 s[14:15], |v91|, s63
	s_nop 1
	v_cndmask_b32_e64 v91, v91, v106, s[14:15]
	v_cndmask_b32_e32 v106, 0, v226, vcc
	v_sub_f32_e32 v91, v91, v106
	v_pk_add_f32 v[86:87], v[86:87], v[90:91] neg_lo:[0,1] neg_hi:[0,1]
	s_nop 0
	v_pk_add_f32 v[90:91], v[86:87], v[92:93]
	s_nop 0
	v_pk_add_f32 v[92:93], v[90:91], v[78:79] neg_lo:[0,1] neg_hi:[0,1]
	v_mul_f32_e64 v86, |v92|, s69
	v_exp_f32_e32 v106, v86
	v_pk_mul_f32 v[86:87], v[98:99], v[94:95]
	v_mul_f32_e64 v99, |v93|, s69
	v_exp_f32_e32 v99, v99
	v_add_f32_e32 v95, 1.0, v106
	v_cmp_gt_f32_e32 vcc, s74, v95
	v_max_f32_e32 v78, v90, v78
	v_add_f32_e32 v99, 1.0, v99
	v_cndmask_b32_e64 v98, 0, 32, vcc
	v_ldexp_f32 v95, v95, v98
	v_log_f32_e32 v98, v95
	v_pk_mul_f32 v[86:87], v[100:101], v[86:87]
	v_max_f32_e32 v79, v91, v79
	v_mul_f32_e32 v90, 0x3f317217, v98
	v_fma_f32 v90, v98, s75, -v90
	v_fmac_f32_e32 v90, 0x3377d1cf, v98
	v_fmac_f32_e32 v90, 0x3f317217, v98
	v_cmp_lt_f32_e64 s[14:15], |v98|, s63
	v_rcp_f32_e32 v94, v107
	v_rcp_f32_e32 v95, v108
	v_cndmask_b32_e64 v90, v98, v90, s[14:15]
	v_cndmask_b32_e32 v98, 0, v226, vcc
	v_cmp_gt_f32_e32 vcc, s74, v99
	v_sub_f32_e32 v90, v90, v98
	s_nop 0
	v_cndmask_b32_e64 v100, 0, 32, vcc
	v_ldexp_f32 v99, v99, v100
	v_log_f32_e32 v99, v99
	v_cndmask_b32_e32 v98, 0, v226, vcc
	v_cmp_lt_f32_e64 vcc, |v83|, s49
	v_mul_f32_e32 v91, 0x3f317217, v99
	v_fma_f32 v91, v99, s75, -v91
	v_fmac_f32_e32 v91, 0x3377d1cf, v99
	v_fmac_f32_e32 v91, 0x3f317217, v99
	v_cmp_lt_f32_e64 s[14:15], |v99|, s63
	v_cndmask_b32_e32 v83, 0, v104, vcc
	v_cmp_lt_f32_e64 vcc, |v82|, s49
	v_cndmask_b32_e64 v91, v99, v91, s[14:15]
	v_sub_f32_e32 v91, v91, v98
	v_cndmask_b32_e32 v82, 0, v105, vcc
	v_cmp_lt_f32_e64 vcc, |v93|, s49
	s_nop 1
	v_cndmask_b32_e32 v91, 0, v91, vcc
	v_cmp_lt_f32_e64 vcc, |v92|, s49
	s_nop 1
	v_cndmask_b32_e32 v90, 0, v90, vcc
	v_cmp_lt_f32_e32 vcc, 0, v69
	v_pk_add_f32 v[92:93], v[78:79], v[90:91]
	v_pk_add_f32 v[90:91], v[76:77], v[82:83]
	v_cndmask_b32_e32 v77, 1.0, v103, vcc
	v_cmp_lt_f32_e32 vcc, 0, v68
	global_store_dwordx4 v[72:73], v[90:93], off
	s_nop 0
	v_cndmask_b32_e32 v76, 1.0, v102, vcc
	v_pk_mul_f32 v[76:77], v[76:77], v[96:97]
	s_nop 0
	v_pk_mul_f32 v[76:77], v[94:95], v[76:77]

.LBB0_1330:
	s_add_u32 s0, s22, s0
	s_addc_u32 s1, s23, s1
	v_lshl_add_u64 v[68:69], v[112:113], 0, v[194:195]
	v_mov_b32_e32 v115, v114
	v_lshl_add_u64 v[72:73], v[68:69], 1, s[0:1]
	v_cvt_pk_bf16_f32 v78, v86, v87
	v_cvt_pk_bf16_f32 v79, v76, v77
	v_pk_mul_f32 v[82:83], v[74:75], v[114:115]
	s_and_b64 vcc, exec, s[10:11]
	s_mov_b64 s[0:1], -1
	global_store_dwordx2 v[72:73], v[78:79], off offset:8
	s_cbranch_vccnz .LBB0_1332
	v_lshlrev_b32_e32 v72, 2, v194
	v_lshlrev_b32_e32 v86, 2, v169
	global_load_dwordx4 v[76:79], v72, s[86:87] offset:32
	s_nop 0
	global_load_dwordx4 v[72:75], v86, s[66:67]
	v_mul_f32_e64 v92, |v84|, s69
	global_load_dwordx4 v[86:89], v86, s[56:57]
	v_max_f32_e32 v93, v84, v84
	v_mul_f32_e64 v94, |v85|, s69
	v_exp_f32_e32 v101, v92
	v_min_f32_e32 v96, 0, v93
	v_exp_f32_e32 v93, v94
	v_mul_f32_e64 v100, |v83|, s69
	v_exp_f32_e32 v103, v100
	v_add_f32_e32 v100, 1.0, v101
	v_max_f32_e32 v95, v85, v85
	v_add_f32_e32 v104, 1.0, v93
	v_cmp_lt_f32_e32 vcc, 0, v85
	v_cmp_gt_f32_e64 s[14:15], s74, v100
	v_min_f32_e32 v97, 0, v95
	v_cndmask_b32_e32 v95, 1.0, v93, vcc
	v_cmp_lt_f32_e32 vcc, 0, v84
	v_cndmask_b32_e64 v93, 0, 32, s[14:15]
	v_cmp_gt_f32_e64 s[16:17], s74, v104
	v_cndmask_b32_e32 v94, 1.0, v101, vcc
	v_ldexp_f32 v93, v100, v93
	v_cndmask_b32_e64 v101, 0, 32, s[16:17]
	v_ldexp_f32 v101, v104, v101
	v_log_f32_e32 v93, v93
	v_mul_f32_e64 v98, |v82|, s69
	v_log_f32_e32 v101, v101
	v_exp_f32_e32 v102, v98
	v_mul_f32_e32 v107, 0x3f317217, v93
	v_fma_f32 v107, v93, s75, -v107
	v_mul_f32_e32 v108, 0x3f317217, v101
	v_add_f32_e32 v105, 1.0, v102
	v_fma_f32 v108, v101, s75, -v108
	v_fmac_f32_e32 v107, 0x3377d1cf, v93
	v_rcp_f32_e32 v98, v100
	v_cmp_gt_f32_e32 vcc, s74, v105
	v_cndmask_b32_e64 v100, 0, v226, s[14:15]
	v_fmac_f32_e32 v108, 0x3377d1cf, v101
	v_fmac_f32_e32 v107, 0x3f317217, v93
	v_cmp_lt_f32_e64 s[14:15], |v93|, s63
	v_max_f32_e32 v99, v82, v82
	v_cndmask_b32_e64 v106, 0, 32, vcc
	v_fmac_f32_e32 v108, 0x3f317217, v101
	v_cndmask_b32_e64 v93, v93, v107, s[14:15]
	v_cmp_lt_f32_e64 s[14:15], |v101|, s63
	v_min_f32_e32 v92, 0, v99
	v_rcp_f32_e32 v99, v104
	v_ldexp_f32 v104, v105, v106
	v_cndmask_b32_e64 v106, 0, v226, s[16:17]
	v_cndmask_b32_e64 v101, v101, v108, s[14:15]
	v_sub_f32_e32 v100, v93, v100
	v_sub_f32_e32 v101, v101, v106
	v_pk_add_f32 v[96:97], v[96:97], v[100:101] neg_lo:[0,1] neg_hi:[0,1]
	v_log_f32_e32 v104, v104
	v_or_b32_e32 v90, v112, v169
	v_mov_b32_e32 v91, v113
	s_mov_b64 s[0:1], 0
	v_mul_f32_e32 v109, 0x3f317217, v104
	v_fma_f32 v109, v104, s75, -v109
	v_fmac_f32_e32 v109, 0x3377d1cf, v104
	v_fmac_f32_e32 v109, 0x3f317217, v104
	v_cmp_lt_f32_e64 s[14:15], |v104|, s63
	s_waitcnt vmcnt(0)
	v_pk_add_f32 v[76:77], v[96:97], v[76:77]
	s_nop 0
	v_pk_add_f32 v[96:97], v[76:77], v[72:73] neg_lo:[0,1] neg_hi:[0,1]
	v_max_f32_e32 v93, v72, v72
	v_mul_f32_e64 v72, |v96|, s69
	v_max_f32_e32 v100, v73, v73
	v_mul_f32_e64 v73, |v97|, s69
	v_exp_f32_e32 v72, v72
	v_exp_f32_e32 v73, v73
	v_cndmask_b32_e64 v104, v104, v109, s[14:15]
	v_max_f32_e32 v76, v76, v93
	v_add_f32_e32 v72, 1.0, v72
	v_add_f32_e32 v73, 1.0, v73
	v_cmp_gt_f32_e64 s[14:15], s74, v72
	v_cmp_gt_f32_e64 s[16:17], s74, v73
	v_max_f32_e32 v77, v77, v100
	v_cndmask_b32_e64 v93, 0, 32, s[14:15]
	v_cndmask_b32_e64 v100, 0, 32, s[16:17]
	v_ldexp_f32 v72, v72, v93
	v_ldexp_f32 v73, v73, v100
	v_log_f32_e32 v72, v72
	v_log_f32_e32 v73, v73
	v_cndmask_b32_e64 v93, 0, v226, s[14:15]
	v_cndmask_b32_e64 v100, 0, v226, s[16:17]
	v_mul_f32_e32 v101, 0x3f317217, v72
	v_mul_f32_e32 v106, 0x3f317217, v73
	v_fma_f32 v101, v72, s75, -v101
	v_fma_f32 v106, v73, s75, -v106
	v_fmac_f32_e32 v101, 0x3377d1cf, v72
	v_fmac_f32_e32 v106, 0x3377d1cf, v73
	v_fmac_f32_e32 v101, 0x3f317217, v72
	v_cmp_lt_f32_e64 s[14:15], |v72|, s63
	v_fmac_f32_e32 v106, 0x3f317217, v73
	s_nop 0
	v_cndmask_b32_e64 v72, v72, v101, s[14:15]
	v_cmp_lt_f32_e64 s[14:15], |v73|, s63
	v_sub_f32_e32 v101, v72, v93
	v_cndmask_b32_e32 v72, 0, v226, vcc
	v_cndmask_b32_e64 v73, v73, v106, s[14:15]
	v_add_f32_e32 v106, 1.0, v103
	v_cmp_gt_f32_e32 vcc, s74, v106
	v_sub_f32_e32 v100, v73, v100
	v_sub_f32_e32 v72, v104, v72
	v_cndmask_b32_e64 v73, 0, 32, vcc
	v_ldexp_f32 v73, v106, v73
	v_log_f32_e32 v73, v73
	v_max_f32_e32 v93, v83, v83
	v_min_f32_e32 v93, 0, v93
	v_mul_f32_e32 v104, 0x3f317217, v73
	v_fma_f32 v104, v73, s75, -v104
	v_fmac_f32_e32 v104, 0x3377d1cf, v73
	v_fmac_f32_e32 v104, 0x3f317217, v73
	v_cmp_lt_f32_e64 s[14:15], |v73|, s63
	s_nop 1
	v_cndmask_b32_e64 v73, v73, v104, s[14:15]
	v_cndmask_b32_e32 v104, 0, v226, vcc
	v_sub_f32_e32 v73, v73, v104
	v_pk_add_f32 v[72:73], v[92:93], v[72:73] neg_lo:[0,1] neg_hi:[0,1]
	s_nop 0
	v_pk_add_f32 v[78:79], v[72:73], v[78:79]
	s_nop 0
	v_pk_add_f32 v[92:93], v[78:79], v[74:75] neg_lo:[0,1] neg_hi:[0,1]
	v_mul_f32_e64 v72, |v92|, s69
	v_exp_f32_e32 v104, v72
	v_pk_mul_f32 v[72:73], v[94:95], v[86:87]
	v_mul_f32_e64 v95, |v93|, s69
	v_exp_f32_e32 v95, v95
	v_add_f32_e32 v87, 1.0, v104
	v_cmp_gt_f32_e32 vcc, s74, v87
	v_max_f32_e32 v74, v78, v74
	v_add_f32_e32 v95, 1.0, v95
	v_cndmask_b32_e64 v94, 0, 32, vcc
	v_ldexp_f32 v87, v87, v94
	v_log_f32_e32 v94, v87
	v_pk_mul_f32 v[72:73], v[98:99], v[72:73]
	v_max_f32_e32 v75, v79, v75
	v_mul_f32_e32 v78, 0x3f317217, v94
	v_fma_f32 v78, v94, s75, -v78
	v_fmac_f32_e32 v78, 0x3377d1cf, v94
	v_fmac_f32_e32 v78, 0x3f317217, v94
	v_cmp_lt_f32_e64 s[14:15], |v94|, s63
	v_rcp_f32_e32 v86, v105
	v_rcp_f32_e32 v87, v106
	v_cndmask_b32_e64 v78, v94, v78, s[14:15]
	v_cndmask_b32_e32 v94, 0, v226, vcc
	v_cmp_gt_f32_e32 vcc, s74, v95
	v_sub_f32_e32 v78, v78, v94
	s_nop 0
	v_cndmask_b32_e64 v98, 0, 32, vcc
	v_ldexp_f32 v95, v95, v98
	v_log_f32_e32 v95, v95
	v_cndmask_b32_e32 v94, 0, v226, vcc
	v_cmp_lt_f32_e64 vcc, |v97|, s49
	v_mul_f32_e32 v79, 0x3f317217, v95
	v_fma_f32 v79, v95, s75, -v79
	v_fmac_f32_e32 v79, 0x3377d1cf, v95
	v_fmac_f32_e32 v79, 0x3f317217, v95
	v_cmp_lt_f32_e64 s[14:15], |v95|, s63
	s_nop 1
	v_cndmask_b32_e64 v79, v95, v79, s[14:15]
	v_cndmask_b32_e32 v95, 0, v100, vcc
	v_cmp_lt_f32_e64 vcc, |v96|, s49
	v_sub_f32_e32 v79, v79, v94
	s_nop 0
	v_cndmask_b32_e32 v94, 0, v101, vcc
	v_cmp_lt_f32_e64 vcc, |v93|, s49
	v_pk_add_f32 v[76:77], v[76:77], v[94:95]
	s_nop 0
	v_cndmask_b32_e32 v79, 0, v79, vcc
	v_cmp_lt_f32_e64 vcc, |v92|, s49
	s_nop 1
	v_cndmask_b32_e32 v78, 0, v78, vcc
	v_cmp_lt_f32_e32 vcc, 0, v83
	v_pk_add_f32 v[78:79], v[74:75], v[78:79]
	s_nop 0
	v_cndmask_b32_e32 v75, 1.0, v103, vcc
	v_cmp_lt_f32_e32 vcc, 0, v82
	s_nop 1
	v_cndmask_b32_e32 v74, 1.0, v102, vcc
	v_pk_mul_f32 v[74:75], v[74:75], v[88:89]
	s_nop 0
	v_pk_mul_f32 v[74:75], v[86:87], v[74:75]
	v_lshl_add_u64 v[86:87], v[90:91], 2, s[94:95]
	global_store_dwordx4 v[86:87], v[76:79], off

.LBB0_1334:
	s_add_u32 s0, s22, s0
	s_addc_u32 s1, s23, s1
	v_mov_b32_e32 v115, v114
	v_lshl_add_u64 v[68:69], v[68:69], 1, s[0:1]
	v_cvt_pk_bf16_f32 v72, v72, v73
	v_cvt_pk_bf16_f32 v73, v74, v75
	v_or_b32_e32 v112, v112, v168
	v_pk_mul_f32 v[82:83], v[70:71], v[114:115]
	s_and_b64 vcc, exec, s[10:11]
	s_mov_b64 s[0:1], -1
	global_store_dwordx2 v[68:69], v[72:73], off offset:16
	s_cbranch_vccnz .LBB0_1336
	v_lshlrev_b32_e32 v68, 2, v194
	v_lshlrev_b32_e32 v76, 2, v168
	global_load_dwordx4 v[72:75], v68, s[86:87] offset:48
	s_nop 0
	global_load_dwordx4 v[68:71], v76, s[66:67]
	v_mul_f32_e64 v84, |v80|, s69
	global_load_dwordx4 v[76:79], v76, s[56:57]
	v_max_f32_e32 v85, v80, v80
	v_mul_f32_e64 v86, |v81|, s69
	v_exp_f32_e32 v93, v84
	v_min_f32_e32 v88, 0, v85
	v_exp_f32_e32 v85, v86
	v_max_f32_e32 v87, v81, v81
	v_mul_f32_e64 v92, |v83|, s69
	v_cmp_lt_f32_e32 vcc, 0, v81
	v_min_f32_e32 v89, 0, v87
	v_exp_f32_e32 v95, v92
	v_add_f32_e32 v92, 1.0, v93
	v_cndmask_b32_e32 v87, 1.0, v85, vcc
	v_cmp_lt_f32_e32 vcc, 0, v80
	v_add_f32_e32 v96, 1.0, v85
	v_cmp_gt_f32_e64 s[14:15], s74, v96
	v_cndmask_b32_e32 v86, 1.0, v93, vcc
	v_cmp_gt_f32_e32 vcc, s74, v92
	v_cndmask_b32_e64 v93, 0, 32, s[14:15]
	v_ldexp_f32 v93, v96, v93
	v_cndmask_b32_e64 v85, 0, 32, vcc
	v_ldexp_f32 v85, v92, v85
	v_log_f32_e32 v85, v85
	v_log_f32_e32 v93, v93
	v_mul_f32_e64 v90, |v82|, s69
	v_exp_f32_e32 v94, v90
	v_mul_f32_e32 v101, 0x3f317217, v85
	v_mul_f32_e32 v102, 0x3f317217, v93
	v_fma_f32 v101, v85, s75, -v101
	v_fma_f32 v102, v93, s75, -v102
	v_fmac_f32_e32 v101, 0x3377d1cf, v85
	v_rcp_f32_e32 v90, v92
	v_cndmask_b32_e32 v92, 0, v226, vcc
	v_fmac_f32_e32 v102, 0x3377d1cf, v93
	v_fmac_f32_e32 v101, 0x3f317217, v85
	v_cmp_lt_f32_e64 vcc, |v85|, s63
	v_max_f32_e32 v91, v82, v82
	v_add_f32_e32 v97, 1.0, v94
	v_fmac_f32_e32 v102, 0x3f317217, v93
	v_cndmask_b32_e32 v85, v85, v101, vcc
	v_cmp_lt_f32_e64 vcc, |v93|, s63
	v_min_f32_e32 v84, 0, v91
	v_rcp_f32_e32 v91, v96
	v_cmp_gt_f32_e64 s[16:17], s74, v97
	v_cndmask_b32_e64 v96, 0, v226, s[14:15]
	v_cndmask_b32_e32 v93, v93, v102, vcc
	v_cndmask_b32_e64 v99, 0, 32, s[16:17]
	v_sub_f32_e32 v92, v85, v92
	v_sub_f32_e32 v93, v93, v96
	v_ldexp_f32 v99, v97, v99
	v_pk_add_f32 v[88:89], v[88:89], v[92:93] neg_lo:[0,1] neg_hi:[0,1]
	v_log_f32_e32 v99, v99
	v_add_f32_e32 v98, 1.0, v95
	v_cndmask_b32_e64 v100, 0, v226, s[16:17]
	s_mov_b64 s[0:1], 0
	v_mul_f32_e32 v103, 0x3f317217, v99
	v_fma_f32 v103, v99, s75, -v103
	v_fmac_f32_e32 v103, 0x3377d1cf, v99
	v_fmac_f32_e32 v103, 0x3f317217, v99
	v_cmp_lt_f32_e64 vcc, |v99|, s63
	s_waitcnt vmcnt(0)
	v_pk_add_f32 v[88:89], v[88:89], v[72:73]
	s_nop 0
	v_pk_add_f32 v[72:73], v[88:89], v[68:69] neg_lo:[0,1] neg_hi:[0,1]
	v_max_f32_e32 v85, v68, v68
	v_mul_f32_e64 v68, |v72|, s69
	v_max_f32_e32 v92, v69, v69
	v_mul_f32_e64 v69, |v73|, s69
	v_exp_f32_e32 v93, v68
	v_exp_f32_e32 v96, v69
	v_max_f32_e32 v68, v88, v85
	v_cndmask_b32_e32 v99, v99, v103, vcc
	v_add_f32_e32 v85, 1.0, v93
	v_add_f32_e32 v88, 1.0, v96
	v_cmp_gt_f32_e32 vcc, s74, v85
	v_max_f32_e32 v69, v89, v92
	v_cmp_gt_f32_e64 s[14:15], s74, v88
	v_cndmask_b32_e64 v89, 0, 32, vcc
	v_ldexp_f32 v85, v85, v89
	v_cndmask_b32_e64 v92, 0, 32, s[14:15]
	v_ldexp_f32 v88, v88, v92
	v_log_f32_e32 v85, v85
	v_log_f32_e32 v88, v88
	v_cndmask_b32_e32 v89, 0, v226, vcc
	v_cndmask_b32_e64 v92, 0, v226, s[14:15]
	v_mul_f32_e32 v93, 0x3f317217, v85
	v_mul_f32_e32 v96, 0x3f317217, v88
	v_fma_f32 v93, v85, s75, -v93
	v_fma_f32 v96, v88, s75, -v96
	v_fmac_f32_e32 v93, 0x3377d1cf, v85
	v_fmac_f32_e32 v96, 0x3377d1cf, v88
	v_fmac_f32_e32 v93, 0x3f317217, v85
	v_cmp_lt_f32_e64 vcc, |v85|, s63
	v_fmac_f32_e32 v96, 0x3f317217, v88
	v_pk_mul_f32 v[76:77], v[86:87], v[76:77]
	v_cndmask_b32_e32 v85, v85, v93, vcc
	v_cmp_lt_f32_e64 vcc, |v88|, s63
	v_sub_f32_e32 v93, v85, v89
	v_pk_mul_f32 v[76:77], v[90:91], v[76:77]
	v_cndmask_b32_e32 v88, v88, v96, vcc
	v_cmp_gt_f32_e32 vcc, s74, v98
	v_sub_f32_e32 v92, v88, v92
	v_sub_f32_e32 v88, v99, v100
	v_cndmask_b32_e64 v85, 0, 32, vcc
	v_ldexp_f32 v85, v98, v85
	v_log_f32_e32 v89, v85
	v_max_f32_e32 v85, v83, v83
	v_min_f32_e32 v85, 0, v85
	v_rcp_f32_e32 v86, v97
	v_mul_f32_e32 v96, 0x3f317217, v89
	v_fma_f32 v96, v89, s75, -v96
	v_fmac_f32_e32 v96, 0x3377d1cf, v89
	v_fmac_f32_e32 v96, 0x3f317217, v89
	v_cmp_lt_f32_e64 s[14:15], |v89|, s63
	s_nop 1
	v_cndmask_b32_e64 v89, v89, v96, s[14:15]
	v_cndmask_b32_e32 v96, 0, v226, vcc
	v_sub_f32_e32 v89, v89, v96
	v_pk_add_f32 v[84:85], v[84:85], v[88:89] neg_lo:[0,1] neg_hi:[0,1]
	s_nop 0
	v_pk_add_f32 v[74:75], v[84:85], v[74:75]
	s_nop 0
	v_pk_add_f32 v[84:85], v[74:75], v[70:71] neg_lo:[0,1] neg_hi:[0,1]
	v_mul_f32_e64 v88, |v84|, s69
	v_exp_f32_e32 v88, v88
	v_mul_f32_e64 v89, |v85|, s69
	v_exp_f32_e32 v89, v89
	v_max_f32_e32 v70, v74, v70
	v_add_f32_e32 v87, 1.0, v88
	v_cmp_gt_f32_e32 vcc, s74, v87
	v_add_f32_e32 v89, 1.0, v89
	v_cndmask_b32_e64 v88, 0, 32, vcc
	v_ldexp_f32 v87, v87, v88
	v_log_f32_e32 v88, v87
	v_max_f32_e32 v71, v75, v71
	v_rcp_f32_e32 v87, v98
	v_mul_f32_e32 v74, 0x3f317217, v88
	v_fma_f32 v74, v88, s75, -v74
	v_fmac_f32_e32 v74, 0x3377d1cf, v88
	v_fmac_f32_e32 v74, 0x3f317217, v88
	v_cmp_lt_f32_e64 s[14:15], |v88|, s63
	s_nop 1
	v_cndmask_b32_e64 v74, v88, v74, s[14:15]
	v_cndmask_b32_e32 v88, 0, v226, vcc
	v_cmp_gt_f32_e32 vcc, s74, v89
	v_sub_f32_e32 v74, v74, v88
	s_nop 0
	v_cndmask_b32_e64 v90, 0, 32, vcc
	v_ldexp_f32 v89, v89, v90
	v_log_f32_e32 v89, v89
	v_cndmask_b32_e32 v88, 0, v226, vcc
	v_cmp_lt_f32_e64 vcc, |v73|, s49
	v_mul_f32_e32 v75, 0x3f317217, v89
	v_fma_f32 v75, v89, s75, -v75
	v_fmac_f32_e32 v75, 0x3377d1cf, v89
	v_fmac_f32_e32 v75, 0x3f317217, v89
	v_cmp_lt_f32_e64 s[14:15], |v89|, s63
	v_cndmask_b32_e32 v73, 0, v92, vcc
	v_cmp_lt_f32_e64 vcc, |v72|, s49
	v_cndmask_b32_e64 v75, v89, v75, s[14:15]
	v_sub_f32_e32 v75, v75, v88
	v_cndmask_b32_e32 v72, 0, v93, vcc
	v_cmp_lt_f32_e64 vcc, |v85|, s49
	v_pk_add_f32 v[68:69], v[68:69], v[72:73]
	s_nop 0
	v_cndmask_b32_e32 v75, 0, v75, vcc
	v_cmp_lt_f32_e64 vcc, |v84|, s49
	s_nop 1
	v_cndmask_b32_e32 v74, 0, v74, vcc
	v_cmp_lt_f32_e32 vcc, 0, v83
	v_pk_add_f32 v[70:71], v[70:71], v[74:75]
	v_lshl_add_u64 v[74:75], v[112:113], 2, s[94:95]
	v_cndmask_b32_e32 v73, 1.0, v95, vcc
	v_cmp_lt_f32_e32 vcc, 0, v82
	global_store_dwordx4 v[74:75], v[68:71], off
	s_nop 0
	v_cndmask_b32_e32 v72, 1.0, v94, vcc
	v_pk_mul_f32 v[72:73], v[72:73], v[78:79]
	v_lshl_add_u64 v[68:69], v[112:113], 1, s[84:85]
	v_pk_mul_f32 v[72:73], v[86:87], v[72:73]
	v_cvt_pk_bf16_f32 v70, v76, v77
	v_cvt_pk_bf16_f32 v71, v72, v73
	global_store_dwordx2 v[68:69], v[70:71], off

.LBB0_1373:
	s_and_b64 vcc, exec, s[0:1]
	s_cbranch_vccz .LBB0_1390
	s_and_b64 vcc, exec, s[10:11]
	s_mov_b64 s[0:1], -1
	s_cbranch_vccnz .LBB0_1376
	v_lshlrev_b32_e32 v52, 2, v194
	global_load_dwordx4 v[96:99], v52, s[86:87]
	global_load_dwordx4 v[92:95], v52, s[66:67]
	global_load_dwordx4 v[100:103], v52, s[56:57]
	v_mul_f32_e64 v53, |v88|, s69
	v_max_f32_e32 v56, v88, v88
	v_mul_f32_e64 v57, |v89|, s69
	v_exp_f32_e32 v82, v53
	v_min_f32_e32 v52, 0, v56
	v_exp_f32_e32 v56, v57
	v_mul_f32_e64 v67, |v91|, s69
	v_cmp_lt_f32_e32 vcc, 0, v89
	v_max_f32_e32 v60, v89, v89
	v_mul_f32_e64 v61, |v90|, s69
	v_max_f32_e32 v66, v90, v90
	v_exp_f32_e32 v87, v67
	v_add_f32_e32 v57, 1.0, v82
	v_cndmask_b32_e32 v67, 1.0, v56, vcc
	v_cmp_lt_f32_e32 vcc, 0, v88
	v_min_f32_e32 v53, 0, v60
	v_exp_f32_e32 v86, v61
	v_min_f32_e32 v60, 0, v66
	v_add_f32_e32 v61, 1.0, v56
	v_cndmask_b32_e32 v66, 1.0, v82, vcc
	v_cmp_gt_f32_e32 vcc, s74, v57
	v_cmp_gt_f32_e64 s[14:15], s74, v61
	v_rcp_f32_e32 v83, v61
	v_cndmask_b32_e64 v56, 0, 32, vcc
	v_cndmask_b32_e64 v106, 0, 32, s[14:15]
	v_ldexp_f32 v56, v57, v56
	v_ldexp_f32 v61, v61, v106
	v_log_f32_e32 v56, v56
	v_log_f32_e32 v61, v61
	v_rcp_f32_e32 v82, v57
	v_cndmask_b32_e32 v57, 0, v226, vcc
	v_mul_f32_e32 v114, 0x3f317217, v56
	v_mul_f32_e32 v115, 0x3f317217, v61
	v_fma_f32 v114, v56, s75, -v114
	v_fma_f32 v115, v61, s75, -v115
	v_fmac_f32_e32 v114, 0x3377d1cf, v56
	v_fmac_f32_e32 v115, 0x3377d1cf, v61
	v_fmac_f32_e32 v114, 0x3f317217, v56
	v_cmp_lt_f32_e64 vcc, |v56|, s63
	v_add_f32_e32 v104, 1.0, v86
	v_fmac_f32_e32 v115, 0x3f317217, v61
	v_cndmask_b32_e32 v56, v56, v114, vcc
	v_cmp_lt_f32_e64 vcc, |v61|, s63
	v_cmp_gt_f32_e64 s[16:17], s74, v104
	v_cndmask_b32_e64 v106, 0, v226, s[14:15]
	v_cndmask_b32_e32 v61, v61, v115, vcc
	v_cndmask_b32_e64 v107, 0, 32, s[16:17]
	v_sub_f32_e32 v56, v56, v57
	v_sub_f32_e32 v57, v61, v106
	v_ldexp_f32 v107, v104, v107
	v_pk_add_f32 v[52:53], v[52:53], v[56:57] neg_lo:[0,1] neg_hi:[0,1]
	v_log_f32_e32 v107, v107
	v_add_f32_e32 v105, 1.0, v87
	v_cndmask_b32_e64 v111, 0, v226, s[16:17]
	s_mov_b64 s[0:1], 0
	v_mul_f32_e32 v116, 0x3f317217, v107
	v_fma_f32 v116, v107, s75, -v116
	v_fmac_f32_e32 v116, 0x3377d1cf, v107
	v_fmac_f32_e32 v116, 0x3f317217, v107
	v_cmp_lt_f32_e64 vcc, |v107|, s63
	s_waitcnt vmcnt(0)
	v_pk_add_f32 v[52:53], v[52:53], v[96:97]
	s_nop 0
	v_pk_add_f32 v[56:57], v[52:53], v[92:93] neg_lo:[0,1] neg_hi:[0,1]
	v_max_f32_e32 v61, v92, v92
	v_mul_f32_e64 v92, |v56|, s69
	v_max_f32_e32 v96, v93, v93
	v_mul_f32_e64 v93, |v57|, s69
	v_exp_f32_e32 v92, v92
	v_exp_f32_e32 v93, v93
	v_max_f32_e32 v52, v52, v61
	v_cndmask_b32_e32 v107, v107, v116, vcc
	v_add_f32_e32 v61, 1.0, v92
	v_add_f32_e32 v92, 1.0, v93
	v_cmp_gt_f32_e32 vcc, s74, v61
	v_cmp_gt_f32_e64 s[14:15], s74, v92
	v_max_f32_e32 v53, v53, v96
	v_cndmask_b32_e64 v93, 0, 32, vcc
	v_cndmask_b32_e64 v96, 0, 32, s[14:15]
	v_ldexp_f32 v61, v61, v93
	v_ldexp_f32 v92, v92, v96
	v_log_f32_e32 v61, v61
	v_log_f32_e32 v92, v92
	v_cndmask_b32_e32 v93, 0, v226, vcc
	v_cndmask_b32_e64 v96, 0, v226, s[14:15]
	v_mul_f32_e32 v97, 0x3f317217, v61
	v_mul_f32_e32 v106, 0x3f317217, v92
	v_fma_f32 v97, v61, s75, -v97
	v_fma_f32 v106, v92, s75, -v106
	v_fmac_f32_e32 v97, 0x3377d1cf, v61
	v_fmac_f32_e32 v106, 0x3377d1cf, v92
	v_fmac_f32_e32 v97, 0x3f317217, v61
	v_cmp_lt_f32_e64 vcc, |v61|, s63
	v_fmac_f32_e32 v106, 0x3f317217, v92
	s_nop 0
	v_cndmask_b32_e32 v61, v61, v97, vcc
	v_cmp_lt_f32_e64 vcc, |v92|, s63
	s_nop 1
	v_cndmask_b32_e32 v92, v92, v106, vcc
	v_cmp_gt_f32_e32 vcc, s74, v105
	v_sub_f32_e32 v106, v61, v93
	v_sub_f32_e32 v114, v92, v96
	v_cndmask_b32_e64 v61, 0, 32, vcc
	v_ldexp_f32 v61, v105, v61
	v_log_f32_e32 v93, v61
	v_max_f32_e32 v61, v91, v91
	v_sub_f32_e32 v92, v107, v111
	v_min_f32_e32 v61, 0, v61
	v_mul_f32_e32 v96, 0x3f317217, v93
	v_fma_f32 v96, v93, s75, -v96
	v_fmac_f32_e32 v96, 0x3377d1cf, v93
	v_fmac_f32_e32 v96, 0x3f317217, v93
	v_cmp_lt_f32_e64 s[14:15], |v93|, s63
	s_nop 1
	v_cndmask_b32_e64 v93, v93, v96, s[14:15]
	v_cndmask_b32_e32 v96, 0, v226, vcc
	v_sub_f32_e32 v93, v93, v96
	v_pk_add_f32 v[60:61], v[60:61], v[92:93] neg_lo:[0,1] neg_hi:[0,1]
	s_nop 0
	v_pk_add_f32 v[92:93], v[60:61], v[98:99]
	s_nop 0
	v_pk_add_f32 v[96:97], v[92:93], v[94:95] neg_lo:[0,1] neg_hi:[0,1]
	s_nop 0
	v_mul_f32_e64 v60, |v96|, s69
	v_exp_f32_e32 v98, v60
	v_pk_mul_f32 v[60:61], v[66:67], v[100:101]
	v_rcp_f32_e32 v66, v104
	v_pk_mul_f32 v[60:61], v[82:83], v[60:61]
	v_add_f32_e32 v67, 1.0, v98
	v_cmp_gt_f32_e32 vcc, s74, v67
	s_nop 1
	v_cndmask_b32_e64 v82, 0, 32, vcc
	v_ldexp_f32 v67, v67, v82
	v_log_f32_e32 v83, v67
	v_max_f32_e32 v82, v94, v94
	v_mul_f32_e64 v94, |v97|, s69
	v_exp_f32_e32 v94, v94
	v_max_f32_e32 v82, v92, v82
	v_mul_f32_e32 v92, 0x3f317217, v83
	v_fma_f32 v92, v83, s75, -v92
	v_fmac_f32_e32 v92, 0x3377d1cf, v83
	v_fmac_f32_e32 v92, 0x3f317217, v83
	v_cmp_lt_f32_e64 s[14:15], |v83|, s63
	v_add_f32_e32 v94, 1.0, v94
	v_rcp_f32_e32 v67, v105
	v_cndmask_b32_e64 v83, v83, v92, s[14:15]
	v_cndmask_b32_e32 v92, 0, v226, vcc
	v_cmp_gt_f32_e32 vcc, s74, v94
	v_sub_f32_e32 v92, v83, v92
	v_cndmask_b32_e64 v98, 0, 32, vcc
	v_ldexp_f32 v94, v94, v98
	v_log_f32_e32 v94, v94
	v_max_f32_e32 v83, v93, v95
	v_mul_f32_e32 v93, 0x3f317217, v94
	v_fma_f32 v93, v94, s75, -v93
	v_fmac_f32_e32 v93, 0x3377d1cf, v94
	v_fmac_f32_e32 v93, 0x3f317217, v94
	v_cmp_lt_f32_e64 s[14:15], |v94|, s63
	s_nop 1
	v_cndmask_b32_e64 v93, v94, v93, s[14:15]
	v_cndmask_b32_e32 v94, 0, v226, vcc
	v_cmp_lt_f32_e64 vcc, |v57|, s49
	v_sub_f32_e32 v93, v93, v94
	s_nop 0
	v_cndmask_b32_e32 v57, 0, v114, vcc
	v_cmp_lt_f32_e64 vcc, |v56|, s49
	s_nop 1
	v_cndmask_b32_e32 v56, 0, v106, vcc
	v_cmp_lt_f32_e64 vcc, |v97|, s49
	s_nop 1
	v_cndmask_b32_e32 v93, 0, v93, vcc
	v_cmp_lt_f32_e64 vcc, |v96|, s49
	s_nop 1
	v_cndmask_b32_e32 v92, 0, v92, vcc
	v_cmp_lt_f32_e32 vcc, 0, v91
	v_pk_add_f32 v[94:95], v[82:83], v[92:93]
	v_pk_add_f32 v[92:93], v[52:53], v[56:57]
	v_cndmask_b32_e32 v53, 1.0, v87, vcc
	v_cmp_lt_f32_e32 vcc, 0, v90
	v_lshl_add_u64 v[56:57], v[112:113], 2, s[94:95]
	global_store_dwordx4 v[56:57], v[92:95], off
	v_cndmask_b32_e32 v52, 1.0, v86, vcc
	v_pk_mul_f32 v[52:53], v[52:53], v[102:103]
	s_nop 0
	v_pk_mul_f32 v[52:53], v[66:67], v[52:53]

.LBB0_1378:
	s_add_u32 s0, s22, s0
	s_addc_u32 s1, s23, s1
	v_mov_b32_e32 v111, v110
	v_lshl_add_u64 v[56:57], v[112:113], 1, s[0:1]
	v_cvt_pk_bf16_f32 v60, v60, v61
	v_cvt_pk_bf16_f32 v61, v52, v53
	v_pk_mul_f32 v[52:53], v[62:63], v[110:111]
	s_and_b64 vcc, exec, s[10:11]
	s_mov_b64 s[0:1], -1
	global_store_dwordx2 v[56:57], v[60:61], off
	s_cbranch_vccnz .LBB0_1380
	v_lshlrev_b32_e32 v56, 2, v194
	v_lshlrev_b32_e32 v66, 2, v170
	global_load_dwordx4 v[86:89], v56, s[86:87] offset:16
	global_load_dwordx4 v[60:63], v66, s[66:67]
	global_load_dwordx4 v[90:93], v66, s[56:57]
	v_mul_f32_e64 v67, |v84|, s69
	v_max_f32_e32 v82, v84, v84
	v_mul_f32_e64 v83, |v85|, s69
	v_exp_f32_e32 v67, v67
	v_min_f32_e32 v94, 0, v82
	v_exp_f32_e32 v82, v83
	v_mul_f32_e64 v98, |v53|, s69
	v_exp_f32_e32 v101, v98
	v_add_f32_e32 v98, 1.0, v67
	v_cmp_lt_f32_e32 vcc, 0, v85
	v_add_f32_e32 v99, 1.0, v82
	v_cmp_gt_f32_e64 s[14:15], s74, v98
	v_cndmask_b32_e32 v83, 1.0, v82, vcc
	v_cmp_lt_f32_e32 vcc, 0, v84
	v_cmp_gt_f32_e64 s[16:17], s74, v99
	v_max_f32_e32 v97, v52, v52
	v_cndmask_b32_e32 v82, 1.0, v67, vcc
	v_cndmask_b32_e64 v67, 0, 32, s[14:15]
	v_cndmask_b32_e64 v103, 0, 32, s[16:17]
	v_ldexp_f32 v67, v98, v67
	v_min_f32_e32 v66, 0, v97
	v_rcp_f32_e32 v97, v99
	v_ldexp_f32 v99, v99, v103
	v_log_f32_e32 v67, v67
	v_mul_f32_e64 v96, |v52|, s69
	v_log_f32_e32 v99, v99
	v_exp_f32_e32 v100, v96
	v_mul_f32_e32 v105, 0x3f317217, v67
	v_fma_f32 v105, v67, s75, -v105
	v_mul_f32_e32 v106, 0x3f317217, v99
	v_add_f32_e32 v102, 1.0, v100
	v_fma_f32 v106, v99, s75, -v106
	v_fmac_f32_e32 v105, 0x3377d1cf, v67
	v_rcp_f32_e32 v96, v98
	v_cmp_gt_f32_e32 vcc, s74, v102
	v_cndmask_b32_e64 v98, 0, v226, s[14:15]
	v_fmac_f32_e32 v106, 0x3377d1cf, v99
	v_fmac_f32_e32 v105, 0x3f317217, v67
	v_cmp_lt_f32_e64 s[14:15], |v67|, s63
	v_cndmask_b32_e64 v104, 0, 32, vcc
	v_fmac_f32_e32 v106, 0x3f317217, v99
	v_cndmask_b32_e64 v67, v67, v105, s[14:15]
	v_cmp_lt_f32_e64 s[14:15], |v99|, s63
	v_max_f32_e32 v95, v85, v85
	v_ldexp_f32 v103, v102, v104
	v_cndmask_b32_e64 v104, 0, v226, s[16:17]
	v_cndmask_b32_e64 v99, v99, v106, s[14:15]
	v_min_f32_e32 v95, 0, v95
	v_sub_f32_e32 v98, v67, v98
	v_sub_f32_e32 v99, v99, v104
	v_pk_add_f32 v[94:95], v[94:95], v[98:99] neg_lo:[0,1] neg_hi:[0,1]
	v_log_f32_e32 v103, v103
	v_or_b32_e32 v56, v108, v170
	v_mov_b32_e32 v57, v109
	v_lshl_add_u64 v[56:57], v[56:57], 2, s[94:95]
	v_mul_f32_e32 v107, 0x3f317217, v103
	v_fma_f32 v107, v103, s75, -v107
	v_fmac_f32_e32 v107, 0x3377d1cf, v103
	v_fmac_f32_e32 v107, 0x3f317217, v103
	v_cmp_lt_f32_e64 s[14:15], |v103|, s63
	s_mov_b64 s[0:1], 0
	s_waitcnt vmcnt(0)
	v_pk_add_f32 v[86:87], v[94:95], v[86:87]
	s_nop 0
	v_pk_add_f32 v[94:95], v[86:87], v[60:61] neg_lo:[0,1] neg_hi:[0,1]
	v_max_f32_e32 v67, v60, v60
	v_mul_f32_e64 v60, |v94|, s69
	v_max_f32_e32 v98, v61, v61
	v_mul_f32_e64 v61, |v95|, s69
	v_exp_f32_e32 v60, v60
	v_exp_f32_e32 v61, v61
	v_cndmask_b32_e64 v103, v103, v107, s[14:15]
	v_max_f32_e32 v86, v86, v67
	v_add_f32_e32 v60, 1.0, v60
	v_add_f32_e32 v61, 1.0, v61
	v_cmp_gt_f32_e64 s[14:15], s74, v60
	v_cmp_gt_f32_e64 s[16:17], s74, v61
	v_max_f32_e32 v87, v87, v98
	v_cndmask_b32_e64 v67, 0, 32, s[14:15]
	v_cndmask_b32_e64 v98, 0, 32, s[16:17]
	v_ldexp_f32 v60, v60, v67
	v_ldexp_f32 v61, v61, v98
	v_log_f32_e32 v60, v60
	v_log_f32_e32 v61, v61
	v_cndmask_b32_e64 v67, 0, v226, s[14:15]
	v_cndmask_b32_e64 v98, 0, v226, s[16:17]
	v_mul_f32_e32 v99, 0x3f317217, v60
	v_mul_f32_e32 v104, 0x3f317217, v61
	v_fma_f32 v99, v60, s75, -v99
	v_fma_f32 v104, v61, s75, -v104
	v_fmac_f32_e32 v99, 0x3377d1cf, v60
	v_fmac_f32_e32 v104, 0x3377d1cf, v61
	v_fmac_f32_e32 v99, 0x3f317217, v60
	v_cmp_lt_f32_e64 s[14:15], |v60|, s63
	v_fmac_f32_e32 v104, 0x3f317217, v61
	s_nop 0
	v_cndmask_b32_e64 v60, v60, v99, s[14:15]
	v_cmp_lt_f32_e64 s[14:15], |v61|, s63
	v_sub_f32_e32 v99, v60, v67
	v_cndmask_b32_e32 v60, 0, v226, vcc
	v_cndmask_b32_e64 v61, v61, v104, s[14:15]
	v_add_f32_e32 v104, 1.0, v101
	v_cmp_gt_f32_e32 vcc, s74, v104
	v_sub_f32_e32 v98, v61, v98
	v_sub_f32_e32 v60, v103, v60
	v_cndmask_b32_e64 v61, 0, 32, vcc
	v_ldexp_f32 v61, v104, v61
	v_log_f32_e32 v61, v61
	v_max_f32_e32 v67, v53, v53
	v_min_f32_e32 v67, 0, v67
	v_mul_f32_e32 v103, 0x3f317217, v61
	v_fma_f32 v103, v61, s75, -v103
	v_fmac_f32_e32 v103, 0x3377d1cf, v61
	v_fmac_f32_e32 v103, 0x3f317217, v61
	v_cmp_lt_f32_e64 s[14:15], |v61|, s63
	s_nop 1
	v_cndmask_b32_e64 v61, v61, v103, s[14:15]
	v_cndmask_b32_e32 v103, 0, v226, vcc
	v_sub_f32_e32 v61, v61, v103
	v_pk_add_f32 v[60:61], v[66:67], v[60:61] neg_lo:[0,1] neg_hi:[0,1]
	s_nop 0
	v_pk_add_f32 v[66:67], v[60:61], v[88:89]
	s_nop 0
	v_pk_add_f32 v[88:89], v[66:67], v[62:63] neg_lo:[0,1] neg_hi:[0,1]
	v_mul_f32_e64 v60, |v88|, s69
	v_exp_f32_e32 v103, v60
	v_pk_mul_f32 v[60:61], v[82:83], v[90:91]
	v_mul_f32_e64 v91, |v89|, s69
	v_exp_f32_e32 v91, v91
	v_add_f32_e32 v83, 1.0, v103
	v_cmp_gt_f32_e32 vcc, s74, v83
	v_max_f32_e32 v62, v66, v62
	v_add_f32_e32 v91, 1.0, v91
	v_cndmask_b32_e64 v90, 0, 32, vcc
	v_ldexp_f32 v83, v83, v90
	v_log_f32_e32 v90, v83
	v_pk_mul_f32 v[60:61], v[96:97], v[60:61]
	v_max_f32_e32 v63, v67, v63
	v_mul_f32_e32 v66, 0x3f317217, v90
	v_fma_f32 v66, v90, s75, -v66
	v_fmac_f32_e32 v66, 0x3377d1cf, v90
	v_fmac_f32_e32 v66, 0x3f317217, v90
	v_cmp_lt_f32_e64 s[14:15], |v90|, s63
	v_rcp_f32_e32 v82, v102
	v_rcp_f32_e32 v83, v104
	v_cndmask_b32_e64 v66, v90, v66, s[14:15]
	v_cndmask_b32_e32 v90, 0, v226, vcc
	v_cmp_gt_f32_e32 vcc, s74, v91
	v_sub_f32_e32 v90, v66, v90
	s_nop 0
	v_cndmask_b32_e64 v96, 0, 32, vcc
	v_ldexp_f32 v91, v91, v96
	v_log_f32_e32 v91, v91
	v_cndmask_b32_e32 v67, 0, v226, vcc
	v_cmp_lt_f32_e64 vcc, |v95|, s49
	v_mul_f32_e32 v66, 0x3f317217, v91
	v_fma_f32 v66, v91, s75, -v66
	v_fmac_f32_e32 v66, 0x3377d1cf, v91
	v_fmac_f32_e32 v66, 0x3f317217, v91
	v_cmp_lt_f32_e64 s[14:15], |v91|, s63
	s_nop 1
	v_cndmask_b32_e64 v66, v91, v66, s[14:15]
	v_sub_f32_e32 v91, v66, v67
	v_cndmask_b32_e32 v67, 0, v98, vcc
	v_cmp_lt_f32_e64 vcc, |v94|, s49
	s_nop 1
	v_cndmask_b32_e32 v66, 0, v99, vcc
	v_cmp_lt_f32_e64 vcc, |v89|, s49
	v_pk_add_f32 v[86:87], v[86:87], v[66:67]
	s_nop 0
	v_cndmask_b32_e32 v89, 0, v91, vcc
	v_cmp_lt_f32_e64 vcc, |v88|, s49
	s_nop 1
	v_cndmask_b32_e32 v88, 0, v90, vcc
	v_cmp_lt_f32_e32 vcc, 0, v53
	v_pk_add_f32 v[88:89], v[62:63], v[88:89]
	global_store_dwordx4 v[56:57], v[86:89], off
	v_cndmask_b32_e32 v63, 1.0, v101, vcc
	v_cmp_lt_f32_e32 vcc, 0, v52
	s_nop 1
	v_cndmask_b32_e32 v62, 1.0, v100, vcc
	v_pk_mul_f32 v[62:63], v[62:63], v[92:93]
	s_nop 0
	v_pk_mul_f32 v[62:63], v[82:83], v[62:63]

.LBB0_1382:
	s_add_u32 s0, s22, s0
	s_addc_u32 s1, s23, s1
	v_lshl_add_u64 v[52:53], v[108:109], 0, v[194:195]
	v_mov_b32_e32 v111, v110
	v_lshl_add_u64 v[56:57], v[52:53], 1, s[0:1]
	v_cvt_pk_bf16_f32 v60, v60, v61
	v_cvt_pk_bf16_f32 v61, v62, v63
	v_pk_mul_f32 v[66:67], v[58:59], v[110:111]
	s_and_b64 vcc, exec, s[10:11]
	s_mov_b64 s[0:1], -1
	global_store_dwordx2 v[56:57], v[60:61], off offset:8
	s_cbranch_vccnz .LBB0_1384
	v_lshlrev_b32_e32 v56, 2, v194
	v_lshlrev_b32_e32 v82, 2, v169
	global_load_dwordx4 v[60:63], v56, s[86:87] offset:32
	s_nop 0
	global_load_dwordx4 v[56:59], v82, s[66:67]
	v_mul_f32_e64 v88, |v80|, s69
	global_load_dwordx4 v[82:85], v82, s[56:57]
	v_max_f32_e32 v89, v80, v80
	v_mul_f32_e64 v90, |v81|, s69
	v_exp_f32_e32 v97, v88
	v_min_f32_e32 v92, 0, v89
	v_exp_f32_e32 v89, v90
	v_mul_f32_e64 v96, |v67|, s69
	v_exp_f32_e32 v99, v96
	v_add_f32_e32 v96, 1.0, v97
	v_max_f32_e32 v91, v81, v81
	v_add_f32_e32 v100, 1.0, v89
	v_cmp_lt_f32_e32 vcc, 0, v81
	v_cmp_gt_f32_e64 s[14:15], s74, v96
	v_min_f32_e32 v93, 0, v91
	v_cndmask_b32_e32 v91, 1.0, v89, vcc
	v_cmp_lt_f32_e32 vcc, 0, v80
	v_cndmask_b32_e64 v89, 0, 32, s[14:15]
	v_cmp_gt_f32_e64 s[16:17], s74, v100
	v_cndmask_b32_e32 v90, 1.0, v97, vcc
	v_ldexp_f32 v89, v96, v89
	v_cndmask_b32_e64 v97, 0, 32, s[16:17]
	v_ldexp_f32 v97, v100, v97
	v_log_f32_e32 v89, v89
	v_mul_f32_e64 v94, |v66|, s69
	v_log_f32_e32 v97, v97
	v_exp_f32_e32 v98, v94
	v_mul_f32_e32 v103, 0x3f317217, v89
	v_fma_f32 v103, v89, s75, -v103
	v_mul_f32_e32 v104, 0x3f317217, v97
	v_add_f32_e32 v101, 1.0, v98
	v_fma_f32 v104, v97, s75, -v104
	v_fmac_f32_e32 v103, 0x3377d1cf, v89
	v_rcp_f32_e32 v94, v96
	v_cmp_gt_f32_e32 vcc, s74, v101
	v_cndmask_b32_e64 v96, 0, v226, s[14:15]
	v_fmac_f32_e32 v104, 0x3377d1cf, v97
	v_fmac_f32_e32 v103, 0x3f317217, v89
	v_cmp_lt_f32_e64 s[14:15], |v89|, s63
	v_max_f32_e32 v95, v66, v66
	v_cndmask_b32_e64 v102, 0, 32, vcc
	v_fmac_f32_e32 v104, 0x3f317217, v97
	v_cndmask_b32_e64 v89, v89, v103, s[14:15]
	v_cmp_lt_f32_e64 s[14:15], |v97|, s63
	v_min_f32_e32 v88, 0, v95
	v_rcp_f32_e32 v95, v100
	v_ldexp_f32 v100, v101, v102
	v_cndmask_b32_e64 v102, 0, v226, s[16:17]
	v_cndmask_b32_e64 v97, v97, v104, s[14:15]
	v_sub_f32_e32 v96, v89, v96
	v_sub_f32_e32 v97, v97, v102
	v_pk_add_f32 v[92:93], v[92:93], v[96:97] neg_lo:[0,1] neg_hi:[0,1]
	v_log_f32_e32 v100, v100
	v_or_b32_e32 v86, v108, v169
	v_mov_b32_e32 v87, v109
	s_mov_b64 s[0:1], 0
	v_mul_f32_e32 v105, 0x3f317217, v100
	v_fma_f32 v105, v100, s75, -v105
	v_fmac_f32_e32 v105, 0x3377d1cf, v100
	v_fmac_f32_e32 v105, 0x3f317217, v100
	v_cmp_lt_f32_e64 s[14:15], |v100|, s63
	s_waitcnt vmcnt(0)
	v_pk_add_f32 v[60:61], v[92:93], v[60:61]
	s_nop 0
	v_pk_add_f32 v[92:93], v[60:61], v[56:57] neg_lo:[0,1] neg_hi:[0,1]
	v_max_f32_e32 v89, v56, v56
	v_mul_f32_e64 v56, |v92|, s69
	v_max_f32_e32 v96, v57, v57
	v_mul_f32_e64 v57, |v93|, s69
	v_exp_f32_e32 v56, v56
	v_exp_f32_e32 v57, v57
	v_cndmask_b32_e64 v100, v100, v105, s[14:15]
	v_max_f32_e32 v60, v60, v89
	v_add_f32_e32 v56, 1.0, v56
	v_add_f32_e32 v57, 1.0, v57
	v_cmp_gt_f32_e64 s[14:15], s74, v56
	v_cmp_gt_f32_e64 s[16:17], s74, v57
	v_max_f32_e32 v61, v61, v96
	v_cndmask_b32_e64 v89, 0, 32, s[14:15]
	v_cndmask_b32_e64 v96, 0, 32, s[16:17]
	v_ldexp_f32 v56, v56, v89
	v_ldexp_f32 v57, v57, v96
	v_log_f32_e32 v56, v56
	v_log_f32_e32 v57, v57
	v_cndmask_b32_e64 v89, 0, v226, s[14:15]
	v_cndmask_b32_e64 v96, 0, v226, s[16:17]
	v_mul_f32_e32 v97, 0x3f317217, v56
	v_mul_f32_e32 v102, 0x3f317217, v57
	v_fma_f32 v97, v56, s75, -v97
	v_fma_f32 v102, v57, s75, -v102
	v_fmac_f32_e32 v97, 0x3377d1cf, v56
	v_fmac_f32_e32 v102, 0x3377d1cf, v57
	v_fmac_f32_e32 v97, 0x3f317217, v56
	v_cmp_lt_f32_e64 s[14:15], |v56|, s63
	v_fmac_f32_e32 v102, 0x3f317217, v57
	s_nop 0
	v_cndmask_b32_e64 v56, v56, v97, s[14:15]
	v_cmp_lt_f32_e64 s[14:15], |v57|, s63
	v_sub_f32_e32 v97, v56, v89
	v_cndmask_b32_e32 v56, 0, v226, vcc
	v_cndmask_b32_e64 v57, v57, v102, s[14:15]
	v_add_f32_e32 v102, 1.0, v99
	v_cmp_gt_f32_e32 vcc, s74, v102
	v_sub_f32_e32 v96, v57, v96
	v_sub_f32_e32 v56, v100, v56
	v_cndmask_b32_e64 v57, 0, 32, vcc
	v_ldexp_f32 v57, v102, v57
	v_log_f32_e32 v57, v57
	v_max_f32_e32 v89, v67, v67
	v_min_f32_e32 v89, 0, v89
	v_mul_f32_e32 v100, 0x3f317217, v57
	v_fma_f32 v100, v57, s75, -v100
	v_fmac_f32_e32 v100, 0x3377d1cf, v57
	v_fmac_f32_e32 v100, 0x3f317217, v57
	v_cmp_lt_f32_e64 s[14:15], |v57|, s63
	s_nop 1
	v_cndmask_b32_e64 v57, v57, v100, s[14:15]
	v_cndmask_b32_e32 v100, 0, v226, vcc
	v_sub_f32_e32 v57, v57, v100
	v_pk_add_f32 v[56:57], v[88:89], v[56:57] neg_lo:[0,1] neg_hi:[0,1]
	s_nop 0
	v_pk_add_f32 v[62:63], v[56:57], v[62:63]
	s_nop 0
	v_pk_add_f32 v[88:89], v[62:63], v[58:59] neg_lo:[0,1] neg_hi:[0,1]
	v_mul_f32_e64 v56, |v88|, s69
	v_exp_f32_e32 v100, v56
	v_pk_mul_f32 v[56:57], v[90:91], v[82:83]
	v_mul_f32_e64 v91, |v89|, s69
	v_exp_f32_e32 v91, v91
	v_add_f32_e32 v83, 1.0, v100
	v_cmp_gt_f32_e32 vcc, s74, v83
	v_max_f32_e32 v58, v62, v58
	v_add_f32_e32 v91, 1.0, v91
	v_cndmask_b32_e64 v90, 0, 32, vcc
	v_ldexp_f32 v83, v83, v90
	v_log_f32_e32 v90, v83
	v_pk_mul_f32 v[56:57], v[94:95], v[56:57]
	v_max_f32_e32 v59, v63, v59
	v_mul_f32_e32 v62, 0x3f317217, v90
	v_fma_f32 v62, v90, s75, -v62
	v_fmac_f32_e32 v62, 0x3377d1cf, v90
	v_fmac_f32_e32 v62, 0x3f317217, v90
	v_cmp_lt_f32_e64 s[14:15], |v90|, s63
	v_rcp_f32_e32 v82, v101
	v_rcp_f32_e32 v83, v102
	v_cndmask_b32_e64 v62, v90, v62, s[14:15]
	v_cndmask_b32_e32 v90, 0, v226, vcc
	v_cmp_gt_f32_e32 vcc, s74, v91
	v_sub_f32_e32 v62, v62, v90
	s_nop 0
	v_cndmask_b32_e64 v94, 0, 32, vcc
	v_ldexp_f32 v91, v91, v94
	v_log_f32_e32 v91, v91
	v_cndmask_b32_e32 v90, 0, v226, vcc
	v_cmp_lt_f32_e64 vcc, |v93|, s49
	v_mul_f32_e32 v63, 0x3f317217, v91
	v_fma_f32 v63, v91, s75, -v63
	v_fmac_f32_e32 v63, 0x3377d1cf, v91
	v_fmac_f32_e32 v63, 0x3f317217, v91
	v_cmp_lt_f32_e64 s[14:15], |v91|, s63
	s_nop 1
	v_cndmask_b32_e64 v63, v91, v63, s[14:15]
	v_cndmask_b32_e32 v91, 0, v96, vcc
	v_cmp_lt_f32_e64 vcc, |v92|, s49
	v_sub_f32_e32 v63, v63, v90
	s_nop 0
	v_cndmask_b32_e32 v90, 0, v97, vcc
	v_cmp_lt_f32_e64 vcc, |v89|, s49
	v_pk_add_f32 v[60:61], v[60:61], v[90:91]
	s_nop 0
	v_cndmask_b32_e32 v63, 0, v63, vcc
	v_cmp_lt_f32_e64 vcc, |v88|, s49
	s_nop 1
	v_cndmask_b32_e32 v62, 0, v62, vcc
	v_cmp_lt_f32_e32 vcc, 0, v67
	v_pk_add_f32 v[62:63], v[58:59], v[62:63]
	s_nop 0
	v_cndmask_b32_e32 v59, 1.0, v99, vcc
	v_cmp_lt_f32_e32 vcc, 0, v66
	s_nop 1
	v_cndmask_b32_e32 v58, 1.0, v98, vcc
	v_pk_mul_f32 v[58:59], v[58:59], v[84:85]
	s_nop 0
	v_pk_mul_f32 v[58:59], v[82:83], v[58:59]
	v_lshl_add_u64 v[82:83], v[86:87], 2, s[94:95]
	global_store_dwordx4 v[82:83], v[60:63], off

.LBB0_1386:
	s_add_u32 s0, s22, s0
	s_addc_u32 s1, s23, s1
	v_mov_b32_e32 v111, v110
	v_lshl_add_u64 v[52:53], v[52:53], 1, s[0:1]
	v_cvt_pk_bf16_f32 v56, v56, v57
	v_cvt_pk_bf16_f32 v57, v58, v59
	v_or_b32_e32 v108, v108, v168
	v_pk_mul_f32 v[66:67], v[54:55], v[110:111]
	s_and_b64 vcc, exec, s[10:11]
	s_mov_b64 s[0:1], -1
	global_store_dwordx2 v[52:53], v[56:57], off offset:16
	s_cbranch_vccnz .LBB0_1388
	v_lshlrev_b32_e32 v52, 2, v194
	v_lshlrev_b32_e32 v60, 2, v168
	global_load_dwordx4 v[56:59], v52, s[86:87] offset:48
	s_nop 0
	global_load_dwordx4 v[52:55], v60, s[66:67]
	v_mul_f32_e64 v80, |v64|, s69
	global_load_dwordx4 v[60:63], v60, s[56:57]
	v_max_f32_e32 v81, v64, v64
	v_mul_f32_e64 v82, |v65|, s69
	v_exp_f32_e32 v89, v80
	v_min_f32_e32 v84, 0, v81
	v_exp_f32_e32 v81, v82
	v_max_f32_e32 v83, v65, v65
	v_mul_f32_e64 v88, |v67|, s69
	v_cmp_lt_f32_e32 vcc, 0, v65
	v_min_f32_e32 v85, 0, v83
	v_exp_f32_e32 v91, v88
	v_add_f32_e32 v88, 1.0, v89
	v_cndmask_b32_e32 v83, 1.0, v81, vcc
	v_cmp_lt_f32_e32 vcc, 0, v64
	v_add_f32_e32 v92, 1.0, v81
	v_cmp_gt_f32_e64 s[14:15], s74, v92
	v_cndmask_b32_e32 v82, 1.0, v89, vcc
	v_cmp_gt_f32_e32 vcc, s74, v88
	v_cndmask_b32_e64 v89, 0, 32, s[14:15]
	v_ldexp_f32 v89, v92, v89
	v_cndmask_b32_e64 v81, 0, 32, vcc
	v_ldexp_f32 v81, v88, v81
	v_log_f32_e32 v81, v81
	v_log_f32_e32 v89, v89
	v_mul_f32_e64 v86, |v66|, s69
	v_exp_f32_e32 v90, v86
	v_mul_f32_e32 v97, 0x3f317217, v81
	v_mul_f32_e32 v98, 0x3f317217, v89
	v_fma_f32 v97, v81, s75, -v97
	v_fma_f32 v98, v89, s75, -v98
	v_fmac_f32_e32 v97, 0x3377d1cf, v81
	v_rcp_f32_e32 v86, v88
	v_cndmask_b32_e32 v88, 0, v226, vcc
	v_fmac_f32_e32 v98, 0x3377d1cf, v89
	v_fmac_f32_e32 v97, 0x3f317217, v81
	v_cmp_lt_f32_e64 vcc, |v81|, s63
	v_max_f32_e32 v87, v66, v66
	v_add_f32_e32 v93, 1.0, v90
	v_fmac_f32_e32 v98, 0x3f317217, v89
	v_cndmask_b32_e32 v81, v81, v97, vcc
	v_cmp_lt_f32_e64 vcc, |v89|, s63
	v_min_f32_e32 v80, 0, v87
	v_rcp_f32_e32 v87, v92
	v_cmp_gt_f32_e64 s[16:17], s74, v93
	v_cndmask_b32_e64 v92, 0, v226, s[14:15]
	v_cndmask_b32_e32 v89, v89, v98, vcc
	v_cndmask_b32_e64 v95, 0, 32, s[16:17]
	v_sub_f32_e32 v88, v81, v88
	v_sub_f32_e32 v89, v89, v92
	v_ldexp_f32 v95, v93, v95
	v_pk_add_f32 v[84:85], v[84:85], v[88:89] neg_lo:[0,1] neg_hi:[0,1]
	v_log_f32_e32 v95, v95
	v_add_f32_e32 v94, 1.0, v91
	v_cndmask_b32_e64 v96, 0, v226, s[16:17]
	s_mov_b64 s[0:1], 0
	v_mul_f32_e32 v99, 0x3f317217, v95
	v_fma_f32 v99, v95, s75, -v99
	v_fmac_f32_e32 v99, 0x3377d1cf, v95
	v_fmac_f32_e32 v99, 0x3f317217, v95
	v_cmp_lt_f32_e64 vcc, |v95|, s63
	s_waitcnt vmcnt(0)
	v_pk_add_f32 v[84:85], v[84:85], v[56:57]
	s_nop 0
	v_pk_add_f32 v[56:57], v[84:85], v[52:53] neg_lo:[0,1] neg_hi:[0,1]
	v_max_f32_e32 v81, v52, v52
	v_mul_f32_e64 v52, |v56|, s69
	v_max_f32_e32 v88, v53, v53
	v_mul_f32_e64 v53, |v57|, s69
	v_exp_f32_e32 v89, v52
	v_exp_f32_e32 v92, v53
	v_max_f32_e32 v52, v84, v81
	v_cndmask_b32_e32 v95, v95, v99, vcc
	v_add_f32_e32 v81, 1.0, v89
	v_add_f32_e32 v84, 1.0, v92
	v_cmp_gt_f32_e32 vcc, s74, v81
	v_max_f32_e32 v53, v85, v88
	v_cmp_gt_f32_e64 s[14:15], s74, v84
	v_cndmask_b32_e64 v85, 0, 32, vcc
	v_ldexp_f32 v81, v81, v85
	v_cndmask_b32_e64 v88, 0, 32, s[14:15]
	v_ldexp_f32 v84, v84, v88
	v_log_f32_e32 v81, v81
	v_log_f32_e32 v84, v84
	v_cndmask_b32_e32 v85, 0, v226, vcc
	v_cndmask_b32_e64 v88, 0, v226, s[14:15]
	v_mul_f32_e32 v89, 0x3f317217, v81
	v_mul_f32_e32 v92, 0x3f317217, v84
	v_fma_f32 v89, v81, s75, -v89
	v_fma_f32 v92, v84, s75, -v92
	v_fmac_f32_e32 v89, 0x3377d1cf, v81
	v_fmac_f32_e32 v92, 0x3377d1cf, v84
	v_fmac_f32_e32 v89, 0x3f317217, v81
	v_cmp_lt_f32_e64 vcc, |v81|, s63
	v_fmac_f32_e32 v92, 0x3f317217, v84
	v_pk_mul_f32 v[60:61], v[82:83], v[60:61]
	v_cndmask_b32_e32 v81, v81, v89, vcc
	v_cmp_lt_f32_e64 vcc, |v84|, s63
	v_sub_f32_e32 v89, v81, v85
	v_pk_mul_f32 v[60:61], v[86:87], v[60:61]
	v_cndmask_b32_e32 v84, v84, v92, vcc
	v_cmp_gt_f32_e32 vcc, s74, v94
	v_sub_f32_e32 v88, v84, v88
	v_sub_f32_e32 v84, v95, v96
	v_cndmask_b32_e64 v81, 0, 32, vcc
	v_ldexp_f32 v81, v94, v81
	v_log_f32_e32 v85, v81
	v_max_f32_e32 v81, v67, v67
	v_min_f32_e32 v81, 0, v81
	v_rcp_f32_e32 v82, v93
	v_mul_f32_e32 v92, 0x3f317217, v85
	v_fma_f32 v92, v85, s75, -v92
	v_fmac_f32_e32 v92, 0x3377d1cf, v85
	v_fmac_f32_e32 v92, 0x3f317217, v85
	v_cmp_lt_f32_e64 s[14:15], |v85|, s63
	s_nop 1
	v_cndmask_b32_e64 v85, v85, v92, s[14:15]
	v_cndmask_b32_e32 v92, 0, v226, vcc
	v_sub_f32_e32 v85, v85, v92
	v_pk_add_f32 v[80:81], v[80:81], v[84:85] neg_lo:[0,1] neg_hi:[0,1]
	s_nop 0
	v_pk_add_f32 v[58:59], v[80:81], v[58:59]
	s_nop 0
	v_pk_add_f32 v[80:81], v[58:59], v[54:55] neg_lo:[0,1] neg_hi:[0,1]
	v_mul_f32_e64 v84, |v80|, s69
	v_exp_f32_e32 v84, v84
	v_mul_f32_e64 v85, |v81|, s69
	v_exp_f32_e32 v85, v85
	v_max_f32_e32 v54, v58, v54
	v_add_f32_e32 v83, 1.0, v84
	v_cmp_gt_f32_e32 vcc, s74, v83
	v_add_f32_e32 v85, 1.0, v85
	v_cndmask_b32_e64 v84, 0, 32, vcc
	v_ldexp_f32 v83, v83, v84
	v_log_f32_e32 v84, v83
	v_max_f32_e32 v55, v59, v55
	v_rcp_f32_e32 v83, v94
	v_mul_f32_e32 v58, 0x3f317217, v84
	v_fma_f32 v58, v84, s75, -v58
	v_fmac_f32_e32 v58, 0x3377d1cf, v84
	v_fmac_f32_e32 v58, 0x3f317217, v84
	v_cmp_lt_f32_e64 s[14:15], |v84|, s63
	s_nop 1
	v_cndmask_b32_e64 v58, v84, v58, s[14:15]
	v_cndmask_b32_e32 v84, 0, v226, vcc
	v_cmp_gt_f32_e32 vcc, s74, v85
	v_sub_f32_e32 v58, v58, v84
	s_nop 0
	v_cndmask_b32_e64 v86, 0, 32, vcc
	v_ldexp_f32 v85, v85, v86
	v_log_f32_e32 v85, v85
	v_cndmask_b32_e32 v84, 0, v226, vcc
	v_cmp_lt_f32_e64 vcc, |v57|, s49
	v_mul_f32_e32 v59, 0x3f317217, v85
	v_fma_f32 v59, v85, s75, -v59
	v_fmac_f32_e32 v59, 0x3377d1cf, v85
	v_fmac_f32_e32 v59, 0x3f317217, v85
	v_cmp_lt_f32_e64 s[14:15], |v85|, s63
	v_cndmask_b32_e32 v57, 0, v88, vcc
	v_cmp_lt_f32_e64 vcc, |v56|, s49
	v_cndmask_b32_e64 v59, v85, v59, s[14:15]
	v_sub_f32_e32 v59, v59, v84
	v_cndmask_b32_e32 v56, 0, v89, vcc
	v_cmp_lt_f32_e64 vcc, |v81|, s49
	v_pk_add_f32 v[52:53], v[52:53], v[56:57]
	s_nop 0
	v_cndmask_b32_e32 v59, 0, v59, vcc
	v_cmp_lt_f32_e64 vcc, |v80|, s49
	s_nop 1
	v_cndmask_b32_e32 v58, 0, v58, vcc
	v_cmp_lt_f32_e32 vcc, 0, v67
	v_pk_add_f32 v[54:55], v[54:55], v[58:59]
	v_lshl_add_u64 v[58:59], v[108:109], 2, s[94:95]
	v_cndmask_b32_e32 v57, 1.0, v91, vcc
	v_cmp_lt_f32_e32 vcc, 0, v66
	global_store_dwordx4 v[58:59], v[52:55], off
	s_nop 0
	v_cndmask_b32_e32 v56, 1.0, v90, vcc
	v_pk_mul_f32 v[56:57], v[56:57], v[62:63]
	v_lshl_add_u64 v[52:53], v[108:109], 1, s[84:85]
	v_pk_mul_f32 v[56:57], v[82:83], v[56:57]
	v_cvt_pk_bf16_f32 v54, v60, v61
	v_cvt_pk_bf16_f32 v55, v56, v57
	global_store_dwordx2 v[52:53], v[54:55], off

.LBB0_1409:
	s_and_b64 vcc, exec, s[0:1]
	s_cbranch_vccz .LBB0_1426
	s_and_b64 vcc, exec, s[10:11]
	s_mov_b64 s[0:1], -1
	s_cbranch_vccnz .LBB0_1412
	v_lshlrev_b32_e32 v36, 2, v194
	global_load_dwordx4 v[76:79], v36, s[86:87]
	global_load_dwordx4 v[64:67], v36, s[66:67]
	global_load_dwordx4 v[80:83], v36, s[56:57]
	v_mul_f32_e64 v37, |v60|, s69
	v_mul_f32_e64 v41, |v61|, s69
	v_exp_f32_e32 v37, v37
	v_exp_f32_e32 v54, v41
	v_mul_f32_e64 v45, |v62|, s69
	v_max_f32_e32 v50, v62, v62
	v_cmp_lt_f32_e32 vcc, 0, v61
	v_max_f32_e32 v44, v61, v61
	v_mul_f32_e64 v51, |v63|, s69
	v_exp_f32_e32 v84, v45
	v_min_f32_e32 v36, 0, v50
	v_add_f32_e32 v50, 1.0, v37
	v_cndmask_b32_e32 v45, 1.0, v54, vcc
	v_cmp_lt_f32_e32 vcc, 0, v60
	v_min_f32_e32 v41, 0, v44
	v_exp_f32_e32 v85, v51
	v_add_f32_e32 v51, 1.0, v54
	v_cndmask_b32_e32 v44, 1.0, v37, vcc
	v_cmp_gt_f32_e32 vcc, s74, v50
	v_cmp_gt_f32_e64 s[14:15], s74, v51
	v_rcp_f32_e32 v55, v51
	v_cndmask_b32_e64 v37, 0, 32, vcc
	v_cndmask_b32_e64 v58, 0, 32, s[14:15]
	v_ldexp_f32 v37, v50, v37
	v_ldexp_f32 v51, v51, v58
	v_log_f32_e32 v37, v37
	v_log_f32_e32 v51, v51
	v_rcp_f32_e32 v54, v50
	v_cndmask_b32_e32 v50, 0, v226, vcc
	v_mul_f32_e32 v94, 0x3f317217, v37
	v_mul_f32_e32 v95, 0x3f317217, v51
	v_fma_f32 v94, v37, s75, -v94
	v_fma_f32 v95, v51, s75, -v95
	v_fmac_f32_e32 v94, 0x3377d1cf, v37
	v_fmac_f32_e32 v95, 0x3377d1cf, v51
	v_fmac_f32_e32 v94, 0x3f317217, v37
	v_cmp_lt_f32_e64 vcc, |v37|, s63
	v_add_f32_e32 v86, 1.0, v84
	v_fmac_f32_e32 v95, 0x3f317217, v51
	v_cndmask_b32_e32 v37, v37, v94, vcc
	v_cmp_lt_f32_e64 vcc, |v51|, s63
	v_max_f32_e32 v40, v60, v60
	v_cmp_gt_f32_e64 s[16:17], s74, v86
	v_cndmask_b32_e64 v58, 0, v226, s[14:15]
	v_cndmask_b32_e32 v51, v51, v95, vcc
	v_min_f32_e32 v40, 0, v40
	v_cndmask_b32_e64 v59, 0, 32, s[16:17]
	v_sub_f32_e32 v50, v37, v50
	v_sub_f32_e32 v51, v51, v58
	v_ldexp_f32 v59, v86, v59
	v_pk_add_f32 v[40:41], v[40:41], v[50:51] neg_lo:[0,1] neg_hi:[0,1]
	v_log_f32_e32 v59, v59
	v_add_f32_e32 v87, 1.0, v85
	v_cndmask_b32_e64 v91, 0, v226, s[16:17]
	s_mov_b64 s[0:1], 0
	v_mul_f32_e32 v96, 0x3f317217, v59
	v_fma_f32 v96, v59, s75, -v96
	v_fmac_f32_e32 v96, 0x3377d1cf, v59
	v_fmac_f32_e32 v96, 0x3f317217, v59
	v_cmp_lt_f32_e64 vcc, |v59|, s63
	s_waitcnt vmcnt(0)
	v_pk_add_f32 v[40:41], v[40:41], v[76:77]
	s_nop 0
	v_pk_add_f32 v[50:51], v[40:41], v[64:65] neg_lo:[0,1] neg_hi:[0,1]
	v_max_f32_e32 v37, v64, v64
	v_mul_f32_e64 v64, |v50|, s69
	v_max_f32_e32 v58, v65, v65
	v_mul_f32_e64 v65, |v51|, s69
	v_exp_f32_e32 v64, v64
	v_exp_f32_e32 v65, v65
	v_max_f32_e32 v40, v40, v37
	v_cndmask_b32_e32 v59, v59, v96, vcc
	v_add_f32_e32 v37, 1.0, v64
	v_max_f32_e32 v41, v41, v58
	v_add_f32_e32 v58, 1.0, v65
	v_cmp_gt_f32_e32 vcc, s74, v37
	v_cmp_gt_f32_e64 s[14:15], s74, v58
	s_nop 0
	v_cndmask_b32_e64 v64, 0, 32, vcc
	v_cndmask_b32_e64 v65, 0, 32, s[14:15]
	v_ldexp_f32 v37, v37, v64
	v_ldexp_f32 v58, v58, v65
	v_log_f32_e32 v37, v37
	v_log_f32_e32 v58, v58
	v_cndmask_b32_e32 v64, 0, v226, vcc
	v_cndmask_b32_e64 v65, 0, v226, s[14:15]
	v_mul_f32_e32 v76, 0x3f317217, v37
	v_mul_f32_e32 v77, 0x3f317217, v58
	v_fma_f32 v76, v37, s75, -v76
	v_fma_f32 v77, v58, s75, -v77
	v_fmac_f32_e32 v76, 0x3377d1cf, v37
	v_fmac_f32_e32 v77, 0x3377d1cf, v58
	v_fmac_f32_e32 v76, 0x3f317217, v37
	v_cmp_lt_f32_e64 vcc, |v37|, s63
	v_fmac_f32_e32 v77, 0x3f317217, v58
	s_nop 0
	v_cndmask_b32_e32 v37, v37, v76, vcc
	v_cmp_lt_f32_e64 vcc, |v58|, s63
	v_sub_f32_e32 v76, v37, v64
	s_nop 0
	v_cndmask_b32_e32 v58, v58, v77, vcc
	v_cmp_gt_f32_e32 vcc, s74, v87
	v_sub_f32_e32 v77, v58, v65
	v_sub_f32_e32 v58, v59, v91
	v_cndmask_b32_e64 v37, 0, 32, vcc
	v_ldexp_f32 v37, v87, v37
	v_log_f32_e32 v64, v37
	v_max_f32_e32 v37, v63, v63
	v_min_f32_e32 v37, 0, v37
	v_mul_f32_e32 v59, 0x3f317217, v64
	v_fma_f32 v59, v64, s75, -v59
	v_fmac_f32_e32 v59, 0x3377d1cf, v64
	v_fmac_f32_e32 v59, 0x3f317217, v64
	v_cmp_lt_f32_e64 s[14:15], |v64|, s63
	s_nop 1
	v_cndmask_b32_e64 v59, v64, v59, s[14:15]
	v_cndmask_b32_e32 v64, 0, v226, vcc
	v_sub_f32_e32 v59, v59, v64
	v_pk_add_f32 v[36:37], v[36:37], v[58:59] neg_lo:[0,1] neg_hi:[0,1]
	s_nop 0
	v_pk_add_f32 v[58:59], v[36:37], v[78:79]
	s_nop 0
	v_pk_add_f32 v[64:65], v[58:59], v[66:67] neg_lo:[0,1] neg_hi:[0,1]
	s_nop 0
	v_mul_f32_e64 v36, |v64|, s69
	v_exp_f32_e32 v78, v36
	v_pk_mul_f32 v[36:37], v[44:45], v[80:81]
	v_rcp_f32_e32 v44, v86
	v_pk_mul_f32 v[36:37], v[54:55], v[36:37]
	v_add_f32_e32 v45, 1.0, v78
	v_cmp_gt_f32_e32 vcc, s74, v45
	s_nop 1
	v_cndmask_b32_e64 v54, 0, 32, vcc
	v_ldexp_f32 v45, v45, v54
	v_log_f32_e32 v55, v45
	v_max_f32_e32 v54, v66, v66
	v_mul_f32_e64 v66, |v65|, s69
	v_exp_f32_e32 v66, v66
	v_max_f32_e32 v54, v58, v54
	v_mul_f32_e32 v58, 0x3f317217, v55
	v_fma_f32 v58, v55, s75, -v58
	v_fmac_f32_e32 v58, 0x3377d1cf, v55
	v_fmac_f32_e32 v58, 0x3f317217, v55
	v_cmp_lt_f32_e64 s[14:15], |v55|, s63
	v_add_f32_e32 v66, 1.0, v66
	v_rcp_f32_e32 v45, v87
	v_cndmask_b32_e64 v55, v55, v58, s[14:15]
	v_cndmask_b32_e32 v58, 0, v226, vcc
	v_cmp_gt_f32_e32 vcc, s74, v66
	v_sub_f32_e32 v58, v55, v58
	v_cndmask_b32_e64 v78, 0, 32, vcc
	v_ldexp_f32 v66, v66, v78
	v_log_f32_e32 v66, v66
	v_max_f32_e32 v55, v59, v67
	v_mul_f32_e32 v59, 0x3f317217, v66
	v_fma_f32 v59, v66, s75, -v59
	v_fmac_f32_e32 v59, 0x3377d1cf, v66
	v_fmac_f32_e32 v59, 0x3f317217, v66
	v_cmp_lt_f32_e64 s[14:15], |v66|, s63
	s_nop 1
	v_cndmask_b32_e64 v59, v66, v59, s[14:15]
	v_cndmask_b32_e32 v66, 0, v226, vcc
	v_cmp_lt_f32_e64 vcc, |v51|, s49
	v_sub_f32_e32 v59, v59, v66
	s_nop 0
	v_cndmask_b32_e32 v51, 0, v77, vcc
	v_cmp_lt_f32_e64 vcc, |v50|, s49
	s_nop 1
	v_cndmask_b32_e32 v50, 0, v76, vcc
	v_cmp_lt_f32_e64 vcc, |v65|, s49
	s_nop 1
	v_cndmask_b32_e32 v59, 0, v59, vcc
	v_cmp_lt_f32_e64 vcc, |v64|, s49
	v_pk_add_f32 v[64:65], v[40:41], v[50:51]
	s_nop 0
	v_cndmask_b32_e32 v58, 0, v58, vcc
	v_cmp_lt_f32_e32 vcc, 0, v63
	v_pk_add_f32 v[66:67], v[54:55], v[58:59]
	s_nop 0
	v_cndmask_b32_e32 v41, 1.0, v85, vcc
	v_cmp_lt_f32_e32 vcc, 0, v62
	s_nop 1
	v_cndmask_b32_e32 v40, 1.0, v84, vcc
	v_pk_mul_f32 v[40:41], v[40:41], v[82:83]
	s_nop 0
	v_pk_mul_f32 v[40:41], v[44:45], v[40:41]
	v_lshl_add_u64 v[44:45], v[92:93], 2, s[94:95]
	global_store_dwordx4 v[44:45], v[64:67], off

.LBB0_1414:
	s_add_u32 s0, s22, s0
	s_addc_u32 s1, s23, s1
	v_lshl_add_u64 v[44:45], v[92:93], 1, s[0:1]
	v_cvt_pk_bf16_f32 v36, v36, v37
	v_cvt_pk_bf16_f32 v37, v40, v41
	v_mov_b32_e32 v91, v90
	global_store_dwordx2 v[44:45], v[36:37], off
	v_pk_mul_f32 v[36:37], v[46:47], v[90:91]
	s_and_b64 vcc, exec, s[10:11]
	s_mov_b64 s[0:1], -1
	s_cbranch_vccnz .LBB0_1416
	v_lshlrev_b32_e32 v40, 2, v194
	v_lshlrev_b32_e32 v50, 2, v170
	global_load_dwordx4 v[58:61], v40, s[86:87] offset:16
	global_load_dwordx4 v[44:47], v50, s[66:67]
	global_load_dwordx4 v[62:65], v50, s[56:57]
	v_mul_f32_e64 v51, |v56|, s69
	v_max_f32_e32 v54, v56, v56
	v_mul_f32_e64 v55, |v57|, s69
	v_exp_f32_e32 v51, v51
	v_min_f32_e32 v66, 0, v54
	v_exp_f32_e32 v54, v55
	v_mul_f32_e64 v78, |v37|, s69
	v_exp_f32_e32 v81, v78
	v_add_f32_e32 v78, 1.0, v51
	v_cmp_lt_f32_e32 vcc, 0, v57
	v_add_f32_e32 v79, 1.0, v54
	v_cmp_gt_f32_e64 s[14:15], s74, v78
	v_cndmask_b32_e32 v55, 1.0, v54, vcc
	v_cmp_lt_f32_e32 vcc, 0, v56
	v_cmp_gt_f32_e64 s[16:17], s74, v79
	v_max_f32_e32 v77, v36, v36
	v_cndmask_b32_e32 v54, 1.0, v51, vcc
	v_cndmask_b32_e64 v51, 0, 32, s[14:15]
	v_cndmask_b32_e64 v83, 0, 32, s[16:17]
	v_ldexp_f32 v51, v78, v51
	v_min_f32_e32 v50, 0, v77
	v_rcp_f32_e32 v77, v79
	v_ldexp_f32 v79, v79, v83
	v_log_f32_e32 v51, v51
	v_mul_f32_e64 v76, |v36|, s69
	v_log_f32_e32 v79, v79
	v_exp_f32_e32 v80, v76
	v_mul_f32_e32 v85, 0x3f317217, v51
	v_fma_f32 v85, v51, s75, -v85
	v_mul_f32_e32 v86, 0x3f317217, v79
	v_add_f32_e32 v82, 1.0, v80
	v_fma_f32 v86, v79, s75, -v86
	v_fmac_f32_e32 v85, 0x3377d1cf, v51
	v_rcp_f32_e32 v76, v78
	v_cmp_gt_f32_e32 vcc, s74, v82
	v_cndmask_b32_e64 v78, 0, v226, s[14:15]
	v_fmac_f32_e32 v86, 0x3377d1cf, v79
	v_fmac_f32_e32 v85, 0x3f317217, v51
	v_cmp_lt_f32_e64 s[14:15], |v51|, s63
	v_cndmask_b32_e64 v84, 0, 32, vcc
	v_fmac_f32_e32 v86, 0x3f317217, v79
	v_cndmask_b32_e64 v51, v51, v85, s[14:15]
	v_cmp_lt_f32_e64 s[14:15], |v79|, s63
	v_max_f32_e32 v67, v57, v57
	v_ldexp_f32 v83, v82, v84
	v_cndmask_b32_e64 v84, 0, v226, s[16:17]
	v_cndmask_b32_e64 v79, v79, v86, s[14:15]
	v_min_f32_e32 v67, 0, v67
	v_sub_f32_e32 v78, v51, v78
	v_sub_f32_e32 v79, v79, v84
	v_pk_add_f32 v[66:67], v[66:67], v[78:79] neg_lo:[0,1] neg_hi:[0,1]
	v_log_f32_e32 v83, v83
	v_or_b32_e32 v40, v88, v170
	v_mov_b32_e32 v41, v89
	v_lshl_add_u64 v[40:41], v[40:41], 2, s[94:95]
	v_mul_f32_e32 v87, 0x3f317217, v83
	v_fma_f32 v87, v83, s75, -v87
	v_fmac_f32_e32 v87, 0x3377d1cf, v83
	v_fmac_f32_e32 v87, 0x3f317217, v83
	v_cmp_lt_f32_e64 s[14:15], |v83|, s63
	s_mov_b64 s[0:1], 0
	s_waitcnt vmcnt(0)
	v_pk_add_f32 v[58:59], v[66:67], v[58:59]
	s_nop 0
	v_pk_add_f32 v[66:67], v[58:59], v[44:45] neg_lo:[0,1] neg_hi:[0,1]
	v_max_f32_e32 v51, v44, v44
	v_mul_f32_e64 v44, |v66|, s69
	v_max_f32_e32 v78, v45, v45
	v_mul_f32_e64 v45, |v67|, s69
	v_exp_f32_e32 v44, v44
	v_exp_f32_e32 v45, v45
	v_cndmask_b32_e64 v83, v83, v87, s[14:15]
	v_max_f32_e32 v58, v58, v51
	v_add_f32_e32 v44, 1.0, v44
	v_add_f32_e32 v45, 1.0, v45
	v_cmp_gt_f32_e64 s[14:15], s74, v44
	v_cmp_gt_f32_e64 s[16:17], s74, v45
	v_max_f32_e32 v59, v59, v78
	v_cndmask_b32_e64 v51, 0, 32, s[14:15]
	v_cndmask_b32_e64 v78, 0, 32, s[16:17]
	v_ldexp_f32 v44, v44, v51
	v_ldexp_f32 v45, v45, v78
	v_log_f32_e32 v44, v44
	v_log_f32_e32 v45, v45
	v_cndmask_b32_e64 v51, 0, v226, s[14:15]
	v_cndmask_b32_e64 v78, 0, v226, s[16:17]
	v_mul_f32_e32 v79, 0x3f317217, v44
	v_mul_f32_e32 v84, 0x3f317217, v45
	v_fma_f32 v79, v44, s75, -v79
	v_fma_f32 v84, v45, s75, -v84
	v_fmac_f32_e32 v79, 0x3377d1cf, v44
	v_fmac_f32_e32 v84, 0x3377d1cf, v45
	v_fmac_f32_e32 v79, 0x3f317217, v44
	v_cmp_lt_f32_e64 s[14:15], |v44|, s63
	v_fmac_f32_e32 v84, 0x3f317217, v45
	s_nop 0
	v_cndmask_b32_e64 v44, v44, v79, s[14:15]
	v_cmp_lt_f32_e64 s[14:15], |v45|, s63
	v_sub_f32_e32 v79, v44, v51
	v_cndmask_b32_e32 v44, 0, v226, vcc
	v_cndmask_b32_e64 v45, v45, v84, s[14:15]
	v_add_f32_e32 v84, 1.0, v81
	v_cmp_gt_f32_e32 vcc, s74, v84
	v_sub_f32_e32 v78, v45, v78
	v_sub_f32_e32 v44, v83, v44
	v_cndmask_b32_e64 v45, 0, 32, vcc
	v_ldexp_f32 v45, v84, v45
	v_log_f32_e32 v45, v45
	v_max_f32_e32 v51, v37, v37
	v_min_f32_e32 v51, 0, v51
	v_mul_f32_e32 v83, 0x3f317217, v45
	v_fma_f32 v83, v45, s75, -v83
	v_fmac_f32_e32 v83, 0x3377d1cf, v45
	v_fmac_f32_e32 v83, 0x3f317217, v45
	v_cmp_lt_f32_e64 s[14:15], |v45|, s63
	s_nop 1
	v_cndmask_b32_e64 v45, v45, v83, s[14:15]
	v_cndmask_b32_e32 v83, 0, v226, vcc
	v_sub_f32_e32 v45, v45, v83
	v_pk_add_f32 v[44:45], v[50:51], v[44:45] neg_lo:[0,1] neg_hi:[0,1]
	s_nop 0
	v_pk_add_f32 v[50:51], v[44:45], v[60:61]
	s_nop 0
	v_pk_add_f32 v[60:61], v[50:51], v[46:47] neg_lo:[0,1] neg_hi:[0,1]
	v_mul_f32_e64 v44, |v60|, s69
	v_exp_f32_e32 v83, v44
	v_pk_mul_f32 v[44:45], v[54:55], v[62:63]
	v_mul_f32_e64 v63, |v61|, s69
	v_exp_f32_e32 v63, v63
	v_add_f32_e32 v55, 1.0, v83
	v_cmp_gt_f32_e32 vcc, s74, v55
	v_max_f32_e32 v46, v50, v46
	v_add_f32_e32 v63, 1.0, v63
	v_cndmask_b32_e64 v62, 0, 32, vcc
	v_ldexp_f32 v55, v55, v62
	v_log_f32_e32 v62, v55
	v_pk_mul_f32 v[44:45], v[76:77], v[44:45]
	v_max_f32_e32 v47, v51, v47
	v_mul_f32_e32 v50, 0x3f317217, v62
	v_fma_f32 v50, v62, s75, -v50
	v_fmac_f32_e32 v50, 0x3377d1cf, v62
	v_fmac_f32_e32 v50, 0x3f317217, v62
	v_cmp_lt_f32_e64 s[14:15], |v62|, s63
	v_rcp_f32_e32 v54, v82
	v_rcp_f32_e32 v55, v84
	v_cndmask_b32_e64 v50, v62, v50, s[14:15]
	v_cndmask_b32_e32 v62, 0, v226, vcc
	v_cmp_gt_f32_e32 vcc, s74, v63
	v_sub_f32_e32 v62, v50, v62
	s_nop 0
	v_cndmask_b32_e64 v76, 0, 32, vcc
	v_ldexp_f32 v63, v63, v76
	v_log_f32_e32 v63, v63
	v_cndmask_b32_e32 v51, 0, v226, vcc
	v_cmp_lt_f32_e64 vcc, |v67|, s49
	v_mul_f32_e32 v50, 0x3f317217, v63
	v_fma_f32 v50, v63, s75, -v50
	v_fmac_f32_e32 v50, 0x3377d1cf, v63
	v_fmac_f32_e32 v50, 0x3f317217, v63
	v_cmp_lt_f32_e64 s[14:15], |v63|, s63
	s_nop 1
	v_cndmask_b32_e64 v50, v63, v50, s[14:15]
	v_sub_f32_e32 v63, v50, v51
	v_cndmask_b32_e32 v51, 0, v78, vcc
	v_cmp_lt_f32_e64 vcc, |v66|, s49
	s_nop 1
	v_cndmask_b32_e32 v50, 0, v79, vcc
	v_cmp_lt_f32_e64 vcc, |v61|, s49
	v_pk_add_f32 v[58:59], v[58:59], v[50:51]
	s_nop 0
	v_cndmask_b32_e32 v61, 0, v63, vcc
	v_cmp_lt_f32_e64 vcc, |v60|, s49
	s_nop 1
	v_cndmask_b32_e32 v60, 0, v62, vcc
	v_cmp_lt_f32_e32 vcc, 0, v37
	v_pk_add_f32 v[60:61], v[46:47], v[60:61]
	global_store_dwordx4 v[40:41], v[58:61], off
	v_cndmask_b32_e32 v47, 1.0, v81, vcc
	v_cmp_lt_f32_e32 vcc, 0, v36
	s_nop 1
	v_cndmask_b32_e32 v46, 1.0, v80, vcc
	v_pk_mul_f32 v[46:47], v[46:47], v[64:65]
	s_nop 0
	v_pk_mul_f32 v[46:47], v[54:55], v[46:47]

.LBB0_1418:
	s_add_u32 s0, s22, s0
	s_addc_u32 s1, s23, s1
	v_lshl_add_u64 v[36:37], v[88:89], 0, v[194:195]
	v_mov_b32_e32 v91, v90
	v_lshl_add_u64 v[40:41], v[36:37], 1, s[0:1]
	v_cvt_pk_bf16_f32 v44, v44, v45
	v_cvt_pk_bf16_f32 v45, v46, v47
	v_pk_mul_f32 v[50:51], v[42:43], v[90:91]
	s_and_b64 vcc, exec, s[10:11]
	s_mov_b64 s[0:1], -1
	global_store_dwordx2 v[40:41], v[44:45], off offset:8
	s_cbranch_vccnz .LBB0_1420
	v_lshlrev_b32_e32 v40, 2, v194
	v_lshlrev_b32_e32 v54, 2, v169
	global_load_dwordx4 v[44:47], v40, s[86:87] offset:32
	s_nop 0
	global_load_dwordx4 v[40:43], v54, s[66:67]
	v_mul_f32_e64 v60, |v52|, s69
	global_load_dwordx4 v[54:57], v54, s[56:57]
	v_max_f32_e32 v61, v52, v52
	v_mul_f32_e64 v62, |v53|, s69
	v_exp_f32_e32 v77, v60
	v_min_f32_e32 v64, 0, v61
	v_exp_f32_e32 v61, v62
	v_mul_f32_e64 v76, |v51|, s69
	v_exp_f32_e32 v79, v76
	v_add_f32_e32 v76, 1.0, v77
	v_max_f32_e32 v63, v53, v53
	v_add_f32_e32 v80, 1.0, v61
	v_cmp_lt_f32_e32 vcc, 0, v53
	v_cmp_gt_f32_e64 s[14:15], s74, v76
	v_min_f32_e32 v65, 0, v63
	v_cndmask_b32_e32 v63, 1.0, v61, vcc
	v_cmp_lt_f32_e32 vcc, 0, v52
	v_cndmask_b32_e64 v61, 0, 32, s[14:15]
	v_cmp_gt_f32_e64 s[16:17], s74, v80
	v_cndmask_b32_e32 v62, 1.0, v77, vcc
	v_ldexp_f32 v61, v76, v61
	v_cndmask_b32_e64 v77, 0, 32, s[16:17]
	v_ldexp_f32 v77, v80, v77
	v_log_f32_e32 v61, v61
	v_mul_f32_e64 v66, |v50|, s69
	v_log_f32_e32 v77, v77
	v_exp_f32_e32 v78, v66
	v_mul_f32_e32 v83, 0x3f317217, v61
	v_fma_f32 v83, v61, s75, -v83
	v_mul_f32_e32 v84, 0x3f317217, v77
	v_add_f32_e32 v81, 1.0, v78
	v_fma_f32 v84, v77, s75, -v84
	v_fmac_f32_e32 v83, 0x3377d1cf, v61
	v_rcp_f32_e32 v66, v76
	v_cmp_gt_f32_e32 vcc, s74, v81
	v_cndmask_b32_e64 v76, 0, v226, s[14:15]
	v_fmac_f32_e32 v84, 0x3377d1cf, v77
	v_fmac_f32_e32 v83, 0x3f317217, v61
	v_cmp_lt_f32_e64 s[14:15], |v61|, s63
	v_max_f32_e32 v67, v50, v50
	v_cndmask_b32_e64 v82, 0, 32, vcc
	v_fmac_f32_e32 v84, 0x3f317217, v77
	v_cndmask_b32_e64 v61, v61, v83, s[14:15]
	v_cmp_lt_f32_e64 s[14:15], |v77|, s63
	v_min_f32_e32 v60, 0, v67
	v_rcp_f32_e32 v67, v80
	v_ldexp_f32 v80, v81, v82
	v_cndmask_b32_e64 v82, 0, v226, s[16:17]
	v_cndmask_b32_e64 v77, v77, v84, s[14:15]
	v_sub_f32_e32 v76, v61, v76
	v_sub_f32_e32 v77, v77, v82
	v_pk_add_f32 v[64:65], v[64:65], v[76:77] neg_lo:[0,1] neg_hi:[0,1]
	v_log_f32_e32 v80, v80
	v_or_b32_e32 v58, v88, v169
	v_mov_b32_e32 v59, v89
	s_mov_b64 s[0:1], 0
	v_mul_f32_e32 v85, 0x3f317217, v80
	v_fma_f32 v85, v80, s75, -v85
	v_fmac_f32_e32 v85, 0x3377d1cf, v80
	v_fmac_f32_e32 v85, 0x3f317217, v80
	v_cmp_lt_f32_e64 s[14:15], |v80|, s63
	s_waitcnt vmcnt(0)
	v_pk_add_f32 v[44:45], v[64:65], v[44:45]
	s_nop 0
	v_pk_add_f32 v[64:65], v[44:45], v[40:41] neg_lo:[0,1] neg_hi:[0,1]
	v_max_f32_e32 v61, v40, v40
	v_mul_f32_e64 v40, |v64|, s69
	v_max_f32_e32 v76, v41, v41
	v_mul_f32_e64 v41, |v65|, s69
	v_exp_f32_e32 v40, v40
	v_exp_f32_e32 v41, v41
	v_cndmask_b32_e64 v80, v80, v85, s[14:15]
	v_max_f32_e32 v44, v44, v61
	v_add_f32_e32 v40, 1.0, v40
	v_add_f32_e32 v41, 1.0, v41
	v_cmp_gt_f32_e64 s[14:15], s74, v40
	v_cmp_gt_f32_e64 s[16:17], s74, v41
	v_max_f32_e32 v45, v45, v76
	v_cndmask_b32_e64 v61, 0, 32, s[14:15]
	v_cndmask_b32_e64 v76, 0, 32, s[16:17]
	v_ldexp_f32 v40, v40, v61
	v_ldexp_f32 v41, v41, v76
	v_log_f32_e32 v40, v40
	v_log_f32_e32 v41, v41
	v_cndmask_b32_e64 v61, 0, v226, s[14:15]
	v_cndmask_b32_e64 v76, 0, v226, s[16:17]
	v_mul_f32_e32 v77, 0x3f317217, v40
	v_mul_f32_e32 v82, 0x3f317217, v41
	v_fma_f32 v77, v40, s75, -v77
	v_fma_f32 v82, v41, s75, -v82
	v_fmac_f32_e32 v77, 0x3377d1cf, v40
	v_fmac_f32_e32 v82, 0x3377d1cf, v41
	v_fmac_f32_e32 v77, 0x3f317217, v40
	v_cmp_lt_f32_e64 s[14:15], |v40|, s63
	v_fmac_f32_e32 v82, 0x3f317217, v41
	s_nop 0
	v_cndmask_b32_e64 v40, v40, v77, s[14:15]
	v_cmp_lt_f32_e64 s[14:15], |v41|, s63
	v_sub_f32_e32 v77, v40, v61
	v_cndmask_b32_e32 v40, 0, v226, vcc
	v_cndmask_b32_e64 v41, v41, v82, s[14:15]
	v_add_f32_e32 v82, 1.0, v79
	v_cmp_gt_f32_e32 vcc, s74, v82
	v_sub_f32_e32 v76, v41, v76
	v_sub_f32_e32 v40, v80, v40
	v_cndmask_b32_e64 v41, 0, 32, vcc
	v_ldexp_f32 v41, v82, v41
	v_log_f32_e32 v41, v41
	v_max_f32_e32 v61, v51, v51
	v_min_f32_e32 v61, 0, v61
	v_mul_f32_e32 v80, 0x3f317217, v41
	v_fma_f32 v80, v41, s75, -v80
	v_fmac_f32_e32 v80, 0x3377d1cf, v41
	v_fmac_f32_e32 v80, 0x3f317217, v41
	v_cmp_lt_f32_e64 s[14:15], |v41|, s63
	s_nop 1
	v_cndmask_b32_e64 v41, v41, v80, s[14:15]
	v_cndmask_b32_e32 v80, 0, v226, vcc
	v_sub_f32_e32 v41, v41, v80
	v_pk_add_f32 v[40:41], v[60:61], v[40:41] neg_lo:[0,1] neg_hi:[0,1]
	s_nop 0
	v_pk_add_f32 v[46:47], v[40:41], v[46:47]
	s_nop 0
	v_pk_add_f32 v[60:61], v[46:47], v[42:43] neg_lo:[0,1] neg_hi:[0,1]
	v_mul_f32_e64 v40, |v60|, s69
	v_exp_f32_e32 v80, v40
	v_pk_mul_f32 v[40:41], v[62:63], v[54:55]
	v_mul_f32_e64 v63, |v61|, s69
	v_exp_f32_e32 v63, v63
	v_add_f32_e32 v55, 1.0, v80
	v_cmp_gt_f32_e32 vcc, s74, v55
	v_max_f32_e32 v42, v46, v42
	v_add_f32_e32 v63, 1.0, v63
	v_cndmask_b32_e64 v62, 0, 32, vcc
	v_ldexp_f32 v55, v55, v62
	v_log_f32_e32 v62, v55
	v_pk_mul_f32 v[40:41], v[66:67], v[40:41]
	v_max_f32_e32 v43, v47, v43
	v_mul_f32_e32 v46, 0x3f317217, v62
	v_fma_f32 v46, v62, s75, -v46
	v_fmac_f32_e32 v46, 0x3377d1cf, v62
	v_fmac_f32_e32 v46, 0x3f317217, v62
	v_cmp_lt_f32_e64 s[14:15], |v62|, s63
	v_rcp_f32_e32 v54, v81
	v_rcp_f32_e32 v55, v82
	v_cndmask_b32_e64 v46, v62, v46, s[14:15]
	v_cndmask_b32_e32 v62, 0, v226, vcc
	v_cmp_gt_f32_e32 vcc, s74, v63
	v_sub_f32_e32 v46, v46, v62
	s_nop 0
	v_cndmask_b32_e64 v66, 0, 32, vcc
	v_ldexp_f32 v63, v63, v66
	v_log_f32_e32 v63, v63
	v_cndmask_b32_e32 v62, 0, v226, vcc
	v_cmp_lt_f32_e64 vcc, |v65|, s49
	v_mul_f32_e32 v47, 0x3f317217, v63
	v_fma_f32 v47, v63, s75, -v47
	v_fmac_f32_e32 v47, 0x3377d1cf, v63
	v_fmac_f32_e32 v47, 0x3f317217, v63
	v_cmp_lt_f32_e64 s[14:15], |v63|, s63
	s_nop 1
	v_cndmask_b32_e64 v47, v63, v47, s[14:15]
	v_cndmask_b32_e32 v63, 0, v76, vcc
	v_cmp_lt_f32_e64 vcc, |v64|, s49
	v_sub_f32_e32 v47, v47, v62
	s_nop 0
	v_cndmask_b32_e32 v62, 0, v77, vcc
	v_cmp_lt_f32_e64 vcc, |v61|, s49
	v_pk_add_f32 v[44:45], v[44:45], v[62:63]
	s_nop 0
	v_cndmask_b32_e32 v47, 0, v47, vcc
	v_cmp_lt_f32_e64 vcc, |v60|, s49
	s_nop 1
	v_cndmask_b32_e32 v46, 0, v46, vcc
	v_cmp_lt_f32_e32 vcc, 0, v51
	v_pk_add_f32 v[46:47], v[42:43], v[46:47]
	s_nop 0
	v_cndmask_b32_e32 v43, 1.0, v79, vcc
	v_cmp_lt_f32_e32 vcc, 0, v50
	s_nop 1
	v_cndmask_b32_e32 v42, 1.0, v78, vcc
	v_pk_mul_f32 v[42:43], v[42:43], v[56:57]
	s_nop 0
	v_pk_mul_f32 v[42:43], v[54:55], v[42:43]
	v_lshl_add_u64 v[54:55], v[58:59], 2, s[94:95]
	global_store_dwordx4 v[54:55], v[44:47], off

.LBB0_1422:
	s_add_u32 s0, s22, s0
	s_addc_u32 s1, s23, s1
	v_mov_b32_e32 v91, v90
	v_lshl_add_u64 v[36:37], v[36:37], 1, s[0:1]
	v_cvt_pk_bf16_f32 v40, v40, v41
	v_cvt_pk_bf16_f32 v41, v42, v43
	v_or_b32_e32 v88, v88, v168
	v_pk_mul_f32 v[50:51], v[38:39], v[90:91]
	s_and_b64 vcc, exec, s[10:11]
	s_mov_b64 s[0:1], -1
	global_store_dwordx2 v[36:37], v[40:41], off offset:16
	s_cbranch_vccnz .LBB0_1424
	v_lshlrev_b32_e32 v36, 2, v194
	v_lshlrev_b32_e32 v44, 2, v168
	global_load_dwordx4 v[40:43], v36, s[86:87] offset:48
	s_nop 0
	global_load_dwordx4 v[36:39], v44, s[66:67]
	v_mul_f32_e64 v52, |v48|, s69
	global_load_dwordx4 v[44:47], v44, s[56:57]
	v_max_f32_e32 v53, v48, v48
	v_mul_f32_e64 v54, |v49|, s69
	v_exp_f32_e32 v62, v52
	v_min_f32_e32 v60, 0, v53
	v_exp_f32_e32 v53, v54
	v_max_f32_e32 v55, v49, v49
	v_cmp_lt_f32_e32 vcc, 0, v49
	v_min_f32_e32 v61, 0, v55
	v_add_f32_e32 v63, 1.0, v62
	v_cndmask_b32_e32 v55, 1.0, v53, vcc
	v_cmp_lt_f32_e32 vcc, 0, v48
	v_add_f32_e32 v64, 1.0, v53
	v_cmp_gt_f32_e64 s[14:15], s74, v64
	v_cndmask_b32_e32 v54, 1.0, v62, vcc
	v_cmp_gt_f32_e32 vcc, s74, v63
	v_cndmask_b32_e64 v62, 0, 32, s[14:15]
	v_ldexp_f32 v62, v64, v62
	v_cndmask_b32_e64 v53, 0, 32, vcc
	v_ldexp_f32 v53, v63, v53
	v_log_f32_e32 v53, v53
	v_log_f32_e32 v62, v62
	v_mul_f32_e64 v56, |v50|, s69
	v_exp_f32_e32 v58, v56
	v_mul_f32_e32 v77, 0x3f317217, v53
	v_mul_f32_e32 v78, 0x3f317217, v62
	v_fma_f32 v77, v53, s75, -v77
	v_fma_f32 v78, v62, s75, -v78
	v_fmac_f32_e32 v77, 0x3377d1cf, v53
	v_rcp_f32_e32 v56, v63
	v_cndmask_b32_e32 v63, 0, v226, vcc
	v_fmac_f32_e32 v78, 0x3377d1cf, v62
	v_fmac_f32_e32 v77, 0x3f317217, v53
	v_cmp_lt_f32_e64 vcc, |v53|, s63
	v_max_f32_e32 v57, v50, v50
	v_add_f32_e32 v65, 1.0, v58
	v_fmac_f32_e32 v78, 0x3f317217, v62
	v_cndmask_b32_e32 v53, v53, v77, vcc
	v_cmp_lt_f32_e64 vcc, |v62|, s63
	v_min_f32_e32 v52, 0, v57
	v_rcp_f32_e32 v57, v64
	v_cmp_gt_f32_e64 s[16:17], s74, v65
	v_cndmask_b32_e64 v64, 0, v226, s[14:15]
	v_cndmask_b32_e32 v77, v62, v78, vcc
	v_cndmask_b32_e64 v67, 0, 32, s[16:17]
	v_sub_f32_e32 v62, v53, v63
	v_sub_f32_e32 v63, v77, v64
	v_ldexp_f32 v67, v65, v67
	v_pk_add_f32 v[60:61], v[60:61], v[62:63] neg_lo:[0,1] neg_hi:[0,1]
	v_log_f32_e32 v67, v67
	v_mul_f32_e64 v59, |v51|, s69
	v_exp_f32_e32 v59, v59
	v_cndmask_b32_e64 v76, 0, v226, s[16:17]
	v_mul_f32_e32 v79, 0x3f317217, v67
	v_fma_f32 v79, v67, s75, -v79
	v_fmac_f32_e32 v79, 0x3377d1cf, v67
	v_fmac_f32_e32 v79, 0x3f317217, v67
	v_cmp_lt_f32_e64 vcc, |v67|, s63
	v_add_f32_e32 v66, 1.0, v59
	s_mov_b64 s[0:1], 0
	v_cndmask_b32_e32 v67, v67, v79, vcc
	s_waitcnt vmcnt(0)
	v_pk_add_f32 v[60:61], v[60:61], v[40:41]
	s_nop 0
	v_pk_add_f32 v[40:41], v[60:61], v[36:37] neg_lo:[0,1] neg_hi:[0,1]
	v_max_f32_e32 v53, v36, v36
	v_mul_f32_e64 v36, |v40|, s69
	v_max_f32_e32 v62, v37, v37
	v_mul_f32_e64 v37, |v41|, s69
	v_exp_f32_e32 v63, v36
	v_exp_f32_e32 v64, v37
	v_max_f32_e32 v36, v60, v53
	v_max_f32_e32 v37, v61, v62
	v_add_f32_e32 v53, 1.0, v63
	v_add_f32_e32 v60, 1.0, v64
	v_cmp_gt_f32_e32 vcc, s74, v53
	v_cmp_gt_f32_e64 s[14:15], s74, v60
	v_pk_mul_f32 v[44:45], v[54:55], v[44:45]
	v_cndmask_b32_e64 v61, 0, 32, vcc
	v_cndmask_b32_e64 v62, 0, 32, s[14:15]
	v_ldexp_f32 v53, v53, v61
	v_ldexp_f32 v60, v60, v62
	v_log_f32_e32 v53, v53
	v_log_f32_e32 v60, v60
	v_cndmask_b32_e32 v61, 0, v226, vcc
	v_cndmask_b32_e64 v62, 0, v226, s[14:15]
	v_mul_f32_e32 v63, 0x3f317217, v53
	v_mul_f32_e32 v64, 0x3f317217, v60
	v_fma_f32 v63, v53, s75, -v63
	v_fma_f32 v64, v60, s75, -v64
	v_fmac_f32_e32 v63, 0x3377d1cf, v53
	v_fmac_f32_e32 v64, 0x3377d1cf, v60
	v_fmac_f32_e32 v63, 0x3f317217, v53
	v_cmp_lt_f32_e64 vcc, |v53|, s63
	v_fmac_f32_e32 v64, 0x3f317217, v60
	v_pk_mul_f32 v[44:45], v[56:57], v[44:45]
	v_cndmask_b32_e32 v53, v53, v63, vcc
	v_cmp_lt_f32_e64 vcc, |v60|, s63
	v_sub_f32_e32 v63, v53, v61
	v_rcp_f32_e32 v54, v65
	v_cndmask_b32_e32 v60, v60, v64, vcc
	v_cmp_gt_f32_e32 vcc, s74, v66
	v_sub_f32_e32 v62, v60, v62
	v_sub_f32_e32 v60, v67, v76
	v_cndmask_b32_e64 v53, 0, 32, vcc
	v_ldexp_f32 v53, v66, v53
	v_log_f32_e32 v61, v53
	v_max_f32_e32 v53, v51, v51
	v_min_f32_e32 v53, 0, v53
	v_mul_f32_e32 v64, 0x3f317217, v61
	v_fma_f32 v64, v61, s75, -v64
	v_fmac_f32_e32 v64, 0x3377d1cf, v61
	v_fmac_f32_e32 v64, 0x3f317217, v61
	v_cmp_lt_f32_e64 s[14:15], |v61|, s63
	s_nop 1
	v_cndmask_b32_e64 v61, v61, v64, s[14:15]
	v_cndmask_b32_e32 v64, 0, v226, vcc
	v_sub_f32_e32 v61, v61, v64
	v_pk_add_f32 v[52:53], v[52:53], v[60:61] neg_lo:[0,1] neg_hi:[0,1]
	s_nop 0
	v_pk_add_f32 v[42:43], v[52:53], v[42:43]
	s_nop 0
	v_pk_add_f32 v[52:53], v[42:43], v[38:39] neg_lo:[0,1] neg_hi:[0,1]
	v_mul_f32_e64 v60, |v52|, s69
	v_exp_f32_e32 v60, v60
	v_mul_f32_e64 v57, |v53|, s69
	v_exp_f32_e32 v57, v57
	v_max_f32_e32 v38, v42, v38
	v_add_f32_e32 v55, 1.0, v60
	v_cmp_gt_f32_e32 vcc, s74, v55
	v_add_f32_e32 v57, 1.0, v57
	v_cndmask_b32_e64 v56, 0, 32, vcc
	v_ldexp_f32 v55, v55, v56
	v_log_f32_e32 v56, v55
	v_max_f32_e32 v39, v43, v39
	v_rcp_f32_e32 v55, v66
	v_mul_f32_e32 v42, 0x3f317217, v56
	v_fma_f32 v42, v56, s75, -v42
	v_fmac_f32_e32 v42, 0x3377d1cf, v56
	v_fmac_f32_e32 v42, 0x3f317217, v56
	v_cmp_lt_f32_e64 s[14:15], |v56|, s63
	s_nop 1
	v_cndmask_b32_e64 v42, v56, v42, s[14:15]
	v_cndmask_b32_e32 v56, 0, v226, vcc
	v_cmp_gt_f32_e32 vcc, s74, v57
	v_sub_f32_e32 v42, v42, v56
	s_nop 0
	v_cndmask_b32_e64 v60, 0, 32, vcc
	v_ldexp_f32 v57, v57, v60
	v_log_f32_e32 v57, v57
	v_cndmask_b32_e32 v56, 0, v226, vcc
	v_cmp_lt_f32_e64 vcc, |v41|, s49
	v_mul_f32_e32 v43, 0x3f317217, v57
	v_fma_f32 v43, v57, s75, -v43
	v_fmac_f32_e32 v43, 0x3377d1cf, v57
	v_fmac_f32_e32 v43, 0x3f317217, v57
	v_cmp_lt_f32_e64 s[14:15], |v57|, s63
	v_cndmask_b32_e32 v41, 0, v62, vcc
	v_cmp_lt_f32_e64 vcc, |v40|, s49
	v_cndmask_b32_e64 v43, v57, v43, s[14:15]
	v_sub_f32_e32 v43, v43, v56
	v_cndmask_b32_e32 v40, 0, v63, vcc
	v_cmp_lt_f32_e64 vcc, |v53|, s49
	v_pk_add_f32 v[36:37], v[36:37], v[40:41]
	s_nop 0
	v_cndmask_b32_e32 v43, 0, v43, vcc
	v_cmp_lt_f32_e64 vcc, |v52|, s49
	s_nop 1
	v_cndmask_b32_e32 v42, 0, v42, vcc
	v_cmp_lt_f32_e32 vcc, 0, v51
	v_pk_add_f32 v[38:39], v[38:39], v[42:43]
	v_lshl_add_u64 v[42:43], v[88:89], 2, s[94:95]
	v_cndmask_b32_e32 v41, 1.0, v59, vcc
	v_cmp_lt_f32_e32 vcc, 0, v50
	global_store_dwordx4 v[42:43], v[36:39], off
	s_nop 0
	v_cndmask_b32_e32 v40, 1.0, v58, vcc
	v_pk_mul_f32 v[40:41], v[40:41], v[46:47]
	v_lshl_add_u64 v[36:37], v[88:89], 1, s[84:85]
	v_pk_mul_f32 v[40:41], v[54:55], v[40:41]
	v_cvt_pk_bf16_f32 v38, v44, v45
	v_cvt_pk_bf16_f32 v39, v40, v41
	global_store_dwordx2 v[36:37], v[38:39], off

.LBB0_1445:
	s_and_b64 vcc, exec, s[0:1]
	s_cbranch_vccz .LBB0_1462
	s_and_b64 vcc, exec, s[10:11]
	s_mov_b64 s[0:1], -1
	s_cbranch_vccnz .LBB0_1448
	v_lshlrev_b32_e32 v20, 2, v194
	global_load_dwordx4 v[52:55], v20, s[86:87]
	global_load_dwordx4 v[48:51], v20, s[66:67]
	global_load_dwordx4 v[56:59], v20, s[56:57]
	v_mul_f32_e64 v21, |v44|, s69
	v_max_f32_e32 v24, v44, v44
	v_mul_f32_e64 v25, |v45|, s69
	v_exp_f32_e32 v38, v21
	v_min_f32_e32 v20, 0, v24
	v_exp_f32_e32 v24, v25
	v_mul_f32_e64 v35, |v47|, s69
	v_cmp_lt_f32_e32 vcc, 0, v45
	v_max_f32_e32 v28, v45, v45
	v_mul_f32_e64 v29, |v46|, s69
	v_max_f32_e32 v34, v46, v46
	v_exp_f32_e32 v43, v35
	v_add_f32_e32 v25, 1.0, v38
	v_cndmask_b32_e32 v35, 1.0, v24, vcc
	v_cmp_lt_f32_e32 vcc, 0, v44
	v_min_f32_e32 v21, 0, v28
	v_exp_f32_e32 v42, v29
	v_min_f32_e32 v28, 0, v34
	v_add_f32_e32 v29, 1.0, v24
	v_cndmask_b32_e32 v34, 1.0, v38, vcc
	v_cmp_gt_f32_e32 vcc, s74, v25
	v_cmp_gt_f32_e64 s[14:15], s74, v29
	v_rcp_f32_e32 v39, v29
	v_cndmask_b32_e64 v24, 0, 32, vcc
	v_cndmask_b32_e64 v62, 0, 32, s[14:15]
	v_ldexp_f32 v24, v25, v24
	v_ldexp_f32 v29, v29, v62
	v_log_f32_e32 v24, v24
	v_log_f32_e32 v29, v29
	v_rcp_f32_e32 v38, v25
	v_cndmask_b32_e32 v25, 0, v226, vcc
	v_mul_f32_e32 v74, 0x3f317217, v24
	v_mul_f32_e32 v75, 0x3f317217, v29
	v_fma_f32 v74, v24, s75, -v74
	v_fma_f32 v75, v29, s75, -v75
	v_fmac_f32_e32 v74, 0x3377d1cf, v24
	v_fmac_f32_e32 v75, 0x3377d1cf, v29
	v_fmac_f32_e32 v74, 0x3f317217, v24
	v_cmp_lt_f32_e64 vcc, |v24|, s63
	v_add_f32_e32 v60, 1.0, v42
	v_fmac_f32_e32 v75, 0x3f317217, v29
	v_cndmask_b32_e32 v24, v24, v74, vcc
	v_cmp_lt_f32_e64 vcc, |v29|, s63
	v_cmp_gt_f32_e64 s[16:17], s74, v60
	v_cndmask_b32_e64 v62, 0, v226, s[14:15]
	v_cndmask_b32_e32 v29, v29, v75, vcc
	v_cndmask_b32_e64 v63, 0, 32, s[16:17]
	v_sub_f32_e32 v24, v24, v25
	v_sub_f32_e32 v25, v29, v62
	v_ldexp_f32 v63, v60, v63
	v_pk_add_f32 v[20:21], v[20:21], v[24:25] neg_lo:[0,1] neg_hi:[0,1]
	v_log_f32_e32 v63, v63
	v_add_f32_e32 v61, 1.0, v43
	v_cndmask_b32_e64 v67, 0, v226, s[16:17]
	s_mov_b64 s[0:1], 0
	v_mul_f32_e32 v76, 0x3f317217, v63
	v_fma_f32 v76, v63, s75, -v76
	v_fmac_f32_e32 v76, 0x3377d1cf, v63
	v_fmac_f32_e32 v76, 0x3f317217, v63
	v_cmp_lt_f32_e64 vcc, |v63|, s63
	s_waitcnt vmcnt(0)
	v_pk_add_f32 v[20:21], v[20:21], v[52:53]
	s_nop 0
	v_pk_add_f32 v[24:25], v[20:21], v[48:49] neg_lo:[0,1] neg_hi:[0,1]
	v_max_f32_e32 v29, v48, v48
	v_mul_f32_e64 v48, |v24|, s69
	v_max_f32_e32 v52, v49, v49
	v_mul_f32_e64 v49, |v25|, s69
	v_exp_f32_e32 v48, v48
	v_exp_f32_e32 v49, v49
	v_max_f32_e32 v20, v20, v29
	v_cndmask_b32_e32 v63, v63, v76, vcc
	v_add_f32_e32 v29, 1.0, v48
	v_add_f32_e32 v48, 1.0, v49
	v_cmp_gt_f32_e32 vcc, s74, v29
	v_cmp_gt_f32_e64 s[14:15], s74, v48
	v_max_f32_e32 v21, v21, v52
	v_cndmask_b32_e64 v49, 0, 32, vcc
	v_cndmask_b32_e64 v52, 0, 32, s[14:15]
	v_ldexp_f32 v29, v29, v49
	v_ldexp_f32 v48, v48, v52
	v_log_f32_e32 v29, v29
	v_log_f32_e32 v48, v48
	v_cndmask_b32_e32 v49, 0, v226, vcc
	v_cndmask_b32_e64 v52, 0, v226, s[14:15]
	v_mul_f32_e32 v53, 0x3f317217, v29
	v_mul_f32_e32 v62, 0x3f317217, v48
	v_fma_f32 v53, v29, s75, -v53
	v_fma_f32 v62, v48, s75, -v62
	v_fmac_f32_e32 v53, 0x3377d1cf, v29
	v_fmac_f32_e32 v62, 0x3377d1cf, v48
	v_fmac_f32_e32 v53, 0x3f317217, v29
	v_cmp_lt_f32_e64 vcc, |v29|, s63
	v_fmac_f32_e32 v62, 0x3f317217, v48
	s_nop 0
	v_cndmask_b32_e32 v29, v29, v53, vcc
	v_cmp_lt_f32_e64 vcc, |v48|, s63
	s_nop 1
	v_cndmask_b32_e32 v48, v48, v62, vcc
	v_cmp_gt_f32_e32 vcc, s74, v61
	v_sub_f32_e32 v62, v29, v49
	v_sub_f32_e32 v74, v48, v52
	v_cndmask_b32_e64 v29, 0, 32, vcc
	v_ldexp_f32 v29, v61, v29
	v_log_f32_e32 v49, v29
	v_max_f32_e32 v29, v47, v47
	v_sub_f32_e32 v48, v63, v67
	v_min_f32_e32 v29, 0, v29
	v_mul_f32_e32 v52, 0x3f317217, v49
	v_fma_f32 v52, v49, s75, -v52
	v_fmac_f32_e32 v52, 0x3377d1cf, v49
	v_fmac_f32_e32 v52, 0x3f317217, v49
	v_cmp_lt_f32_e64 s[14:15], |v49|, s63
	s_nop 1
	v_cndmask_b32_e64 v49, v49, v52, s[14:15]
	v_cndmask_b32_e32 v52, 0, v226, vcc
	v_sub_f32_e32 v49, v49, v52
	v_pk_add_f32 v[28:29], v[28:29], v[48:49] neg_lo:[0,1] neg_hi:[0,1]
	s_nop 0
	v_pk_add_f32 v[48:49], v[28:29], v[54:55]
	s_nop 0
	v_pk_add_f32 v[52:53], v[48:49], v[50:51] neg_lo:[0,1] neg_hi:[0,1]
	s_nop 0
	v_mul_f32_e64 v28, |v52|, s69
	v_exp_f32_e32 v54, v28
	v_pk_mul_f32 v[28:29], v[34:35], v[56:57]
	v_rcp_f32_e32 v34, v60
	v_pk_mul_f32 v[28:29], v[38:39], v[28:29]
	v_add_f32_e32 v35, 1.0, v54
	v_cmp_gt_f32_e32 vcc, s74, v35
	s_nop 1
	v_cndmask_b32_e64 v38, 0, 32, vcc
	v_ldexp_f32 v35, v35, v38
	v_log_f32_e32 v39, v35
	v_max_f32_e32 v38, v50, v50
	v_mul_f32_e64 v50, |v53|, s69
	v_exp_f32_e32 v50, v50
	v_max_f32_e32 v38, v48, v38
	v_mul_f32_e32 v48, 0x3f317217, v39
	v_fma_f32 v48, v39, s75, -v48
	v_fmac_f32_e32 v48, 0x3377d1cf, v39
	v_fmac_f32_e32 v48, 0x3f317217, v39
	v_cmp_lt_f32_e64 s[14:15], |v39|, s63
	v_add_f32_e32 v50, 1.0, v50
	v_rcp_f32_e32 v35, v61
	v_cndmask_b32_e64 v39, v39, v48, s[14:15]
	v_cndmask_b32_e32 v48, 0, v226, vcc
	v_cmp_gt_f32_e32 vcc, s74, v50
	v_sub_f32_e32 v48, v39, v48
	v_cndmask_b32_e64 v54, 0, 32, vcc
	v_ldexp_f32 v50, v50, v54
	v_log_f32_e32 v50, v50
	v_max_f32_e32 v39, v49, v51
	v_mul_f32_e32 v49, 0x3f317217, v50
	v_fma_f32 v49, v50, s75, -v49
	v_fmac_f32_e32 v49, 0x3377d1cf, v50
	v_fmac_f32_e32 v49, 0x3f317217, v50
	v_cmp_lt_f32_e64 s[14:15], |v50|, s63
	s_nop 1
	v_cndmask_b32_e64 v49, v50, v49, s[14:15]
	v_cndmask_b32_e32 v50, 0, v226, vcc
	v_cmp_lt_f32_e64 vcc, |v25|, s49
	v_sub_f32_e32 v49, v49, v50
	s_nop 0
	v_cndmask_b32_e32 v25, 0, v74, vcc
	v_cmp_lt_f32_e64 vcc, |v24|, s49
	s_nop 1
	v_cndmask_b32_e32 v24, 0, v62, vcc
	v_cmp_lt_f32_e64 vcc, |v53|, s49
	s_nop 1
	v_cndmask_b32_e32 v49, 0, v49, vcc
	v_cmp_lt_f32_e64 vcc, |v52|, s49
	s_nop 1
	v_cndmask_b32_e32 v48, 0, v48, vcc
	v_cmp_lt_f32_e32 vcc, 0, v47
	v_pk_add_f32 v[50:51], v[38:39], v[48:49]
	v_pk_add_f32 v[48:49], v[20:21], v[24:25]
	v_cndmask_b32_e32 v21, 1.0, v43, vcc
	v_cmp_lt_f32_e32 vcc, 0, v46
	v_lshl_add_u64 v[24:25], v[72:73], 2, s[94:95]
	global_store_dwordx4 v[24:25], v[48:51], off
	v_cndmask_b32_e32 v20, 1.0, v42, vcc
	v_pk_mul_f32 v[20:21], v[20:21], v[58:59]
	s_nop 0
	v_pk_mul_f32 v[20:21], v[34:35], v[20:21]

.LBB0_1450:
	s_add_u32 s0, s22, s0
	s_addc_u32 s1, s23, s1
	v_mov_b32_e32 v67, v66
	v_lshl_add_u64 v[24:25], v[72:73], 1, s[0:1]
	v_cvt_pk_bf16_f32 v28, v28, v29
	v_cvt_pk_bf16_f32 v29, v20, v21
	v_pk_mul_f32 v[20:21], v[30:31], v[66:67]
	s_and_b64 vcc, exec, s[10:11]
	s_mov_b64 s[0:1], -1
	global_store_dwordx2 v[24:25], v[28:29], off
	s_cbranch_vccnz .LBB0_1452
	v_lshlrev_b32_e32 v24, 2, v194
	v_lshlrev_b32_e32 v34, 2, v170
	global_load_dwordx4 v[42:45], v24, s[86:87] offset:16
	global_load_dwordx4 v[28:31], v34, s[66:67]
	global_load_dwordx4 v[46:49], v34, s[56:57]
	v_mul_f32_e64 v35, |v40|, s69
	v_max_f32_e32 v38, v40, v40
	v_mul_f32_e64 v39, |v41|, s69
	v_exp_f32_e32 v35, v35
	v_min_f32_e32 v50, 0, v38
	v_exp_f32_e32 v38, v39
	v_mul_f32_e64 v54, |v21|, s69
	v_exp_f32_e32 v57, v54
	v_add_f32_e32 v54, 1.0, v35
	v_cmp_lt_f32_e32 vcc, 0, v41
	v_add_f32_e32 v55, 1.0, v38
	v_cmp_gt_f32_e64 s[14:15], s74, v54
	v_cndmask_b32_e32 v39, 1.0, v38, vcc
	v_cmp_lt_f32_e32 vcc, 0, v40
	v_cmp_gt_f32_e64 s[16:17], s74, v55
	v_max_f32_e32 v53, v20, v20
	v_cndmask_b32_e32 v38, 1.0, v35, vcc
	v_cndmask_b32_e64 v35, 0, 32, s[14:15]
	v_cndmask_b32_e64 v59, 0, 32, s[16:17]
	v_ldexp_f32 v35, v54, v35
	v_min_f32_e32 v34, 0, v53
	v_rcp_f32_e32 v53, v55
	v_ldexp_f32 v55, v55, v59
	v_log_f32_e32 v35, v35
	v_mul_f32_e64 v52, |v20|, s69
	v_log_f32_e32 v55, v55
	v_exp_f32_e32 v56, v52
	v_mul_f32_e32 v61, 0x3f317217, v35
	v_fma_f32 v61, v35, s75, -v61
	v_mul_f32_e32 v62, 0x3f317217, v55
	v_add_f32_e32 v58, 1.0, v56
	v_fma_f32 v62, v55, s75, -v62
	v_fmac_f32_e32 v61, 0x3377d1cf, v35
	v_rcp_f32_e32 v52, v54
	v_cmp_gt_f32_e32 vcc, s74, v58
	v_cndmask_b32_e64 v54, 0, v226, s[14:15]
	v_fmac_f32_e32 v62, 0x3377d1cf, v55
	v_fmac_f32_e32 v61, 0x3f317217, v35
	v_cmp_lt_f32_e64 s[14:15], |v35|, s63
	v_cndmask_b32_e64 v60, 0, 32, vcc
	v_fmac_f32_e32 v62, 0x3f317217, v55
	v_cndmask_b32_e64 v35, v35, v61, s[14:15]
	v_cmp_lt_f32_e64 s[14:15], |v55|, s63
	v_max_f32_e32 v51, v41, v41
	v_ldexp_f32 v59, v58, v60
	v_cndmask_b32_e64 v60, 0, v226, s[16:17]
	v_cndmask_b32_e64 v55, v55, v62, s[14:15]
	v_min_f32_e32 v51, 0, v51
	v_sub_f32_e32 v54, v35, v54
	v_sub_f32_e32 v55, v55, v60
	v_pk_add_f32 v[50:51], v[50:51], v[54:55] neg_lo:[0,1] neg_hi:[0,1]
	v_log_f32_e32 v59, v59
	v_or_b32_e32 v24, v64, v170
	v_mov_b32_e32 v25, v65
	v_lshl_add_u64 v[24:25], v[24:25], 2, s[94:95]
	v_mul_f32_e32 v63, 0x3f317217, v59
	v_fma_f32 v63, v59, s75, -v63
	v_fmac_f32_e32 v63, 0x3377d1cf, v59
	v_fmac_f32_e32 v63, 0x3f317217, v59
	v_cmp_lt_f32_e64 s[14:15], |v59|, s63
	s_mov_b64 s[0:1], 0
	s_waitcnt vmcnt(0)
	v_pk_add_f32 v[42:43], v[50:51], v[42:43]
	s_nop 0
	v_pk_add_f32 v[50:51], v[42:43], v[28:29] neg_lo:[0,1] neg_hi:[0,1]
	v_max_f32_e32 v35, v28, v28
	v_mul_f32_e64 v28, |v50|, s69
	v_max_f32_e32 v54, v29, v29
	v_mul_f32_e64 v29, |v51|, s69
	v_exp_f32_e32 v28, v28
	v_exp_f32_e32 v29, v29
	v_cndmask_b32_e64 v59, v59, v63, s[14:15]
	v_max_f32_e32 v42, v42, v35
	v_add_f32_e32 v28, 1.0, v28
	v_add_f32_e32 v29, 1.0, v29
	v_cmp_gt_f32_e64 s[14:15], s74, v28
	v_cmp_gt_f32_e64 s[16:17], s74, v29
	v_max_f32_e32 v43, v43, v54
	v_cndmask_b32_e64 v35, 0, 32, s[14:15]
	v_cndmask_b32_e64 v54, 0, 32, s[16:17]
	v_ldexp_f32 v28, v28, v35
	v_ldexp_f32 v29, v29, v54
	v_log_f32_e32 v28, v28
	v_log_f32_e32 v29, v29
	v_cndmask_b32_e64 v35, 0, v226, s[14:15]
	v_cndmask_b32_e64 v54, 0, v226, s[16:17]
	v_mul_f32_e32 v55, 0x3f317217, v28
	v_mul_f32_e32 v60, 0x3f317217, v29
	v_fma_f32 v55, v28, s75, -v55
	v_fma_f32 v60, v29, s75, -v60
	v_fmac_f32_e32 v55, 0x3377d1cf, v28
	v_fmac_f32_e32 v60, 0x3377d1cf, v29
	v_fmac_f32_e32 v55, 0x3f317217, v28
	v_cmp_lt_f32_e64 s[14:15], |v28|, s63
	v_fmac_f32_e32 v60, 0x3f317217, v29
	s_nop 0
	v_cndmask_b32_e64 v28, v28, v55, s[14:15]
	v_cmp_lt_f32_e64 s[14:15], |v29|, s63
	v_sub_f32_e32 v55, v28, v35
	v_cndmask_b32_e32 v28, 0, v226, vcc
	v_cndmask_b32_e64 v29, v29, v60, s[14:15]
	v_add_f32_e32 v60, 1.0, v57
	v_cmp_gt_f32_e32 vcc, s74, v60
	v_sub_f32_e32 v54, v29, v54
	v_sub_f32_e32 v28, v59, v28
	v_cndmask_b32_e64 v29, 0, 32, vcc
	v_ldexp_f32 v29, v60, v29
	v_log_f32_e32 v29, v29
	v_max_f32_e32 v35, v21, v21
	v_min_f32_e32 v35, 0, v35
	v_mul_f32_e32 v59, 0x3f317217, v29
	v_fma_f32 v59, v29, s75, -v59
	v_fmac_f32_e32 v59, 0x3377d1cf, v29
	v_fmac_f32_e32 v59, 0x3f317217, v29
	v_cmp_lt_f32_e64 s[14:15], |v29|, s63
	s_nop 1
	v_cndmask_b32_e64 v29, v29, v59, s[14:15]
	v_cndmask_b32_e32 v59, 0, v226, vcc
	v_sub_f32_e32 v29, v29, v59
	v_pk_add_f32 v[28:29], v[34:35], v[28:29] neg_lo:[0,1] neg_hi:[0,1]
	s_nop 0
	v_pk_add_f32 v[34:35], v[28:29], v[44:45]
	s_nop 0
	v_pk_add_f32 v[44:45], v[34:35], v[30:31] neg_lo:[0,1] neg_hi:[0,1]
	v_mul_f32_e64 v28, |v44|, s69
	v_exp_f32_e32 v59, v28
	v_pk_mul_f32 v[28:29], v[38:39], v[46:47]
	v_mul_f32_e64 v47, |v45|, s69
	v_exp_f32_e32 v47, v47
	v_add_f32_e32 v39, 1.0, v59
	v_cmp_gt_f32_e32 vcc, s74, v39
	v_max_f32_e32 v30, v34, v30
	v_add_f32_e32 v47, 1.0, v47
	v_cndmask_b32_e64 v46, 0, 32, vcc
	v_ldexp_f32 v39, v39, v46
	v_log_f32_e32 v46, v39
	v_pk_mul_f32 v[28:29], v[52:53], v[28:29]
	v_max_f32_e32 v31, v35, v31
	v_mul_f32_e32 v34, 0x3f317217, v46
	v_fma_f32 v34, v46, s75, -v34
	v_fmac_f32_e32 v34, 0x3377d1cf, v46
	v_fmac_f32_e32 v34, 0x3f317217, v46
	v_cmp_lt_f32_e64 s[14:15], |v46|, s63
	v_rcp_f32_e32 v38, v58
	v_rcp_f32_e32 v39, v60
	v_cndmask_b32_e64 v34, v46, v34, s[14:15]
	v_cndmask_b32_e32 v46, 0, v226, vcc
	v_cmp_gt_f32_e32 vcc, s74, v47
	v_sub_f32_e32 v46, v34, v46
	s_nop 0
	v_cndmask_b32_e64 v52, 0, 32, vcc
	v_ldexp_f32 v47, v47, v52
	v_log_f32_e32 v47, v47
	v_cndmask_b32_e32 v35, 0, v226, vcc
	v_cmp_lt_f32_e64 vcc, |v51|, s49
	v_mul_f32_e32 v34, 0x3f317217, v47
	v_fma_f32 v34, v47, s75, -v34
	v_fmac_f32_e32 v34, 0x3377d1cf, v47
	v_fmac_f32_e32 v34, 0x3f317217, v47
	v_cmp_lt_f32_e64 s[14:15], |v47|, s63
	s_nop 1
	v_cndmask_b32_e64 v34, v47, v34, s[14:15]
	v_sub_f32_e32 v47, v34, v35
	v_cndmask_b32_e32 v35, 0, v54, vcc
	v_cmp_lt_f32_e64 vcc, |v50|, s49
	s_nop 1
	v_cndmask_b32_e32 v34, 0, v55, vcc
	v_cmp_lt_f32_e64 vcc, |v45|, s49
	v_pk_add_f32 v[42:43], v[42:43], v[34:35]
	s_nop 0
	v_cndmask_b32_e32 v45, 0, v47, vcc
	v_cmp_lt_f32_e64 vcc, |v44|, s49
	s_nop 1
	v_cndmask_b32_e32 v44, 0, v46, vcc
	v_cmp_lt_f32_e32 vcc, 0, v21
	v_pk_add_f32 v[44:45], v[30:31], v[44:45]
	global_store_dwordx4 v[24:25], v[42:45], off
	v_cndmask_b32_e32 v31, 1.0, v57, vcc
	v_cmp_lt_f32_e32 vcc, 0, v20
	s_nop 1
	v_cndmask_b32_e32 v30, 1.0, v56, vcc
	v_pk_mul_f32 v[30:31], v[30:31], v[48:49]
	s_nop 0
	v_pk_mul_f32 v[30:31], v[38:39], v[30:31]

.LBB0_1454:
	s_add_u32 s0, s22, s0
	s_addc_u32 s1, s23, s1
	v_lshl_add_u64 v[20:21], v[64:65], 0, v[194:195]
	v_mov_b32_e32 v67, v66
	v_lshl_add_u64 v[24:25], v[20:21], 1, s[0:1]
	v_cvt_pk_bf16_f32 v28, v28, v29
	v_cvt_pk_bf16_f32 v29, v30, v31
	v_pk_mul_f32 v[34:35], v[26:27], v[66:67]
	s_and_b64 vcc, exec, s[10:11]
	s_mov_b64 s[0:1], -1
	global_store_dwordx2 v[24:25], v[28:29], off offset:8
	s_cbranch_vccnz .LBB0_1456
	v_lshlrev_b32_e32 v24, 2, v194
	v_lshlrev_b32_e32 v38, 2, v169
	global_load_dwordx4 v[28:31], v24, s[86:87] offset:32
	s_nop 0
	global_load_dwordx4 v[24:27], v38, s[66:67]
	v_mul_f32_e64 v44, |v36|, s69
	global_load_dwordx4 v[38:41], v38, s[56:57]
	v_max_f32_e32 v45, v36, v36
	v_mul_f32_e64 v46, |v37|, s69
	v_exp_f32_e32 v53, v44
	v_min_f32_e32 v48, 0, v45
	v_exp_f32_e32 v45, v46
	v_mul_f32_e64 v52, |v35|, s69
	v_exp_f32_e32 v55, v52
	v_add_f32_e32 v52, 1.0, v53
	v_max_f32_e32 v47, v37, v37
	v_add_f32_e32 v56, 1.0, v45
	v_cmp_lt_f32_e32 vcc, 0, v37
	v_cmp_gt_f32_e64 s[14:15], s74, v52
	v_min_f32_e32 v49, 0, v47
	v_cndmask_b32_e32 v47, 1.0, v45, vcc
	v_cmp_lt_f32_e32 vcc, 0, v36
	v_cndmask_b32_e64 v45, 0, 32, s[14:15]
	v_cmp_gt_f32_e64 s[16:17], s74, v56
	v_cndmask_b32_e32 v46, 1.0, v53, vcc
	v_ldexp_f32 v45, v52, v45
	v_cndmask_b32_e64 v53, 0, 32, s[16:17]
	v_ldexp_f32 v53, v56, v53
	v_log_f32_e32 v45, v45
	v_mul_f32_e64 v50, |v34|, s69
	v_log_f32_e32 v53, v53
	v_exp_f32_e32 v54, v50
	v_mul_f32_e32 v59, 0x3f317217, v45
	v_fma_f32 v59, v45, s75, -v59
	v_mul_f32_e32 v60, 0x3f317217, v53
	v_add_f32_e32 v57, 1.0, v54
	v_fma_f32 v60, v53, s75, -v60
	v_fmac_f32_e32 v59, 0x3377d1cf, v45
	v_rcp_f32_e32 v50, v52
	v_cmp_gt_f32_e32 vcc, s74, v57
	v_cndmask_b32_e64 v52, 0, v226, s[14:15]
	v_fmac_f32_e32 v60, 0x3377d1cf, v53
	v_fmac_f32_e32 v59, 0x3f317217, v45
	v_cmp_lt_f32_e64 s[14:15], |v45|, s63
	v_max_f32_e32 v51, v34, v34
	v_cndmask_b32_e64 v58, 0, 32, vcc
	v_fmac_f32_e32 v60, 0x3f317217, v53
	v_cndmask_b32_e64 v45, v45, v59, s[14:15]
	v_cmp_lt_f32_e64 s[14:15], |v53|, s63
	v_min_f32_e32 v44, 0, v51
	v_rcp_f32_e32 v51, v56
	v_ldexp_f32 v56, v57, v58
	v_cndmask_b32_e64 v58, 0, v226, s[16:17]
	v_cndmask_b32_e64 v53, v53, v60, s[14:15]
	v_sub_f32_e32 v52, v45, v52
	v_sub_f32_e32 v53, v53, v58
	v_pk_add_f32 v[48:49], v[48:49], v[52:53] neg_lo:[0,1] neg_hi:[0,1]
	v_log_f32_e32 v56, v56
	v_or_b32_e32 v42, v64, v169
	v_mov_b32_e32 v43, v65
	s_mov_b64 s[0:1], 0
	v_mul_f32_e32 v61, 0x3f317217, v56
	v_fma_f32 v61, v56, s75, -v61
	v_fmac_f32_e32 v61, 0x3377d1cf, v56
	v_fmac_f32_e32 v61, 0x3f317217, v56
	v_cmp_lt_f32_e64 s[14:15], |v56|, s63
	s_waitcnt vmcnt(0)
	v_pk_add_f32 v[28:29], v[48:49], v[28:29]
	s_nop 0
	v_pk_add_f32 v[48:49], v[28:29], v[24:25] neg_lo:[0,1] neg_hi:[0,1]
	v_max_f32_e32 v45, v24, v24
	v_mul_f32_e64 v24, |v48|, s69
	v_max_f32_e32 v52, v25, v25
	v_mul_f32_e64 v25, |v49|, s69
	v_exp_f32_e32 v24, v24
	v_exp_f32_e32 v25, v25
	v_cndmask_b32_e64 v56, v56, v61, s[14:15]
	v_max_f32_e32 v28, v28, v45
	v_add_f32_e32 v24, 1.0, v24
	v_add_f32_e32 v25, 1.0, v25
	v_cmp_gt_f32_e64 s[14:15], s74, v24
	v_cmp_gt_f32_e64 s[16:17], s74, v25
	v_max_f32_e32 v29, v29, v52
	v_cndmask_b32_e64 v45, 0, 32, s[14:15]
	v_cndmask_b32_e64 v52, 0, 32, s[16:17]
	v_ldexp_f32 v24, v24, v45
	v_ldexp_f32 v25, v25, v52
	v_log_f32_e32 v24, v24
	v_log_f32_e32 v25, v25
	v_cndmask_b32_e64 v45, 0, v226, s[14:15]
	v_cndmask_b32_e64 v52, 0, v226, s[16:17]
	v_mul_f32_e32 v53, 0x3f317217, v24
	v_mul_f32_e32 v58, 0x3f317217, v25
	v_fma_f32 v53, v24, s75, -v53
	v_fma_f32 v58, v25, s75, -v58
	v_fmac_f32_e32 v53, 0x3377d1cf, v24
	v_fmac_f32_e32 v58, 0x3377d1cf, v25
	v_fmac_f32_e32 v53, 0x3f317217, v24
	v_cmp_lt_f32_e64 s[14:15], |v24|, s63
	v_fmac_f32_e32 v58, 0x3f317217, v25
	s_nop 0
	v_cndmask_b32_e64 v24, v24, v53, s[14:15]
	v_cmp_lt_f32_e64 s[14:15], |v25|, s63
	v_sub_f32_e32 v53, v24, v45
	v_cndmask_b32_e32 v24, 0, v226, vcc
	v_cndmask_b32_e64 v25, v25, v58, s[14:15]
	v_add_f32_e32 v58, 1.0, v55
	v_cmp_gt_f32_e32 vcc, s74, v58
	v_sub_f32_e32 v52, v25, v52
	v_sub_f32_e32 v24, v56, v24
	v_cndmask_b32_e64 v25, 0, 32, vcc
	v_ldexp_f32 v25, v58, v25
	v_log_f32_e32 v25, v25
	v_max_f32_e32 v45, v35, v35
	v_min_f32_e32 v45, 0, v45
	v_mul_f32_e32 v56, 0x3f317217, v25
	v_fma_f32 v56, v25, s75, -v56
	v_fmac_f32_e32 v56, 0x3377d1cf, v25
	v_fmac_f32_e32 v56, 0x3f317217, v25
	v_cmp_lt_f32_e64 s[14:15], |v25|, s63
	s_nop 1
	v_cndmask_b32_e64 v25, v25, v56, s[14:15]
	v_cndmask_b32_e32 v56, 0, v226, vcc
	v_sub_f32_e32 v25, v25, v56
	v_pk_add_f32 v[24:25], v[44:45], v[24:25] neg_lo:[0,1] neg_hi:[0,1]
	s_nop 0
	v_pk_add_f32 v[30:31], v[24:25], v[30:31]
	s_nop 0
	v_pk_add_f32 v[44:45], v[30:31], v[26:27] neg_lo:[0,1] neg_hi:[0,1]
	v_mul_f32_e64 v24, |v44|, s69
	v_exp_f32_e32 v56, v24
	v_pk_mul_f32 v[24:25], v[46:47], v[38:39]
	v_mul_f32_e64 v47, |v45|, s69
	v_exp_f32_e32 v47, v47
	v_add_f32_e32 v39, 1.0, v56
	v_cmp_gt_f32_e32 vcc, s74, v39
	v_max_f32_e32 v26, v30, v26
	v_add_f32_e32 v47, 1.0, v47
	v_cndmask_b32_e64 v46, 0, 32, vcc
	v_ldexp_f32 v39, v39, v46
	v_log_f32_e32 v46, v39
	v_pk_mul_f32 v[24:25], v[50:51], v[24:25]
	v_max_f32_e32 v27, v31, v27
	v_mul_f32_e32 v30, 0x3f317217, v46
	v_fma_f32 v30, v46, s75, -v30
	v_fmac_f32_e32 v30, 0x3377d1cf, v46
	v_fmac_f32_e32 v30, 0x3f317217, v46
	v_cmp_lt_f32_e64 s[14:15], |v46|, s63
	v_rcp_f32_e32 v38, v57
	v_rcp_f32_e32 v39, v58
	v_cndmask_b32_e64 v30, v46, v30, s[14:15]
	v_cndmask_b32_e32 v46, 0, v226, vcc
	v_cmp_gt_f32_e32 vcc, s74, v47
	v_sub_f32_e32 v30, v30, v46
	s_nop 0
	v_cndmask_b32_e64 v50, 0, 32, vcc
	v_ldexp_f32 v47, v47, v50
	v_log_f32_e32 v47, v47
	v_cndmask_b32_e32 v46, 0, v226, vcc
	v_cmp_lt_f32_e64 vcc, |v49|, s49
	v_mul_f32_e32 v31, 0x3f317217, v47
	v_fma_f32 v31, v47, s75, -v31
	v_fmac_f32_e32 v31, 0x3377d1cf, v47
	v_fmac_f32_e32 v31, 0x3f317217, v47
	v_cmp_lt_f32_e64 s[14:15], |v47|, s63
	s_nop 1
	v_cndmask_b32_e64 v31, v47, v31, s[14:15]
	v_cndmask_b32_e32 v47, 0, v52, vcc
	v_cmp_lt_f32_e64 vcc, |v48|, s49
	v_sub_f32_e32 v31, v31, v46
	s_nop 0
	v_cndmask_b32_e32 v46, 0, v53, vcc
	v_cmp_lt_f32_e64 vcc, |v45|, s49
	v_pk_add_f32 v[28:29], v[28:29], v[46:47]
	s_nop 0
	v_cndmask_b32_e32 v31, 0, v31, vcc
	v_cmp_lt_f32_e64 vcc, |v44|, s49
	s_nop 1
	v_cndmask_b32_e32 v30, 0, v30, vcc
	v_cmp_lt_f32_e32 vcc, 0, v35
	v_pk_add_f32 v[30:31], v[26:27], v[30:31]
	s_nop 0
	v_cndmask_b32_e32 v27, 1.0, v55, vcc
	v_cmp_lt_f32_e32 vcc, 0, v34
	s_nop 1
	v_cndmask_b32_e32 v26, 1.0, v54, vcc
	v_pk_mul_f32 v[26:27], v[26:27], v[40:41]
	s_nop 0
	v_pk_mul_f32 v[26:27], v[38:39], v[26:27]
	v_lshl_add_u64 v[38:39], v[42:43], 2, s[94:95]
	global_store_dwordx4 v[38:39], v[28:31], off

.LBB0_1458:
	s_add_u32 s0, s22, s0
	s_addc_u32 s1, s23, s1
	v_mov_b32_e32 v67, v66
	v_lshl_add_u64 v[20:21], v[20:21], 1, s[0:1]
	v_cvt_pk_bf16_f32 v24, v24, v25
	v_cvt_pk_bf16_f32 v25, v26, v27
	v_or_b32_e32 v64, v64, v168
	v_pk_mul_f32 v[34:35], v[22:23], v[66:67]
	s_and_b64 vcc, exec, s[10:11]
	s_mov_b64 s[0:1], -1
	global_store_dwordx2 v[20:21], v[24:25], off offset:16
	s_cbranch_vccnz .LBB0_1460
	v_lshlrev_b32_e32 v20, 2, v194
	v_lshlrev_b32_e32 v28, 2, v168
	global_load_dwordx4 v[24:27], v20, s[86:87] offset:48
	s_nop 0
	global_load_dwordx4 v[20:23], v28, s[66:67]
	v_mul_f32_e64 v36, |v32|, s69
	global_load_dwordx4 v[28:31], v28, s[56:57]
	v_max_f32_e32 v37, v32, v32
	v_mul_f32_e64 v38, |v33|, s69
	v_exp_f32_e32 v45, v36
	v_min_f32_e32 v40, 0, v37
	v_exp_f32_e32 v37, v38
	v_max_f32_e32 v39, v33, v33
	v_mul_f32_e64 v44, |v35|, s69
	v_cmp_lt_f32_e32 vcc, 0, v33
	v_min_f32_e32 v41, 0, v39
	v_exp_f32_e32 v47, v44
	v_add_f32_e32 v44, 1.0, v45
	v_cndmask_b32_e32 v39, 1.0, v37, vcc
	v_cmp_lt_f32_e32 vcc, 0, v32
	v_add_f32_e32 v48, 1.0, v37
	v_cmp_gt_f32_e64 s[14:15], s74, v48
	v_cndmask_b32_e32 v38, 1.0, v45, vcc
	v_cmp_gt_f32_e32 vcc, s74, v44
	v_cndmask_b32_e64 v45, 0, 32, s[14:15]
	v_ldexp_f32 v45, v48, v45
	v_cndmask_b32_e64 v37, 0, 32, vcc
	v_ldexp_f32 v37, v44, v37
	v_log_f32_e32 v37, v37
	v_log_f32_e32 v45, v45
	v_mul_f32_e64 v42, |v34|, s69
	v_exp_f32_e32 v46, v42
	v_mul_f32_e32 v53, 0x3f317217, v37
	v_mul_f32_e32 v54, 0x3f317217, v45
	v_fma_f32 v53, v37, s75, -v53
	v_fma_f32 v54, v45, s75, -v54
	v_fmac_f32_e32 v53, 0x3377d1cf, v37
	v_rcp_f32_e32 v42, v44
	v_cndmask_b32_e32 v44, 0, v226, vcc
	v_fmac_f32_e32 v54, 0x3377d1cf, v45
	v_fmac_f32_e32 v53, 0x3f317217, v37
	v_cmp_lt_f32_e64 vcc, |v37|, s63
	v_max_f32_e32 v43, v34, v34
	v_add_f32_e32 v49, 1.0, v46
	v_fmac_f32_e32 v54, 0x3f317217, v45
	v_cndmask_b32_e32 v37, v37, v53, vcc
	v_cmp_lt_f32_e64 vcc, |v45|, s63
	v_min_f32_e32 v36, 0, v43
	v_rcp_f32_e32 v43, v48
	v_cmp_gt_f32_e64 s[16:17], s74, v49
	v_cndmask_b32_e64 v48, 0, v226, s[14:15]
	v_cndmask_b32_e32 v45, v45, v54, vcc
	v_cndmask_b32_e64 v51, 0, 32, s[16:17]
	v_sub_f32_e32 v44, v37, v44
	v_sub_f32_e32 v45, v45, v48
	v_ldexp_f32 v51, v49, v51
	v_pk_add_f32 v[40:41], v[40:41], v[44:45] neg_lo:[0,1] neg_hi:[0,1]
	v_log_f32_e32 v51, v51
	v_add_f32_e32 v50, 1.0, v47
	v_cndmask_b32_e64 v52, 0, v226, s[16:17]
	s_mov_b64 s[0:1], 0
	v_mul_f32_e32 v55, 0x3f317217, v51
	v_fma_f32 v55, v51, s75, -v55
	v_fmac_f32_e32 v55, 0x3377d1cf, v51
	v_fmac_f32_e32 v55, 0x3f317217, v51
	v_cmp_lt_f32_e64 vcc, |v51|, s63
	s_waitcnt vmcnt(0)
	v_pk_add_f32 v[40:41], v[40:41], v[24:25]
	s_nop 0
	v_pk_add_f32 v[24:25], v[40:41], v[20:21] neg_lo:[0,1] neg_hi:[0,1]
	v_max_f32_e32 v37, v20, v20
	v_mul_f32_e64 v20, |v24|, s69
	v_max_f32_e32 v44, v21, v21
	v_mul_f32_e64 v21, |v25|, s69
	v_exp_f32_e32 v45, v20
	v_exp_f32_e32 v48, v21
	v_max_f32_e32 v20, v40, v37
	v_cndmask_b32_e32 v51, v51, v55, vcc
	v_add_f32_e32 v37, 1.0, v45
	v_add_f32_e32 v40, 1.0, v48
	v_cmp_gt_f32_e32 vcc, s74, v37
	v_max_f32_e32 v21, v41, v44
	v_cmp_gt_f32_e64 s[14:15], s74, v40
	v_cndmask_b32_e64 v41, 0, 32, vcc
	v_ldexp_f32 v37, v37, v41
	v_cndmask_b32_e64 v44, 0, 32, s[14:15]
	v_ldexp_f32 v40, v40, v44
	v_log_f32_e32 v37, v37
	v_log_f32_e32 v40, v40
	v_cndmask_b32_e32 v41, 0, v226, vcc
	v_cndmask_b32_e64 v44, 0, v226, s[14:15]
	v_mul_f32_e32 v45, 0x3f317217, v37
	v_mul_f32_e32 v48, 0x3f317217, v40
	v_fma_f32 v45, v37, s75, -v45
	v_fma_f32 v48, v40, s75, -v48
	v_fmac_f32_e32 v45, 0x3377d1cf, v37
	v_fmac_f32_e32 v48, 0x3377d1cf, v40
	v_fmac_f32_e32 v45, 0x3f317217, v37
	v_cmp_lt_f32_e64 vcc, |v37|, s63
	v_fmac_f32_e32 v48, 0x3f317217, v40
	v_pk_mul_f32 v[28:29], v[38:39], v[28:29]
	v_cndmask_b32_e32 v37, v37, v45, vcc
	v_cmp_lt_f32_e64 vcc, |v40|, s63
	v_sub_f32_e32 v45, v37, v41
	v_pk_mul_f32 v[28:29], v[42:43], v[28:29]
	v_cndmask_b32_e32 v40, v40, v48, vcc
	v_cmp_gt_f32_e32 vcc, s74, v50
	v_sub_f32_e32 v44, v40, v44
	v_sub_f32_e32 v40, v51, v52
	v_cndmask_b32_e64 v37, 0, 32, vcc
	v_ldexp_f32 v37, v50, v37
	v_log_f32_e32 v41, v37
	v_max_f32_e32 v37, v35, v35
	v_min_f32_e32 v37, 0, v37
	v_rcp_f32_e32 v38, v49
	v_mul_f32_e32 v48, 0x3f317217, v41
	v_fma_f32 v48, v41, s75, -v48
	v_fmac_f32_e32 v48, 0x3377d1cf, v41
	v_fmac_f32_e32 v48, 0x3f317217, v41
	v_cmp_lt_f32_e64 s[14:15], |v41|, s63
	s_nop 1
	v_cndmask_b32_e64 v41, v41, v48, s[14:15]
	v_cndmask_b32_e32 v48, 0, v226, vcc
	v_sub_f32_e32 v41, v41, v48
	v_pk_add_f32 v[36:37], v[36:37], v[40:41] neg_lo:[0,1] neg_hi:[0,1]
	s_nop 0
	v_pk_add_f32 v[26:27], v[36:37], v[26:27]
	s_nop 0
	v_pk_add_f32 v[36:37], v[26:27], v[22:23] neg_lo:[0,1] neg_hi:[0,1]
	v_mul_f32_e64 v40, |v36|, s69
	v_exp_f32_e32 v40, v40
	v_mul_f32_e64 v41, |v37|, s69
	v_exp_f32_e32 v41, v41
	v_max_f32_e32 v22, v26, v22
	v_add_f32_e32 v39, 1.0, v40
	v_cmp_gt_f32_e32 vcc, s74, v39
	v_add_f32_e32 v41, 1.0, v41
	v_cndmask_b32_e64 v40, 0, 32, vcc
	v_ldexp_f32 v39, v39, v40
	v_log_f32_e32 v40, v39
	v_max_f32_e32 v23, v27, v23
	v_rcp_f32_e32 v39, v50
	v_mul_f32_e32 v26, 0x3f317217, v40
	v_fma_f32 v26, v40, s75, -v26
	v_fmac_f32_e32 v26, 0x3377d1cf, v40
	v_fmac_f32_e32 v26, 0x3f317217, v40
	v_cmp_lt_f32_e64 s[14:15], |v40|, s63
	s_nop 1
	v_cndmask_b32_e64 v26, v40, v26, s[14:15]
	v_cndmask_b32_e32 v40, 0, v226, vcc
	v_cmp_gt_f32_e32 vcc, s74, v41
	v_sub_f32_e32 v26, v26, v40
	s_nop 0
	v_cndmask_b32_e64 v42, 0, 32, vcc
	v_ldexp_f32 v41, v41, v42
	v_log_f32_e32 v41, v41
	v_cndmask_b32_e32 v40, 0, v226, vcc
	v_cmp_lt_f32_e64 vcc, |v25|, s49
	v_mul_f32_e32 v27, 0x3f317217, v41
	v_fma_f32 v27, v41, s75, -v27
	v_fmac_f32_e32 v27, 0x3377d1cf, v41
	v_fmac_f32_e32 v27, 0x3f317217, v41
	v_cmp_lt_f32_e64 s[14:15], |v41|, s63
	v_cndmask_b32_e32 v25, 0, v44, vcc
	v_cmp_lt_f32_e64 vcc, |v24|, s49
	v_cndmask_b32_e64 v27, v41, v27, s[14:15]
	v_sub_f32_e32 v27, v27, v40
	v_cndmask_b32_e32 v24, 0, v45, vcc
	v_cmp_lt_f32_e64 vcc, |v37|, s49
	v_pk_add_f32 v[20:21], v[20:21], v[24:25]
	s_nop 0
	v_cndmask_b32_e32 v27, 0, v27, vcc
	v_cmp_lt_f32_e64 vcc, |v36|, s49
	s_nop 1
	v_cndmask_b32_e32 v26, 0, v26, vcc
	v_cmp_lt_f32_e32 vcc, 0, v35
	v_pk_add_f32 v[22:23], v[22:23], v[26:27]
	v_lshl_add_u64 v[26:27], v[64:65], 2, s[94:95]
	v_cndmask_b32_e32 v25, 1.0, v47, vcc
	v_cmp_lt_f32_e32 vcc, 0, v34
	global_store_dwordx4 v[26:27], v[20:23], off
	s_nop 0
	v_cndmask_b32_e32 v24, 1.0, v46, vcc
	v_pk_mul_f32 v[24:25], v[24:25], v[30:31]
	v_lshl_add_u64 v[20:21], v[64:65], 1, s[84:85]
	v_pk_mul_f32 v[24:25], v[38:39], v[24:25]
	v_cvt_pk_bf16_f32 v22, v28, v29
	v_cvt_pk_bf16_f32 v23, v24, v25
	global_store_dwordx2 v[20:21], v[22:23], off

.LBB0_1481:
	s_and_b64 vcc, exec, s[0:1]
	s_cbranch_vccz .LBB0_1498
	s_mov_b64 s[0:1], -1
	s_and_b64 vcc, exec, s[10:11]
	v_lshlrev_b32_e32 v44, 2, v194
	s_cbranch_vccnz .LBB0_1484
	global_load_dwordx4 v[40:43], v44, s[86:87]
	global_load_dwordx4 v[36:39], v44, s[66:67]
	global_load_dwordx4 v[32:35], v44, s[56:57]
	v_mul_f32_e64 v4, |v28|, s69
	v_max_f32_e32 v5, v28, v28
	v_mul_f32_e64 v9, |v29|, s69
	v_exp_f32_e32 v22, v4
	v_min_f32_e32 v8, 0, v5
	v_exp_f32_e32 v5, v9
	v_mul_f32_e64 v13, |v30|, s69
	v_max_f32_e32 v18, v30, v30
	v_cmp_lt_f32_e32 vcc, 0, v29
	v_max_f32_e32 v12, v29, v29
	v_mul_f32_e64 v19, |v31|, s69
	v_exp_f32_e32 v45, v13
	v_min_f32_e32 v4, 0, v18
	v_add_f32_e32 v18, 1.0, v22
	v_cndmask_b32_e32 v13, 1.0, v5, vcc
	v_cmp_lt_f32_e32 vcc, 0, v28
	v_min_f32_e32 v9, 0, v12
	v_exp_f32_e32 v46, v19
	v_add_f32_e32 v19, 1.0, v5
	v_cndmask_b32_e32 v12, 1.0, v22, vcc
	v_cmp_gt_f32_e32 vcc, s74, v18
	v_cmp_gt_f32_e64 s[6:7], s74, v19
	v_rcp_f32_e32 v23, v19
	v_cndmask_b32_e64 v5, 0, 32, vcc
	v_cndmask_b32_e64 v26, 0, 32, s[6:7]
	v_ldexp_f32 v5, v18, v5
	v_ldexp_f32 v19, v19, v26
	v_log_f32_e32 v5, v5
	v_log_f32_e32 v19, v19
	v_rcp_f32_e32 v22, v18
	v_cndmask_b32_e32 v18, 0, v226, vcc
	v_mul_f32_e32 v55, 0x3f317217, v5
	v_mul_f32_e32 v56, 0x3f317217, v19
	v_fma_f32 v55, v5, s75, -v55
	v_fma_f32 v56, v19, s75, -v56
	v_fmac_f32_e32 v55, 0x3377d1cf, v5
	v_fmac_f32_e32 v56, 0x3377d1cf, v19
	v_fmac_f32_e32 v55, 0x3f317217, v5
	v_cmp_lt_f32_e64 vcc, |v5|, s63
	v_add_f32_e32 v47, 1.0, v45
	v_fmac_f32_e32 v56, 0x3f317217, v19
	v_cndmask_b32_e32 v5, v5, v55, vcc
	v_cmp_lt_f32_e64 vcc, |v19|, s63
	v_cmp_gt_f32_e64 s[8:9], s74, v47
	v_cndmask_b32_e64 v26, 0, v226, s[6:7]
	v_cndmask_b32_e32 v19, v19, v56, vcc
	v_cndmask_b32_e64 v27, 0, 32, s[8:9]
	v_sub_f32_e32 v18, v5, v18
	v_sub_f32_e32 v19, v19, v26
	v_ldexp_f32 v27, v47, v27
	v_pk_add_f32 v[8:9], v[8:9], v[18:19] neg_lo:[0,1] neg_hi:[0,1]
	v_log_f32_e32 v27, v27
	v_add_f32_e32 v51, 1.0, v46
	v_cndmask_b32_e64 v54, 0, v226, s[8:9]
	s_mov_b64 s[0:1], 0
	v_mul_f32_e32 v57, 0x3f317217, v27
	v_fma_f32 v57, v27, s75, -v57
	v_fmac_f32_e32 v57, 0x3377d1cf, v27
	v_fmac_f32_e32 v57, 0x3f317217, v27
	v_cmp_lt_f32_e64 vcc, |v27|, s63
	s_waitcnt vmcnt(0)
	v_pk_add_f32 v[8:9], v[8:9], v[40:41]
	s_nop 0
	v_pk_add_f32 v[18:19], v[8:9], v[36:37] neg_lo:[0,1] neg_hi:[0,1]
	v_max_f32_e32 v5, v36, v36
	v_mul_f32_e64 v36, |v18|, s69
	v_max_f32_e32 v26, v37, v37
	v_mul_f32_e64 v37, |v19|, s69
	v_exp_f32_e32 v36, v36
	v_exp_f32_e32 v37, v37
	v_max_f32_e32 v8, v8, v5
	v_cndmask_b32_e32 v27, v27, v57, vcc
	v_add_f32_e32 v5, 1.0, v36
	v_max_f32_e32 v9, v9, v26
	v_add_f32_e32 v26, 1.0, v37
	v_cmp_gt_f32_e32 vcc, s74, v5
	v_cmp_gt_f32_e64 s[6:7], s74, v26
	s_nop 0
	v_cndmask_b32_e64 v36, 0, 32, vcc
	v_cndmask_b32_e64 v37, 0, 32, s[6:7]
	v_ldexp_f32 v5, v5, v36
	v_ldexp_f32 v26, v26, v37
	v_log_f32_e32 v5, v5
	v_log_f32_e32 v26, v26
	v_cndmask_b32_e32 v36, 0, v226, vcc
	v_cndmask_b32_e64 v37, 0, v226, s[6:7]
	v_mul_f32_e32 v40, 0x3f317217, v5
	v_mul_f32_e32 v41, 0x3f317217, v26
	v_fma_f32 v40, v5, s75, -v40
	v_fma_f32 v41, v26, s75, -v41
	v_fmac_f32_e32 v40, 0x3377d1cf, v5
	v_fmac_f32_e32 v41, 0x3377d1cf, v26
	v_fmac_f32_e32 v40, 0x3f317217, v5
	v_cmp_lt_f32_e64 vcc, |v5|, s63
	v_fmac_f32_e32 v41, 0x3f317217, v26
	s_nop 0
	v_cndmask_b32_e32 v5, v5, v40, vcc
	v_cmp_lt_f32_e64 vcc, |v26|, s63
	v_sub_f32_e32 v40, v5, v36
	s_nop 0
	v_cndmask_b32_e32 v26, v26, v41, vcc
	v_cmp_gt_f32_e32 vcc, s74, v51
	v_sub_f32_e32 v41, v26, v37
	v_sub_f32_e32 v26, v27, v54
	v_cndmask_b32_e64 v5, 0, 32, vcc
	v_ldexp_f32 v5, v51, v5
	v_log_f32_e32 v36, v5
	v_max_f32_e32 v5, v31, v31
	v_min_f32_e32 v5, 0, v5
	v_mul_f32_e32 v27, 0x3f317217, v36
	v_fma_f32 v27, v36, s75, -v27
	v_fmac_f32_e32 v27, 0x3377d1cf, v36
	v_fmac_f32_e32 v27, 0x3f317217, v36
	v_cmp_lt_f32_e64 s[6:7], |v36|, s63
	s_nop 1
	v_cndmask_b32_e64 v27, v36, v27, s[6:7]
	v_cndmask_b32_e32 v36, 0, v226, vcc
	v_sub_f32_e32 v27, v27, v36
	v_pk_add_f32 v[4:5], v[4:5], v[26:27] neg_lo:[0,1] neg_hi:[0,1]
	s_nop 0
	v_pk_add_f32 v[26:27], v[4:5], v[42:43]
	s_nop 0
	v_pk_add_f32 v[36:37], v[26:27], v[38:39] neg_lo:[0,1] neg_hi:[0,1]
	s_nop 0
	v_mul_f32_e64 v4, |v36|, s69
	v_exp_f32_e32 v42, v4
	v_pk_mul_f32 v[4:5], v[12:13], v[32:33]
	v_mul_f32_e64 v32, |v37|, s69
	v_pk_mul_f32 v[4:5], v[22:23], v[4:5]
	v_add_f32_e32 v13, 1.0, v42
	v_cmp_gt_f32_e32 vcc, s74, v13
	v_exp_f32_e32 v32, v32
	v_rcp_f32_e32 v12, v47
	v_cndmask_b32_e64 v22, 0, 32, vcc
	v_ldexp_f32 v13, v13, v22
	v_log_f32_e32 v23, v13
	v_max_f32_e32 v22, v26, v38
	v_add_f32_e32 v32, 1.0, v32
	v_mul_f32_e32 v26, 0x3f317217, v23
	v_fma_f32 v26, v23, s75, -v26
	v_fmac_f32_e32 v26, 0x3377d1cf, v23
	v_fmac_f32_e32 v26, 0x3f317217, v23
	v_cmp_lt_f32_e64 s[6:7], |v23|, s63
	v_rcp_f32_e32 v13, v51
	s_nop 0
	v_cndmask_b32_e64 v23, v23, v26, s[6:7]
	v_cndmask_b32_e32 v26, 0, v226, vcc
	v_cmp_gt_f32_e32 vcc, s74, v32
	v_sub_f32_e32 v26, v23, v26
	v_cndmask_b32_e64 v33, 0, 32, vcc
	v_ldexp_f32 v32, v32, v33
	v_log_f32_e32 v32, v32
	v_max_f32_e32 v23, v27, v39
	v_mul_f32_e32 v27, 0x3f317217, v32
	v_fma_f32 v27, v32, s75, -v27
	v_fmac_f32_e32 v27, 0x3377d1cf, v32
	v_fmac_f32_e32 v27, 0x3f317217, v32
	v_cmp_lt_f32_e64 s[6:7], |v32|, s63
	s_nop 1
	v_cndmask_b32_e64 v27, v32, v27, s[6:7]
	v_cndmask_b32_e32 v32, 0, v226, vcc
	v_cmp_lt_f32_e64 vcc, |v19|, s49
	v_sub_f32_e32 v27, v27, v32
	s_nop 0
	v_cndmask_b32_e32 v19, 0, v41, vcc
	v_cmp_lt_f32_e64 vcc, |v18|, s49
	s_nop 1
	v_cndmask_b32_e32 v18, 0, v40, vcc
	v_cmp_lt_f32_e64 vcc, |v37|, s49
	s_nop 1
	v_cndmask_b32_e32 v27, 0, v27, vcc
	v_cmp_lt_f32_e64 vcc, |v36|, s49
	v_pk_add_f32 v[36:37], v[8:9], v[18:19]
	s_nop 0
	v_cndmask_b32_e32 v26, 0, v26, vcc
	v_cmp_lt_f32_e32 vcc, 0, v31
	v_pk_add_f32 v[38:39], v[22:23], v[26:27]
	s_nop 0
	v_cndmask_b32_e32 v9, 1.0, v46, vcc
	v_cmp_lt_f32_e32 vcc, 0, v30
	s_nop 1
	v_cndmask_b32_e32 v8, 1.0, v45, vcc
	v_pk_mul_f32 v[8:9], v[8:9], v[34:35]
	s_nop 0
	v_pk_mul_f32 v[8:9], v[12:13], v[8:9]
	v_lshl_add_u64 v[12:13], v[52:53], 2, s[94:95]
	global_store_dwordx4 v[12:13], v[36:39], off

.LBB0_1486:
	s_add_u32 s0, s22, s0
	s_addc_u32 s1, s23, s1
	v_lshl_add_u64 v[12:13], v[52:53], 1, s[0:1]
	v_cvt_pk_bf16_f32 v4, v4, v5
	v_cvt_pk_bf16_f32 v5, v8, v9
	v_mov_b32_e32 v51, v50
	global_store_dwordx2 v[12:13], v[4:5], off
	v_pk_mul_f32 v[4:5], v[14:15], v[50:51]
	s_and_b64 vcc, exec, s[10:11]
	s_mov_b64 s[0:1], -1
	s_cbranch_vccnz .LBB0_1488
	global_load_dwordx4 v[26:29], v44, s[86:87] offset:16
	v_lshlrev_b32_e32 v18, 2, v170
	global_load_dwordx4 v[12:15], v18, s[66:67]
	global_load_dwordx4 v[30:33], v18, s[56:57]
	v_mul_f32_e64 v19, |v24|, s69
	v_mul_f32_e64 v23, |v25|, s69
	v_exp_f32_e32 v40, v19
	v_exp_f32_e32 v23, v23
	v_mul_f32_e64 v35, |v4|, s69
	v_cmp_lt_f32_e32 vcc, 0, v25
	v_max_f32_e32 v34, v25, v25
	v_exp_f32_e32 v38, v35
	v_add_f32_e32 v41, 1.0, v40
	v_cndmask_b32_e32 v35, 1.0, v23, vcc
	v_cmp_lt_f32_e32 vcc, 0, v24
	v_min_f32_e32 v19, 0, v34
	v_add_f32_e32 v42, 1.0, v23
	v_cndmask_b32_e32 v34, 1.0, v40, vcc
	v_cmp_gt_f32_e32 vcc, s74, v41
	v_cmp_gt_f32_e64 s[6:7], s74, v42
	v_max_f32_e32 v22, v24, v24
	v_cndmask_b32_e64 v23, 0, 32, vcc
	v_cndmask_b32_e64 v40, 0, 32, s[6:7]
	v_ldexp_f32 v23, v41, v23
	v_ldexp_f32 v40, v42, v40
	v_log_f32_e32 v23, v23
	v_log_f32_e32 v40, v40
	v_max_f32_e32 v36, v4, v4
	v_add_f32_e32 v43, 1.0, v38
	v_mul_f32_e32 v46, 0x3f317217, v23
	v_mul_f32_e32 v47, 0x3f317217, v40
	v_fma_f32 v46, v23, s75, -v46
	v_fma_f32 v47, v40, s75, -v47
	v_fmac_f32_e32 v46, 0x3377d1cf, v23
	v_min_f32_e32 v18, 0, v22
	v_min_f32_e32 v22, 0, v36
	v_rcp_f32_e32 v36, v41
	v_cmp_gt_f32_e64 s[8:9], s74, v43
	v_cndmask_b32_e32 v41, 0, v226, vcc
	v_fmac_f32_e32 v47, 0x3377d1cf, v40
	v_fmac_f32_e32 v46, 0x3f317217, v23
	v_cmp_lt_f32_e64 vcc, |v23|, s63
	v_mul_f32_e64 v37, |v5|, s69
	v_cndmask_b32_e64 v45, 0, 32, s[8:9]
	v_fmac_f32_e32 v47, 0x3f317217, v40
	v_cndmask_b32_e32 v23, v23, v46, vcc
	v_cmp_lt_f32_e64 vcc, |v40|, s63
	v_exp_f32_e32 v39, v37
	v_rcp_f32_e32 v37, v42
	v_ldexp_f32 v42, v43, v45
	v_cndmask_b32_e64 v45, 0, v226, s[6:7]
	v_cndmask_b32_e32 v46, v40, v47, vcc
	v_sub_f32_e32 v40, v23, v41
	v_sub_f32_e32 v41, v46, v45
	v_pk_add_f32 v[18:19], v[18:19], v[40:41] neg_lo:[0,1] neg_hi:[0,1]
	v_log_f32_e32 v42, v42
	v_or_b32_e32 v8, v48, v170
	v_mov_b32_e32 v9, v49
	v_lshl_add_u64 v[8:9], v[8:9], 2, s[94:95]
	v_mul_f32_e32 v51, 0x3f317217, v42
	v_fma_f32 v51, v42, s75, -v51
	v_fmac_f32_e32 v51, 0x3377d1cf, v42
	v_fmac_f32_e32 v51, 0x3f317217, v42
	v_cmp_lt_f32_e64 vcc, |v42|, s63
	s_mov_b64 s[0:1], 0
	s_waitcnt vmcnt(0)
	v_pk_add_f32 v[26:27], v[18:19], v[26:27]
	v_cndmask_b32_e32 v42, v42, v51, vcc
	v_pk_add_f32 v[18:19], v[26:27], v[12:13] neg_lo:[0,1] neg_hi:[0,1]
	v_max_f32_e32 v23, v12, v12
	v_mul_f32_e64 v12, |v18|, s69
	v_mul_f32_e64 v40, |v19|, s69
	v_exp_f32_e32 v41, v12
	v_exp_f32_e32 v40, v40
	v_max_f32_e32 v12, v26, v23
	v_add_f32_e32 v23, 1.0, v41
	v_add_f32_e32 v26, 1.0, v40
	v_cmp_gt_f32_e32 vcc, s74, v23
	v_max_f32_e32 v13, v27, v13
	v_cmp_gt_f32_e64 s[6:7], s74, v26
	v_cndmask_b32_e64 v27, 0, 32, vcc
	v_ldexp_f32 v23, v23, v27
	v_cndmask_b32_e64 v40, 0, 32, s[6:7]
	v_ldexp_f32 v26, v26, v40
	v_log_f32_e32 v23, v23
	v_log_f32_e32 v26, v26
	v_cndmask_b32_e32 v27, 0, v226, vcc
	v_cndmask_b32_e64 v40, 0, v226, s[6:7]
	v_mul_f32_e32 v41, 0x3f317217, v23
	v_mul_f32_e32 v45, 0x3f317217, v26
	v_fma_f32 v41, v23, s75, -v41
	v_fma_f32 v45, v26, s75, -v45
	v_fmac_f32_e32 v41, 0x3377d1cf, v23
	v_fmac_f32_e32 v45, 0x3377d1cf, v26
	v_fmac_f32_e32 v41, 0x3f317217, v23
	v_cmp_lt_f32_e64 vcc, |v23|, s63
	v_fmac_f32_e32 v45, 0x3f317217, v26
	s_nop 0
	v_cndmask_b32_e32 v23, v23, v41, vcc
	v_cmp_lt_f32_e64 vcc, |v26|, s63
	v_sub_f32_e32 v41, v23, v27
	v_cndmask_b32_e64 v23, 0, v226, s[8:9]
	v_cndmask_b32_e32 v26, v26, v45, vcc
	v_add_f32_e32 v45, 1.0, v39
	v_cmp_gt_f32_e32 vcc, s74, v45
	v_sub_f32_e32 v40, v26, v40
	s_nop 0
	v_cndmask_b32_e64 v26, 0, 32, vcc
	v_ldexp_f32 v26, v45, v26
	v_log_f32_e32 v27, v26
	v_sub_f32_e32 v26, v42, v23
	v_max_f32_e32 v23, v5, v5
	v_min_f32_e32 v23, 0, v23
	v_mul_f32_e32 v42, 0x3f317217, v27
	v_fma_f32 v42, v27, s75, -v42
	v_fmac_f32_e32 v42, 0x3377d1cf, v27
	v_fmac_f32_e32 v42, 0x3f317217, v27
	v_cmp_lt_f32_e64 s[6:7], |v27|, s63
	s_nop 1
	v_cndmask_b32_e64 v27, v27, v42, s[6:7]
	v_cndmask_b32_e32 v42, 0, v226, vcc
	v_sub_f32_e32 v27, v27, v42
	v_pk_add_f32 v[22:23], v[22:23], v[26:27] neg_lo:[0,1] neg_hi:[0,1]
	s_nop 0
	v_pk_add_f32 v[26:27], v[22:23], v[28:29]
	s_nop 0
	v_pk_add_f32 v[28:29], v[26:27], v[14:15] neg_lo:[0,1] neg_hi:[0,1]
	v_mul_f32_e64 v22, |v28|, s69
	v_exp_f32_e32 v42, v22
	v_pk_mul_f32 v[22:23], v[34:35], v[30:31]
	v_mul_f32_e64 v35, |v29|, s69
	v_exp_f32_e32 v35, v35
	v_add_f32_e32 v31, 1.0, v42
	v_cmp_gt_f32_e32 vcc, s74, v31
	v_max_f32_e32 v14, v26, v14
	v_add_f32_e32 v35, 1.0, v35
	v_cndmask_b32_e64 v34, 0, 32, vcc
	v_ldexp_f32 v31, v31, v34
	v_log_f32_e32 v34, v31
	v_pk_mul_f32 v[22:23], v[36:37], v[22:23]
	v_max_f32_e32 v15, v27, v15
	v_mul_f32_e32 v26, 0x3f317217, v34
	v_fma_f32 v26, v34, s75, -v26
	v_fmac_f32_e32 v26, 0x3377d1cf, v34
	v_fmac_f32_e32 v26, 0x3f317217, v34
	v_cmp_lt_f32_e64 s[6:7], |v34|, s63
	v_rcp_f32_e32 v30, v43
	v_rcp_f32_e32 v31, v45
	v_cndmask_b32_e64 v26, v34, v26, s[6:7]
	v_cndmask_b32_e32 v34, 0, v226, vcc
	v_cmp_gt_f32_e32 vcc, s74, v35
	v_sub_f32_e32 v26, v26, v34
	s_nop 0
	v_cndmask_b32_e64 v36, 0, 32, vcc
	v_ldexp_f32 v35, v35, v36
	v_log_f32_e32 v35, v35
	v_cndmask_b32_e32 v34, 0, v226, vcc
	v_cmp_lt_f32_e64 vcc, |v19|, s49
	v_mul_f32_e32 v27, 0x3f317217, v35
	v_fma_f32 v27, v35, s75, -v27
	v_fmac_f32_e32 v27, 0x3377d1cf, v35
	v_fmac_f32_e32 v27, 0x3f317217, v35
	v_cmp_lt_f32_e64 s[6:7], |v35|, s63
	v_cndmask_b32_e32 v19, 0, v40, vcc
	v_cmp_lt_f32_e64 vcc, |v18|, s49
	v_cndmask_b32_e64 v27, v35, v27, s[6:7]
	v_sub_f32_e32 v27, v27, v34
	v_cndmask_b32_e32 v18, 0, v41, vcc
	v_cmp_lt_f32_e64 vcc, |v29|, s49
	s_nop 1
	v_cndmask_b32_e32 v27, 0, v27, vcc
	v_cmp_lt_f32_e64 vcc, |v28|, s49
	s_nop 1
	v_cndmask_b32_e32 v26, 0, v26, vcc
	v_cmp_lt_f32_e32 vcc, 0, v5
	v_pk_add_f32 v[28:29], v[14:15], v[26:27]
	v_pk_add_f32 v[26:27], v[12:13], v[18:19]
	v_cndmask_b32_e32 v13, 1.0, v39, vcc
	v_cmp_lt_f32_e32 vcc, 0, v4
	global_store_dwordx4 v[8:9], v[26:29], off
	s_nop 0
	v_cndmask_b32_e32 v12, 1.0, v38, vcc
	v_pk_mul_f32 v[12:13], v[12:13], v[32:33]
	s_nop 0
	v_pk_mul_f32 v[12:13], v[30:31], v[12:13]

.LBB0_1490:
	s_add_u32 s0, s22, s0
	s_addc_u32 s1, s23, s1
	v_lshl_add_u64 v[4:5], v[48:49], 0, v[194:195]
	v_mov_b32_e32 v51, v50
	v_lshl_add_u64 v[8:9], v[4:5], 1, s[0:1]
	v_cvt_pk_bf16_f32 v14, v22, v23
	v_cvt_pk_bf16_f32 v15, v12, v13
	v_pk_mul_f32 v[18:19], v[10:11], v[50:51]
	s_and_b64 vcc, exec, s[10:11]
	s_mov_b64 s[0:1], -1
	global_store_dwordx2 v[8:9], v[14:15], off offset:8
	s_cbranch_vccnz .LBB0_1492
	global_load_dwordx4 v[22:25], v44, s[86:87] offset:32
	v_lshlrev_b32_e32 v8, 2, v169
	global_load_dwordx4 v[12:15], v8, s[66:67]
	s_nop 0
	global_load_dwordx4 v[8:11], v8, s[56:57]
	v_mul_f32_e64 v28, |v20|, s69
	v_exp_f32_e32 v36, v28
	v_max_f32_e32 v28, v20, v20
	v_min_f32_e32 v28, 0, v28
	v_or_b32_e32 v26, v48, v169
	v_add_f32_e32 v29, 1.0, v36
	v_cmp_gt_f32_e32 vcc, s74, v29
	v_rcp_f32_e32 v30, v29
	v_mov_b32_e32 v27, v49
	v_cndmask_b32_e64 v31, 0, 32, vcc
	v_ldexp_f32 v29, v29, v31
	v_log_f32_e32 v29, v29
	s_mov_b64 s[0:1], 0
	v_mul_f32_e32 v31, 0x3f317217, v29
	v_fma_f32 v31, v29, s75, -v31
	v_fmac_f32_e32 v31, 0x3377d1cf, v29
	v_fmac_f32_e32 v31, 0x3f317217, v29
	v_cmp_lt_f32_e64 s[6:7], |v29|, s63
	s_nop 1
	v_cndmask_b32_e64 v29, v29, v31, s[6:7]
	v_cndmask_b32_e32 v31, 0, v226, vcc
	v_sub_f32_e32 v32, v29, v31
	v_mul_f32_e64 v29, |v21|, s69
	v_exp_f32_e32 v37, v29
	v_max_f32_e32 v29, v21, v21
	v_min_f32_e32 v29, 0, v29
	v_add_f32_e32 v33, 1.0, v37
	v_cmp_gt_f32_e32 vcc, s74, v33
	v_rcp_f32_e32 v31, v33
	s_nop 0
	v_cndmask_b32_e64 v34, 0, 32, vcc
	v_ldexp_f32 v33, v33, v34
	v_log_f32_e32 v33, v33
	s_nop 0
	v_mul_f32_e32 v34, 0x3f317217, v33
	v_fma_f32 v34, v33, s75, -v34
	v_fmac_f32_e32 v34, 0x3377d1cf, v33
	v_fmac_f32_e32 v34, 0x3f317217, v33
	v_cmp_lt_f32_e64 s[6:7], |v33|, s63
	s_nop 1
	v_cndmask_b32_e64 v33, v33, v34, s[6:7]
	v_cndmask_b32_e32 v34, 0, v226, vcc
	v_sub_f32_e32 v33, v33, v34
	v_pk_add_f32 v[28:29], v[28:29], v[32:33] neg_lo:[0,1] neg_hi:[0,1]
	s_waitcnt vmcnt(0)
	v_pk_add_f32 v[32:33], v[28:29], v[22:23]
	s_nop 0
	v_pk_add_f32 v[28:29], v[32:33], v[12:13] neg_lo:[0,1] neg_hi:[0,1]
	v_max_f32_e32 v22, v12, v12
	v_mul_f32_e64 v12, |v28|, s69
	v_exp_f32_e32 v12, v12
	v_max_f32_e32 v22, v32, v22
	v_cmp_lt_f32_e64 s[8:9], |v28|, s49
	v_cmp_lt_f32_e64 s[12:13], |v29|, s49
	v_add_f32_e32 v12, 1.0, v12
	v_cmp_gt_f32_e32 vcc, s74, v12
	s_nop 1
	v_cndmask_b32_e64 v23, 0, 32, vcc
	v_ldexp_f32 v12, v12, v23
	v_log_f32_e32 v12, v12
	s_nop 0
	v_mul_f32_e32 v23, 0x3f317217, v12
	v_fma_f32 v23, v12, s75, -v23
	v_fmac_f32_e32 v23, 0x3377d1cf, v12
	v_fmac_f32_e32 v23, 0x3f317217, v12
	v_cmp_lt_f32_e64 s[6:7], |v12|, s63
	s_nop 1
	v_cndmask_b32_e64 v12, v12, v23, s[6:7]
	v_cndmask_b32_e32 v23, 0, v226, vcc
	v_sub_f32_e32 v34, v12, v23
	v_max_f32_e32 v23, v33, v13
	v_mul_f32_e64 v12, |v29|, s69
	v_exp_f32_e32 v12, v12
	s_nop 0
	v_add_f32_e32 v12, 1.0, v12
	v_cmp_gt_f32_e32 vcc, s74, v12
	s_nop 1
	v_cndmask_b32_e64 v13, 0, 32, vcc
	v_ldexp_f32 v12, v12, v13
	v_log_f32_e32 v12, v12
	s_nop 0
	v_mul_f32_e32 v13, 0x3f317217, v12
	v_fma_f32 v13, v12, s75, -v13
	v_fmac_f32_e32 v13, 0x3377d1cf, v12
	v_fmac_f32_e32 v13, 0x3f317217, v12
	v_cmp_lt_f32_e64 s[6:7], |v12|, s63
	s_nop 1
	v_cndmask_b32_e64 v12, v12, v13, s[6:7]
	v_cndmask_b32_e32 v13, 0, v226, vcc
	v_cmp_lt_f32_e32 vcc, 0, v20
	v_cmp_lt_f32_e64 s[6:7], 0, v21
	v_sub_f32_e32 v35, v12, v13
	v_cndmask_b32_e32 v12, 1.0, v36, vcc
	v_cndmask_b32_e64 v13, 1.0, v37, s[6:7]
	v_pk_mul_f32 v[8:9], v[12:13], v[8:9]
	v_mul_f32_e64 v12, |v18|, s69
	v_exp_f32_e32 v36, v12
	v_pk_mul_f32 v[8:9], v[30:31], v[8:9]
	v_max_f32_e32 v30, v18, v18
	v_min_f32_e32 v30, 0, v30
	v_add_f32_e32 v13, 1.0, v36
	v_cmp_gt_f32_e32 vcc, s74, v13
	v_rcp_f32_e32 v12, v13
	s_nop 0
	v_cndmask_b32_e64 v31, 0, 32, vcc
	v_ldexp_f32 v13, v13, v31
	v_log_f32_e32 v13, v13
	s_nop 0
	v_mul_f32_e32 v31, 0x3f317217, v13
	v_fma_f32 v31, v13, s75, -v31
	v_fmac_f32_e32 v31, 0x3377d1cf, v13
	v_fmac_f32_e32 v31, 0x3f317217, v13
	v_cmp_lt_f32_e64 s[6:7], |v13|, s63
	s_nop 1
	v_cndmask_b32_e64 v13, v13, v31, s[6:7]
	v_cndmask_b32_e32 v31, 0, v226, vcc
	v_sub_f32_e32 v32, v13, v31
	v_mul_f32_e64 v13, |v19|, s69
	v_exp_f32_e32 v37, v13
	v_max_f32_e32 v31, v19, v19
	v_min_f32_e32 v31, 0, v31
	v_add_f32_e32 v33, 1.0, v37
	v_cmp_gt_f32_e32 vcc, s74, v33
	v_rcp_f32_e32 v13, v33
	s_nop 0
	v_cndmask_b32_e64 v38, 0, 32, vcc
	v_ldexp_f32 v33, v33, v38
	v_log_f32_e32 v33, v33
	s_nop 0
	v_mul_f32_e32 v38, 0x3f317217, v33
	v_fma_f32 v38, v33, s75, -v38
	v_fmac_f32_e32 v38, 0x3377d1cf, v33
	v_fmac_f32_e32 v38, 0x3f317217, v33
	v_cmp_lt_f32_e64 s[6:7], |v33|, s63
	s_nop 1
	v_cndmask_b32_e64 v33, v33, v38, s[6:7]
	v_cndmask_b32_e32 v38, 0, v226, vcc
	v_sub_f32_e32 v33, v33, v38
	v_pk_add_f32 v[30:31], v[30:31], v[32:33] neg_lo:[0,1] neg_hi:[0,1]
	s_nop 0
	v_pk_add_f32 v[24:25], v[30:31], v[24:25]
	v_pk_add_f32 v[32:33], v[24:25], v[14:15] neg_lo:[0,1] neg_hi:[0,1]
	v_max_f32_e32 v30, v24, v14
	v_mul_f32_e64 v14, |v32|, s69
	v_exp_f32_e32 v14, v14
	s_nop 0
	v_add_f32_e32 v14, 1.0, v14
	v_cmp_gt_f32_e32 vcc, s74, v14
	s_nop 1
	v_cndmask_b32_e64 v24, 0, 32, vcc
	v_ldexp_f32 v14, v14, v24
	v_log_f32_e32 v14, v14
	s_nop 0
	v_mul_f32_e32 v24, 0x3f317217, v14
	v_fma_f32 v24, v14, s75, -v24
	v_fmac_f32_e32 v24, 0x3377d1cf, v14
	v_fmac_f32_e32 v24, 0x3f317217, v14
	v_cmp_lt_f32_e64 s[6:7], |v14|, s63
	s_nop 1
	v_cndmask_b32_e64 v14, v14, v24, s[6:7]
	v_cndmask_b32_e32 v24, 0, v226, vcc
	v_sub_f32_e32 v24, v14, v24
	v_max_f32_e32 v31, v25, v15
	v_mul_f32_e64 v14, |v33|, s69
	v_exp_f32_e32 v14, v14
	s_nop 0
	v_add_f32_e32 v14, 1.0, v14
	v_cmp_gt_f32_e32 vcc, s74, v14
	s_nop 1
	v_cndmask_b32_e64 v15, 0, 32, vcc
	v_ldexp_f32 v14, v14, v15
	v_log_f32_e32 v14, v14
	s_nop 0
	v_mul_f32_e32 v15, 0x3f317217, v14
	v_fma_f32 v15, v14, s75, -v15
	v_fmac_f32_e32 v15, 0x3377d1cf, v14
	v_fmac_f32_e32 v15, 0x3f317217, v14
	v_cmp_lt_f32_e64 s[6:7], |v14|, s63
	s_nop 1
	v_cndmask_b32_e64 v14, v14, v15, s[6:7]
	v_cndmask_b32_e32 v15, 0, v226, vcc
	v_sub_f32_e32 v25, v14, v15
	v_cmp_lt_f32_e64 vcc, |v32|, s49
	v_cmp_lt_f32_e64 s[6:7], |v33|, s49
	v_cndmask_b32_e64 v15, 0, v35, s[12:13]
	v_cndmask_b32_e64 v14, 0, v34, s[8:9]
	v_cndmask_b32_e64 v25, 0, v25, s[6:7]
	v_cndmask_b32_e32 v24, 0, v24, vcc
	v_cmp_lt_f32_e32 vcc, 0, v18
	v_cmp_lt_f32_e64 s[6:7], 0, v19
	v_pk_add_f32 v[22:23], v[22:23], v[14:15]
	v_cndmask_b32_e32 v14, 1.0, v36, vcc
	v_cndmask_b32_e64 v15, 1.0, v37, s[6:7]
	v_pk_mul_f32 v[10:11], v[14:15], v[10:11]
	v_pk_add_f32 v[24:25], v[30:31], v[24:25]
	v_pk_mul_f32 v[10:11], v[12:13], v[10:11]
	v_lshl_add_u64 v[12:13], v[26:27], 2, s[94:95]
	global_store_dwordx4 v[12:13], v[22:25], off

.LBB0_1494:
	s_add_u32 s0, s22, s0
	s_addc_u32 s1, s23, s1
	v_mov_b32_e32 v51, v50
	v_lshl_add_u64 v[4:5], v[4:5], 1, s[0:1]
	v_cvt_pk_bf16_f32 v8, v8, v9
	v_cvt_pk_bf16_f32 v9, v10, v11
	v_or_b32_e32 v48, v48, v168
	v_pk_mul_f32 v[18:19], v[6:7], v[50:51]
	s_and_b64 vcc, exec, s[10:11]
	s_mov_b64 s[0:1], -1
	global_store_dwordx2 v[4:5], v[8:9], off offset:16
	s_cbranch_vccnz .LBB0_1496
	global_load_dwordx4 v[12:15], v44, s[86:87] offset:48
	v_lshlrev_b32_e32 v4, 2, v168
	global_load_dwordx4 v[8:11], v4, s[66:67]
	s_nop 0
	global_load_dwordx4 v[4:7], v4, s[56:57]
	v_mul_f32_e64 v20, |v16|, s69
	v_exp_f32_e32 v28, v20
	v_max_f32_e32 v20, v16, v16
	v_min_f32_e32 v20, 0, v20
	s_mov_b64 s[0:1], 0
	v_add_f32_e32 v21, 1.0, v28
	v_cmp_gt_f32_e32 vcc, s74, v21
	v_rcp_f32_e32 v22, v21
	s_nop 0
	v_cndmask_b32_e64 v23, 0, 32, vcc
	v_ldexp_f32 v21, v21, v23
	v_log_f32_e32 v21, v21
	s_nop 0
	v_mul_f32_e32 v23, 0x3f317217, v21
	v_fma_f32 v23, v21, s75, -v23
	v_fmac_f32_e32 v23, 0x3377d1cf, v21
	v_fmac_f32_e32 v23, 0x3f317217, v21
	v_cmp_lt_f32_e64 s[6:7], |v21|, s63
	s_nop 1
	v_cndmask_b32_e64 v21, v21, v23, s[6:7]
	v_cndmask_b32_e32 v23, 0, v226, vcc
	v_sub_f32_e32 v24, v21, v23
	v_mul_f32_e64 v21, |v17|, s69
	v_exp_f32_e32 v29, v21
	v_max_f32_e32 v21, v17, v17
	v_min_f32_e32 v21, 0, v21
	v_add_f32_e32 v25, 1.0, v29
	v_cmp_gt_f32_e32 vcc, s74, v25
	v_rcp_f32_e32 v23, v25
	s_nop 0
	v_cndmask_b32_e64 v26, 0, 32, vcc
	v_ldexp_f32 v25, v25, v26
	v_log_f32_e32 v25, v25
	s_nop 0
	v_mul_f32_e32 v26, 0x3f317217, v25
	v_fma_f32 v26, v25, s75, -v26
	v_fmac_f32_e32 v26, 0x3377d1cf, v25
	v_fmac_f32_e32 v26, 0x3f317217, v25
	v_cmp_lt_f32_e64 s[6:7], |v25|, s63
	s_nop 1
	v_cndmask_b32_e64 v25, v25, v26, s[6:7]
	v_cndmask_b32_e32 v26, 0, v226, vcc
	v_sub_f32_e32 v25, v25, v26
	v_pk_add_f32 v[20:21], v[20:21], v[24:25] neg_lo:[0,1] neg_hi:[0,1]
	s_waitcnt vmcnt(0)
	v_pk_add_f32 v[24:25], v[20:21], v[12:13]
	s_nop 0
	v_pk_add_f32 v[20:21], v[24:25], v[8:9] neg_lo:[0,1] neg_hi:[0,1]
	v_max_f32_e32 v12, v8, v8
	v_mul_f32_e64 v8, |v20|, s69
	v_exp_f32_e32 v8, v8
	v_max_f32_e32 v12, v24, v12
	v_cmp_lt_f32_e64 s[8:9], |v20|, s49
	v_cmp_lt_f32_e64 s[10:11], |v21|, s49
	v_add_f32_e32 v8, 1.0, v8
	v_cmp_gt_f32_e32 vcc, s74, v8
	s_nop 1
	v_cndmask_b32_e64 v13, 0, 32, vcc
	v_ldexp_f32 v8, v8, v13
	v_log_f32_e32 v8, v8
	s_nop 0
	v_mul_f32_e32 v13, 0x3f317217, v8
	v_fma_f32 v13, v8, s75, -v13
	v_fmac_f32_e32 v13, 0x3377d1cf, v8
	v_fmac_f32_e32 v13, 0x3f317217, v8
	v_cmp_lt_f32_e64 s[6:7], |v8|, s63
	s_nop 1
	v_cndmask_b32_e64 v8, v8, v13, s[6:7]
	v_cndmask_b32_e32 v13, 0, v226, vcc
	v_sub_f32_e32 v26, v8, v13
	v_max_f32_e32 v13, v25, v9
	v_mul_f32_e64 v8, |v21|, s69
	v_exp_f32_e32 v8, v8
	s_nop 0
	v_add_f32_e32 v8, 1.0, v8
	v_cmp_gt_f32_e32 vcc, s74, v8
	s_nop 1
	v_cndmask_b32_e64 v9, 0, 32, vcc
	v_ldexp_f32 v8, v8, v9
	v_log_f32_e32 v8, v8
	s_nop 0
	v_mul_f32_e32 v9, 0x3f317217, v8
	v_fma_f32 v9, v8, s75, -v9
	v_fmac_f32_e32 v9, 0x3377d1cf, v8
	v_fmac_f32_e32 v9, 0x3f317217, v8
	v_cmp_lt_f32_e64 s[6:7], |v8|, s63
	s_nop 1
	v_cndmask_b32_e64 v8, v8, v9, s[6:7]
	v_cndmask_b32_e32 v9, 0, v226, vcc
	v_cmp_lt_f32_e32 vcc, 0, v16
	v_cmp_lt_f32_e64 s[6:7], 0, v17
	v_sub_f32_e32 v27, v8, v9
	v_cndmask_b32_e32 v8, 1.0, v28, vcc
	v_cndmask_b32_e64 v9, 1.0, v29, s[6:7]
	v_pk_mul_f32 v[4:5], v[8:9], v[4:5]
	v_mul_f32_e64 v8, |v18|, s69
	v_exp_f32_e32 v28, v8
	v_pk_mul_f32 v[4:5], v[22:23], v[4:5]
	v_max_f32_e32 v22, v18, v18
	v_min_f32_e32 v22, 0, v22
	v_add_f32_e32 v9, 1.0, v28
	v_cmp_gt_f32_e32 vcc, s74, v9
	v_rcp_f32_e32 v8, v9
	v_cvt_pk_bf16_f32 v4, v4, v5
	v_cndmask_b32_e64 v23, 0, 32, vcc
	v_ldexp_f32 v9, v9, v23
	v_log_f32_e32 v9, v9
	s_nop 0
	v_mul_f32_e32 v23, 0x3f317217, v9
	v_fma_f32 v23, v9, s75, -v23
	v_fmac_f32_e32 v23, 0x3377d1cf, v9
	v_fmac_f32_e32 v23, 0x3f317217, v9
	v_cmp_lt_f32_e64 s[6:7], |v9|, s63
	s_nop 1
	v_cndmask_b32_e64 v9, v9, v23, s[6:7]
	v_cndmask_b32_e32 v23, 0, v226, vcc
	v_sub_f32_e32 v24, v9, v23
	v_mul_f32_e64 v9, |v19|, s69
	v_exp_f32_e32 v29, v9
	v_max_f32_e32 v23, v19, v19
	v_min_f32_e32 v23, 0, v23
	v_add_f32_e32 v25, 1.0, v29
	v_cmp_gt_f32_e32 vcc, s74, v25
	v_rcp_f32_e32 v9, v25
	s_nop 0
	v_cndmask_b32_e64 v30, 0, 32, vcc
	v_ldexp_f32 v25, v25, v30
	v_log_f32_e32 v25, v25
	s_nop 0
	v_mul_f32_e32 v30, 0x3f317217, v25
	v_fma_f32 v30, v25, s75, -v30
	v_fmac_f32_e32 v30, 0x3377d1cf, v25
	v_fmac_f32_e32 v30, 0x3f317217, v25
	v_cmp_lt_f32_e64 s[6:7], |v25|, s63
	s_nop 1
	v_cndmask_b32_e64 v25, v25, v30, s[6:7]
	v_cndmask_b32_e32 v30, 0, v226, vcc
	v_sub_f32_e32 v25, v25, v30
	v_pk_add_f32 v[22:23], v[22:23], v[24:25] neg_lo:[0,1] neg_hi:[0,1]
	s_nop 0
	v_pk_add_f32 v[14:15], v[22:23], v[14:15]
	v_pk_add_f32 v[24:25], v[14:15], v[10:11] neg_lo:[0,1] neg_hi:[0,1]
	v_max_f32_e32 v22, v14, v10
	v_mul_f32_e64 v10, |v24|, s69
	v_exp_f32_e32 v10, v10
	s_nop 0
	v_add_f32_e32 v10, 1.0, v10
	v_cmp_gt_f32_e32 vcc, s74, v10
	s_nop 1
	v_cndmask_b32_e64 v14, 0, 32, vcc
	v_ldexp_f32 v10, v10, v14
	v_log_f32_e32 v10, v10
	s_nop 0
	v_mul_f32_e32 v14, 0x3f317217, v10
	v_fma_f32 v14, v10, s75, -v14
	v_fmac_f32_e32 v14, 0x3377d1cf, v10
	v_fmac_f32_e32 v14, 0x3f317217, v10
	v_cmp_lt_f32_e64 s[6:7], |v10|, s63
	s_nop 1
	v_cndmask_b32_e64 v10, v10, v14, s[6:7]
	v_cndmask_b32_e32 v14, 0, v226, vcc
	v_sub_f32_e32 v14, v10, v14
	v_max_f32_e32 v23, v15, v11
	v_mul_f32_e64 v10, |v25|, s69
	v_exp_f32_e32 v10, v10
	s_nop 0
	v_add_f32_e32 v10, 1.0, v10
	v_cmp_gt_f32_e32 vcc, s74, v10
	s_nop 1
	v_cndmask_b32_e64 v11, 0, 32, vcc
	v_ldexp_f32 v10, v10, v11
	v_log_f32_e32 v10, v10
	s_nop 0
	v_mul_f32_e32 v11, 0x3f317217, v10
	v_fma_f32 v11, v10, s75, -v11
	v_fmac_f32_e32 v11, 0x3377d1cf, v10
	v_fmac_f32_e32 v11, 0x3f317217, v10
	v_cmp_lt_f32_e64 s[6:7], |v10|, s63
	s_nop 1
	v_cndmask_b32_e64 v10, v10, v11, s[6:7]
	v_cndmask_b32_e32 v11, 0, v226, vcc
	v_sub_f32_e32 v15, v10, v11
	v_cmp_lt_f32_e64 vcc, |v24|, s49
	v_cmp_lt_f32_e64 s[6:7], |v25|, s49
	v_cndmask_b32_e64 v11, 0, v27, s[10:11]
	v_cndmask_b32_e64 v10, 0, v26, s[8:9]
	v_cndmask_b32_e64 v15, 0, v15, s[6:7]
	v_cndmask_b32_e32 v14, 0, v14, vcc
	v_cmp_lt_f32_e32 vcc, 0, v18
	v_cmp_lt_f32_e64 s[6:7], 0, v19
	v_pk_add_f32 v[12:13], v[12:13], v[10:11]
	v_cndmask_b32_e32 v10, 1.0, v28, vcc
	v_cndmask_b32_e64 v11, 1.0, v29, s[6:7]
	v_pk_mul_f32 v[6:7], v[10:11], v[6:7]
	v_pk_add_f32 v[14:15], v[22:23], v[14:15]
	v_pk_mul_f32 v[6:7], v[8:9], v[6:7]
	v_lshl_add_u64 v[8:9], v[48:49], 2, s[94:95]
	global_store_dwordx4 v[8:9], v[12:15], off
	v_lshl_add_u64 v[8:9], v[48:49], 1, s[84:85]
	v_cvt_pk_bf16_f32 v5, v6, v7
	global_store_dwordx2 v[8:9], v[4:5], off

.LBB0_1563:
	s_or_b64 exec, exec, s[0:1]
	s_waitcnt lgkmcnt(0)
	s_barrier
	v_pk_mul_f32 v[74:75], v[142:143], v[94:95]
	v_pk_mul_f32 v[72:73], v[140:141], v[92:93]
	v_pk_mul_f32 v[82:83], v[98:99], v[146:147]
	v_pk_mul_f32 v[80:81], v[96:97], v[144:145]
	ds_read_b128 v[108:111], v162 offset:50688
	ds_read_b128 v[112:115], v162 offset:50704
	ds_read_b128 v[116:119], v163 offset:50688
	ds_read_b128 v[120:123], v163 offset:50704
	ds_read_b128 v[140:143], v160 offset:50688
	ds_read_b128 v[144:147], v160 offset:50704
	ds_read_b128 v[164:167], v161 offset:50688
	ds_read_b128 v[180:183], v161 offset:50704
	ds_read_b128 v[184:187], v159 offset:50688
	ds_read_b128 v[188:191], v159 offset:50704
	ds_read_b128 v[228:231], v158 offset:50688
	ds_read_b128 v[232:235], v158 offset:50704
	ds_read_b128 v[236:239], v156 offset:50688
	ds_read_b128 v[240:243], v156 offset:50704
	ds_read_b128 v[244:247], v157 offset:50688
	ds_read_b128 v[248:251], v157 offset:50704
	ds_read_u16 v252, v220 offset:27648
	ds_read_u16 v253, v221 offset:27360
	ds_read_u16 v92, v221 offset:27648
	ds_read_u16 v93, v221 offset:27936
	ds_read_u16 v94, v221 offset:31680
	ds_read_u16 v95, v221 offset:31968
	ds_read_u16 v96, v221 offset:32256
	ds_read_u16 v97, v221 offset:32544
	v_pk_mul_f32 v[78:79], v[102:103], v[150:151]
	v_pk_mul_f32 v[76:77], v[100:101], v[148:149]
	v_pk_mul_f32 v[70:71], v[106:107], v[154:155]
	v_pk_mul_f32 v[68:69], v[104:105], v[152:153]
	v_pk_mul_f32 v[66:67], v[66:67], v[126:127]
	v_pk_mul_f32 v[64:65], v[64:65], v[124:125]
	v_pk_mul_f32 v[62:63], v[130:131], v[62:63]
	v_pk_mul_f32 v[60:61], v[128:129], v[60:61]
	v_pk_mul_f32 v[58:59], v[134:135], v[58:59]
	v_pk_mul_f32 v[56:57], v[132:133], v[56:57]
	v_pk_mul_f32 v[54:55], v[138:139], v[54:55]
	v_pk_mul_f32 v[52:53], v[136:137], v[52:53]
	s_waitcnt lgkmcnt(0)
	v_add_f32_e32 v0, v108, v109
	v_add_f32_e32 v1, v110, v111
	v_add_f32_e32 v0, v0, v1
	v_add_f32_e32 v1, v112, v113
	v_add_f32_e32 v0, v0, v1
	v_add_f32_e32 v1, v114, v115
	v_add_f32_e32 v0, v1, v0
	v_fmamk_f32 v0, v0, 0x3c000000, v222
	v_rsq_f32_e32 v0, v0
	v_lshlrev_b32_e32 v1, 16, v252
	v_mul_f32_e32 v0, v88, v0
	v_mul_f32_e32 v0, v0, v1
	v_bfe_u32 v1, v0, 16, 1
	v_add3_u32 v0, v0, v1, s48
	ds_write_b16_d16_hi v220, v0 offset:36864
	v_add_f32_e32 v0, v116, v117
	v_add_f32_e32 v1, v118, v119
	v_add_f32_e32 v0, v0, v1
	v_add_f32_e32 v1, v120, v121
	v_add_f32_e32 v0, v0, v1
	v_add_f32_e32 v1, v122, v123
	v_add_f32_e32 v0, v1, v0
	v_fmamk_f32 v0, v0, 0x3c000000, v222
	v_rsq_f32_e32 v0, v0
	v_lshlrev_b32_e32 v1, 16, v253
	v_mul_f32_e32 v0, v89, v0
	v_mul_f32_e32 v0, v0, v1
	v_bfe_u32 v1, v0, 16, 1
	v_add3_u32 v0, v0, v1, s48
	ds_write_b16_d16_hi v221, v0 offset:36576
	v_add_f32_e32 v0, v140, v141
	v_add_f32_e32 v1, v142, v143
	v_add_f32_e32 v0, v0, v1
	v_add_f32_e32 v1, v144, v145
	v_add_f32_e32 v0, v0, v1
	v_add_f32_e32 v1, v146, v147
	v_add_f32_e32 v0, v1, v0
	v_fmamk_f32 v0, v0, 0x3c000000, v222
	v_rsq_f32_e32 v0, v0
	v_lshlrev_b32_e32 v1, 16, v92
	v_mul_f32_e32 v0, v90, v0
	v_mul_f32_e32 v0, v0, v1
	v_bfe_u32 v1, v0, 16, 1
	v_add3_u32 v0, v0, v1, s48
	ds_write_b16_d16_hi v221, v0 offset:36864
	v_add_f32_e32 v0, v164, v165
	v_add_f32_e32 v1, v166, v167
	v_add_f32_e32 v0, v0, v1
	v_add_f32_e32 v1, v180, v181
	v_add_f32_e32 v0, v0, v1
	v_add_f32_e32 v1, v182, v183
	v_add_f32_e32 v0, v1, v0
	v_fmamk_f32 v0, v0, 0x3c000000, v222
	v_rsq_f32_e32 v0, v0
	v_lshlrev_b32_e32 v1, 16, v93
	v_mul_f32_e32 v0, v91, v0
	v_mul_f32_e32 v0, v0, v1
	v_bfe_u32 v1, v0, 16, 1
	v_add3_u32 v0, v0, v1, s48
	ds_write_b16_d16_hi v221, v0 offset:37152
	v_add_f32_e32 v0, v184, v185
	v_add_f32_e32 v1, v186, v187
	v_add_f32_e32 v0, v0, v1
	v_add_f32_e32 v1, v188, v189
	v_add_f32_e32 v0, v0, v1
	v_add_f32_e32 v1, v190, v191
	v_add_f32_e32 v0, v1, v0
	v_fmamk_f32 v0, v0, 0x3c000000, v222
	v_rsq_f32_e32 v0, v0
	v_lshlrev_b32_e32 v1, 16, v94
	v_mul_f32_e32 v0, v84, v0
	v_mul_f32_e32 v0, v0, v1
	v_bfe_u32 v1, v0, 16, 1
	v_add3_u32 v0, v0, v1, s48
	ds_write_b16_d16_hi v221, v0 offset:40896
	v_add_f32_e32 v0, v228, v229
	v_add_f32_e32 v1, v230, v231
	v_add_f32_e32 v0, v0, v1
	v_add_f32_e32 v1, v232, v233
	v_add_f32_e32 v0, v0, v1
	v_add_f32_e32 v1, v234, v235
	v_add_f32_e32 v0, v1, v0
	v_fmamk_f32 v0, v0, 0x3c000000, v222
	v_rsq_f32_e32 v0, v0
	v_lshlrev_b32_e32 v1, 16, v95
	v_mul_f32_e32 v0, v85, v0
	v_mul_f32_e32 v0, v0, v1
	v_bfe_u32 v1, v0, 16, 1
	v_add3_u32 v0, v0, v1, s48
	ds_write_b16_d16_hi v221, v0 offset:41184
	v_add_f32_e32 v0, v236, v237
	v_add_f32_e32 v1, v238, v239
	v_add_f32_e32 v0, v0, v1
	v_add_f32_e32 v1, v240, v241
	v_add_f32_e32 v0, v0, v1
	v_add_f32_e32 v1, v242, v243
	v_add_f32_e32 v0, v1, v0
	v_fmamk_f32 v0, v0, 0x3c000000, v222
	v_rsq_f32_e32 v0, v0
	v_lshlrev_b32_e32 v1, 16, v96
	v_mul_f32_e32 v0, v86, v0
	v_mul_f32_e32 v0, v0, v1
	v_bfe_u32 v1, v0, 16, 1
	v_add3_u32 v0, v0, v1, s48
	ds_write_b16_d16_hi v221, v0 offset:41472
	v_add_f32_e32 v0, v244, v245
	v_add_f32_e32 v1, v246, v247
	v_add_f32_e32 v0, v0, v1
	v_add_f32_e32 v1, v248, v249
	v_add_f32_e32 v0, v0, v1
	v_add_f32_e32 v1, v250, v251
	v_add_f32_e32 v0, v1, v0
	v_fmamk_f32 v0, v0, 0x3c000000, v222
	v_rsq_f32_e32 v0, v0
	v_lshlrev_b32_e32 v1, 16, v97
	v_mul_f32_e32 v0, v87, v0
	v_mul_f32_e32 v0, v0, v1
	v_bfe_u32 v1, v0, 16, 1
	v_add3_u32 v0, v0, v1, s48
	ds_write_b16_d16_hi v221, v0 offset:41760

.LBB0_1579:
	s_or_b64 exec, exec, s[0:1]
	v_pk_mul_f32 v[78:79], v[102:103], v[162:163]
	s_waitcnt lgkmcnt(0)
	s_barrier
	v_add_u32_e32 v162, 0, v208
	v_pk_mul_f32 v[74:75], v[154:155], v[94:95]
	v_pk_mul_f32 v[72:73], v[152:153], v[92:93]
	v_pk_mul_f32 v[82:83], v[98:99], v[158:159]
	v_pk_mul_f32 v[80:81], v[96:97], v[156:157]
	v_add_u32_e32 v163, 0, v209
	v_pk_mul_f32 v[76:77], v[100:101], v[160:161]
	v_add_u32_e32 v160, 0, v210
	v_add_u32_e32 v161, 0, v211
	v_add_u32_e32 v159, 0, v212
	v_add_u32_e32 v158, 0, v213
	v_add_u32_e32 v156, 0, v214
	v_add_u32_e32 v157, 0, v215
	ds_read_b128 v[108:111], v162 offset:50688
	ds_read_b128 v[112:115], v162 offset:50704
	ds_read_b128 v[116:119], v163 offset:50688
	ds_read_b128 v[120:123], v163 offset:50704
	ds_read_b128 v[124:127], v160 offset:50688
	ds_read_b128 v[128:131], v160 offset:50704
	ds_read_b128 v[132:135], v161 offset:50688
	ds_read_b128 v[152:155], v161 offset:50704
	ds_read_b128 v[180:183], v159 offset:50688
	ds_read_b128 v[184:187], v159 offset:50704
	ds_read_b128 v[188:191], v158 offset:50688
	ds_read_b128 v[228:231], v158 offset:50704
	ds_read_b128 v[232:235], v156 offset:50688
	ds_read_b128 v[236:239], v156 offset:50704
	ds_read_b128 v[240:243], v157 offset:50688
	ds_read_b128 v[244:247], v157 offset:50704
	ds_read_u16 v102, v220 offset:27648
	ds_read_u16 v103, v221 offset:27360
	ds_read_u16 v252, v221 offset:27648
	ds_read_u16 v253, v221 offset:27936
	ds_read_u16 v92, v221 offset:31680
	ds_read_u16 v93, v221 offset:31968
	ds_read_u16 v94, v221 offset:32256
	ds_read_u16 v95, v221 offset:32544
	v_pk_mul_f32 v[70:71], v[106:107], v[166:167]
	v_pk_mul_f32 v[68:69], v[104:105], v[164:165]
	v_pk_mul_f32 v[66:67], v[66:67], v[138:139]
	v_pk_mul_f32 v[64:65], v[64:65], v[136:137]
	v_pk_mul_f32 v[62:63], v[142:143], v[62:63]
	v_pk_mul_f32 v[60:61], v[140:141], v[60:61]
	v_pk_mul_f32 v[58:59], v[146:147], v[58:59]
	v_pk_mul_f32 v[56:57], v[144:145], v[56:57]
	v_pk_mul_f32 v[54:55], v[150:151], v[54:55]
	v_pk_mul_f32 v[52:53], v[148:149], v[52:53]
	s_cmp_gt_u32 s3, 64
	s_waitcnt lgkmcnt(0)
	v_add_f32_e32 v0, v108, v109
	v_add_f32_e32 v1, v110, v111
	v_add_f32_e32 v0, v0, v1
	v_add_f32_e32 v1, v112, v113
	v_add_f32_e32 v0, v0, v1
	v_add_f32_e32 v1, v114, v115
	v_add_f32_e32 v0, v1, v0
	v_fmamk_f32 v0, v0, 0x3c000000, v222
	v_rsq_f32_e32 v0, v0
	v_lshlrev_b32_e32 v1, 16, v102
	v_mul_f32_e32 v0, v88, v0
	v_mul_f32_e32 v0, v0, v1
	v_bfe_u32 v1, v0, 16, 1
	v_add3_u32 v0, v0, v1, s48
	ds_write_b16_d16_hi v220, v0 offset:36864
	v_add_f32_e32 v0, v116, v117
	v_add_f32_e32 v1, v118, v119
	v_add_f32_e32 v0, v0, v1
	v_add_f32_e32 v1, v120, v121
	v_add_f32_e32 v0, v0, v1
	v_add_f32_e32 v1, v122, v123
	v_add_f32_e32 v0, v1, v0
	v_fmamk_f32 v0, v0, 0x3c000000, v222
	v_rsq_f32_e32 v0, v0
	v_lshlrev_b32_e32 v1, 16, v103
	v_mul_f32_e32 v0, v89, v0
	v_mul_f32_e32 v0, v0, v1
	v_bfe_u32 v1, v0, 16, 1
	v_add3_u32 v0, v0, v1, s48
	ds_write_b16_d16_hi v221, v0 offset:36576
	v_add_f32_e32 v0, v124, v125
	v_add_f32_e32 v1, v126, v127
	v_add_f32_e32 v0, v0, v1
	v_add_f32_e32 v1, v128, v129
	v_add_f32_e32 v0, v0, v1
	v_add_f32_e32 v1, v130, v131
	v_add_f32_e32 v0, v1, v0
	v_fmamk_f32 v0, v0, 0x3c000000, v222
	v_rsq_f32_e32 v0, v0
	v_lshlrev_b32_e32 v1, 16, v252
	v_mul_f32_e32 v0, v90, v0
	v_mul_f32_e32 v0, v0, v1
	v_bfe_u32 v1, v0, 16, 1
	v_add3_u32 v0, v0, v1, s48
	ds_write_b16_d16_hi v221, v0 offset:36864
	v_add_f32_e32 v0, v132, v133
	v_add_f32_e32 v1, v134, v135
	v_add_f32_e32 v0, v0, v1
	v_add_f32_e32 v1, v152, v153
	v_add_f32_e32 v0, v0, v1
	v_add_f32_e32 v1, v154, v155
	v_add_f32_e32 v0, v1, v0
	v_fmamk_f32 v0, v0, 0x3c000000, v222
	v_rsq_f32_e32 v0, v0
	v_lshlrev_b32_e32 v1, 16, v253
	v_mul_f32_e32 v0, v91, v0
	v_mul_f32_e32 v0, v0, v1
	v_bfe_u32 v1, v0, 16, 1
	v_add3_u32 v0, v0, v1, s48
	ds_write_b16_d16_hi v221, v0 offset:37152
	v_add_f32_e32 v0, v180, v181
	v_add_f32_e32 v1, v182, v183
	v_add_f32_e32 v0, v0, v1
	v_add_f32_e32 v1, v184, v185
	v_add_f32_e32 v0, v0, v1
	v_add_f32_e32 v1, v186, v187
	v_add_f32_e32 v0, v1, v0
	v_fmamk_f32 v0, v0, 0x3c000000, v222
	v_rsq_f32_e32 v0, v0
	v_lshlrev_b32_e32 v1, 16, v92
	v_mul_f32_e32 v0, v84, v0
	v_mul_f32_e32 v0, v0, v1
	v_bfe_u32 v1, v0, 16, 1
	v_add3_u32 v0, v0, v1, s48
	ds_write_b16_d16_hi v221, v0 offset:40896
	v_add_f32_e32 v0, v188, v189
	v_add_f32_e32 v1, v190, v191
	v_add_f32_e32 v0, v0, v1
	v_add_f32_e32 v1, v228, v229
	v_add_f32_e32 v0, v0, v1
	v_add_f32_e32 v1, v230, v231
	v_add_f32_e32 v0, v1, v0
	v_fmamk_f32 v0, v0, 0x3c000000, v222
	v_rsq_f32_e32 v0, v0
	v_lshlrev_b32_e32 v1, 16, v93
	v_mul_f32_e32 v0, v85, v0
	v_mul_f32_e32 v0, v0, v1
	v_bfe_u32 v1, v0, 16, 1
	v_add3_u32 v0, v0, v1, s48
	ds_write_b16_d16_hi v221, v0 offset:41184
	v_add_f32_e32 v0, v232, v233
	v_add_f32_e32 v1, v234, v235
	v_add_f32_e32 v0, v0, v1
	v_add_f32_e32 v1, v236, v237
	v_add_f32_e32 v0, v0, v1
	v_add_f32_e32 v1, v238, v239
	v_add_f32_e32 v0, v1, v0
	v_fmamk_f32 v0, v0, 0x3c000000, v222
	v_rsq_f32_e32 v0, v0
	v_lshlrev_b32_e32 v1, 16, v94
	v_mul_f32_e32 v0, v86, v0
	v_mul_f32_e32 v0, v0, v1
	v_bfe_u32 v1, v0, 16, 1
	v_add3_u32 v0, v0, v1, s48
	ds_write_b16_d16_hi v221, v0 offset:41472
	v_add_f32_e32 v0, v240, v241
	v_add_f32_e32 v1, v242, v243
	v_add_f32_e32 v0, v0, v1
	v_add_f32_e32 v1, v244, v245
	v_add_f32_e32 v0, v0, v1
	v_add_f32_e32 v1, v246, v247
	v_add_f32_e32 v0, v1, v0
	v_fmamk_f32 v0, v0, 0x3c000000, v222
	v_rsq_f32_e32 v0, v0
	v_lshlrev_b32_e32 v1, 16, v95
	v_mul_f32_e32 v0, v87, v0
	v_mul_f32_e32 v0, v0, v1
	v_bfe_u32 v1, v0, 16, 1
	v_add3_u32 v0, v0, v1, s48
	ds_write_b16_d16_hi v221, v0 offset:41760
	s_cbranch_scc1 .LBB0_1564
	s_waitcnt vmcnt(0)
	v_add_f32_dpp v86, v47, v47 row_shr:1 row_mask:0xf bank_mask:0xf bound_ctrl:1
	v_add_f32_dpp v88, v49, v49 row_shr:1 row_mask:0xf bank_mask:0xf bound_ctrl:1
	v_add_f32_dpp v0, v44, v44 row_shr:1 row_mask:0xf bank_mask:0xf bound_ctrl:1
	v_add_f32_dpp v86, v86, v86 row_shr:2 row_mask:0xf bank_mask:0xf bound_ctrl:1
	v_add_f32_dpp v88, v88, v88 row_shr:2 row_mask:0xf bank_mask:0xf bound_ctrl:1
	v_add_f32_dpp v3, v45, v45 row_shr:1 row_mask:0xf bank_mask:0xf bound_ctrl:1
	v_add_f32_dpp v86, v86, v86 row_shr:4 row_mask:0xf bank_mask:0xf bound_ctrl:1
	v_add_f32_dpp v88, v88, v88 row_shr:4 row_mask:0xf bank_mask:0xf bound_ctrl:1
	v_add_f32_dpp v84, v46, v46 row_shr:1 row_mask:0xf bank_mask:0xf bound_ctrl:1
	v_add_f32_dpp v95, v86, v86 row_shr:8 row_mask:0xf bank_mask:0xf bound_ctrl:1
	v_add_f32_dpp v86, v48, v48 row_shr:1 row_mask:0xf bank_mask:0xf bound_ctrl:1
	v_add_f32_dpp v93, v88, v88 row_shr:8 row_mask:0xf bank_mask:0xf bound_ctrl:1
	v_add_f32_dpp v88, v50, v50 row_shr:1 row_mask:0xf bank_mask:0xf bound_ctrl:1
	v_add_f32_dpp v90, v51, v51 row_shr:1 row_mask:0xf bank_mask:0xf bound_ctrl:1
	v_add_f32_dpp v0, v0, v0 row_shr:2 row_mask:0xf bank_mask:0xf bound_ctrl:1
	v_add_f32_dpp v3, v3, v3 row_shr:2 row_mask:0xf bank_mask:0xf bound_ctrl:1
	v_add_f32_dpp v84, v84, v84 row_shr:2 row_mask:0xf bank_mask:0xf bound_ctrl:1
	v_add_f32_dpp v86, v86, v86 row_shr:2 row_mask:0xf bank_mask:0xf bound_ctrl:1
	v_add_f32_dpp v88, v88, v88 row_shr:2 row_mask:0xf bank_mask:0xf bound_ctrl:1
	v_add_f32_dpp v90, v90, v90 row_shr:2 row_mask:0xf bank_mask:0xf bound_ctrl:1
	v_add_f32_dpp v0, v0, v0 row_shr:4 row_mask:0xf bank_mask:0xf bound_ctrl:1
	v_add_f32_dpp v3, v3, v3 row_shr:4 row_mask:0xf bank_mask:0xf bound_ctrl:1
	v_add_f32_dpp v84, v84, v84 row_shr:4 row_mask:0xf bank_mask:0xf bound_ctrl:1
	v_add_f32_dpp v86, v86, v86 row_shr:4 row_mask:0xf bank_mask:0xf bound_ctrl:1
	v_add_f32_dpp v88, v88, v88 row_shr:4 row_mask:0xf bank_mask:0xf bound_ctrl:1
	v_add_f32_dpp v90, v90, v90 row_shr:4 row_mask:0xf bank_mask:0xf bound_ctrl:1
	s_waitcnt lgkmcnt(0)
	s_barrier
	s_cmp_lg_u32 s3, 1
	v_add_f32_dpp v0, v0, v0 row_shr:8 row_mask:0xf bank_mask:0xf bound_ctrl:1
	v_mov_b32_e32 v1, 0
	v_add_f32_dpp v3, v3, v3 row_shr:8 row_mask:0xf bank_mask:0xf bound_ctrl:1
	v_mov_b32_e32 v97, 0
	v_add_f32_dpp v84, v84, v84 row_shr:8 row_mask:0xf bank_mask:0xf bound_ctrl:1
	v_mov_b32_e32 v85, 0
	v_mov_b32_e32 v96, 0
	v_add_f32_dpp v86, v86, v86 row_shr:8 row_mask:0xf bank_mask:0xf bound_ctrl:1
	v_mov_b32_e32 v87, 0
	v_mov_b32_e32 v94, 0
	v_add_f32_dpp v88, v88, v88 row_shr:8 row_mask:0xf bank_mask:0xf bound_ctrl:1
	v_mov_b32_e32 v89, 0
	v_add_f32_dpp v91, v90, v90 row_shr:8 row_mask:0xf bank_mask:0xf bound_ctrl:1
	v_mov_b32_e32 v92, 0
	s_cselect_b64 s[0:1], -1, 0
	v_mov_b32_dpp v1, v0 row_bcast:15 row_mask:0xa bank_mask:0xf
	v_mov_b32_dpp v97, v3 row_bcast:15 row_mask:0xa bank_mask:0xf
	v_mov_b32_dpp v85, v84 row_bcast:15 row_mask:0xa bank_mask:0xf
	v_mov_b32_dpp v96, v95 row_bcast:15 row_mask:0xa bank_mask:0xf
	v_mov_b32_dpp v87, v86 row_bcast:15 row_mask:0xa bank_mask:0xf
	v_mov_b32_dpp v94, v93 row_bcast:15 row_mask:0xa bank_mask:0xf
	v_mov_b32_dpp v89, v88 row_bcast:15 row_mask:0xa bank_mask:0xf
	v_mov_b32_dpp v92, v91 row_bcast:15 row_mask:0xa bank_mask:0xf
	s_or_b64 s[50:51], s[52:53], s[0:1]
	s_and_saveexec_b64 s[0:1], s[50:51]
	s_cbranch_execz .LBB0_1582
	v_cndmask_b32_e64 v98, v218, v216, s[16:17]
	v_ashrrev_i32_e32 v99, 31, v98
	v_lshlrev_b64 v[98:99], 11, v[98:99]
	v_add_u32_e32 v90, v200, v172
	v_lshl_add_u64 v[102:103], v[174:175], 0, v[98:99]
	ds_read_b128 v[98:101], v90 offset:36864
	s_waitcnt lgkmcnt(0)
	global_store_dwordx4 v[102:103], v[98:101], off

.LBB0_1796:
	s_or_b64 exec, exec, s[0:1]
	s_waitcnt lgkmcnt(0)
	s_barrier
	v_pk_mul_f32 v[74:75], v[142:143], v[94:95]
	v_pk_mul_f32 v[72:73], v[140:141], v[92:93]
	v_pk_mul_f32 v[82:83], v[98:99], v[146:147]
	v_pk_mul_f32 v[80:81], v[96:97], v[144:145]
	ds_read_b128 v[108:111], v162 offset:50688
	ds_read_b128 v[112:115], v162 offset:50704
	ds_read_b128 v[116:119], v163 offset:50688
	ds_read_b128 v[120:123], v163 offset:50704
	ds_read_b128 v[140:143], v160 offset:50688
	ds_read_b128 v[144:147], v160 offset:50704
	ds_read_b128 v[164:167], v161 offset:50688
	ds_read_b128 v[180:183], v161 offset:50704
	ds_read_b128 v[184:187], v159 offset:50688
	ds_read_b128 v[188:191], v159 offset:50704
	ds_read_b128 v[216:219], v158 offset:50688
	ds_read_b128 v[228:231], v158 offset:50704
	ds_read_b128 v[232:235], v156 offset:50688
	ds_read_b128 v[236:239], v156 offset:50704
	ds_read_b128 v[240:243], v157 offset:50688
	ds_read_b128 v[244:247], v157 offset:50704
	ds_read_u16 v215, v213 offset:27648
	ds_read_u16 v220, v214 offset:27360
	ds_read_u16 v221, v214 offset:27648
	ds_read_u16 v252, v214 offset:27936
	ds_read_u16 v253, v214 offset:31680
	ds_read_u16 v92, v214 offset:31968
	ds_read_u16 v93, v214 offset:32256
	ds_read_u16 v94, v214 offset:32544
	v_pk_mul_f32 v[78:79], v[102:103], v[150:151]
	v_pk_mul_f32 v[76:77], v[100:101], v[148:149]
	v_pk_mul_f32 v[70:71], v[106:107], v[154:155]
	v_pk_mul_f32 v[68:69], v[104:105], v[152:153]
	v_pk_mul_f32 v[66:67], v[66:67], v[126:127]
	v_pk_mul_f32 v[64:65], v[64:65], v[124:125]
	v_pk_mul_f32 v[62:63], v[130:131], v[62:63]
	v_pk_mul_f32 v[60:61], v[128:129], v[60:61]
	v_pk_mul_f32 v[58:59], v[134:135], v[58:59]
	v_pk_mul_f32 v[56:57], v[132:133], v[56:57]
	v_pk_mul_f32 v[54:55], v[138:139], v[54:55]
	v_pk_mul_f32 v[52:53], v[136:137], v[52:53]
	s_waitcnt lgkmcnt(0)
	v_add_f32_e32 v0, v108, v109
	v_add_f32_e32 v1, v110, v111
	v_add_f32_e32 v0, v0, v1
	v_add_f32_e32 v1, v112, v113
	v_add_f32_e32 v0, v0, v1
	v_add_f32_e32 v1, v114, v115
	v_add_f32_e32 v0, v1, v0
	v_fmamk_f32 v0, v0, 0x3c000000, v222
	v_rsq_f32_e32 v0, v0
	v_lshlrev_b32_e32 v1, 16, v215
	v_mul_f32_e32 v0, v88, v0
	v_mul_f32_e32 v0, v0, v1
	v_bfe_u32 v1, v0, 16, 1
	v_add3_u32 v0, v0, v1, s48
	ds_write_b16_d16_hi v213, v0 offset:36864
	v_add_f32_e32 v0, v116, v117
	v_add_f32_e32 v1, v118, v119
	v_add_f32_e32 v0, v0, v1
	v_add_f32_e32 v1, v120, v121
	v_add_f32_e32 v0, v0, v1
	v_add_f32_e32 v1, v122, v123
	v_add_f32_e32 v0, v1, v0
	v_fmamk_f32 v0, v0, 0x3c000000, v222
	v_rsq_f32_e32 v0, v0
	v_lshlrev_b32_e32 v1, 16, v220
	v_mul_f32_e32 v0, v89, v0
	v_mul_f32_e32 v0, v0, v1
	v_bfe_u32 v1, v0, 16, 1
	v_add3_u32 v0, v0, v1, s48
	ds_write_b16_d16_hi v214, v0 offset:36576
	v_add_f32_e32 v0, v140, v141
	v_add_f32_e32 v1, v142, v143
	v_add_f32_e32 v0, v0, v1
	v_add_f32_e32 v1, v144, v145
	v_add_f32_e32 v0, v0, v1
	v_add_f32_e32 v1, v146, v147
	v_add_f32_e32 v0, v1, v0
	v_fmamk_f32 v0, v0, 0x3c000000, v222
	v_rsq_f32_e32 v0, v0
	v_lshlrev_b32_e32 v1, 16, v221
	v_mul_f32_e32 v0, v90, v0
	v_mul_f32_e32 v0, v0, v1
	v_bfe_u32 v1, v0, 16, 1
	v_add3_u32 v0, v0, v1, s48
	ds_write_b16_d16_hi v214, v0 offset:36864
	v_add_f32_e32 v0, v164, v165
	v_add_f32_e32 v1, v166, v167
	v_add_f32_e32 v0, v0, v1
	v_add_f32_e32 v1, v180, v181
	v_add_f32_e32 v0, v0, v1
	v_add_f32_e32 v1, v182, v183
	v_add_f32_e32 v0, v1, v0
	v_fmamk_f32 v0, v0, 0x3c000000, v222
	v_rsq_f32_e32 v0, v0
	v_lshlrev_b32_e32 v1, 16, v252
	v_mul_f32_e32 v0, v91, v0
	v_mul_f32_e32 v0, v0, v1
	v_bfe_u32 v1, v0, 16, 1
	v_add3_u32 v0, v0, v1, s48
	ds_write_b16_d16_hi v214, v0 offset:37152
	v_add_f32_e32 v0, v184, v185
	v_add_f32_e32 v1, v186, v187
	v_add_f32_e32 v0, v0, v1
	v_add_f32_e32 v1, v188, v189
	v_add_f32_e32 v0, v0, v1
	v_add_f32_e32 v1, v190, v191
	v_add_f32_e32 v0, v1, v0
	v_fmamk_f32 v0, v0, 0x3c000000, v222
	v_rsq_f32_e32 v0, v0
	v_lshlrev_b32_e32 v1, 16, v253
	v_mul_f32_e32 v0, v84, v0
	v_mul_f32_e32 v0, v0, v1
	v_bfe_u32 v1, v0, 16, 1
	v_add3_u32 v0, v0, v1, s48
	ds_write_b16_d16_hi v214, v0 offset:40896
	v_add_f32_e32 v0, v216, v217
	v_add_f32_e32 v1, v218, v219
	v_add_f32_e32 v0, v0, v1
	v_add_f32_e32 v1, v228, v229
	v_add_f32_e32 v0, v0, v1
	v_add_f32_e32 v1, v230, v231
	v_add_f32_e32 v0, v1, v0
	v_fmamk_f32 v0, v0, 0x3c000000, v222
	v_rsq_f32_e32 v0, v0
	v_lshlrev_b32_e32 v1, 16, v92
	v_mul_f32_e32 v0, v85, v0
	v_mul_f32_e32 v0, v0, v1
	v_bfe_u32 v1, v0, 16, 1
	v_add3_u32 v0, v0, v1, s48
	ds_write_b16_d16_hi v214, v0 offset:41184
	v_add_f32_e32 v0, v232, v233
	v_add_f32_e32 v1, v234, v235
	v_add_f32_e32 v0, v0, v1
	v_add_f32_e32 v1, v236, v237
	v_add_f32_e32 v0, v0, v1
	v_add_f32_e32 v1, v238, v239
	v_add_f32_e32 v0, v1, v0
	v_fmamk_f32 v0, v0, 0x3c000000, v222
	v_rsq_f32_e32 v0, v0
	v_lshlrev_b32_e32 v1, 16, v93
	v_mul_f32_e32 v0, v86, v0
	v_mul_f32_e32 v0, v0, v1
	v_bfe_u32 v1, v0, 16, 1
	v_add3_u32 v0, v0, v1, s48
	ds_write_b16_d16_hi v214, v0 offset:41472
	v_add_f32_e32 v0, v240, v241
	v_add_f32_e32 v1, v242, v243
	v_add_f32_e32 v0, v0, v1
	v_add_f32_e32 v1, v244, v245
	v_add_f32_e32 v0, v0, v1
	v_add_f32_e32 v1, v246, v247
	v_add_f32_e32 v0, v1, v0
	v_fmamk_f32 v0, v0, 0x3c000000, v222
	v_rsq_f32_e32 v0, v0
	v_lshlrev_b32_e32 v1, 16, v94
	v_mul_f32_e32 v0, v87, v0
	v_mul_f32_e32 v0, v0, v1
	v_bfe_u32 v1, v0, 16, 1
	v_add3_u32 v0, v0, v1, s48
	ds_write_b16_d16_hi v214, v0 offset:41760

.LBB0_1812:
	s_or_b64 exec, exec, s[0:1]
	v_pk_mul_f32 v[78:79], v[102:103], v[162:163]
	s_waitcnt lgkmcnt(0)
	s_barrier
	v_add_u32_e32 v162, 0, v202
	v_pk_mul_f32 v[74:75], v[154:155], v[94:95]
	v_pk_mul_f32 v[72:73], v[152:153], v[92:93]
	v_pk_mul_f32 v[82:83], v[98:99], v[158:159]
	v_pk_mul_f32 v[80:81], v[96:97], v[156:157]
	v_add_u32_e32 v163, 0, v203
	v_pk_mul_f32 v[76:77], v[100:101], v[160:161]
	v_add_u32_e32 v160, 0, v204
	v_add_u32_e32 v161, 0, v205
	v_add_u32_e32 v159, 0, v206
	v_add_u32_e32 v158, 0, v207
	v_add_u32_e32 v156, 0, v208
	v_add_u32_e32 v157, 0, v209
	ds_read_b128 v[108:111], v162 offset:50688
	ds_read_b128 v[112:115], v162 offset:50704
	ds_read_b128 v[116:119], v163 offset:50688
	ds_read_b128 v[120:123], v163 offset:50704
	ds_read_b128 v[124:127], v160 offset:50688
	ds_read_b128 v[128:131], v160 offset:50704
	ds_read_b128 v[132:135], v161 offset:50688
	ds_read_b128 v[152:155], v161 offset:50704
	ds_read_b128 v[180:183], v159 offset:50688
	ds_read_b128 v[184:187], v159 offset:50704
	ds_read_b128 v[188:191], v158 offset:50688
	ds_read_b128 v[216:219], v158 offset:50704
	ds_read_b128 v[228:231], v156 offset:50688
	ds_read_b128 v[232:235], v156 offset:50704
	ds_read_b128 v[236:239], v157 offset:50688
	ds_read_b128 v[240:243], v157 offset:50704
	ds_read_u16 v102, v213 offset:27648
	ds_read_u16 v103, v214 offset:27360
	ds_read_u16 v215, v214 offset:27648
	ds_read_u16 v220, v214 offset:27936
	ds_read_u16 v221, v214 offset:31680
	ds_read_u16 v252, v214 offset:31968
	ds_read_u16 v253, v214 offset:32256
	ds_read_u16 v92, v214 offset:32544
	v_pk_mul_f32 v[70:71], v[106:107], v[166:167]
	v_pk_mul_f32 v[68:69], v[104:105], v[164:165]
	v_pk_mul_f32 v[66:67], v[66:67], v[138:139]
	v_pk_mul_f32 v[64:65], v[64:65], v[136:137]
	v_pk_mul_f32 v[62:63], v[142:143], v[62:63]
	v_pk_mul_f32 v[60:61], v[140:141], v[60:61]
	v_pk_mul_f32 v[58:59], v[146:147], v[58:59]
	v_pk_mul_f32 v[56:57], v[144:145], v[56:57]
	v_pk_mul_f32 v[54:55], v[150:151], v[54:55]
	v_pk_mul_f32 v[52:53], v[148:149], v[52:53]
	s_cmp_gt_u32 s3, 64
	s_waitcnt lgkmcnt(0)
	v_add_f32_e32 v0, v108, v109
	v_add_f32_e32 v1, v110, v111
	v_add_f32_e32 v0, v0, v1
	v_add_f32_e32 v1, v112, v113
	v_add_f32_e32 v0, v0, v1
	v_add_f32_e32 v1, v114, v115
	v_add_f32_e32 v0, v1, v0
	v_fmamk_f32 v0, v0, 0x3c000000, v222
	v_rsq_f32_e32 v0, v0
	v_lshlrev_b32_e32 v1, 16, v102
	v_mul_f32_e32 v0, v88, v0
	v_mul_f32_e32 v0, v0, v1
	v_bfe_u32 v1, v0, 16, 1
	v_add3_u32 v0, v0, v1, s48
	ds_write_b16_d16_hi v213, v0 offset:36864
	v_add_f32_e32 v0, v116, v117
	v_add_f32_e32 v1, v118, v119
	v_add_f32_e32 v0, v0, v1
	v_add_f32_e32 v1, v120, v121
	v_add_f32_e32 v0, v0, v1
	v_add_f32_e32 v1, v122, v123
	v_add_f32_e32 v0, v1, v0
	v_fmamk_f32 v0, v0, 0x3c000000, v222
	v_rsq_f32_e32 v0, v0
	v_lshlrev_b32_e32 v1, 16, v103
	v_mul_f32_e32 v0, v89, v0
	v_mul_f32_e32 v0, v0, v1
	v_bfe_u32 v1, v0, 16, 1
	v_add3_u32 v0, v0, v1, s48
	ds_write_b16_d16_hi v214, v0 offset:36576
	v_add_f32_e32 v0, v124, v125
	v_add_f32_e32 v1, v126, v127
	v_add_f32_e32 v0, v0, v1
	v_add_f32_e32 v1, v128, v129
	v_add_f32_e32 v0, v0, v1
	v_add_f32_e32 v1, v130, v131
	v_add_f32_e32 v0, v1, v0
	v_fmamk_f32 v0, v0, 0x3c000000, v222
	v_rsq_f32_e32 v0, v0
	v_lshlrev_b32_e32 v1, 16, v215
	v_mul_f32_e32 v0, v90, v0
	v_mul_f32_e32 v0, v0, v1
	v_bfe_u32 v1, v0, 16, 1
	v_add3_u32 v0, v0, v1, s48
	ds_write_b16_d16_hi v214, v0 offset:36864
	v_add_f32_e32 v0, v132, v133
	v_add_f32_e32 v1, v134, v135
	v_add_f32_e32 v0, v0, v1
	v_add_f32_e32 v1, v152, v153
	v_add_f32_e32 v0, v0, v1
	v_add_f32_e32 v1, v154, v155
	v_add_f32_e32 v0, v1, v0
	v_fmamk_f32 v0, v0, 0x3c000000, v222
	v_rsq_f32_e32 v0, v0
	v_lshlrev_b32_e32 v1, 16, v220
	v_mul_f32_e32 v0, v91, v0
	v_mul_f32_e32 v0, v0, v1
	v_bfe_u32 v1, v0, 16, 1
	v_add3_u32 v0, v0, v1, s48
	ds_write_b16_d16_hi v214, v0 offset:37152
	v_add_f32_e32 v0, v180, v181
	v_add_f32_e32 v1, v182, v183
	v_add_f32_e32 v0, v0, v1
	v_add_f32_e32 v1, v184, v185
	v_add_f32_e32 v0, v0, v1
	v_add_f32_e32 v1, v186, v187
	v_add_f32_e32 v0, v1, v0
	v_fmamk_f32 v0, v0, 0x3c000000, v222
	v_rsq_f32_e32 v0, v0
	v_lshlrev_b32_e32 v1, 16, v221
	v_mul_f32_e32 v0, v84, v0
	v_mul_f32_e32 v0, v0, v1
	v_bfe_u32 v1, v0, 16, 1
	v_add3_u32 v0, v0, v1, s48
	ds_write_b16_d16_hi v214, v0 offset:40896
	v_add_f32_e32 v0, v188, v189
	v_add_f32_e32 v1, v190, v191
	v_add_f32_e32 v0, v0, v1
	v_add_f32_e32 v1, v216, v217
	v_add_f32_e32 v0, v0, v1
	v_add_f32_e32 v1, v218, v219
	v_add_f32_e32 v0, v1, v0
	v_fmamk_f32 v0, v0, 0x3c000000, v222
	v_rsq_f32_e32 v0, v0
	v_lshlrev_b32_e32 v1, 16, v252
	v_mul_f32_e32 v0, v85, v0
	v_mul_f32_e32 v0, v0, v1
	v_bfe_u32 v1, v0, 16, 1
	v_add3_u32 v0, v0, v1, s48
	ds_write_b16_d16_hi v214, v0 offset:41184
	v_add_f32_e32 v0, v228, v229
	v_add_f32_e32 v1, v230, v231
	v_add_f32_e32 v0, v0, v1
	v_add_f32_e32 v1, v232, v233
	v_add_f32_e32 v0, v0, v1
	v_add_f32_e32 v1, v234, v235
	v_add_f32_e32 v0, v1, v0
	v_fmamk_f32 v0, v0, 0x3c000000, v222
	v_rsq_f32_e32 v0, v0
	v_lshlrev_b32_e32 v1, 16, v253
	v_mul_f32_e32 v0, v86, v0
	v_mul_f32_e32 v0, v0, v1
	v_bfe_u32 v1, v0, 16, 1
	v_add3_u32 v0, v0, v1, s48
	ds_write_b16_d16_hi v214, v0 offset:41472
	v_add_f32_e32 v0, v236, v237
	v_add_f32_e32 v1, v238, v239
	v_add_f32_e32 v0, v0, v1
	v_add_f32_e32 v1, v240, v241
	v_add_f32_e32 v0, v0, v1
	v_add_f32_e32 v1, v242, v243
	v_add_f32_e32 v0, v1, v0
	v_fmamk_f32 v0, v0, 0x3c000000, v222
	v_rsq_f32_e32 v0, v0
	v_lshlrev_b32_e32 v1, 16, v92
	v_mul_f32_e32 v0, v87, v0
	v_mul_f32_e32 v0, v0, v1
	v_bfe_u32 v1, v0, 16, 1
	v_add3_u32 v0, v0, v1, s48
	ds_write_b16_d16_hi v214, v0 offset:41760
	s_cbranch_scc1 .LBB0_1797
	s_waitcnt vmcnt(0)
	v_add_f32_dpp v86, v51, v51 row_shr:1 row_mask:0xf bank_mask:0xf bound_ctrl:1
	v_add_f32_dpp v88, v45, v45 row_shr:1 row_mask:0xf bank_mask:0xf bound_ctrl:1
	v_add_f32_dpp v0, v48, v48 row_shr:1 row_mask:0xf bank_mask:0xf bound_ctrl:1
	v_add_f32_dpp v86, v86, v86 row_shr:2 row_mask:0xf bank_mask:0xf bound_ctrl:1
	v_add_f32_dpp v88, v88, v88 row_shr:2 row_mask:0xf bank_mask:0xf bound_ctrl:1
	v_add_f32_dpp v3, v49, v49 row_shr:1 row_mask:0xf bank_mask:0xf bound_ctrl:1
	v_add_f32_dpp v86, v86, v86 row_shr:4 row_mask:0xf bank_mask:0xf bound_ctrl:1
	v_add_f32_dpp v88, v88, v88 row_shr:4 row_mask:0xf bank_mask:0xf bound_ctrl:1
	v_add_f32_dpp v84, v50, v50 row_shr:1 row_mask:0xf bank_mask:0xf bound_ctrl:1
	v_add_f32_dpp v95, v86, v86 row_shr:8 row_mask:0xf bank_mask:0xf bound_ctrl:1
	v_add_f32_dpp v86, v44, v44 row_shr:1 row_mask:0xf bank_mask:0xf bound_ctrl:1
	v_add_f32_dpp v93, v88, v88 row_shr:8 row_mask:0xf bank_mask:0xf bound_ctrl:1
	v_add_f32_dpp v88, v46, v46 row_shr:1 row_mask:0xf bank_mask:0xf bound_ctrl:1
	v_add_f32_dpp v90, v47, v47 row_shr:1 row_mask:0xf bank_mask:0xf bound_ctrl:1
	v_add_f32_dpp v0, v0, v0 row_shr:2 row_mask:0xf bank_mask:0xf bound_ctrl:1
	v_add_f32_dpp v3, v3, v3 row_shr:2 row_mask:0xf bank_mask:0xf bound_ctrl:1
	v_add_f32_dpp v84, v84, v84 row_shr:2 row_mask:0xf bank_mask:0xf bound_ctrl:1
	v_add_f32_dpp v86, v86, v86 row_shr:2 row_mask:0xf bank_mask:0xf bound_ctrl:1
	v_add_f32_dpp v88, v88, v88 row_shr:2 row_mask:0xf bank_mask:0xf bound_ctrl:1
	v_add_f32_dpp v90, v90, v90 row_shr:2 row_mask:0xf bank_mask:0xf bound_ctrl:1
	v_add_f32_dpp v0, v0, v0 row_shr:4 row_mask:0xf bank_mask:0xf bound_ctrl:1
	v_add_f32_dpp v3, v3, v3 row_shr:4 row_mask:0xf bank_mask:0xf bound_ctrl:1
	v_add_f32_dpp v84, v84, v84 row_shr:4 row_mask:0xf bank_mask:0xf bound_ctrl:1
	v_add_f32_dpp v86, v86, v86 row_shr:4 row_mask:0xf bank_mask:0xf bound_ctrl:1
	v_add_f32_dpp v88, v88, v88 row_shr:4 row_mask:0xf bank_mask:0xf bound_ctrl:1
	v_add_f32_dpp v90, v90, v90 row_shr:4 row_mask:0xf bank_mask:0xf bound_ctrl:1
	s_waitcnt lgkmcnt(0)
	s_barrier
	s_cmp_lg_u32 s53, 0
	v_add_f32_dpp v0, v0, v0 row_shr:8 row_mask:0xf bank_mask:0xf bound_ctrl:1
	v_mov_b32_e32 v1, 0
	v_add_f32_dpp v3, v3, v3 row_shr:8 row_mask:0xf bank_mask:0xf bound_ctrl:1
	v_mov_b32_e32 v97, 0
	v_add_f32_dpp v84, v84, v84 row_shr:8 row_mask:0xf bank_mask:0xf bound_ctrl:1
	v_mov_b32_e32 v85, 0
	v_mov_b32_e32 v96, 0
	v_add_f32_dpp v86, v86, v86 row_shr:8 row_mask:0xf bank_mask:0xf bound_ctrl:1
	v_mov_b32_e32 v87, 0
	v_mov_b32_e32 v94, 0
	v_add_f32_dpp v88, v88, v88 row_shr:8 row_mask:0xf bank_mask:0xf bound_ctrl:1
	v_mov_b32_e32 v89, 0
	v_add_f32_dpp v91, v90, v90 row_shr:8 row_mask:0xf bank_mask:0xf bound_ctrl:1
	v_mov_b32_e32 v92, 0
	s_cselect_b64 s[0:1], -1, 0
	v_mov_b32_dpp v1, v0 row_bcast:15 row_mask:0xa bank_mask:0xf
	v_mov_b32_dpp v97, v3 row_bcast:15 row_mask:0xa bank_mask:0xf
	v_mov_b32_dpp v85, v84 row_bcast:15 row_mask:0xa bank_mask:0xf
	v_mov_b32_dpp v96, v95 row_bcast:15 row_mask:0xa bank_mask:0xf
	v_mov_b32_dpp v87, v86 row_bcast:15 row_mask:0xa bank_mask:0xf
	v_mov_b32_dpp v94, v93 row_bcast:15 row_mask:0xa bank_mask:0xf
	v_mov_b32_dpp v89, v88 row_bcast:15 row_mask:0xa bank_mask:0xf
	v_mov_b32_dpp v92, v91 row_bcast:15 row_mask:0xa bank_mask:0xf
	s_or_b64 s[50:51], s[18:19], s[0:1]
	s_and_saveexec_b64 s[0:1], s[50:51]
	s_cbranch_execz .LBB0_1815
	v_add_u32_e32 v90, s53, v210
	v_subrev_u32_e32 v90, 32, v90
	v_cndmask_b32_e64 v98, v90, v211, s[16:17]
	v_ashrrev_i32_e32 v99, 31, v98
	v_lshlrev_b64 v[98:99], 11, v[98:99]
	v_add_u32_e32 v90, v173, v176
	v_lshl_add_u64 v[102:103], v[178:179], 0, v[98:99]
	ds_read_b128 v[98:101], v90 offset:36864
	s_waitcnt lgkmcnt(0)
	global_store_dwordx4 v[102:103], v[98:101], off
